# removed the redundant compiler s_waitcnt lgkmcnt(0) at the head of every MFMA block (the inline-asm wait before the barrier already covers it; 78 sites); on top of v022
# speedup vs baseline: 1.0047x; 1.0047x over previous
.LBB0_183:
	s_ashr_i32 s13, s12, 31
	s_lshl_b64 s[24:25], s[12:13], 19
	s_add_u32 s24, s80, s24
	s_addc_u32 s25, s81, s25
	s_and_b64 s[30:31], s[4:5], exec
	s_cselect_b32 s13, s25, s45
	s_cselect_b32 s66, s24, s44
	s_ashr_i32 s11, s10, 31
	s_lshl_b64 s[30:31], s[10:11], 19
	s_add_u32 s30, s52, s30
	s_addc_u32 s31, s53, s31
	s_and_b64 s[48:49], s[4:5], exec
	s_cselect_b32 s11, s31, s47
	s_cselect_b32 s67, s30, s46
	s_add_u32 s44, s44, 0x40080
	s_addc_u32 s45, s45, 0
	s_add_u32 s68, s46, 0x100
	s_addc_u32 s69, s47, 0
	s_mov_b32 s70, -2
	ds_read_b128 v[140:143], v147
	ds_read_b128 v[150:153], v147 offset:1024
	ds_read_b128 v[154:157], v147 offset:2048
	ds_read_b128 v[158:161], v147 offset:3072
	ds_read_b128 v[162:165], v148
	ds_read_b128 v[166:169], v148 offset:1024
	ds_read_b128 v[170:173], v148 offset:2048
	ds_read_b128 v[174:177], v148 offset:3072
	s_add_u32 s18, s44, 0xfffc0080
	s_addc_u32 s19, s45, -1
	s_cmp_eq_u32 s70, 12
	s_cselect_b32 s49, s13, s19
	s_cselect_b32 s48, s66, s18
	s_cselect_b32 s47, s11, s69
	s_cselect_b32 s46, s67, s68
	v_lshl_add_u64 v[178:179], s[44:45], 0, v[132:133]
	s_add_i32 m0, s37, 0xc000
	ds_read_b128 v[184:187], v149
	ds_read_b128 v[188:191], v149 offset:1024
	ds_read_b128 v[192:195], v149 offset:2048
	ds_read_b128 v[196:199], v149 offset:3072
	ds_read_b128 v[200:203], v149 offset:4096
	ds_read_b128 v[204:207], v149 offset:5120
	ds_read_b128 v[208:211], v149 offset:6144
	ds_read_b128 v[212:215], v149 offset:7168
	global_load_lds_dwordx4 v[178:179], off
	v_lshl_add_u64 v[178:179], s[44:45], 0, v[134:135]
	s_add_i32 m0, s37, 0xe000
	s_nop 0
	global_load_lds_dwordx4 v[178:179], off
	s_waitcnt vmcnt(8)
	s_waitcnt lgkmcnt(0)
	s_barrier
	s_setprio 1
	v_mfma_f32_16x16x32_bf16 v[124:127], v[140:143], v[184:187], 0
	v_mfma_f32_16x16x32_bf16 v[124:127], v[150:153], v[188:191], v[124:127]
	v_mfma_f32_16x16x32_bf16 v[120:123], v[154:157], v[184:187], 0
	v_mfma_f32_16x16x32_bf16 v[120:123], v[158:161], v[188:191], v[120:123]
	v_mfma_f32_16x16x32_bf16 v[108:111], v[140:143], v[192:195], 0
	v_mfma_f32_16x16x32_bf16 v[108:111], v[150:153], v[196:199], v[108:111]
	v_mfma_f32_16x16x32_bf16 v[104:107], v[154:157], v[192:195], 0
	v_mfma_f32_16x16x32_bf16 v[104:107], v[158:161], v[196:199], v[104:107]
	v_mfma_f32_16x16x32_bf16 v[92:95], v[140:143], v[200:203], 0
	v_mfma_f32_16x16x32_bf16 v[92:95], v[150:153], v[204:207], v[92:95]
	v_mfma_f32_16x16x32_bf16 v[88:91], v[154:157], v[200:203], 0
	v_mfma_f32_16x16x32_bf16 v[88:91], v[158:161], v[204:207], v[88:91]
	v_mfma_f32_16x16x32_bf16 v[76:79], v[140:143], v[208:211], 0
	v_mfma_f32_16x16x32_bf16 v[76:79], v[150:153], v[212:215], v[76:79]
	v_mfma_f32_16x16x32_bf16 v[72:75], v[154:157], v[208:211], 0
	v_mfma_f32_16x16x32_bf16 v[72:75], v[158:161], v[212:215], v[72:75]
	v_mfma_f32_16x16x32_bf16 v[116:119], v[162:165], v[184:187], 0
	v_mfma_f32_16x16x32_bf16 v[116:119], v[166:169], v[188:191], v[116:119]
	v_mfma_f32_16x16x32_bf16 v[112:115], v[170:173], v[184:187], 0
	v_mfma_f32_16x16x32_bf16 v[112:115], v[174:177], v[188:191], v[112:115]
	v_mfma_f32_16x16x32_bf16 v[100:103], v[162:165], v[192:195], 0
	v_mfma_f32_16x16x32_bf16 v[100:103], v[166:169], v[196:199], v[100:103]
	v_mfma_f32_16x16x32_bf16 v[96:99], v[170:173], v[192:195], 0
	v_mfma_f32_16x16x32_bf16 v[96:99], v[174:177], v[196:199], v[96:99]
	v_mfma_f32_16x16x32_bf16 v[84:87], v[162:165], v[200:203], 0
	v_mfma_f32_16x16x32_bf16 v[84:87], v[166:169], v[204:207], v[84:87]
	v_mfma_f32_16x16x32_bf16 v[80:83], v[170:173], v[200:203], 0
	v_mfma_f32_16x16x32_bf16 v[80:83], v[174:177], v[204:207], v[80:83]
	v_mfma_f32_16x16x32_bf16 v[68:71], v[162:165], v[208:211], 0
	v_mfma_f32_16x16x32_bf16 v[68:71], v[166:169], v[212:215], v[68:71]
	v_mfma_f32_16x16x32_bf16 v[64:67], v[170:173], v[208:211], 0
	v_mfma_f32_16x16x32_bf16 v[64:67], v[174:177], v[212:215], v[64:67]
	s_setprio 0
	s_barrier
	s_add_i32 s18, s62, s54
	v_lshl_add_u64 v[178:179], s[46:47], 0, v[130:131]
	s_mov_b32 m0, s18
	ds_read_b128 v[184:187], v149 offset:16384
	ds_read_b128 v[188:191], v149 offset:17408
	ds_read_b128 v[192:195], v149 offset:18432
	ds_read_b128 v[196:199], v149 offset:19456
	ds_read_b128 v[200:203], v149 offset:20480
	ds_read_b128 v[204:207], v149 offset:21504
	ds_read_b128 v[208:211], v149 offset:22528
	ds_read_b128 v[212:215], v149 offset:23552
	global_load_lds_dwordx4 v[178:179], off
	s_add_i32 m0, s18, 0x2000
	s_add_u32 s72, s46, 0x40000
	v_lshl_add_u64 v[216:217], s[46:47], 0, v[128:129]
	s_addc_u32 s73, s47, 0
	s_add_i32 s18, s63, s54
	global_load_lds_dwordx4 v[216:217], off
	v_lshl_add_u64 v[218:219], s[72:73], 0, v[130:131]
	s_mov_b32 m0, s18
	v_lshl_add_u64 v[220:221], s[48:49], 0, v[128:129]
	global_load_lds_dwordx4 v[218:219], off
	v_lshl_add_u64 v[218:219], s[72:73], 0, v[128:129]
	s_add_i32 m0, s18, 0x2000
	s_nop 0
	global_load_lds_dwordx4 v[218:219], off
	v_lshl_add_u64 v[218:219], s[48:49], 0, v[130:131]
	s_mov_b32 m0, s37
	s_nop 0
	global_load_lds_dwordx4 v[218:219], off
	s_mov_b32 m0, s56
	s_nop 0
	global_load_lds_dwordx4 v[220:221], off
	s_waitcnt vmcnt(8)
	s_waitcnt lgkmcnt(0)
	s_barrier
	s_setprio 1
	v_mfma_f32_16x16x32_bf16 v[60:63], v[140:143], v[184:187], 0
	v_mfma_f32_16x16x32_bf16 v[60:63], v[150:153], v[188:191], v[60:63]
	v_mfma_f32_16x16x32_bf16 v[56:59], v[154:157], v[184:187], 0
	v_mfma_f32_16x16x32_bf16 v[56:59], v[158:161], v[188:191], v[56:59]
	v_mfma_f32_16x16x32_bf16 v[44:47], v[140:143], v[192:195], 0
	v_mfma_f32_16x16x32_bf16 v[44:47], v[150:153], v[196:199], v[44:47]
	v_mfma_f32_16x16x32_bf16 v[40:43], v[154:157], v[192:195], 0
	v_mfma_f32_16x16x32_bf16 v[40:43], v[158:161], v[196:199], v[40:43]
	v_mfma_f32_16x16x32_bf16 v[28:31], v[140:143], v[200:203], 0
	v_mfma_f32_16x16x32_bf16 v[28:31], v[150:153], v[204:207], v[28:31]
	v_mfma_f32_16x16x32_bf16 v[24:27], v[154:157], v[200:203], 0
	v_mfma_f32_16x16x32_bf16 v[24:27], v[158:161], v[204:207], v[24:27]
	v_mfma_f32_16x16x32_bf16 v[12:15], v[140:143], v[208:211], 0
	v_mfma_f32_16x16x32_bf16 v[12:15], v[150:153], v[212:215], v[12:15]
	v_mfma_f32_16x16x32_bf16 v[8:11], v[154:157], v[208:211], 0
	v_mfma_f32_16x16x32_bf16 v[8:11], v[158:161], v[212:215], v[8:11]
	v_mfma_f32_16x16x32_bf16 v[52:55], v[162:165], v[184:187], 0
	v_mfma_f32_16x16x32_bf16 v[52:55], v[166:169], v[188:191], v[52:55]
	v_mfma_f32_16x16x32_bf16 v[48:51], v[170:173], v[184:187], 0
	v_mfma_f32_16x16x32_bf16 v[48:51], v[174:177], v[188:191], v[48:51]
	v_mfma_f32_16x16x32_bf16 v[36:39], v[162:165], v[192:195], 0
	v_mfma_f32_16x16x32_bf16 v[36:39], v[166:169], v[196:199], v[36:39]
	v_mfma_f32_16x16x32_bf16 v[32:35], v[170:173], v[192:195], 0
	v_mfma_f32_16x16x32_bf16 v[32:35], v[174:177], v[196:199], v[32:35]
	v_mfma_f32_16x16x32_bf16 v[20:23], v[162:165], v[200:203], 0
	v_mfma_f32_16x16x32_bf16 v[20:23], v[166:169], v[204:207], v[20:23]
	v_mfma_f32_16x16x32_bf16 v[16:19], v[170:173], v[200:203], 0
	v_mfma_f32_16x16x32_bf16 v[16:19], v[174:177], v[204:207], v[16:19]
	v_mfma_f32_16x16x32_bf16 v[4:7], v[162:165], v[208:211], 0
	v_mfma_f32_16x16x32_bf16 v[4:7], v[166:169], v[212:215], v[4:7]
	v_mfma_f32_16x16x32_bf16 v[0:3], v[170:173], v[208:211], 0
	v_mfma_f32_16x16x32_bf16 v[0:3], v[174:177], v[212:215], v[0:3]
	s_setprio 0
	s_barrier
	s_branch .Lmid_gemm0
.LBB0_184:
	ds_read_b128 v[140:143], v147
	ds_read_b128 v[150:153], v147 offset:1024
	ds_read_b128 v[154:157], v147 offset:2048
	ds_read_b128 v[158:161], v147 offset:3072
	ds_read_b128 v[162:165], v148
	ds_read_b128 v[166:169], v148 offset:1024
	ds_read_b128 v[170:173], v148 offset:2048
	ds_read_b128 v[174:177], v148 offset:3072
	s_add_u32 s18, s44, 0xfffc0080
	s_addc_u32 s19, s45, -1
	s_cmp_eq_u32 s70, 12
	s_cselect_b32 s49, s13, s19
	s_cselect_b32 s48, s66, s18
	s_cselect_b32 s47, s11, s69
	s_cselect_b32 s46, s67, s68
	v_lshl_add_u64 v[178:179], s[44:45], 0, v[132:133]
	s_add_i32 m0, s37, 0xc000
	ds_read_b128 v[184:187], v149
	ds_read_b128 v[188:191], v149 offset:1024
	ds_read_b128 v[192:195], v149 offset:2048
	ds_read_b128 v[196:199], v149 offset:3072
	ds_read_b128 v[200:203], v149 offset:4096
	ds_read_b128 v[204:207], v149 offset:5120
	ds_read_b128 v[208:211], v149 offset:6144
	ds_read_b128 v[212:215], v149 offset:7168
	global_load_lds_dwordx4 v[178:179], off
	v_lshl_add_u64 v[178:179], s[44:45], 0, v[134:135]
	s_add_i32 m0, s37, 0xe000
	s_nop 0
	global_load_lds_dwordx4 v[178:179], off
	s_waitcnt vmcnt(8)
	s_waitcnt lgkmcnt(0)
	s_barrier
	s_setprio 1
	v_mfma_f32_16x16x32_bf16 v[124:127], v[140:143], v[184:187], v[124:127]
	v_mfma_f32_16x16x32_bf16 v[124:127], v[150:153], v[188:191], v[124:127]
	v_mfma_f32_16x16x32_bf16 v[120:123], v[154:157], v[184:187], v[120:123]
	v_mfma_f32_16x16x32_bf16 v[120:123], v[158:161], v[188:191], v[120:123]
	v_mfma_f32_16x16x32_bf16 v[108:111], v[140:143], v[192:195], v[108:111]
	v_mfma_f32_16x16x32_bf16 v[108:111], v[150:153], v[196:199], v[108:111]
	v_mfma_f32_16x16x32_bf16 v[104:107], v[154:157], v[192:195], v[104:107]
	v_mfma_f32_16x16x32_bf16 v[104:107], v[158:161], v[196:199], v[104:107]
	v_mfma_f32_16x16x32_bf16 v[92:95], v[140:143], v[200:203], v[92:95]
	v_mfma_f32_16x16x32_bf16 v[92:95], v[150:153], v[204:207], v[92:95]
	v_mfma_f32_16x16x32_bf16 v[88:91], v[154:157], v[200:203], v[88:91]
	v_mfma_f32_16x16x32_bf16 v[88:91], v[158:161], v[204:207], v[88:91]
	v_mfma_f32_16x16x32_bf16 v[76:79], v[140:143], v[208:211], v[76:79]
	v_mfma_f32_16x16x32_bf16 v[76:79], v[150:153], v[212:215], v[76:79]
	v_mfma_f32_16x16x32_bf16 v[72:75], v[154:157], v[208:211], v[72:75]
	v_mfma_f32_16x16x32_bf16 v[72:75], v[158:161], v[212:215], v[72:75]
	v_mfma_f32_16x16x32_bf16 v[116:119], v[162:165], v[184:187], v[116:119]
	v_mfma_f32_16x16x32_bf16 v[116:119], v[166:169], v[188:191], v[116:119]
	v_mfma_f32_16x16x32_bf16 v[112:115], v[170:173], v[184:187], v[112:115]
	v_mfma_f32_16x16x32_bf16 v[112:115], v[174:177], v[188:191], v[112:115]
	v_mfma_f32_16x16x32_bf16 v[100:103], v[162:165], v[192:195], v[100:103]
	v_mfma_f32_16x16x32_bf16 v[100:103], v[166:169], v[196:199], v[100:103]
	v_mfma_f32_16x16x32_bf16 v[96:99], v[170:173], v[192:195], v[96:99]
	v_mfma_f32_16x16x32_bf16 v[96:99], v[174:177], v[196:199], v[96:99]
	v_mfma_f32_16x16x32_bf16 v[84:87], v[162:165], v[200:203], v[84:87]
	v_mfma_f32_16x16x32_bf16 v[84:87], v[166:169], v[204:207], v[84:87]
	v_mfma_f32_16x16x32_bf16 v[80:83], v[170:173], v[200:203], v[80:83]
	v_mfma_f32_16x16x32_bf16 v[80:83], v[174:177], v[204:207], v[80:83]
	v_mfma_f32_16x16x32_bf16 v[68:71], v[162:165], v[208:211], v[68:71]
	v_mfma_f32_16x16x32_bf16 v[68:71], v[166:169], v[212:215], v[68:71]
	v_mfma_f32_16x16x32_bf16 v[64:67], v[170:173], v[208:211], v[64:67]
	v_mfma_f32_16x16x32_bf16 v[64:67], v[174:177], v[212:215], v[64:67]
	s_setprio 0
	s_barrier
	s_add_i32 s18, s62, s54
	v_lshl_add_u64 v[178:179], s[46:47], 0, v[130:131]
	s_mov_b32 m0, s18
	ds_read_b128 v[184:187], v149 offset:16384
	ds_read_b128 v[188:191], v149 offset:17408
	ds_read_b128 v[192:195], v149 offset:18432
	ds_read_b128 v[196:199], v149 offset:19456
	ds_read_b128 v[200:203], v149 offset:20480
	ds_read_b128 v[204:207], v149 offset:21504
	ds_read_b128 v[208:211], v149 offset:22528
	ds_read_b128 v[212:215], v149 offset:23552
	global_load_lds_dwordx4 v[178:179], off
	s_add_i32 m0, s18, 0x2000
	s_add_u32 s72, s46, 0x40000
	v_lshl_add_u64 v[216:217], s[46:47], 0, v[128:129]
	s_addc_u32 s73, s47, 0
	s_add_i32 s18, s63, s54
	global_load_lds_dwordx4 v[216:217], off
	v_lshl_add_u64 v[218:219], s[72:73], 0, v[130:131]
	s_mov_b32 m0, s18
	v_lshl_add_u64 v[220:221], s[48:49], 0, v[128:129]
	global_load_lds_dwordx4 v[218:219], off
	v_lshl_add_u64 v[218:219], s[72:73], 0, v[128:129]
	s_add_i32 m0, s18, 0x2000
	s_nop 0
	global_load_lds_dwordx4 v[218:219], off
	v_lshl_add_u64 v[218:219], s[48:49], 0, v[130:131]
	s_mov_b32 m0, s37
	s_nop 0
	global_load_lds_dwordx4 v[218:219], off
	s_mov_b32 m0, s56
	s_nop 0
	global_load_lds_dwordx4 v[220:221], off
	s_waitcnt vmcnt(8)
	s_waitcnt lgkmcnt(0)
	s_barrier
	s_setprio 1
	v_mfma_f32_16x16x32_bf16 v[60:63], v[140:143], v[184:187], v[60:63]
	v_mfma_f32_16x16x32_bf16 v[60:63], v[150:153], v[188:191], v[60:63]
	v_mfma_f32_16x16x32_bf16 v[56:59], v[154:157], v[184:187], v[56:59]
	v_mfma_f32_16x16x32_bf16 v[56:59], v[158:161], v[188:191], v[56:59]
	v_mfma_f32_16x16x32_bf16 v[44:47], v[140:143], v[192:195], v[44:47]
	v_mfma_f32_16x16x32_bf16 v[44:47], v[150:153], v[196:199], v[44:47]
	v_mfma_f32_16x16x32_bf16 v[40:43], v[154:157], v[192:195], v[40:43]
	v_mfma_f32_16x16x32_bf16 v[40:43], v[158:161], v[196:199], v[40:43]
	v_mfma_f32_16x16x32_bf16 v[28:31], v[140:143], v[200:203], v[28:31]
	v_mfma_f32_16x16x32_bf16 v[28:31], v[150:153], v[204:207], v[28:31]
	v_mfma_f32_16x16x32_bf16 v[24:27], v[154:157], v[200:203], v[24:27]
	v_mfma_f32_16x16x32_bf16 v[24:27], v[158:161], v[204:207], v[24:27]
	v_mfma_f32_16x16x32_bf16 v[12:15], v[140:143], v[208:211], v[12:15]
	v_mfma_f32_16x16x32_bf16 v[12:15], v[150:153], v[212:215], v[12:15]
	v_mfma_f32_16x16x32_bf16 v[8:11], v[154:157], v[208:211], v[8:11]
	v_mfma_f32_16x16x32_bf16 v[8:11], v[158:161], v[212:215], v[8:11]
	v_mfma_f32_16x16x32_bf16 v[52:55], v[162:165], v[184:187], v[52:55]
	v_mfma_f32_16x16x32_bf16 v[52:55], v[166:169], v[188:191], v[52:55]
	v_mfma_f32_16x16x32_bf16 v[48:51], v[170:173], v[184:187], v[48:51]
	v_mfma_f32_16x16x32_bf16 v[48:51], v[174:177], v[188:191], v[48:51]
	v_mfma_f32_16x16x32_bf16 v[36:39], v[162:165], v[192:195], v[36:39]
	v_mfma_f32_16x16x32_bf16 v[36:39], v[166:169], v[196:199], v[36:39]
	v_mfma_f32_16x16x32_bf16 v[32:35], v[170:173], v[192:195], v[32:35]
	v_mfma_f32_16x16x32_bf16 v[32:35], v[174:177], v[196:199], v[32:35]
	v_mfma_f32_16x16x32_bf16 v[20:23], v[162:165], v[200:203], v[20:23]
	v_mfma_f32_16x16x32_bf16 v[20:23], v[166:169], v[204:207], v[20:23]
	v_mfma_f32_16x16x32_bf16 v[16:19], v[170:173], v[200:203], v[16:19]
	v_mfma_f32_16x16x32_bf16 v[16:19], v[174:177], v[204:207], v[16:19]
	v_mfma_f32_16x16x32_bf16 v[4:7], v[162:165], v[208:211], v[4:7]
	v_mfma_f32_16x16x32_bf16 v[4:7], v[166:169], v[212:215], v[4:7]
	v_mfma_f32_16x16x32_bf16 v[0:3], v[170:173], v[208:211], v[0:3]
	v_mfma_f32_16x16x32_bf16 v[0:3], v[174:177], v[212:215], v[0:3]
	s_setprio 0
	s_barrier
.Lmid_gemm0:
	s_add_i32 s18, 0, 0x18000
	s_add_i32 s19, 0, 0x1c000
	v_add_u32_e32 v158, s18, v145
	v_add_u32_e32 v174, s19, v145
	ds_read_b128 v[140:143], v158
	ds_read_b128 v[150:153], v158 offset:1024
	ds_read_b128 v[154:157], v158 offset:2048
	ds_read_b128 v[158:161], v158 offset:3072
	ds_read_b128 v[162:165], v174
	ds_read_b128 v[166:169], v174 offset:1024
	ds_read_b128 v[170:173], v174 offset:2048
	ds_read_b128 v[174:177], v174 offset:3072
	s_add_u32 s48, s48, 0x40000
	s_addc_u32 s49, s49, 0
	s_mov_b32 m0, s57
	v_lshl_add_u64 v[222:223], s[48:49], 0, v[130:131]
	ds_read_b128 v[184:187], v149 offset:32768
	ds_read_b128 v[188:191], v149 offset:33792
	ds_read_b128 v[192:195], v149 offset:34816
	ds_read_b128 v[196:199], v149 offset:35840
	ds_read_b128 v[200:203], v149 offset:36864
	ds_read_b128 v[204:207], v149 offset:37888
	ds_read_b128 v[208:211], v149 offset:38912
	ds_read_b128 v[212:215], v149 offset:39936
	global_load_lds_dwordx4 v[222:223], off
	v_lshl_add_u64 v[222:223], s[48:49], 0, v[128:129]
	s_mov_b32 m0, s58
	s_nop 0
	global_load_lds_dwordx4 v[222:223], off
	s_waitcnt vmcnt(8)
	s_waitcnt lgkmcnt(0)
	s_barrier
	s_setprio 1
	v_mfma_f32_16x16x32_bf16 v[124:127], v[140:143], v[184:187], v[124:127]
	v_mfma_f32_16x16x32_bf16 v[124:127], v[150:153], v[188:191], v[124:127]
	v_mfma_f32_16x16x32_bf16 v[120:123], v[154:157], v[184:187], v[120:123]
	v_mfma_f32_16x16x32_bf16 v[120:123], v[158:161], v[188:191], v[120:123]
	v_mfma_f32_16x16x32_bf16 v[108:111], v[140:143], v[192:195], v[108:111]
	v_mfma_f32_16x16x32_bf16 v[108:111], v[150:153], v[196:199], v[108:111]
	v_mfma_f32_16x16x32_bf16 v[104:107], v[154:157], v[192:195], v[104:107]
	v_mfma_f32_16x16x32_bf16 v[104:107], v[158:161], v[196:199], v[104:107]
	v_mfma_f32_16x16x32_bf16 v[92:95], v[140:143], v[200:203], v[92:95]
	v_mfma_f32_16x16x32_bf16 v[92:95], v[150:153], v[204:207], v[92:95]
	v_mfma_f32_16x16x32_bf16 v[88:91], v[154:157], v[200:203], v[88:91]
	v_mfma_f32_16x16x32_bf16 v[88:91], v[158:161], v[204:207], v[88:91]
	v_mfma_f32_16x16x32_bf16 v[76:79], v[140:143], v[208:211], v[76:79]
	v_mfma_f32_16x16x32_bf16 v[76:79], v[150:153], v[212:215], v[76:79]
	v_mfma_f32_16x16x32_bf16 v[72:75], v[154:157], v[208:211], v[72:75]
	v_mfma_f32_16x16x32_bf16 v[72:75], v[158:161], v[212:215], v[72:75]
	v_mfma_f32_16x16x32_bf16 v[116:119], v[162:165], v[184:187], v[116:119]
	v_mfma_f32_16x16x32_bf16 v[116:119], v[166:169], v[188:191], v[116:119]
	v_mfma_f32_16x16x32_bf16 v[112:115], v[170:173], v[184:187], v[112:115]
	v_mfma_f32_16x16x32_bf16 v[112:115], v[174:177], v[188:191], v[112:115]
	v_mfma_f32_16x16x32_bf16 v[100:103], v[162:165], v[192:195], v[100:103]
	v_mfma_f32_16x16x32_bf16 v[100:103], v[166:169], v[196:199], v[100:103]
	v_mfma_f32_16x16x32_bf16 v[96:99], v[170:173], v[192:195], v[96:99]
	v_mfma_f32_16x16x32_bf16 v[96:99], v[174:177], v[196:199], v[96:99]
	v_mfma_f32_16x16x32_bf16 v[84:87], v[162:165], v[200:203], v[84:87]
	v_mfma_f32_16x16x32_bf16 v[84:87], v[166:169], v[204:207], v[84:87]
	v_mfma_f32_16x16x32_bf16 v[80:83], v[170:173], v[200:203], v[80:83]
	v_mfma_f32_16x16x32_bf16 v[80:83], v[174:177], v[204:207], v[80:83]
	v_mfma_f32_16x16x32_bf16 v[68:71], v[162:165], v[208:211], v[68:71]
	v_mfma_f32_16x16x32_bf16 v[68:71], v[166:169], v[212:215], v[68:71]
	v_mfma_f32_16x16x32_bf16 v[64:67], v[170:173], v[208:211], v[64:67]
	v_mfma_f32_16x16x32_bf16 v[64:67], v[174:177], v[212:215], v[64:67]
	s_setprio 0
	s_barrier
	s_add_i32 s18, s18, s54
	v_lshl_add_u64 v[178:179], v[178:179], 0, s[6:7]
	s_mov_b32 m0, s18
	ds_read_b128 v[184:187], v149 offset:49152
	ds_read_b128 v[188:191], v149 offset:50176
	ds_read_b128 v[192:195], v149 offset:51200
	ds_read_b128 v[196:199], v149 offset:52224
	ds_read_b128 v[200:203], v149 offset:53248
	ds_read_b128 v[204:207], v149 offset:54272
	ds_read_b128 v[208:211], v149 offset:55296
	ds_read_b128 v[212:215], v149 offset:56320
	global_load_lds_dwordx4 v[178:179], off
	s_add_i32 m0, s18, 0x2000
	s_add_u32 s46, s46, 0x40080
	v_lshl_add_u64 v[178:179], v[216:217], 0, s[6:7]
	s_addc_u32 s47, s47, 0
	s_add_i32 s18, s19, s54
	global_load_lds_dwordx4 v[178:179], off
	v_lshl_add_u64 v[178:179], s[46:47], 0, v[130:131]
	s_mov_b32 m0, s18
	s_nop 0
	global_load_lds_dwordx4 v[178:179], off
	v_lshl_add_u64 v[178:179], s[46:47], 0, v[128:129]
	s_add_i32 m0, s18, 0x2000
	s_nop 0
	global_load_lds_dwordx4 v[178:179], off
	v_lshl_add_u64 v[178:179], v[218:219], 0, s[6:7]
	s_mov_b32 m0, s60
	s_nop 0
	global_load_lds_dwordx4 v[178:179], off
	v_lshl_add_u64 v[178:179], v[220:221], 0, s[6:7]
	s_mov_b32 m0, s61
	s_nop 0
	global_load_lds_dwordx4 v[178:179], off
	s_waitcnt vmcnt(8)
	s_waitcnt lgkmcnt(0)
	s_barrier
	s_setprio 1
	v_mfma_f32_16x16x32_bf16 v[60:63], v[140:143], v[184:187], v[60:63]
	v_mfma_f32_16x16x32_bf16 v[60:63], v[150:153], v[188:191], v[60:63]
	v_mfma_f32_16x16x32_bf16 v[56:59], v[154:157], v[184:187], v[56:59]
	v_mfma_f32_16x16x32_bf16 v[56:59], v[158:161], v[188:191], v[56:59]
	v_mfma_f32_16x16x32_bf16 v[44:47], v[140:143], v[192:195], v[44:47]
	v_mfma_f32_16x16x32_bf16 v[44:47], v[150:153], v[196:199], v[44:47]
	v_mfma_f32_16x16x32_bf16 v[40:43], v[154:157], v[192:195], v[40:43]
	v_mfma_f32_16x16x32_bf16 v[40:43], v[158:161], v[196:199], v[40:43]
	v_mfma_f32_16x16x32_bf16 v[28:31], v[140:143], v[200:203], v[28:31]
	v_mfma_f32_16x16x32_bf16 v[28:31], v[150:153], v[204:207], v[28:31]
	v_mfma_f32_16x16x32_bf16 v[24:27], v[154:157], v[200:203], v[24:27]
	v_mfma_f32_16x16x32_bf16 v[24:27], v[158:161], v[204:207], v[24:27]
	v_mfma_f32_16x16x32_bf16 v[12:15], v[140:143], v[208:211], v[12:15]
	v_mfma_f32_16x16x32_bf16 v[12:15], v[150:153], v[212:215], v[12:15]
	v_mfma_f32_16x16x32_bf16 v[8:11], v[154:157], v[208:211], v[8:11]
	v_mfma_f32_16x16x32_bf16 v[8:11], v[158:161], v[212:215], v[8:11]
	v_mfma_f32_16x16x32_bf16 v[52:55], v[162:165], v[184:187], v[52:55]
	v_mfma_f32_16x16x32_bf16 v[52:55], v[166:169], v[188:191], v[52:55]
	v_mfma_f32_16x16x32_bf16 v[48:51], v[170:173], v[184:187], v[48:51]
	v_mfma_f32_16x16x32_bf16 v[48:51], v[174:177], v[188:191], v[48:51]
	v_mfma_f32_16x16x32_bf16 v[36:39], v[162:165], v[192:195], v[36:39]
	v_mfma_f32_16x16x32_bf16 v[36:39], v[166:169], v[196:199], v[36:39]
	v_mfma_f32_16x16x32_bf16 v[32:35], v[170:173], v[192:195], v[32:35]
	v_mfma_f32_16x16x32_bf16 v[32:35], v[174:177], v[196:199], v[32:35]
	v_mfma_f32_16x16x32_bf16 v[20:23], v[162:165], v[200:203], v[20:23]
	v_mfma_f32_16x16x32_bf16 v[20:23], v[166:169], v[204:207], v[20:23]
	v_mfma_f32_16x16x32_bf16 v[16:19], v[170:173], v[200:203], v[16:19]
	v_mfma_f32_16x16x32_bf16 v[16:19], v[174:177], v[204:207], v[16:19]
	v_mfma_f32_16x16x32_bf16 v[4:7], v[162:165], v[208:211], v[4:7]
	v_mfma_f32_16x16x32_bf16 v[4:7], v[166:169], v[212:215], v[4:7]
	v_mfma_f32_16x16x32_bf16 v[0:3], v[170:173], v[208:211], v[0:3]
	v_mfma_f32_16x16x32_bf16 v[0:3], v[174:177], v[212:215], v[0:3]
	s_setprio 0
	s_barrier
	s_add_i32 s70, s70, 2
	s_add_u32 s44, s44, 0x100
	s_addc_u32 s45, s45, 0
	s_add_u32 s68, s68, 0x100
	s_addc_u32 s69, s69, 0
	s_cmp_gt_u32 s70, 13
	s_cbranch_scc0 .LBB0_184
	s_and_b64 vcc, exec, s[8:9]
	s_cbranch_vccz .LBB0_187
	s_barrier

.LBB0_263:
	s_add_u32 s84, s54, 0x100
	s_addc_u32 s85, s55, 0
	s_mov_b32 s86, -2
	ds_read_b128 v[152:155], v149
	ds_read_b128 v[156:159], v149 offset:1024
	ds_read_b128 v[160:163], v149 offset:2048
	ds_read_b128 v[164:167], v149 offset:3072
	ds_read_b128 v[168:171], v150
	ds_read_b128 v[172:175], v150 offset:1024
	ds_read_b128 v[176:179], v150 offset:2048
	ds_read_b128 v[184:187], v150 offset:3072
	s_add_u32 s54, s52, 0x100
	s_addc_u32 s55, s53, 0
	s_cmp_eq_u32 s86, 40
	s_cselect_b32 s59, s7, s55
	s_cselect_b32 s58, s6, s54
	s_cselect_b32 s57, s49, s85
	s_cselect_b32 s56, s48, s84
	v_lshl_add_u64 v[144:145], s[52:53], 0, v[136:137]
	s_add_i32 m0, s63, 0xc000
	ds_read_b128 v[188:191], v151
	ds_read_b128 v[192:195], v151 offset:1024
	ds_read_b128 v[196:199], v151 offset:2048
	ds_read_b128 v[200:203], v151 offset:3072
	ds_read_b128 v[204:207], v151 offset:4096
	ds_read_b128 v[208:211], v151 offset:5120
	ds_read_b128 v[212:215], v151 offset:6144
	ds_read_b128 v[216:219], v151 offset:7168
	global_load_lds_dwordx4 v[144:145], off
	v_lshl_add_u64 v[144:145], s[52:53], 0, v[138:139]
	s_add_i32 m0, s63, 0xe000
	s_nop 0
	global_load_lds_dwordx4 v[144:145], off
	s_waitcnt vmcnt(8)
	s_waitcnt lgkmcnt(0)
	s_barrier
	s_setprio 1
	v_mfma_f32_16x16x32_bf16 v[124:127], v[152:155], v[188:191], 0
	v_mfma_f32_16x16x32_bf16 v[124:127], v[156:159], v[192:195], v[124:127]
	v_mfma_f32_16x16x32_bf16 v[120:123], v[160:163], v[188:191], 0
	v_mfma_f32_16x16x32_bf16 v[120:123], v[164:167], v[192:195], v[120:123]
	v_mfma_f32_16x16x32_bf16 v[116:119], v[152:155], v[196:199], 0
	v_mfma_f32_16x16x32_bf16 v[116:119], v[156:159], v[200:203], v[116:119]
	v_mfma_f32_16x16x32_bf16 v[108:111], v[160:163], v[196:199], 0
	v_mfma_f32_16x16x32_bf16 v[108:111], v[164:167], v[200:203], v[108:111]
	v_mfma_f32_16x16x32_bf16 v[100:103], v[152:155], v[204:207], 0
	v_mfma_f32_16x16x32_bf16 v[100:103], v[156:159], v[208:211], v[100:103]
	v_mfma_f32_16x16x32_bf16 v[92:95], v[160:163], v[204:207], 0
	v_mfma_f32_16x16x32_bf16 v[92:95], v[164:167], v[208:211], v[92:95]
	v_mfma_f32_16x16x32_bf16 v[84:87], v[152:155], v[212:215], 0
	v_mfma_f32_16x16x32_bf16 v[84:87], v[156:159], v[216:219], v[84:87]
	v_mfma_f32_16x16x32_bf16 v[76:79], v[160:163], v[212:215], 0
	v_mfma_f32_16x16x32_bf16 v[76:79], v[164:167], v[216:219], v[76:79]
	v_mfma_f32_16x16x32_bf16 v[112:115], v[168:171], v[188:191], 0
	v_mfma_f32_16x16x32_bf16 v[112:115], v[172:175], v[192:195], v[112:115]
	v_mfma_f32_16x16x32_bf16 v[104:107], v[176:179], v[188:191], 0
	v_mfma_f32_16x16x32_bf16 v[104:107], v[184:187], v[192:195], v[104:107]
	v_mfma_f32_16x16x32_bf16 v[96:99], v[168:171], v[196:199], 0
	v_mfma_f32_16x16x32_bf16 v[96:99], v[172:175], v[200:203], v[96:99]
	v_mfma_f32_16x16x32_bf16 v[88:91], v[176:179], v[196:199], 0
	v_mfma_f32_16x16x32_bf16 v[88:91], v[184:187], v[200:203], v[88:91]
	v_mfma_f32_16x16x32_bf16 v[80:83], v[168:171], v[204:207], 0
	v_mfma_f32_16x16x32_bf16 v[80:83], v[172:175], v[208:211], v[80:83]
	v_mfma_f32_16x16x32_bf16 v[72:75], v[176:179], v[204:207], 0
	v_mfma_f32_16x16x32_bf16 v[72:75], v[184:187], v[208:211], v[72:75]
	v_mfma_f32_16x16x32_bf16 v[68:71], v[168:171], v[212:215], 0
	v_mfma_f32_16x16x32_bf16 v[68:71], v[172:175], v[216:219], v[68:71]
	v_mfma_f32_16x16x32_bf16 v[64:67], v[176:179], v[212:215], 0
	v_mfma_f32_16x16x32_bf16 v[64:67], v[184:187], v[216:219], v[64:67]
	s_setprio 0
	s_barrier
	s_add_i32 s18, s70, s62
	v_lshl_add_u64 v[144:145], s[56:57], 0, v[130:131]
	s_mov_b32 m0, s18
	ds_read_b128 v[188:191], v151 offset:16384
	ds_read_b128 v[192:195], v151 offset:17408
	ds_read_b128 v[196:199], v151 offset:18432
	ds_read_b128 v[200:203], v151 offset:19456
	ds_read_b128 v[204:207], v151 offset:20480
	ds_read_b128 v[208:211], v151 offset:21504
	ds_read_b128 v[212:215], v151 offset:22528
	ds_read_b128 v[216:219], v151 offset:23552
	global_load_lds_dwordx4 v[144:145], off
	s_add_i32 m0, s18, 0x2000
	s_add_u32 s52, s56, 0xb0000
	v_lshl_add_u64 v[220:221], s[56:57], 0, v[134:135]
	s_addc_u32 s53, s57, 0
	s_add_i32 s18, s71, s62
	global_load_lds_dwordx4 v[220:221], off
	v_lshl_add_u64 v[222:223], s[52:53], 0, v[130:131]
	s_mov_b32 m0, s18
	v_lshl_add_u64 v[224:225], s[58:59], 0, v[132:133]
	global_load_lds_dwordx4 v[222:223], off
	v_lshl_add_u64 v[222:223], s[52:53], 0, v[134:135]
	s_add_i32 m0, s18, 0x2000
	s_nop 0
	global_load_lds_dwordx4 v[222:223], off
	v_lshl_add_u64 v[222:223], s[58:59], 0, v[128:129]
	s_mov_b32 m0, s63
	s_nop 0
	global_load_lds_dwordx4 v[222:223], off
	s_mov_b32 m0, s64
	s_nop 0
	global_load_lds_dwordx4 v[224:225], off
	s_waitcnt vmcnt(8)
	s_waitcnt lgkmcnt(0)
	s_barrier
	s_setprio 1
	v_mfma_f32_16x16x32_bf16 v[60:63], v[152:155], v[188:191], 0
	v_mfma_f32_16x16x32_bf16 v[60:63], v[156:159], v[192:195], v[60:63]
	v_mfma_f32_16x16x32_bf16 v[56:59], v[160:163], v[188:191], 0
	v_mfma_f32_16x16x32_bf16 v[56:59], v[164:167], v[192:195], v[56:59]
	v_mfma_f32_16x16x32_bf16 v[52:55], v[152:155], v[196:199], 0
	v_mfma_f32_16x16x32_bf16 v[52:55], v[156:159], v[200:203], v[52:55]
	v_mfma_f32_16x16x32_bf16 v[44:47], v[160:163], v[196:199], 0
	v_mfma_f32_16x16x32_bf16 v[44:47], v[164:167], v[200:203], v[44:47]
	v_mfma_f32_16x16x32_bf16 v[36:39], v[152:155], v[204:207], 0
	v_mfma_f32_16x16x32_bf16 v[36:39], v[156:159], v[208:211], v[36:39]
	v_mfma_f32_16x16x32_bf16 v[28:31], v[160:163], v[204:207], 0
	v_mfma_f32_16x16x32_bf16 v[28:31], v[164:167], v[208:211], v[28:31]
	v_mfma_f32_16x16x32_bf16 v[20:23], v[152:155], v[212:215], 0
	v_mfma_f32_16x16x32_bf16 v[20:23], v[156:159], v[216:219], v[20:23]
	v_mfma_f32_16x16x32_bf16 v[12:15], v[160:163], v[212:215], 0
	v_mfma_f32_16x16x32_bf16 v[12:15], v[164:167], v[216:219], v[12:15]
	v_mfma_f32_16x16x32_bf16 v[48:51], v[168:171], v[188:191], 0
	v_mfma_f32_16x16x32_bf16 v[48:51], v[172:175], v[192:195], v[48:51]
	v_mfma_f32_16x16x32_bf16 v[40:43], v[176:179], v[188:191], 0
	v_mfma_f32_16x16x32_bf16 v[40:43], v[184:187], v[192:195], v[40:43]
	v_mfma_f32_16x16x32_bf16 v[32:35], v[168:171], v[196:199], 0
	v_mfma_f32_16x16x32_bf16 v[32:35], v[172:175], v[200:203], v[32:35]
	v_mfma_f32_16x16x32_bf16 v[24:27], v[176:179], v[196:199], 0
	v_mfma_f32_16x16x32_bf16 v[24:27], v[184:187], v[200:203], v[24:27]
	v_mfma_f32_16x16x32_bf16 v[16:19], v[168:171], v[204:207], 0
	v_mfma_f32_16x16x32_bf16 v[16:19], v[172:175], v[208:211], v[16:19]
	v_mfma_f32_16x16x32_bf16 v[8:11], v[176:179], v[204:207], 0
	v_mfma_f32_16x16x32_bf16 v[8:11], v[184:187], v[208:211], v[8:11]
	v_mfma_f32_16x16x32_bf16 v[4:7], v[168:171], v[212:215], 0
	v_mfma_f32_16x16x32_bf16 v[4:7], v[172:175], v[216:219], v[4:7]
	v_mfma_f32_16x16x32_bf16 v[0:3], v[176:179], v[212:215], 0
	v_mfma_f32_16x16x32_bf16 v[0:3], v[184:187], v[216:219], v[0:3]
	s_setprio 0
	s_barrier
	s_branch .Lmid_gemm1
.LBB0_264:
	ds_read_b128 v[152:155], v149
	ds_read_b128 v[156:159], v149 offset:1024
	ds_read_b128 v[160:163], v149 offset:2048
	ds_read_b128 v[164:167], v149 offset:3072
	ds_read_b128 v[168:171], v150
	ds_read_b128 v[172:175], v150 offset:1024
	ds_read_b128 v[176:179], v150 offset:2048
	ds_read_b128 v[184:187], v150 offset:3072
	s_add_u32 s54, s52, 0x100
	s_addc_u32 s55, s53, 0
	s_cmp_eq_u32 s86, 40
	s_cselect_b32 s59, s7, s55
	s_cselect_b32 s58, s6, s54
	s_cselect_b32 s57, s49, s85
	s_cselect_b32 s56, s48, s84
	v_lshl_add_u64 v[144:145], s[52:53], 0, v[136:137]
	s_add_i32 m0, s63, 0xc000
	ds_read_b128 v[188:191], v151
	ds_read_b128 v[192:195], v151 offset:1024
	ds_read_b128 v[196:199], v151 offset:2048
	ds_read_b128 v[200:203], v151 offset:3072
	ds_read_b128 v[204:207], v151 offset:4096
	ds_read_b128 v[208:211], v151 offset:5120
	ds_read_b128 v[212:215], v151 offset:6144
	ds_read_b128 v[216:219], v151 offset:7168
	global_load_lds_dwordx4 v[144:145], off
	v_lshl_add_u64 v[144:145], s[52:53], 0, v[138:139]
	s_add_i32 m0, s63, 0xe000
	s_nop 0
	global_load_lds_dwordx4 v[144:145], off
	s_waitcnt vmcnt(8)
	s_waitcnt lgkmcnt(0)
	s_barrier
	s_setprio 1
	v_mfma_f32_16x16x32_bf16 v[124:127], v[152:155], v[188:191], v[124:127]
	v_mfma_f32_16x16x32_bf16 v[124:127], v[156:159], v[192:195], v[124:127]
	v_mfma_f32_16x16x32_bf16 v[120:123], v[160:163], v[188:191], v[120:123]
	v_mfma_f32_16x16x32_bf16 v[120:123], v[164:167], v[192:195], v[120:123]
	v_mfma_f32_16x16x32_bf16 v[116:119], v[152:155], v[196:199], v[116:119]
	v_mfma_f32_16x16x32_bf16 v[116:119], v[156:159], v[200:203], v[116:119]
	v_mfma_f32_16x16x32_bf16 v[108:111], v[160:163], v[196:199], v[108:111]
	v_mfma_f32_16x16x32_bf16 v[108:111], v[164:167], v[200:203], v[108:111]
	v_mfma_f32_16x16x32_bf16 v[100:103], v[152:155], v[204:207], v[100:103]
	v_mfma_f32_16x16x32_bf16 v[100:103], v[156:159], v[208:211], v[100:103]
	v_mfma_f32_16x16x32_bf16 v[92:95], v[160:163], v[204:207], v[92:95]
	v_mfma_f32_16x16x32_bf16 v[92:95], v[164:167], v[208:211], v[92:95]
	v_mfma_f32_16x16x32_bf16 v[84:87], v[152:155], v[212:215], v[84:87]
	v_mfma_f32_16x16x32_bf16 v[84:87], v[156:159], v[216:219], v[84:87]
	v_mfma_f32_16x16x32_bf16 v[76:79], v[160:163], v[212:215], v[76:79]
	v_mfma_f32_16x16x32_bf16 v[76:79], v[164:167], v[216:219], v[76:79]
	v_mfma_f32_16x16x32_bf16 v[112:115], v[168:171], v[188:191], v[112:115]
	v_mfma_f32_16x16x32_bf16 v[112:115], v[172:175], v[192:195], v[112:115]
	v_mfma_f32_16x16x32_bf16 v[104:107], v[176:179], v[188:191], v[104:107]
	v_mfma_f32_16x16x32_bf16 v[104:107], v[184:187], v[192:195], v[104:107]
	v_mfma_f32_16x16x32_bf16 v[96:99], v[168:171], v[196:199], v[96:99]
	v_mfma_f32_16x16x32_bf16 v[96:99], v[172:175], v[200:203], v[96:99]
	v_mfma_f32_16x16x32_bf16 v[88:91], v[176:179], v[196:199], v[88:91]
	v_mfma_f32_16x16x32_bf16 v[88:91], v[184:187], v[200:203], v[88:91]
	v_mfma_f32_16x16x32_bf16 v[80:83], v[168:171], v[204:207], v[80:83]
	v_mfma_f32_16x16x32_bf16 v[80:83], v[172:175], v[208:211], v[80:83]
	v_mfma_f32_16x16x32_bf16 v[72:75], v[176:179], v[204:207], v[72:75]
	v_mfma_f32_16x16x32_bf16 v[72:75], v[184:187], v[208:211], v[72:75]
	v_mfma_f32_16x16x32_bf16 v[68:71], v[168:171], v[212:215], v[68:71]
	v_mfma_f32_16x16x32_bf16 v[68:71], v[172:175], v[216:219], v[68:71]
	v_mfma_f32_16x16x32_bf16 v[64:67], v[176:179], v[212:215], v[64:67]
	v_mfma_f32_16x16x32_bf16 v[64:67], v[184:187], v[216:219], v[64:67]
	s_setprio 0
	s_barrier
	s_add_i32 s18, s70, s62
	v_lshl_add_u64 v[144:145], s[56:57], 0, v[130:131]
	s_mov_b32 m0, s18
	ds_read_b128 v[188:191], v151 offset:16384
	ds_read_b128 v[192:195], v151 offset:17408
	ds_read_b128 v[196:199], v151 offset:18432
	ds_read_b128 v[200:203], v151 offset:19456
	ds_read_b128 v[204:207], v151 offset:20480
	ds_read_b128 v[208:211], v151 offset:21504
	ds_read_b128 v[212:215], v151 offset:22528
	ds_read_b128 v[216:219], v151 offset:23552
	global_load_lds_dwordx4 v[144:145], off
	s_add_i32 m0, s18, 0x2000
	s_add_u32 s52, s56, 0xb0000
	v_lshl_add_u64 v[220:221], s[56:57], 0, v[134:135]
	s_addc_u32 s53, s57, 0
	s_add_i32 s18, s71, s62
	global_load_lds_dwordx4 v[220:221], off
	v_lshl_add_u64 v[222:223], s[52:53], 0, v[130:131]
	s_mov_b32 m0, s18
	v_lshl_add_u64 v[224:225], s[58:59], 0, v[132:133]
	global_load_lds_dwordx4 v[222:223], off
	v_lshl_add_u64 v[222:223], s[52:53], 0, v[134:135]
	s_add_i32 m0, s18, 0x2000
	s_nop 0
	global_load_lds_dwordx4 v[222:223], off
	v_lshl_add_u64 v[222:223], s[58:59], 0, v[128:129]
	s_mov_b32 m0, s63
	s_nop 0
	global_load_lds_dwordx4 v[222:223], off
	s_mov_b32 m0, s64
	s_nop 0
	global_load_lds_dwordx4 v[224:225], off
	s_waitcnt vmcnt(8)
	s_waitcnt lgkmcnt(0)
	s_barrier
	s_setprio 1
	v_mfma_f32_16x16x32_bf16 v[60:63], v[152:155], v[188:191], v[60:63]
	v_mfma_f32_16x16x32_bf16 v[60:63], v[156:159], v[192:195], v[60:63]
	v_mfma_f32_16x16x32_bf16 v[56:59], v[160:163], v[188:191], v[56:59]
	v_mfma_f32_16x16x32_bf16 v[56:59], v[164:167], v[192:195], v[56:59]
	v_mfma_f32_16x16x32_bf16 v[52:55], v[152:155], v[196:199], v[52:55]
	v_mfma_f32_16x16x32_bf16 v[52:55], v[156:159], v[200:203], v[52:55]
	v_mfma_f32_16x16x32_bf16 v[44:47], v[160:163], v[196:199], v[44:47]
	v_mfma_f32_16x16x32_bf16 v[44:47], v[164:167], v[200:203], v[44:47]
	v_mfma_f32_16x16x32_bf16 v[36:39], v[152:155], v[204:207], v[36:39]
	v_mfma_f32_16x16x32_bf16 v[36:39], v[156:159], v[208:211], v[36:39]
	v_mfma_f32_16x16x32_bf16 v[28:31], v[160:163], v[204:207], v[28:31]
	v_mfma_f32_16x16x32_bf16 v[28:31], v[164:167], v[208:211], v[28:31]
	v_mfma_f32_16x16x32_bf16 v[20:23], v[152:155], v[212:215], v[20:23]
	v_mfma_f32_16x16x32_bf16 v[20:23], v[156:159], v[216:219], v[20:23]
	v_mfma_f32_16x16x32_bf16 v[12:15], v[160:163], v[212:215], v[12:15]
	v_mfma_f32_16x16x32_bf16 v[12:15], v[164:167], v[216:219], v[12:15]
	v_mfma_f32_16x16x32_bf16 v[48:51], v[168:171], v[188:191], v[48:51]
	v_mfma_f32_16x16x32_bf16 v[48:51], v[172:175], v[192:195], v[48:51]
	v_mfma_f32_16x16x32_bf16 v[40:43], v[176:179], v[188:191], v[40:43]
	v_mfma_f32_16x16x32_bf16 v[40:43], v[184:187], v[192:195], v[40:43]
	v_mfma_f32_16x16x32_bf16 v[32:35], v[168:171], v[196:199], v[32:35]
	v_mfma_f32_16x16x32_bf16 v[32:35], v[172:175], v[200:203], v[32:35]
	v_mfma_f32_16x16x32_bf16 v[24:27], v[176:179], v[196:199], v[24:27]
	v_mfma_f32_16x16x32_bf16 v[24:27], v[184:187], v[200:203], v[24:27]
	v_mfma_f32_16x16x32_bf16 v[16:19], v[168:171], v[204:207], v[16:19]
	v_mfma_f32_16x16x32_bf16 v[16:19], v[172:175], v[208:211], v[16:19]
	v_mfma_f32_16x16x32_bf16 v[8:11], v[176:179], v[204:207], v[8:11]
	v_mfma_f32_16x16x32_bf16 v[8:11], v[184:187], v[208:211], v[8:11]
	v_mfma_f32_16x16x32_bf16 v[4:7], v[168:171], v[212:215], v[4:7]
	v_mfma_f32_16x16x32_bf16 v[4:7], v[172:175], v[216:219], v[4:7]
	v_mfma_f32_16x16x32_bf16 v[0:3], v[176:179], v[212:215], v[0:3]
	v_mfma_f32_16x16x32_bf16 v[0:3], v[184:187], v[216:219], v[0:3]
	s_setprio 0
	s_barrier
.Lmid_gemm1:
	s_add_i32 s18, 0, 0x18000
	s_add_i32 s19, 0, 0x1c000
	v_add_u32_e32 v164, s18, v147
	v_add_u32_e32 v181, s19, v147
	ds_read_b128 v[152:155], v164
	ds_read_b128 v[156:159], v164 offset:1024
	ds_read_b128 v[160:163], v164 offset:2048
	ds_read_b128 v[164:167], v164 offset:3072
	ds_read_b128 v[168:171], v181
	ds_read_b128 v[172:175], v181 offset:1024
	ds_read_b128 v[176:179], v181 offset:2048
	ds_read_b128 v[184:187], v181 offset:3072
	s_add_u32 s52, s58, 0xb0000
	s_addc_u32 s53, s59, 0
	s_mov_b32 m0, s65
	v_lshl_add_u64 v[226:227], s[52:53], 0, v[128:129]
	ds_read_b128 v[188:191], v151 offset:32768
	ds_read_b128 v[192:195], v151 offset:33792
	ds_read_b128 v[196:199], v151 offset:34816
	ds_read_b128 v[200:203], v151 offset:35840
	ds_read_b128 v[204:207], v151 offset:36864
	ds_read_b128 v[208:211], v151 offset:37888
	ds_read_b128 v[212:215], v151 offset:38912
	ds_read_b128 v[216:219], v151 offset:39936
	global_load_lds_dwordx4 v[226:227], off
	v_lshl_add_u64 v[226:227], s[52:53], 0, v[132:133]
	s_mov_b32 m0, s66
	s_nop 0
	global_load_lds_dwordx4 v[226:227], off
	s_waitcnt vmcnt(8)
	s_waitcnt lgkmcnt(0)
	s_barrier
	s_setprio 1
	v_mfma_f32_16x16x32_bf16 v[124:127], v[152:155], v[188:191], v[124:127]
	v_mfma_f32_16x16x32_bf16 v[124:127], v[156:159], v[192:195], v[124:127]
	v_mfma_f32_16x16x32_bf16 v[120:123], v[160:163], v[188:191], v[120:123]
	v_mfma_f32_16x16x32_bf16 v[120:123], v[164:167], v[192:195], v[120:123]
	v_mfma_f32_16x16x32_bf16 v[116:119], v[152:155], v[196:199], v[116:119]
	v_mfma_f32_16x16x32_bf16 v[116:119], v[156:159], v[200:203], v[116:119]
	v_mfma_f32_16x16x32_bf16 v[108:111], v[160:163], v[196:199], v[108:111]
	v_mfma_f32_16x16x32_bf16 v[108:111], v[164:167], v[200:203], v[108:111]
	v_mfma_f32_16x16x32_bf16 v[100:103], v[152:155], v[204:207], v[100:103]
	v_mfma_f32_16x16x32_bf16 v[100:103], v[156:159], v[208:211], v[100:103]
	v_mfma_f32_16x16x32_bf16 v[92:95], v[160:163], v[204:207], v[92:95]
	v_mfma_f32_16x16x32_bf16 v[92:95], v[164:167], v[208:211], v[92:95]
	v_mfma_f32_16x16x32_bf16 v[84:87], v[152:155], v[212:215], v[84:87]
	v_mfma_f32_16x16x32_bf16 v[84:87], v[156:159], v[216:219], v[84:87]
	v_mfma_f32_16x16x32_bf16 v[76:79], v[160:163], v[212:215], v[76:79]
	v_mfma_f32_16x16x32_bf16 v[76:79], v[164:167], v[216:219], v[76:79]
	v_mfma_f32_16x16x32_bf16 v[112:115], v[168:171], v[188:191], v[112:115]
	v_mfma_f32_16x16x32_bf16 v[112:115], v[172:175], v[192:195], v[112:115]
	v_mfma_f32_16x16x32_bf16 v[104:107], v[176:179], v[188:191], v[104:107]
	v_mfma_f32_16x16x32_bf16 v[104:107], v[184:187], v[192:195], v[104:107]
	v_mfma_f32_16x16x32_bf16 v[96:99], v[168:171], v[196:199], v[96:99]
	v_mfma_f32_16x16x32_bf16 v[96:99], v[172:175], v[200:203], v[96:99]
	v_mfma_f32_16x16x32_bf16 v[88:91], v[176:179], v[196:199], v[88:91]
	v_mfma_f32_16x16x32_bf16 v[88:91], v[184:187], v[200:203], v[88:91]
	v_mfma_f32_16x16x32_bf16 v[80:83], v[168:171], v[204:207], v[80:83]
	v_mfma_f32_16x16x32_bf16 v[80:83], v[172:175], v[208:211], v[80:83]
	v_mfma_f32_16x16x32_bf16 v[72:75], v[176:179], v[204:207], v[72:75]
	v_mfma_f32_16x16x32_bf16 v[72:75], v[184:187], v[208:211], v[72:75]
	v_mfma_f32_16x16x32_bf16 v[68:71], v[168:171], v[212:215], v[68:71]
	v_mfma_f32_16x16x32_bf16 v[68:71], v[172:175], v[216:219], v[68:71]
	v_mfma_f32_16x16x32_bf16 v[64:67], v[176:179], v[212:215], v[64:67]
	v_mfma_f32_16x16x32_bf16 v[64:67], v[184:187], v[216:219], v[64:67]
	s_setprio 0
	s_barrier
	s_add_i32 s18, s18, s62
	v_lshl_add_u64 v[144:145], v[144:145], 0, s[8:9]
	s_mov_b32 m0, s18
	ds_read_b128 v[188:191], v151 offset:49152
	ds_read_b128 v[192:195], v151 offset:50176
	ds_read_b128 v[196:199], v151 offset:51200
	ds_read_b128 v[200:203], v151 offset:52224
	ds_read_b128 v[204:207], v151 offset:53248
	ds_read_b128 v[208:211], v151 offset:54272
	ds_read_b128 v[212:215], v151 offset:55296
	ds_read_b128 v[216:219], v151 offset:56320
	global_load_lds_dwordx4 v[144:145], off
	s_add_i32 m0, s18, 0x2000
	s_add_u32 s52, s56, 0xb0080
	v_lshl_add_u64 v[144:145], v[220:221], 0, s[8:9]
	s_addc_u32 s53, s57, 0
	s_add_i32 s18, s19, s62
	global_load_lds_dwordx4 v[144:145], off
	v_lshl_add_u64 v[144:145], s[52:53], 0, v[130:131]
	s_mov_b32 m0, s18
	s_nop 0
	global_load_lds_dwordx4 v[144:145], off
	v_lshl_add_u64 v[144:145], s[52:53], 0, v[134:135]
	s_add_i32 m0, s18, 0x2000
	s_nop 0
	global_load_lds_dwordx4 v[144:145], off
	v_lshl_add_u64 v[144:145], v[222:223], 0, s[8:9]
	s_mov_b32 m0, s68
	s_nop 0
	global_load_lds_dwordx4 v[144:145], off
	v_lshl_add_u64 v[144:145], v[224:225], 0, s[8:9]
	s_mov_b32 m0, s69
	s_nop 0
	global_load_lds_dwordx4 v[144:145], off
	s_waitcnt vmcnt(8)
	s_waitcnt lgkmcnt(0)
	s_barrier
	s_setprio 1
	v_mfma_f32_16x16x32_bf16 v[60:63], v[152:155], v[188:191], v[60:63]
	v_mfma_f32_16x16x32_bf16 v[60:63], v[156:159], v[192:195], v[60:63]
	v_mfma_f32_16x16x32_bf16 v[56:59], v[160:163], v[188:191], v[56:59]
	v_mfma_f32_16x16x32_bf16 v[56:59], v[164:167], v[192:195], v[56:59]
	v_mfma_f32_16x16x32_bf16 v[52:55], v[152:155], v[196:199], v[52:55]
	v_mfma_f32_16x16x32_bf16 v[52:55], v[156:159], v[200:203], v[52:55]
	v_mfma_f32_16x16x32_bf16 v[44:47], v[160:163], v[196:199], v[44:47]
	v_mfma_f32_16x16x32_bf16 v[44:47], v[164:167], v[200:203], v[44:47]
	v_mfma_f32_16x16x32_bf16 v[36:39], v[152:155], v[204:207], v[36:39]
	v_mfma_f32_16x16x32_bf16 v[36:39], v[156:159], v[208:211], v[36:39]
	v_mfma_f32_16x16x32_bf16 v[28:31], v[160:163], v[204:207], v[28:31]
	v_mfma_f32_16x16x32_bf16 v[28:31], v[164:167], v[208:211], v[28:31]
	v_mfma_f32_16x16x32_bf16 v[20:23], v[152:155], v[212:215], v[20:23]
	v_mfma_f32_16x16x32_bf16 v[20:23], v[156:159], v[216:219], v[20:23]
	v_mfma_f32_16x16x32_bf16 v[12:15], v[160:163], v[212:215], v[12:15]
	v_mfma_f32_16x16x32_bf16 v[12:15], v[164:167], v[216:219], v[12:15]
	v_mfma_f32_16x16x32_bf16 v[48:51], v[168:171], v[188:191], v[48:51]
	v_mfma_f32_16x16x32_bf16 v[48:51], v[172:175], v[192:195], v[48:51]
	v_mfma_f32_16x16x32_bf16 v[40:43], v[176:179], v[188:191], v[40:43]
	v_mfma_f32_16x16x32_bf16 v[40:43], v[184:187], v[192:195], v[40:43]
	v_mfma_f32_16x16x32_bf16 v[32:35], v[168:171], v[196:199], v[32:35]
	v_mfma_f32_16x16x32_bf16 v[32:35], v[172:175], v[200:203], v[32:35]
	v_mfma_f32_16x16x32_bf16 v[24:27], v[176:179], v[196:199], v[24:27]
	v_mfma_f32_16x16x32_bf16 v[24:27], v[184:187], v[200:203], v[24:27]
	v_mfma_f32_16x16x32_bf16 v[16:19], v[168:171], v[204:207], v[16:19]
	v_mfma_f32_16x16x32_bf16 v[16:19], v[172:175], v[208:211], v[16:19]
	v_mfma_f32_16x16x32_bf16 v[8:11], v[176:179], v[204:207], v[8:11]
	v_mfma_f32_16x16x32_bf16 v[8:11], v[184:187], v[208:211], v[8:11]
	v_mfma_f32_16x16x32_bf16 v[4:7], v[168:171], v[212:215], v[4:7]
	v_mfma_f32_16x16x32_bf16 v[4:7], v[172:175], v[216:219], v[4:7]
	v_mfma_f32_16x16x32_bf16 v[0:3], v[176:179], v[212:215], v[0:3]
	v_mfma_f32_16x16x32_bf16 v[0:3], v[184:187], v[216:219], v[0:3]
	s_setprio 0
	s_barrier
	s_add_i32 s86, s86, 2
	s_add_u32 s84, s84, 0x100
	s_addc_u32 s85, s85, 0
	s_cmp_gt_u32 s86, 41
	s_mov_b64 s[52:53], s[54:55]
	s_cbranch_scc0 .LBB0_264
	s_and_b64 vcc, exec, s[10:11]
	s_cbranch_vccz .LBB0_267
	s_barrier

.LBB0_386:
	s_ashr_i32 s49, s48, 31
	s_lshl_b64 s[52:53], s[48:49], 19
	s_add_u32 s52, s80, s52
	s_addc_u32 s53, s81, s53
	s_and_b64 s[54:55], s[4:5], exec
	s_cselect_b32 s49, s53, s59
	s_cselect_b32 s82, s52, s58
	s_ashr_i32 s47, s46, 31
	s_lshl_b64 s[54:55], s[46:47], 19
	s_add_u32 s54, s64, s54
	s_addc_u32 s55, s65, s55
	s_and_b64 s[62:63], s[4:5], exec
	s_cselect_b32 s47, s55, s61
	s_cselect_b32 s83, s54, s60
	s_add_u32 s58, s58, 0x40080
	s_addc_u32 s59, s59, 0
	s_add_u32 s84, s60, 0x100
	s_addc_u32 s85, s61, 0
	s_mov_b32 s86, -2
	ds_read_b128 v[152:155], v148
	ds_read_b128 v[156:159], v148 offset:1024
	ds_read_b128 v[160:163], v148 offset:2048
	ds_read_b128 v[164:167], v148 offset:3072
	ds_read_b128 v[168:171], v149
	ds_read_b128 v[172:175], v149 offset:1024
	ds_read_b128 v[176:179], v149 offset:2048
	ds_read_b128 v[184:187], v149 offset:3072
	s_add_u32 s18, s58, 0xfffc0080
	s_addc_u32 s19, s59, -1
	s_cmp_eq_u32 s86, 12
	s_cselect_b32 s63, s49, s19
	s_cselect_b32 s62, s82, s18
	s_cselect_b32 s61, s47, s85
	s_cselect_b32 s60, s83, s84
	v_lshl_add_u64 v[220:221], s[58:59], 0, v[138:139]
	s_add_i32 m0, s68, 0xc000
	ds_read_b128 v[188:191], v150
	ds_read_b128 v[192:195], v150 offset:1024
	ds_read_b128 v[196:199], v150 offset:2048
	ds_read_b128 v[200:203], v150 offset:3072
	ds_read_b128 v[204:207], v150 offset:4096
	ds_read_b128 v[208:211], v150 offset:5120
	ds_read_b128 v[212:215], v150 offset:6144
	ds_read_b128 v[216:219], v150 offset:7168
	global_load_lds_dwordx4 v[220:221], off
	v_lshl_add_u64 v[220:221], s[58:59], 0, v[140:141]
	s_add_i32 m0, s68, 0xe000
	s_nop 0
	global_load_lds_dwordx4 v[220:221], off
	s_waitcnt vmcnt(8)
	s_waitcnt lgkmcnt(0)
	s_barrier
	s_setprio 1
	v_mfma_f32_16x16x32_bf16 v[124:127], v[152:155], v[188:191], 0
	v_mfma_f32_16x16x32_bf16 v[124:127], v[156:159], v[192:195], v[124:127]
	v_mfma_f32_16x16x32_bf16 v[120:123], v[160:163], v[188:191], 0
	v_mfma_f32_16x16x32_bf16 v[120:123], v[164:167], v[192:195], v[120:123]
	v_mfma_f32_16x16x32_bf16 v[116:119], v[152:155], v[196:199], 0
	v_mfma_f32_16x16x32_bf16 v[116:119], v[156:159], v[200:203], v[116:119]
	v_mfma_f32_16x16x32_bf16 v[112:115], v[160:163], v[196:199], 0
	v_mfma_f32_16x16x32_bf16 v[112:115], v[164:167], v[200:203], v[112:115]
	v_mfma_f32_16x16x32_bf16 v[108:111], v[152:155], v[204:207], 0
	v_mfma_f32_16x16x32_bf16 v[108:111], v[156:159], v[208:211], v[108:111]
	v_mfma_f32_16x16x32_bf16 v[104:107], v[160:163], v[204:207], 0
	v_mfma_f32_16x16x32_bf16 v[104:107], v[164:167], v[208:211], v[104:107]
	v_mfma_f32_16x16x32_bf16 v[100:103], v[152:155], v[212:215], 0
	v_mfma_f32_16x16x32_bf16 v[100:103], v[156:159], v[216:219], v[100:103]
	v_mfma_f32_16x16x32_bf16 v[96:99], v[160:163], v[212:215], 0
	v_mfma_f32_16x16x32_bf16 v[96:99], v[164:167], v[216:219], v[96:99]
	v_mfma_f32_16x16x32_bf16 v[68:71], v[168:171], v[188:191], 0
	v_mfma_f32_16x16x32_bf16 v[68:71], v[172:175], v[192:195], v[68:71]
	v_mfma_f32_16x16x32_bf16 v[64:67], v[176:179], v[188:191], 0
	v_mfma_f32_16x16x32_bf16 v[64:67], v[184:187], v[192:195], v[64:67]
	v_mfma_f32_16x16x32_bf16 v[52:55], v[168:171], v[196:199], 0
	v_mfma_f32_16x16x32_bf16 v[52:55], v[172:175], v[200:203], v[52:55]
	v_mfma_f32_16x16x32_bf16 v[48:51], v[176:179], v[196:199], 0
	v_mfma_f32_16x16x32_bf16 v[48:51], v[184:187], v[200:203], v[48:51]
	v_mfma_f32_16x16x32_bf16 v[44:47], v[168:171], v[204:207], 0
	v_mfma_f32_16x16x32_bf16 v[44:47], v[172:175], v[208:211], v[44:47]
	v_mfma_f32_16x16x32_bf16 v[40:43], v[176:179], v[204:207], 0
	v_mfma_f32_16x16x32_bf16 v[40:43], v[184:187], v[208:211], v[40:43]
	v_mfma_f32_16x16x32_bf16 v[36:39], v[168:171], v[212:215], 0
	v_mfma_f32_16x16x32_bf16 v[36:39], v[172:175], v[216:219], v[36:39]
	v_mfma_f32_16x16x32_bf16 v[32:35], v[176:179], v[212:215], 0
	v_mfma_f32_16x16x32_bf16 v[32:35], v[184:187], v[216:219], v[32:35]
	s_setprio 0
	s_barrier
	s_add_i32 s18, s76, s66
	v_lshl_add_u64 v[220:221], s[60:61], 0, v[132:133]
	s_mov_b32 m0, s18
	ds_read_b128 v[188:191], v150 offset:16384
	ds_read_b128 v[192:195], v150 offset:17408
	ds_read_b128 v[196:199], v150 offset:18432
	ds_read_b128 v[200:203], v150 offset:19456
	ds_read_b128 v[204:207], v150 offset:20480
	ds_read_b128 v[208:211], v150 offset:21504
	ds_read_b128 v[212:215], v150 offset:22528
	ds_read_b128 v[216:219], v150 offset:23552
	global_load_lds_dwordx4 v[220:221], off
	s_add_i32 m0, s18, 0x2000
	s_add_u32 s88, s60, 0x40000
	v_lshl_add_u64 v[222:223], s[60:61], 0, v[128:129]
	s_addc_u32 s89, s61, 0
	s_add_i32 s18, s77, s66
	global_load_lds_dwordx4 v[222:223], off
	v_lshl_add_u64 v[224:225], s[88:89], 0, v[132:133]
	s_mov_b32 m0, s18
	v_lshl_add_u64 v[226:227], s[62:63], 0, v[130:131]
	global_load_lds_dwordx4 v[224:225], off
	v_lshl_add_u64 v[224:225], s[88:89], 0, v[128:129]
	s_add_i32 m0, s18, 0x2000
	s_nop 0
	global_load_lds_dwordx4 v[224:225], off
	v_lshl_add_u64 v[224:225], s[62:63], 0, v[134:135]
	s_mov_b32 m0, s68
	s_nop 0
	global_load_lds_dwordx4 v[224:225], off
	s_mov_b32 m0, s69
	s_nop 0
	global_load_lds_dwordx4 v[226:227], off
	s_waitcnt vmcnt(8)
	s_waitcnt lgkmcnt(0)
	s_barrier
	s_setprio 1
	v_mfma_f32_16x16x32_bf16 v[92:95], v[152:155], v[188:191], 0
	v_mfma_f32_16x16x32_bf16 v[92:95], v[156:159], v[192:195], v[92:95]
	v_mfma_f32_16x16x32_bf16 v[88:91], v[160:163], v[188:191], 0
	v_mfma_f32_16x16x32_bf16 v[88:91], v[164:167], v[192:195], v[88:91]
	v_mfma_f32_16x16x32_bf16 v[84:87], v[152:155], v[196:199], 0
	v_mfma_f32_16x16x32_bf16 v[84:87], v[156:159], v[200:203], v[84:87]
	v_mfma_f32_16x16x32_bf16 v[80:83], v[160:163], v[196:199], 0
	v_mfma_f32_16x16x32_bf16 v[80:83], v[164:167], v[200:203], v[80:83]
	v_mfma_f32_16x16x32_bf16 v[76:79], v[152:155], v[204:207], 0
	v_mfma_f32_16x16x32_bf16 v[76:79], v[156:159], v[208:211], v[76:79]
	v_mfma_f32_16x16x32_bf16 v[72:75], v[160:163], v[204:207], 0
	v_mfma_f32_16x16x32_bf16 v[72:75], v[164:167], v[208:211], v[72:75]
	v_mfma_f32_16x16x32_bf16 v[60:63], v[152:155], v[212:215], 0
	v_mfma_f32_16x16x32_bf16 v[60:63], v[156:159], v[216:219], v[60:63]
	v_mfma_f32_16x16x32_bf16 v[56:59], v[160:163], v[212:215], 0
	v_mfma_f32_16x16x32_bf16 v[56:59], v[164:167], v[216:219], v[56:59]
	v_mfma_f32_16x16x32_bf16 v[28:31], v[168:171], v[188:191], 0
	v_mfma_f32_16x16x32_bf16 v[28:31], v[172:175], v[192:195], v[28:31]
	v_mfma_f32_16x16x32_bf16 v[24:27], v[176:179], v[188:191], 0
	v_mfma_f32_16x16x32_bf16 v[24:27], v[184:187], v[192:195], v[24:27]
	v_mfma_f32_16x16x32_bf16 v[20:23], v[168:171], v[196:199], 0
	v_mfma_f32_16x16x32_bf16 v[20:23], v[172:175], v[200:203], v[20:23]
	v_mfma_f32_16x16x32_bf16 v[16:19], v[176:179], v[196:199], 0
	v_mfma_f32_16x16x32_bf16 v[16:19], v[184:187], v[200:203], v[16:19]
	v_mfma_f32_16x16x32_bf16 v[12:15], v[168:171], v[204:207], 0
	v_mfma_f32_16x16x32_bf16 v[12:15], v[172:175], v[208:211], v[12:15]
	v_mfma_f32_16x16x32_bf16 v[8:11], v[176:179], v[204:207], 0
	v_mfma_f32_16x16x32_bf16 v[8:11], v[184:187], v[208:211], v[8:11]
	v_mfma_f32_16x16x32_bf16 v[4:7], v[168:171], v[212:215], 0
	v_mfma_f32_16x16x32_bf16 v[4:7], v[172:175], v[216:219], v[4:7]
	v_mfma_f32_16x16x32_bf16 v[0:3], v[176:179], v[212:215], 0
	v_mfma_f32_16x16x32_bf16 v[0:3], v[184:187], v[216:219], v[0:3]
	s_setprio 0
	s_barrier
	s_branch .Lmid_gemm2
.LBB0_387:
	ds_read_b128 v[152:155], v148
	ds_read_b128 v[156:159], v148 offset:1024
	ds_read_b128 v[160:163], v148 offset:2048
	ds_read_b128 v[164:167], v148 offset:3072
	ds_read_b128 v[168:171], v149
	ds_read_b128 v[172:175], v149 offset:1024
	ds_read_b128 v[176:179], v149 offset:2048
	ds_read_b128 v[184:187], v149 offset:3072
	s_add_u32 s18, s58, 0xfffc0080
	s_addc_u32 s19, s59, -1
	s_cmp_eq_u32 s86, 12
	s_cselect_b32 s63, s49, s19
	s_cselect_b32 s62, s82, s18
	s_cselect_b32 s61, s47, s85
	s_cselect_b32 s60, s83, s84
	v_lshl_add_u64 v[220:221], s[58:59], 0, v[138:139]
	s_add_i32 m0, s68, 0xc000
	ds_read_b128 v[188:191], v150
	ds_read_b128 v[192:195], v150 offset:1024
	ds_read_b128 v[196:199], v150 offset:2048
	ds_read_b128 v[200:203], v150 offset:3072
	ds_read_b128 v[204:207], v150 offset:4096
	ds_read_b128 v[208:211], v150 offset:5120
	ds_read_b128 v[212:215], v150 offset:6144
	ds_read_b128 v[216:219], v150 offset:7168
	global_load_lds_dwordx4 v[220:221], off
	v_lshl_add_u64 v[220:221], s[58:59], 0, v[140:141]
	s_add_i32 m0, s68, 0xe000
	s_nop 0
	global_load_lds_dwordx4 v[220:221], off
	s_waitcnt vmcnt(8)
	s_waitcnt lgkmcnt(0)
	s_barrier
	s_setprio 1
	v_mfma_f32_16x16x32_bf16 v[124:127], v[152:155], v[188:191], v[124:127]
	v_mfma_f32_16x16x32_bf16 v[124:127], v[156:159], v[192:195], v[124:127]
	v_mfma_f32_16x16x32_bf16 v[120:123], v[160:163], v[188:191], v[120:123]
	v_mfma_f32_16x16x32_bf16 v[120:123], v[164:167], v[192:195], v[120:123]
	v_mfma_f32_16x16x32_bf16 v[116:119], v[152:155], v[196:199], v[116:119]
	v_mfma_f32_16x16x32_bf16 v[116:119], v[156:159], v[200:203], v[116:119]
	v_mfma_f32_16x16x32_bf16 v[112:115], v[160:163], v[196:199], v[112:115]
	v_mfma_f32_16x16x32_bf16 v[112:115], v[164:167], v[200:203], v[112:115]
	v_mfma_f32_16x16x32_bf16 v[108:111], v[152:155], v[204:207], v[108:111]
	v_mfma_f32_16x16x32_bf16 v[108:111], v[156:159], v[208:211], v[108:111]
	v_mfma_f32_16x16x32_bf16 v[104:107], v[160:163], v[204:207], v[104:107]
	v_mfma_f32_16x16x32_bf16 v[104:107], v[164:167], v[208:211], v[104:107]
	v_mfma_f32_16x16x32_bf16 v[100:103], v[152:155], v[212:215], v[100:103]
	v_mfma_f32_16x16x32_bf16 v[100:103], v[156:159], v[216:219], v[100:103]
	v_mfma_f32_16x16x32_bf16 v[96:99], v[160:163], v[212:215], v[96:99]
	v_mfma_f32_16x16x32_bf16 v[96:99], v[164:167], v[216:219], v[96:99]
	v_mfma_f32_16x16x32_bf16 v[68:71], v[168:171], v[188:191], v[68:71]
	v_mfma_f32_16x16x32_bf16 v[68:71], v[172:175], v[192:195], v[68:71]
	v_mfma_f32_16x16x32_bf16 v[64:67], v[176:179], v[188:191], v[64:67]
	v_mfma_f32_16x16x32_bf16 v[64:67], v[184:187], v[192:195], v[64:67]
	v_mfma_f32_16x16x32_bf16 v[52:55], v[168:171], v[196:199], v[52:55]
	v_mfma_f32_16x16x32_bf16 v[52:55], v[172:175], v[200:203], v[52:55]
	v_mfma_f32_16x16x32_bf16 v[48:51], v[176:179], v[196:199], v[48:51]
	v_mfma_f32_16x16x32_bf16 v[48:51], v[184:187], v[200:203], v[48:51]
	v_mfma_f32_16x16x32_bf16 v[44:47], v[168:171], v[204:207], v[44:47]
	v_mfma_f32_16x16x32_bf16 v[44:47], v[172:175], v[208:211], v[44:47]
	v_mfma_f32_16x16x32_bf16 v[40:43], v[176:179], v[204:207], v[40:43]
	v_mfma_f32_16x16x32_bf16 v[40:43], v[184:187], v[208:211], v[40:43]
	v_mfma_f32_16x16x32_bf16 v[36:39], v[168:171], v[212:215], v[36:39]
	v_mfma_f32_16x16x32_bf16 v[36:39], v[172:175], v[216:219], v[36:39]
	v_mfma_f32_16x16x32_bf16 v[32:35], v[176:179], v[212:215], v[32:35]
	v_mfma_f32_16x16x32_bf16 v[32:35], v[184:187], v[216:219], v[32:35]
	s_setprio 0
	s_barrier
	s_add_i32 s18, s76, s66
	v_lshl_add_u64 v[220:221], s[60:61], 0, v[132:133]
	s_mov_b32 m0, s18
	ds_read_b128 v[188:191], v150 offset:16384
	ds_read_b128 v[192:195], v150 offset:17408
	ds_read_b128 v[196:199], v150 offset:18432
	ds_read_b128 v[200:203], v150 offset:19456
	ds_read_b128 v[204:207], v150 offset:20480
	ds_read_b128 v[208:211], v150 offset:21504
	ds_read_b128 v[212:215], v150 offset:22528
	ds_read_b128 v[216:219], v150 offset:23552
	global_load_lds_dwordx4 v[220:221], off
	s_add_i32 m0, s18, 0x2000
	s_add_u32 s88, s60, 0x40000
	v_lshl_add_u64 v[222:223], s[60:61], 0, v[128:129]
	s_addc_u32 s89, s61, 0
	s_add_i32 s18, s77, s66
	global_load_lds_dwordx4 v[222:223], off
	v_lshl_add_u64 v[224:225], s[88:89], 0, v[132:133]
	s_mov_b32 m0, s18
	v_lshl_add_u64 v[226:227], s[62:63], 0, v[130:131]
	global_load_lds_dwordx4 v[224:225], off
	v_lshl_add_u64 v[224:225], s[88:89], 0, v[128:129]
	s_add_i32 m0, s18, 0x2000
	s_nop 0
	global_load_lds_dwordx4 v[224:225], off
	v_lshl_add_u64 v[224:225], s[62:63], 0, v[134:135]
	s_mov_b32 m0, s68
	s_nop 0
	global_load_lds_dwordx4 v[224:225], off
	s_mov_b32 m0, s69
	s_nop 0
	global_load_lds_dwordx4 v[226:227], off
	s_waitcnt vmcnt(8)
	s_waitcnt lgkmcnt(0)
	s_barrier
	s_setprio 1
	v_mfma_f32_16x16x32_bf16 v[92:95], v[152:155], v[188:191], v[92:95]
	v_mfma_f32_16x16x32_bf16 v[92:95], v[156:159], v[192:195], v[92:95]
	v_mfma_f32_16x16x32_bf16 v[88:91], v[160:163], v[188:191], v[88:91]
	v_mfma_f32_16x16x32_bf16 v[88:91], v[164:167], v[192:195], v[88:91]
	v_mfma_f32_16x16x32_bf16 v[84:87], v[152:155], v[196:199], v[84:87]
	v_mfma_f32_16x16x32_bf16 v[84:87], v[156:159], v[200:203], v[84:87]
	v_mfma_f32_16x16x32_bf16 v[80:83], v[160:163], v[196:199], v[80:83]
	v_mfma_f32_16x16x32_bf16 v[80:83], v[164:167], v[200:203], v[80:83]
	v_mfma_f32_16x16x32_bf16 v[76:79], v[152:155], v[204:207], v[76:79]
	v_mfma_f32_16x16x32_bf16 v[76:79], v[156:159], v[208:211], v[76:79]
	v_mfma_f32_16x16x32_bf16 v[72:75], v[160:163], v[204:207], v[72:75]
	v_mfma_f32_16x16x32_bf16 v[72:75], v[164:167], v[208:211], v[72:75]
	v_mfma_f32_16x16x32_bf16 v[60:63], v[152:155], v[212:215], v[60:63]
	v_mfma_f32_16x16x32_bf16 v[60:63], v[156:159], v[216:219], v[60:63]
	v_mfma_f32_16x16x32_bf16 v[56:59], v[160:163], v[212:215], v[56:59]
	v_mfma_f32_16x16x32_bf16 v[56:59], v[164:167], v[216:219], v[56:59]
	v_mfma_f32_16x16x32_bf16 v[28:31], v[168:171], v[188:191], v[28:31]
	v_mfma_f32_16x16x32_bf16 v[28:31], v[172:175], v[192:195], v[28:31]
	v_mfma_f32_16x16x32_bf16 v[24:27], v[176:179], v[188:191], v[24:27]
	v_mfma_f32_16x16x32_bf16 v[24:27], v[184:187], v[192:195], v[24:27]
	v_mfma_f32_16x16x32_bf16 v[20:23], v[168:171], v[196:199], v[20:23]
	v_mfma_f32_16x16x32_bf16 v[20:23], v[172:175], v[200:203], v[20:23]
	v_mfma_f32_16x16x32_bf16 v[16:19], v[176:179], v[196:199], v[16:19]
	v_mfma_f32_16x16x32_bf16 v[16:19], v[184:187], v[200:203], v[16:19]
	v_mfma_f32_16x16x32_bf16 v[12:15], v[168:171], v[204:207], v[12:15]
	v_mfma_f32_16x16x32_bf16 v[12:15], v[172:175], v[208:211], v[12:15]
	v_mfma_f32_16x16x32_bf16 v[8:11], v[176:179], v[204:207], v[8:11]
	v_mfma_f32_16x16x32_bf16 v[8:11], v[184:187], v[208:211], v[8:11]
	v_mfma_f32_16x16x32_bf16 v[4:7], v[168:171], v[212:215], v[4:7]
	v_mfma_f32_16x16x32_bf16 v[4:7], v[172:175], v[216:219], v[4:7]
	v_mfma_f32_16x16x32_bf16 v[0:3], v[176:179], v[212:215], v[0:3]
	v_mfma_f32_16x16x32_bf16 v[0:3], v[184:187], v[216:219], v[0:3]
	s_setprio 0
	s_barrier
.Lmid_gemm2:
	s_add_i32 s18, 0, 0x18000
	s_add_i32 s19, 0, 0x1c000
	v_add_u32_e32 v164, s18, v147
	v_add_u32_e32 v181, s19, v147
	ds_read_b128 v[152:155], v164
	ds_read_b128 v[156:159], v164 offset:1024
	ds_read_b128 v[160:163], v164 offset:2048
	ds_read_b128 v[164:167], v164 offset:3072
	ds_read_b128 v[168:171], v181
	ds_read_b128 v[172:175], v181 offset:1024
	ds_read_b128 v[176:179], v181 offset:2048
	ds_read_b128 v[184:187], v181 offset:3072
	s_add_u32 s62, s62, 0x40000
	s_addc_u32 s63, s63, 0
	s_mov_b32 m0, s70
	v_lshl_add_u64 v[228:229], s[62:63], 0, v[134:135]
	ds_read_b128 v[188:191], v150 offset:32768
	ds_read_b128 v[192:195], v150 offset:33792
	ds_read_b128 v[196:199], v150 offset:34816
	ds_read_b128 v[200:203], v150 offset:35840
	ds_read_b128 v[204:207], v150 offset:36864
	ds_read_b128 v[208:211], v150 offset:37888
	ds_read_b128 v[212:215], v150 offset:38912
	ds_read_b128 v[216:219], v150 offset:39936
	global_load_lds_dwordx4 v[228:229], off
	v_lshl_add_u64 v[228:229], s[62:63], 0, v[130:131]
	s_mov_b32 m0, s71
	s_nop 0
	global_load_lds_dwordx4 v[228:229], off
	s_waitcnt vmcnt(8)
	s_waitcnt lgkmcnt(0)
	s_barrier
	s_setprio 1
	v_mfma_f32_16x16x32_bf16 v[124:127], v[152:155], v[188:191], v[124:127]
	v_mfma_f32_16x16x32_bf16 v[124:127], v[156:159], v[192:195], v[124:127]
	v_mfma_f32_16x16x32_bf16 v[120:123], v[160:163], v[188:191], v[120:123]
	v_mfma_f32_16x16x32_bf16 v[120:123], v[164:167], v[192:195], v[120:123]
	v_mfma_f32_16x16x32_bf16 v[116:119], v[152:155], v[196:199], v[116:119]
	v_mfma_f32_16x16x32_bf16 v[116:119], v[156:159], v[200:203], v[116:119]
	v_mfma_f32_16x16x32_bf16 v[112:115], v[160:163], v[196:199], v[112:115]
	v_mfma_f32_16x16x32_bf16 v[112:115], v[164:167], v[200:203], v[112:115]
	v_mfma_f32_16x16x32_bf16 v[108:111], v[152:155], v[204:207], v[108:111]
	v_mfma_f32_16x16x32_bf16 v[108:111], v[156:159], v[208:211], v[108:111]
	v_mfma_f32_16x16x32_bf16 v[104:107], v[160:163], v[204:207], v[104:107]
	v_mfma_f32_16x16x32_bf16 v[104:107], v[164:167], v[208:211], v[104:107]
	v_mfma_f32_16x16x32_bf16 v[100:103], v[152:155], v[212:215], v[100:103]
	v_mfma_f32_16x16x32_bf16 v[100:103], v[156:159], v[216:219], v[100:103]
	v_mfma_f32_16x16x32_bf16 v[96:99], v[160:163], v[212:215], v[96:99]
	v_mfma_f32_16x16x32_bf16 v[96:99], v[164:167], v[216:219], v[96:99]
	v_mfma_f32_16x16x32_bf16 v[68:71], v[168:171], v[188:191], v[68:71]
	v_mfma_f32_16x16x32_bf16 v[68:71], v[172:175], v[192:195], v[68:71]
	v_mfma_f32_16x16x32_bf16 v[64:67], v[176:179], v[188:191], v[64:67]
	v_mfma_f32_16x16x32_bf16 v[64:67], v[184:187], v[192:195], v[64:67]
	v_mfma_f32_16x16x32_bf16 v[52:55], v[168:171], v[196:199], v[52:55]
	v_mfma_f32_16x16x32_bf16 v[52:55], v[172:175], v[200:203], v[52:55]
	v_mfma_f32_16x16x32_bf16 v[48:51], v[176:179], v[196:199], v[48:51]
	v_mfma_f32_16x16x32_bf16 v[48:51], v[184:187], v[200:203], v[48:51]
	v_mfma_f32_16x16x32_bf16 v[44:47], v[168:171], v[204:207], v[44:47]
	v_mfma_f32_16x16x32_bf16 v[44:47], v[172:175], v[208:211], v[44:47]
	v_mfma_f32_16x16x32_bf16 v[40:43], v[176:179], v[204:207], v[40:43]
	v_mfma_f32_16x16x32_bf16 v[40:43], v[184:187], v[208:211], v[40:43]
	v_mfma_f32_16x16x32_bf16 v[36:39], v[168:171], v[212:215], v[36:39]
	v_mfma_f32_16x16x32_bf16 v[36:39], v[172:175], v[216:219], v[36:39]
	v_mfma_f32_16x16x32_bf16 v[32:35], v[176:179], v[212:215], v[32:35]
	v_mfma_f32_16x16x32_bf16 v[32:35], v[184:187], v[216:219], v[32:35]
	s_setprio 0
	s_barrier
	s_add_i32 s18, s18, s66
	v_lshl_add_u64 v[220:221], v[220:221], 0, s[6:7]
	s_mov_b32 m0, s18
	ds_read_b128 v[188:191], v150 offset:49152
	ds_read_b128 v[192:195], v150 offset:50176
	ds_read_b128 v[196:199], v150 offset:51200
	ds_read_b128 v[200:203], v150 offset:52224
	ds_read_b128 v[204:207], v150 offset:53248
	ds_read_b128 v[208:211], v150 offset:54272
	ds_read_b128 v[212:215], v150 offset:55296
	ds_read_b128 v[216:219], v150 offset:56320
	global_load_lds_dwordx4 v[220:221], off
	s_add_i32 m0, s18, 0x2000
	s_add_u32 s60, s60, 0x40080
	v_lshl_add_u64 v[220:221], v[222:223], 0, s[6:7]
	s_addc_u32 s61, s61, 0
	s_add_i32 s18, s19, s66
	global_load_lds_dwordx4 v[220:221], off
	v_lshl_add_u64 v[220:221], s[60:61], 0, v[132:133]
	s_mov_b32 m0, s18
	s_nop 0
	global_load_lds_dwordx4 v[220:221], off
	v_lshl_add_u64 v[220:221], s[60:61], 0, v[128:129]
	s_add_i32 m0, s18, 0x2000
	s_nop 0
	global_load_lds_dwordx4 v[220:221], off
	v_lshl_add_u64 v[220:221], v[224:225], 0, s[6:7]
	s_mov_b32 m0, s74
	s_nop 0
	global_load_lds_dwordx4 v[220:221], off
	v_lshl_add_u64 v[220:221], v[226:227], 0, s[6:7]
	s_mov_b32 m0, s75
	s_nop 0
	global_load_lds_dwordx4 v[220:221], off
	s_waitcnt vmcnt(8)
	s_waitcnt lgkmcnt(0)
	s_barrier
	s_setprio 1
	v_mfma_f32_16x16x32_bf16 v[92:95], v[152:155], v[188:191], v[92:95]
	v_mfma_f32_16x16x32_bf16 v[92:95], v[156:159], v[192:195], v[92:95]
	v_mfma_f32_16x16x32_bf16 v[88:91], v[160:163], v[188:191], v[88:91]
	v_mfma_f32_16x16x32_bf16 v[88:91], v[164:167], v[192:195], v[88:91]
	v_mfma_f32_16x16x32_bf16 v[84:87], v[152:155], v[196:199], v[84:87]
	v_mfma_f32_16x16x32_bf16 v[84:87], v[156:159], v[200:203], v[84:87]
	v_mfma_f32_16x16x32_bf16 v[80:83], v[160:163], v[196:199], v[80:83]
	v_mfma_f32_16x16x32_bf16 v[80:83], v[164:167], v[200:203], v[80:83]
	v_mfma_f32_16x16x32_bf16 v[76:79], v[152:155], v[204:207], v[76:79]
	v_mfma_f32_16x16x32_bf16 v[76:79], v[156:159], v[208:211], v[76:79]
	v_mfma_f32_16x16x32_bf16 v[72:75], v[160:163], v[204:207], v[72:75]
	v_mfma_f32_16x16x32_bf16 v[72:75], v[164:167], v[208:211], v[72:75]
	v_mfma_f32_16x16x32_bf16 v[60:63], v[152:155], v[212:215], v[60:63]
	v_mfma_f32_16x16x32_bf16 v[60:63], v[156:159], v[216:219], v[60:63]
	v_mfma_f32_16x16x32_bf16 v[56:59], v[160:163], v[212:215], v[56:59]
	v_mfma_f32_16x16x32_bf16 v[56:59], v[164:167], v[216:219], v[56:59]
	v_mfma_f32_16x16x32_bf16 v[28:31], v[168:171], v[188:191], v[28:31]
	v_mfma_f32_16x16x32_bf16 v[28:31], v[172:175], v[192:195], v[28:31]
	v_mfma_f32_16x16x32_bf16 v[24:27], v[176:179], v[188:191], v[24:27]
	v_mfma_f32_16x16x32_bf16 v[24:27], v[184:187], v[192:195], v[24:27]
	v_mfma_f32_16x16x32_bf16 v[20:23], v[168:171], v[196:199], v[20:23]
	v_mfma_f32_16x16x32_bf16 v[20:23], v[172:175], v[200:203], v[20:23]
	v_mfma_f32_16x16x32_bf16 v[16:19], v[176:179], v[196:199], v[16:19]
	v_mfma_f32_16x16x32_bf16 v[16:19], v[184:187], v[200:203], v[16:19]
	v_mfma_f32_16x16x32_bf16 v[12:15], v[168:171], v[204:207], v[12:15]
	v_mfma_f32_16x16x32_bf16 v[12:15], v[172:175], v[208:211], v[12:15]
	v_mfma_f32_16x16x32_bf16 v[8:11], v[176:179], v[204:207], v[8:11]
	v_mfma_f32_16x16x32_bf16 v[8:11], v[184:187], v[208:211], v[8:11]
	v_mfma_f32_16x16x32_bf16 v[4:7], v[168:171], v[212:215], v[4:7]
	v_mfma_f32_16x16x32_bf16 v[4:7], v[172:175], v[216:219], v[4:7]
	v_mfma_f32_16x16x32_bf16 v[0:3], v[176:179], v[212:215], v[0:3]
	v_mfma_f32_16x16x32_bf16 v[0:3], v[184:187], v[216:219], v[0:3]
	s_setprio 0
	s_barrier
	s_add_i32 s86, s86, 2
	s_add_u32 s58, s58, 0x100
	s_addc_u32 s59, s59, 0
	s_add_u32 s84, s84, 0x100
	s_addc_u32 s85, s85, 0
	s_cmp_gt_u32 s86, 13
	s_cbranch_scc0 .LBB0_387
	s_and_b64 vcc, exec, s[8:9]
	s_cbranch_vccz .LBB0_390
	s_barrier

.LBB0_600:
	s_ashr_i32 s49, s48, 31
	s_lshl_b64 s[18:19], s[48:49], 19
	s_add_u32 s52, s38, s18
	s_addc_u32 s53, s39, s19
	s_and_b64 s[18:19], s[4:5], exec
	s_cselect_b32 s49, s53, s59
	s_cselect_b32 s84, s52, s58
	s_ashr_i32 s47, s46, 31
	s_lshl_b64 s[18:19], s[46:47], 19
	s_add_u32 s54, s64, s18
	s_addc_u32 s55, s65, s19
	s_and_b64 s[18:19], s[4:5], exec
	s_cselect_b32 s47, s55, s61
	s_cselect_b32 s85, s54, s60
	s_add_u32 s58, s58, 0x40080
	s_addc_u32 s59, s59, 0
	s_add_u32 s86, s60, 0x100
	s_addc_u32 s87, s61, 0
	s_mov_b32 s88, -2
	ds_read_b128 v[152:155], v149
	ds_read_b128 v[156:159], v149 offset:1024
	ds_read_b128 v[160:163], v149 offset:2048
	ds_read_b128 v[164:167], v149 offset:3072
	ds_read_b128 v[168:171], v150
	ds_read_b128 v[172:175], v150 offset:1024
	ds_read_b128 v[176:179], v150 offset:2048
	ds_read_b128 v[184:187], v150 offset:3072
	s_add_u32 s18, s58, 0xfffc0080
	s_addc_u32 s19, s59, -1
	s_cmp_eq_u32 s88, 12
	s_cselect_b32 s63, s49, s19
	s_cselect_b32 s62, s84, s18
	s_cselect_b32 s61, s47, s87
	s_cselect_b32 s60, s85, s86
	v_lshl_add_u64 v[144:145], s[58:59], 0, v[136:137]
	s_add_i32 m0, s57, 0xc000
	ds_read_b128 v[188:191], v151
	ds_read_b128 v[192:195], v151 offset:1024
	ds_read_b128 v[196:199], v151 offset:2048
	ds_read_b128 v[200:203], v151 offset:3072
	ds_read_b128 v[204:207], v151 offset:4096
	ds_read_b128 v[208:211], v151 offset:5120
	ds_read_b128 v[212:215], v151 offset:6144
	ds_read_b128 v[216:219], v151 offset:7168
	global_load_lds_dwordx4 v[144:145], off
	v_lshl_add_u64 v[144:145], s[58:59], 0, v[138:139]
	s_add_i32 m0, s57, 0xe000
	s_nop 0
	global_load_lds_dwordx4 v[144:145], off
	s_waitcnt vmcnt(8)
	s_waitcnt lgkmcnt(0)
	s_barrier
	s_setprio 1
	v_mfma_f32_16x16x32_bf16 v[124:127], v[152:155], v[188:191], 0
	v_mfma_f32_16x16x32_bf16 v[124:127], v[156:159], v[192:195], v[124:127]
	v_mfma_f32_16x16x32_bf16 v[120:123], v[160:163], v[188:191], 0
	v_mfma_f32_16x16x32_bf16 v[120:123], v[164:167], v[192:195], v[120:123]
	v_mfma_f32_16x16x32_bf16 v[116:119], v[152:155], v[196:199], 0
	v_mfma_f32_16x16x32_bf16 v[116:119], v[156:159], v[200:203], v[116:119]
	v_mfma_f32_16x16x32_bf16 v[108:111], v[160:163], v[196:199], 0
	v_mfma_f32_16x16x32_bf16 v[108:111], v[164:167], v[200:203], v[108:111]
	v_mfma_f32_16x16x32_bf16 v[100:103], v[152:155], v[204:207], 0
	v_mfma_f32_16x16x32_bf16 v[100:103], v[156:159], v[208:211], v[100:103]
	v_mfma_f32_16x16x32_bf16 v[92:95], v[160:163], v[204:207], 0
	v_mfma_f32_16x16x32_bf16 v[92:95], v[164:167], v[208:211], v[92:95]
	v_mfma_f32_16x16x32_bf16 v[84:87], v[152:155], v[212:215], 0
	v_mfma_f32_16x16x32_bf16 v[84:87], v[156:159], v[216:219], v[84:87]
	v_mfma_f32_16x16x32_bf16 v[76:79], v[160:163], v[212:215], 0
	v_mfma_f32_16x16x32_bf16 v[76:79], v[164:167], v[216:219], v[76:79]
	v_mfma_f32_16x16x32_bf16 v[112:115], v[168:171], v[188:191], 0
	v_mfma_f32_16x16x32_bf16 v[112:115], v[172:175], v[192:195], v[112:115]
	v_mfma_f32_16x16x32_bf16 v[104:107], v[176:179], v[188:191], 0
	v_mfma_f32_16x16x32_bf16 v[104:107], v[184:187], v[192:195], v[104:107]
	v_mfma_f32_16x16x32_bf16 v[96:99], v[168:171], v[196:199], 0
	v_mfma_f32_16x16x32_bf16 v[96:99], v[172:175], v[200:203], v[96:99]
	v_mfma_f32_16x16x32_bf16 v[88:91], v[176:179], v[196:199], 0
	v_mfma_f32_16x16x32_bf16 v[88:91], v[184:187], v[200:203], v[88:91]
	v_mfma_f32_16x16x32_bf16 v[80:83], v[168:171], v[204:207], 0
	v_mfma_f32_16x16x32_bf16 v[80:83], v[172:175], v[208:211], v[80:83]
	v_mfma_f32_16x16x32_bf16 v[72:75], v[176:179], v[204:207], 0
	v_mfma_f32_16x16x32_bf16 v[72:75], v[184:187], v[208:211], v[72:75]
	v_mfma_f32_16x16x32_bf16 v[68:71], v[168:171], v[212:215], 0
	v_mfma_f32_16x16x32_bf16 v[68:71], v[172:175], v[216:219], v[68:71]
	v_mfma_f32_16x16x32_bf16 v[64:67], v[176:179], v[212:215], 0
	v_mfma_f32_16x16x32_bf16 v[64:67], v[184:187], v[216:219], v[64:67]
	s_setprio 0
	s_barrier
	s_add_i32 s18, s73, s66
	v_lshl_add_u64 v[144:145], s[60:61], 0, v[130:131]
	s_mov_b32 m0, s18
	ds_read_b128 v[188:191], v151 offset:16384
	ds_read_b128 v[192:195], v151 offset:17408
	ds_read_b128 v[196:199], v151 offset:18432
	ds_read_b128 v[200:203], v151 offset:19456
	ds_read_b128 v[204:207], v151 offset:20480
	ds_read_b128 v[208:211], v151 offset:21504
	ds_read_b128 v[212:215], v151 offset:22528
	ds_read_b128 v[216:219], v151 offset:23552
	global_load_lds_dwordx4 v[144:145], off
	s_add_i32 m0, s18, 0x2000
	s_add_u32 s18, s60, 0x40000
	v_lshl_add_u64 v[220:221], s[60:61], 0, v[134:135]
	s_addc_u32 s19, s61, 0
	s_add_i32 s79, s74, s66
	global_load_lds_dwordx4 v[220:221], off
	v_lshl_add_u64 v[222:223], s[18:19], 0, v[130:131]
	s_mov_b32 m0, s79
	v_lshl_add_u64 v[224:225], s[62:63], 0, v[132:133]
	global_load_lds_dwordx4 v[222:223], off
	v_lshl_add_u64 v[222:223], s[18:19], 0, v[134:135]
	s_add_i32 m0, s79, 0x2000
	s_nop 0
	global_load_lds_dwordx4 v[222:223], off
	v_lshl_add_u64 v[222:223], s[62:63], 0, v[128:129]
	s_mov_b32 m0, s57
	s_nop 0
	global_load_lds_dwordx4 v[222:223], off
	s_mov_b32 m0, s67
	s_nop 0
	global_load_lds_dwordx4 v[224:225], off
	s_waitcnt vmcnt(8)
	s_waitcnt lgkmcnt(0)
	s_barrier
	s_setprio 1
	v_mfma_f32_16x16x32_bf16 v[60:63], v[152:155], v[188:191], 0
	v_mfma_f32_16x16x32_bf16 v[60:63], v[156:159], v[192:195], v[60:63]
	v_mfma_f32_16x16x32_bf16 v[56:59], v[160:163], v[188:191], 0
	v_mfma_f32_16x16x32_bf16 v[56:59], v[164:167], v[192:195], v[56:59]
	v_mfma_f32_16x16x32_bf16 v[52:55], v[152:155], v[196:199], 0
	v_mfma_f32_16x16x32_bf16 v[52:55], v[156:159], v[200:203], v[52:55]
	v_mfma_f32_16x16x32_bf16 v[44:47], v[160:163], v[196:199], 0
	v_mfma_f32_16x16x32_bf16 v[44:47], v[164:167], v[200:203], v[44:47]
	v_mfma_f32_16x16x32_bf16 v[36:39], v[152:155], v[204:207], 0
	v_mfma_f32_16x16x32_bf16 v[36:39], v[156:159], v[208:211], v[36:39]
	v_mfma_f32_16x16x32_bf16 v[28:31], v[160:163], v[204:207], 0
	v_mfma_f32_16x16x32_bf16 v[28:31], v[164:167], v[208:211], v[28:31]
	v_mfma_f32_16x16x32_bf16 v[20:23], v[152:155], v[212:215], 0
	v_mfma_f32_16x16x32_bf16 v[20:23], v[156:159], v[216:219], v[20:23]
	v_mfma_f32_16x16x32_bf16 v[12:15], v[160:163], v[212:215], 0
	v_mfma_f32_16x16x32_bf16 v[12:15], v[164:167], v[216:219], v[12:15]
	v_mfma_f32_16x16x32_bf16 v[48:51], v[168:171], v[188:191], 0
	v_mfma_f32_16x16x32_bf16 v[48:51], v[172:175], v[192:195], v[48:51]
	v_mfma_f32_16x16x32_bf16 v[40:43], v[176:179], v[188:191], 0
	v_mfma_f32_16x16x32_bf16 v[40:43], v[184:187], v[192:195], v[40:43]
	v_mfma_f32_16x16x32_bf16 v[32:35], v[168:171], v[196:199], 0
	v_mfma_f32_16x16x32_bf16 v[32:35], v[172:175], v[200:203], v[32:35]
	v_mfma_f32_16x16x32_bf16 v[24:27], v[176:179], v[196:199], 0
	v_mfma_f32_16x16x32_bf16 v[24:27], v[184:187], v[200:203], v[24:27]
	v_mfma_f32_16x16x32_bf16 v[16:19], v[168:171], v[204:207], 0
	v_mfma_f32_16x16x32_bf16 v[16:19], v[172:175], v[208:211], v[16:19]
	v_mfma_f32_16x16x32_bf16 v[8:11], v[176:179], v[204:207], 0
	v_mfma_f32_16x16x32_bf16 v[8:11], v[184:187], v[208:211], v[8:11]
	v_mfma_f32_16x16x32_bf16 v[4:7], v[168:171], v[212:215], 0
	v_mfma_f32_16x16x32_bf16 v[4:7], v[172:175], v[216:219], v[4:7]
	v_mfma_f32_16x16x32_bf16 v[0:3], v[176:179], v[212:215], 0
	v_mfma_f32_16x16x32_bf16 v[0:3], v[184:187], v[216:219], v[0:3]
	s_setprio 0
	s_barrier
	s_branch .Lmid_gemm3
.LBB0_601:
	ds_read_b128 v[152:155], v149
	ds_read_b128 v[156:159], v149 offset:1024
	ds_read_b128 v[160:163], v149 offset:2048
	ds_read_b128 v[164:167], v149 offset:3072
	ds_read_b128 v[168:171], v150
	ds_read_b128 v[172:175], v150 offset:1024
	ds_read_b128 v[176:179], v150 offset:2048
	ds_read_b128 v[184:187], v150 offset:3072
	s_add_u32 s18, s58, 0xfffc0080
	s_addc_u32 s19, s59, -1
	s_cmp_eq_u32 s88, 12
	s_cselect_b32 s63, s49, s19
	s_cselect_b32 s62, s84, s18
	s_cselect_b32 s61, s47, s87
	s_cselect_b32 s60, s85, s86
	v_lshl_add_u64 v[144:145], s[58:59], 0, v[136:137]
	s_add_i32 m0, s57, 0xc000
	ds_read_b128 v[188:191], v151
	ds_read_b128 v[192:195], v151 offset:1024
	ds_read_b128 v[196:199], v151 offset:2048
	ds_read_b128 v[200:203], v151 offset:3072
	ds_read_b128 v[204:207], v151 offset:4096
	ds_read_b128 v[208:211], v151 offset:5120
	ds_read_b128 v[212:215], v151 offset:6144
	ds_read_b128 v[216:219], v151 offset:7168
	global_load_lds_dwordx4 v[144:145], off
	v_lshl_add_u64 v[144:145], s[58:59], 0, v[138:139]
	s_add_i32 m0, s57, 0xe000
	s_nop 0
	global_load_lds_dwordx4 v[144:145], off
	s_waitcnt vmcnt(8)
	s_waitcnt lgkmcnt(0)
	s_barrier
	s_setprio 1
	v_mfma_f32_16x16x32_bf16 v[124:127], v[152:155], v[188:191], v[124:127]
	v_mfma_f32_16x16x32_bf16 v[124:127], v[156:159], v[192:195], v[124:127]
	v_mfma_f32_16x16x32_bf16 v[120:123], v[160:163], v[188:191], v[120:123]
	v_mfma_f32_16x16x32_bf16 v[120:123], v[164:167], v[192:195], v[120:123]
	v_mfma_f32_16x16x32_bf16 v[116:119], v[152:155], v[196:199], v[116:119]
	v_mfma_f32_16x16x32_bf16 v[116:119], v[156:159], v[200:203], v[116:119]
	v_mfma_f32_16x16x32_bf16 v[108:111], v[160:163], v[196:199], v[108:111]
	v_mfma_f32_16x16x32_bf16 v[108:111], v[164:167], v[200:203], v[108:111]
	v_mfma_f32_16x16x32_bf16 v[100:103], v[152:155], v[204:207], v[100:103]
	v_mfma_f32_16x16x32_bf16 v[100:103], v[156:159], v[208:211], v[100:103]
	v_mfma_f32_16x16x32_bf16 v[92:95], v[160:163], v[204:207], v[92:95]
	v_mfma_f32_16x16x32_bf16 v[92:95], v[164:167], v[208:211], v[92:95]
	v_mfma_f32_16x16x32_bf16 v[84:87], v[152:155], v[212:215], v[84:87]
	v_mfma_f32_16x16x32_bf16 v[84:87], v[156:159], v[216:219], v[84:87]
	v_mfma_f32_16x16x32_bf16 v[76:79], v[160:163], v[212:215], v[76:79]
	v_mfma_f32_16x16x32_bf16 v[76:79], v[164:167], v[216:219], v[76:79]
	v_mfma_f32_16x16x32_bf16 v[112:115], v[168:171], v[188:191], v[112:115]
	v_mfma_f32_16x16x32_bf16 v[112:115], v[172:175], v[192:195], v[112:115]
	v_mfma_f32_16x16x32_bf16 v[104:107], v[176:179], v[188:191], v[104:107]
	v_mfma_f32_16x16x32_bf16 v[104:107], v[184:187], v[192:195], v[104:107]
	v_mfma_f32_16x16x32_bf16 v[96:99], v[168:171], v[196:199], v[96:99]
	v_mfma_f32_16x16x32_bf16 v[96:99], v[172:175], v[200:203], v[96:99]
	v_mfma_f32_16x16x32_bf16 v[88:91], v[176:179], v[196:199], v[88:91]
	v_mfma_f32_16x16x32_bf16 v[88:91], v[184:187], v[200:203], v[88:91]
	v_mfma_f32_16x16x32_bf16 v[80:83], v[168:171], v[204:207], v[80:83]
	v_mfma_f32_16x16x32_bf16 v[80:83], v[172:175], v[208:211], v[80:83]
	v_mfma_f32_16x16x32_bf16 v[72:75], v[176:179], v[204:207], v[72:75]
	v_mfma_f32_16x16x32_bf16 v[72:75], v[184:187], v[208:211], v[72:75]
	v_mfma_f32_16x16x32_bf16 v[68:71], v[168:171], v[212:215], v[68:71]
	v_mfma_f32_16x16x32_bf16 v[68:71], v[172:175], v[216:219], v[68:71]
	v_mfma_f32_16x16x32_bf16 v[64:67], v[176:179], v[212:215], v[64:67]
	v_mfma_f32_16x16x32_bf16 v[64:67], v[184:187], v[216:219], v[64:67]
	s_setprio 0
	s_barrier
	s_add_i32 s18, s73, s66
	v_lshl_add_u64 v[144:145], s[60:61], 0, v[130:131]
	s_mov_b32 m0, s18
	ds_read_b128 v[188:191], v151 offset:16384
	ds_read_b128 v[192:195], v151 offset:17408
	ds_read_b128 v[196:199], v151 offset:18432
	ds_read_b128 v[200:203], v151 offset:19456
	ds_read_b128 v[204:207], v151 offset:20480
	ds_read_b128 v[208:211], v151 offset:21504
	ds_read_b128 v[212:215], v151 offset:22528
	ds_read_b128 v[216:219], v151 offset:23552
	global_load_lds_dwordx4 v[144:145], off
	s_add_i32 m0, s18, 0x2000
	s_add_u32 s18, s60, 0x40000
	v_lshl_add_u64 v[220:221], s[60:61], 0, v[134:135]
	s_addc_u32 s19, s61, 0
	s_add_i32 s79, s74, s66
	global_load_lds_dwordx4 v[220:221], off
	v_lshl_add_u64 v[222:223], s[18:19], 0, v[130:131]
	s_mov_b32 m0, s79
	v_lshl_add_u64 v[224:225], s[62:63], 0, v[132:133]
	global_load_lds_dwordx4 v[222:223], off
	v_lshl_add_u64 v[222:223], s[18:19], 0, v[134:135]
	s_add_i32 m0, s79, 0x2000
	s_nop 0
	global_load_lds_dwordx4 v[222:223], off
	v_lshl_add_u64 v[222:223], s[62:63], 0, v[128:129]
	s_mov_b32 m0, s57
	s_nop 0
	global_load_lds_dwordx4 v[222:223], off
	s_mov_b32 m0, s67
	s_nop 0
	global_load_lds_dwordx4 v[224:225], off
	s_waitcnt vmcnt(8)
	s_waitcnt lgkmcnt(0)
	s_barrier
	s_setprio 1
	v_mfma_f32_16x16x32_bf16 v[60:63], v[152:155], v[188:191], v[60:63]
	v_mfma_f32_16x16x32_bf16 v[60:63], v[156:159], v[192:195], v[60:63]
	v_mfma_f32_16x16x32_bf16 v[56:59], v[160:163], v[188:191], v[56:59]
	v_mfma_f32_16x16x32_bf16 v[56:59], v[164:167], v[192:195], v[56:59]
	v_mfma_f32_16x16x32_bf16 v[52:55], v[152:155], v[196:199], v[52:55]
	v_mfma_f32_16x16x32_bf16 v[52:55], v[156:159], v[200:203], v[52:55]
	v_mfma_f32_16x16x32_bf16 v[44:47], v[160:163], v[196:199], v[44:47]
	v_mfma_f32_16x16x32_bf16 v[44:47], v[164:167], v[200:203], v[44:47]
	v_mfma_f32_16x16x32_bf16 v[36:39], v[152:155], v[204:207], v[36:39]
	v_mfma_f32_16x16x32_bf16 v[36:39], v[156:159], v[208:211], v[36:39]
	v_mfma_f32_16x16x32_bf16 v[28:31], v[160:163], v[204:207], v[28:31]
	v_mfma_f32_16x16x32_bf16 v[28:31], v[164:167], v[208:211], v[28:31]
	v_mfma_f32_16x16x32_bf16 v[20:23], v[152:155], v[212:215], v[20:23]
	v_mfma_f32_16x16x32_bf16 v[20:23], v[156:159], v[216:219], v[20:23]
	v_mfma_f32_16x16x32_bf16 v[12:15], v[160:163], v[212:215], v[12:15]
	v_mfma_f32_16x16x32_bf16 v[12:15], v[164:167], v[216:219], v[12:15]
	v_mfma_f32_16x16x32_bf16 v[48:51], v[168:171], v[188:191], v[48:51]
	v_mfma_f32_16x16x32_bf16 v[48:51], v[172:175], v[192:195], v[48:51]
	v_mfma_f32_16x16x32_bf16 v[40:43], v[176:179], v[188:191], v[40:43]
	v_mfma_f32_16x16x32_bf16 v[40:43], v[184:187], v[192:195], v[40:43]
	v_mfma_f32_16x16x32_bf16 v[32:35], v[168:171], v[196:199], v[32:35]
	v_mfma_f32_16x16x32_bf16 v[32:35], v[172:175], v[200:203], v[32:35]
	v_mfma_f32_16x16x32_bf16 v[24:27], v[176:179], v[196:199], v[24:27]
	v_mfma_f32_16x16x32_bf16 v[24:27], v[184:187], v[200:203], v[24:27]
	v_mfma_f32_16x16x32_bf16 v[16:19], v[168:171], v[204:207], v[16:19]
	v_mfma_f32_16x16x32_bf16 v[16:19], v[172:175], v[208:211], v[16:19]
	v_mfma_f32_16x16x32_bf16 v[8:11], v[176:179], v[204:207], v[8:11]
	v_mfma_f32_16x16x32_bf16 v[8:11], v[184:187], v[208:211], v[8:11]
	v_mfma_f32_16x16x32_bf16 v[4:7], v[168:171], v[212:215], v[4:7]
	v_mfma_f32_16x16x32_bf16 v[4:7], v[172:175], v[216:219], v[4:7]
	v_mfma_f32_16x16x32_bf16 v[0:3], v[176:179], v[212:215], v[0:3]
	v_mfma_f32_16x16x32_bf16 v[0:3], v[184:187], v[216:219], v[0:3]
	s_setprio 0
	s_barrier
.Lmid_gemm3:
	s_add_i32 s79, 0, 0x18000
	s_add_i32 s89, 0, 0x1c000
	v_add_u32_e32 v164, s79, v147
	v_add_u32_e32 v181, s89, v147
	ds_read_b128 v[152:155], v164
	ds_read_b128 v[156:159], v164 offset:1024
	ds_read_b128 v[160:163], v164 offset:2048
	ds_read_b128 v[164:167], v164 offset:3072
	ds_read_b128 v[168:171], v181
	ds_read_b128 v[172:175], v181 offset:1024
	ds_read_b128 v[176:179], v181 offset:2048
	ds_read_b128 v[184:187], v181 offset:3072
	s_add_u32 s18, s62, 0x40000
	s_addc_u32 s19, s63, 0
	s_mov_b32 m0, s68
	v_lshl_add_u64 v[226:227], s[18:19], 0, v[128:129]
	ds_read_b128 v[188:191], v151 offset:32768
	ds_read_b128 v[192:195], v151 offset:33792
	ds_read_b128 v[196:199], v151 offset:34816
	ds_read_b128 v[200:203], v151 offset:35840
	ds_read_b128 v[204:207], v151 offset:36864
	ds_read_b128 v[208:211], v151 offset:37888
	ds_read_b128 v[212:215], v151 offset:38912
	ds_read_b128 v[216:219], v151 offset:39936
	global_load_lds_dwordx4 v[226:227], off
	v_lshl_add_u64 v[226:227], s[18:19], 0, v[132:133]
	s_mov_b32 m0, s69
	s_nop 0
	global_load_lds_dwordx4 v[226:227], off
	s_waitcnt vmcnt(8)
	s_waitcnt lgkmcnt(0)
	s_barrier
	s_setprio 1
	v_mfma_f32_16x16x32_bf16 v[124:127], v[152:155], v[188:191], v[124:127]
	v_mfma_f32_16x16x32_bf16 v[124:127], v[156:159], v[192:195], v[124:127]
	v_mfma_f32_16x16x32_bf16 v[120:123], v[160:163], v[188:191], v[120:123]
	v_mfma_f32_16x16x32_bf16 v[120:123], v[164:167], v[192:195], v[120:123]
	v_mfma_f32_16x16x32_bf16 v[116:119], v[152:155], v[196:199], v[116:119]
	v_mfma_f32_16x16x32_bf16 v[116:119], v[156:159], v[200:203], v[116:119]
	v_mfma_f32_16x16x32_bf16 v[108:111], v[160:163], v[196:199], v[108:111]
	v_mfma_f32_16x16x32_bf16 v[108:111], v[164:167], v[200:203], v[108:111]
	v_mfma_f32_16x16x32_bf16 v[100:103], v[152:155], v[204:207], v[100:103]
	v_mfma_f32_16x16x32_bf16 v[100:103], v[156:159], v[208:211], v[100:103]
	v_mfma_f32_16x16x32_bf16 v[92:95], v[160:163], v[204:207], v[92:95]
	v_mfma_f32_16x16x32_bf16 v[92:95], v[164:167], v[208:211], v[92:95]
	v_mfma_f32_16x16x32_bf16 v[84:87], v[152:155], v[212:215], v[84:87]
	v_mfma_f32_16x16x32_bf16 v[84:87], v[156:159], v[216:219], v[84:87]
	v_mfma_f32_16x16x32_bf16 v[76:79], v[160:163], v[212:215], v[76:79]
	v_mfma_f32_16x16x32_bf16 v[76:79], v[164:167], v[216:219], v[76:79]
	v_mfma_f32_16x16x32_bf16 v[112:115], v[168:171], v[188:191], v[112:115]
	v_mfma_f32_16x16x32_bf16 v[112:115], v[172:175], v[192:195], v[112:115]
	v_mfma_f32_16x16x32_bf16 v[104:107], v[176:179], v[188:191], v[104:107]
	v_mfma_f32_16x16x32_bf16 v[104:107], v[184:187], v[192:195], v[104:107]
	v_mfma_f32_16x16x32_bf16 v[96:99], v[168:171], v[196:199], v[96:99]
	v_mfma_f32_16x16x32_bf16 v[96:99], v[172:175], v[200:203], v[96:99]
	v_mfma_f32_16x16x32_bf16 v[88:91], v[176:179], v[196:199], v[88:91]
	v_mfma_f32_16x16x32_bf16 v[88:91], v[184:187], v[200:203], v[88:91]
	v_mfma_f32_16x16x32_bf16 v[80:83], v[168:171], v[204:207], v[80:83]
	v_mfma_f32_16x16x32_bf16 v[80:83], v[172:175], v[208:211], v[80:83]
	v_mfma_f32_16x16x32_bf16 v[72:75], v[176:179], v[204:207], v[72:75]
	v_mfma_f32_16x16x32_bf16 v[72:75], v[184:187], v[208:211], v[72:75]
	v_mfma_f32_16x16x32_bf16 v[68:71], v[168:171], v[212:215], v[68:71]
	v_mfma_f32_16x16x32_bf16 v[68:71], v[172:175], v[216:219], v[68:71]
	v_mfma_f32_16x16x32_bf16 v[64:67], v[176:179], v[212:215], v[64:67]
	v_mfma_f32_16x16x32_bf16 v[64:67], v[184:187], v[216:219], v[64:67]
	s_setprio 0
	s_barrier
	s_add_i32 s18, s79, s66
	v_lshl_add_u64 v[144:145], v[144:145], 0, s[10:11]
	s_mov_b32 m0, s18
	ds_read_b128 v[188:191], v151 offset:49152
	ds_read_b128 v[192:195], v151 offset:50176
	ds_read_b128 v[196:199], v151 offset:51200
	ds_read_b128 v[200:203], v151 offset:52224
	ds_read_b128 v[204:207], v151 offset:53248
	ds_read_b128 v[208:211], v151 offset:54272
	ds_read_b128 v[212:215], v151 offset:55296
	ds_read_b128 v[216:219], v151 offset:56320
	global_load_lds_dwordx4 v[144:145], off
	s_add_i32 m0, s18, 0x2000
	s_add_u32 s18, s60, 0x40080
	v_lshl_add_u64 v[144:145], v[220:221], 0, s[10:11]
	s_addc_u32 s19, s61, 0
	s_add_i32 s60, s89, s66
	global_load_lds_dwordx4 v[144:145], off
	v_lshl_add_u64 v[144:145], s[18:19], 0, v[130:131]
	s_mov_b32 m0, s60
	s_nop 0
	global_load_lds_dwordx4 v[144:145], off
	v_lshl_add_u64 v[144:145], s[18:19], 0, v[134:135]
	s_add_i32 m0, s60, 0x2000
	s_nop 0
	global_load_lds_dwordx4 v[144:145], off
	v_lshl_add_u64 v[144:145], v[222:223], 0, s[10:11]
	s_mov_b32 m0, s71
	s_nop 0
	global_load_lds_dwordx4 v[144:145], off
	v_lshl_add_u64 v[144:145], v[224:225], 0, s[10:11]
	s_mov_b32 m0, s72
	s_nop 0
	global_load_lds_dwordx4 v[144:145], off
	s_waitcnt vmcnt(8)
	s_waitcnt lgkmcnt(0)
	s_barrier
	s_setprio 1
	v_mfma_f32_16x16x32_bf16 v[60:63], v[152:155], v[188:191], v[60:63]
	v_mfma_f32_16x16x32_bf16 v[60:63], v[156:159], v[192:195], v[60:63]
	v_mfma_f32_16x16x32_bf16 v[56:59], v[160:163], v[188:191], v[56:59]
	v_mfma_f32_16x16x32_bf16 v[56:59], v[164:167], v[192:195], v[56:59]
	v_mfma_f32_16x16x32_bf16 v[52:55], v[152:155], v[196:199], v[52:55]
	v_mfma_f32_16x16x32_bf16 v[52:55], v[156:159], v[200:203], v[52:55]
	v_mfma_f32_16x16x32_bf16 v[44:47], v[160:163], v[196:199], v[44:47]
	v_mfma_f32_16x16x32_bf16 v[44:47], v[164:167], v[200:203], v[44:47]
	v_mfma_f32_16x16x32_bf16 v[36:39], v[152:155], v[204:207], v[36:39]
	v_mfma_f32_16x16x32_bf16 v[36:39], v[156:159], v[208:211], v[36:39]
	v_mfma_f32_16x16x32_bf16 v[28:31], v[160:163], v[204:207], v[28:31]
	v_mfma_f32_16x16x32_bf16 v[28:31], v[164:167], v[208:211], v[28:31]
	v_mfma_f32_16x16x32_bf16 v[20:23], v[152:155], v[212:215], v[20:23]
	v_mfma_f32_16x16x32_bf16 v[20:23], v[156:159], v[216:219], v[20:23]
	v_mfma_f32_16x16x32_bf16 v[12:15], v[160:163], v[212:215], v[12:15]
	v_mfma_f32_16x16x32_bf16 v[12:15], v[164:167], v[216:219], v[12:15]
	v_mfma_f32_16x16x32_bf16 v[48:51], v[168:171], v[188:191], v[48:51]
	v_mfma_f32_16x16x32_bf16 v[48:51], v[172:175], v[192:195], v[48:51]
	v_mfma_f32_16x16x32_bf16 v[40:43], v[176:179], v[188:191], v[40:43]
	v_mfma_f32_16x16x32_bf16 v[40:43], v[184:187], v[192:195], v[40:43]
	v_mfma_f32_16x16x32_bf16 v[32:35], v[168:171], v[196:199], v[32:35]
	v_mfma_f32_16x16x32_bf16 v[32:35], v[172:175], v[200:203], v[32:35]
	v_mfma_f32_16x16x32_bf16 v[24:27], v[176:179], v[196:199], v[24:27]
	v_mfma_f32_16x16x32_bf16 v[24:27], v[184:187], v[200:203], v[24:27]
	v_mfma_f32_16x16x32_bf16 v[16:19], v[168:171], v[204:207], v[16:19]
	v_mfma_f32_16x16x32_bf16 v[16:19], v[172:175], v[208:211], v[16:19]
	v_mfma_f32_16x16x32_bf16 v[8:11], v[176:179], v[204:207], v[8:11]
	v_mfma_f32_16x16x32_bf16 v[8:11], v[184:187], v[208:211], v[8:11]
	v_mfma_f32_16x16x32_bf16 v[4:7], v[168:171], v[212:215], v[4:7]
	v_mfma_f32_16x16x32_bf16 v[4:7], v[172:175], v[216:219], v[4:7]
	v_mfma_f32_16x16x32_bf16 v[0:3], v[176:179], v[212:215], v[0:3]
	v_mfma_f32_16x16x32_bf16 v[0:3], v[184:187], v[216:219], v[0:3]
	s_setprio 0
	s_barrier
	s_add_i32 s88, s88, 2
	s_add_u32 s58, s58, 0x100
	s_addc_u32 s59, s59, 0
	s_add_u32 s86, s86, 0x100
	s_addc_u32 s87, s87, 0
	s_cmp_gt_u32 s88, 13
	s_cbranch_scc0 .LBB0_601
	s_and_b64 vcc, exec, s[12:13]
	s_cbranch_vccz .LBB0_604
	s_barrier

.LBB0_723:
	s_ashr_i32 s31, s30, 31
	s_lshl_b64 s[36:37], s[30:31], 19
	s_add_u32 s36, s80, s36
	s_addc_u32 s37, s81, s37
	s_and_b64 s[44:45], s[10:11], exec
	s_cselect_b32 s31, s37, s49
	s_cselect_b32 s70, s36, s48
	s_ashr_i32 s19, s18, 31
	s_lshl_b64 s[44:45], s[18:19], 19
	s_add_u32 s44, s56, s44
	s_addc_u32 s45, s57, s45
	s_and_b64 s[54:55], s[10:11], exec
	s_cselect_b32 s19, s45, s53
	s_cselect_b32 s71, s44, s52
	s_add_u32 s48, s48, 0x40080
	s_addc_u32 s49, s49, 0
	s_add_u32 s72, s52, 0x100
	s_addc_u32 s73, s53, 0
	s_mov_b32 s74, -2
	ds_read_b128 v[140:143], v147
	ds_read_b128 v[150:153], v147 offset:1024
	ds_read_b128 v[154:157], v147 offset:2048
	ds_read_b128 v[158:161], v147 offset:3072
	ds_read_b128 v[162:165], v148
	ds_read_b128 v[166:169], v148 offset:1024
	ds_read_b128 v[170:173], v148 offset:2048
	ds_read_b128 v[174:177], v148 offset:3072
	s_add_u32 s52, s48, 0xfffc0080
	s_addc_u32 s53, s49, -1
	s_cmp_eq_u32 s74, 12
	s_cselect_b32 s55, s31, s53
	s_cselect_b32 s54, s70, s52
	s_cselect_b32 s53, s19, s73
	s_cselect_b32 s52, s71, s72
	v_lshl_add_u64 v[178:179], s[48:49], 0, v[132:133]
	s_add_i32 m0, s47, 0xc000
	ds_read_b128 v[184:187], v149
	ds_read_b128 v[188:191], v149 offset:1024
	ds_read_b128 v[192:195], v149 offset:2048
	ds_read_b128 v[196:199], v149 offset:3072
	ds_read_b128 v[200:203], v149 offset:4096
	ds_read_b128 v[204:207], v149 offset:5120
	ds_read_b128 v[208:211], v149 offset:6144
	ds_read_b128 v[212:215], v149 offset:7168
	global_load_lds_dwordx4 v[178:179], off
	v_lshl_add_u64 v[178:179], s[48:49], 0, v[134:135]
	s_add_i32 m0, s47, 0xe000
	s_nop 0
	global_load_lds_dwordx4 v[178:179], off
	s_waitcnt vmcnt(8)
	s_waitcnt lgkmcnt(0)
	s_barrier
	s_setprio 1
	v_mfma_f32_16x16x32_bf16 v[124:127], v[140:143], v[184:187], 0
	v_mfma_f32_16x16x32_bf16 v[124:127], v[150:153], v[188:191], v[124:127]
	v_mfma_f32_16x16x32_bf16 v[120:123], v[154:157], v[184:187], 0
	v_mfma_f32_16x16x32_bf16 v[120:123], v[158:161], v[188:191], v[120:123]
	v_mfma_f32_16x16x32_bf16 v[108:111], v[140:143], v[192:195], 0
	v_mfma_f32_16x16x32_bf16 v[108:111], v[150:153], v[196:199], v[108:111]
	v_mfma_f32_16x16x32_bf16 v[104:107], v[154:157], v[192:195], 0
	v_mfma_f32_16x16x32_bf16 v[104:107], v[158:161], v[196:199], v[104:107]
	v_mfma_f32_16x16x32_bf16 v[92:95], v[140:143], v[200:203], 0
	v_mfma_f32_16x16x32_bf16 v[92:95], v[150:153], v[204:207], v[92:95]
	v_mfma_f32_16x16x32_bf16 v[88:91], v[154:157], v[200:203], 0
	v_mfma_f32_16x16x32_bf16 v[88:91], v[158:161], v[204:207], v[88:91]
	v_mfma_f32_16x16x32_bf16 v[76:79], v[140:143], v[208:211], 0
	v_mfma_f32_16x16x32_bf16 v[76:79], v[150:153], v[212:215], v[76:79]
	v_mfma_f32_16x16x32_bf16 v[72:75], v[154:157], v[208:211], 0
	v_mfma_f32_16x16x32_bf16 v[72:75], v[158:161], v[212:215], v[72:75]
	v_mfma_f32_16x16x32_bf16 v[116:119], v[162:165], v[184:187], 0
	v_mfma_f32_16x16x32_bf16 v[116:119], v[166:169], v[188:191], v[116:119]
	v_mfma_f32_16x16x32_bf16 v[112:115], v[170:173], v[184:187], 0
	v_mfma_f32_16x16x32_bf16 v[112:115], v[174:177], v[188:191], v[112:115]
	v_mfma_f32_16x16x32_bf16 v[100:103], v[162:165], v[192:195], 0
	v_mfma_f32_16x16x32_bf16 v[100:103], v[166:169], v[196:199], v[100:103]
	v_mfma_f32_16x16x32_bf16 v[96:99], v[170:173], v[192:195], 0
	v_mfma_f32_16x16x32_bf16 v[96:99], v[174:177], v[196:199], v[96:99]
	v_mfma_f32_16x16x32_bf16 v[84:87], v[162:165], v[200:203], 0
	v_mfma_f32_16x16x32_bf16 v[84:87], v[166:169], v[204:207], v[84:87]
	v_mfma_f32_16x16x32_bf16 v[80:83], v[170:173], v[200:203], 0
	v_mfma_f32_16x16x32_bf16 v[80:83], v[174:177], v[204:207], v[80:83]
	v_mfma_f32_16x16x32_bf16 v[68:71], v[162:165], v[208:211], 0
	v_mfma_f32_16x16x32_bf16 v[68:71], v[166:169], v[212:215], v[68:71]
	v_mfma_f32_16x16x32_bf16 v[64:67], v[170:173], v[208:211], 0
	v_mfma_f32_16x16x32_bf16 v[64:67], v[174:177], v[212:215], v[64:67]
	s_setprio 0
	s_barrier
	s_add_i32 s75, s66, s58
	v_lshl_add_u64 v[178:179], s[52:53], 0, v[130:131]
	s_mov_b32 m0, s75
	ds_read_b128 v[184:187], v149 offset:16384
	ds_read_b128 v[188:191], v149 offset:17408
	ds_read_b128 v[192:195], v149 offset:18432
	ds_read_b128 v[196:199], v149 offset:19456
	ds_read_b128 v[200:203], v149 offset:20480
	ds_read_b128 v[204:207], v149 offset:21504
	ds_read_b128 v[208:211], v149 offset:22528
	ds_read_b128 v[212:215], v149 offset:23552
	global_load_lds_dwordx4 v[178:179], off
	s_add_i32 m0, s75, 0x2000
	s_add_u32 s76, s52, 0x40000
	v_lshl_add_u64 v[216:217], s[52:53], 0, v[128:129]
	s_addc_u32 s77, s53, 0
	s_add_i32 s75, s67, s58
	global_load_lds_dwordx4 v[216:217], off
	v_lshl_add_u64 v[218:219], s[76:77], 0, v[130:131]
	s_mov_b32 m0, s75
	v_lshl_add_u64 v[220:221], s[54:55], 0, v[128:129]
	global_load_lds_dwordx4 v[218:219], off
	v_lshl_add_u64 v[218:219], s[76:77], 0, v[128:129]
	s_add_i32 m0, s75, 0x2000
	s_nop 0
	global_load_lds_dwordx4 v[218:219], off
	v_lshl_add_u64 v[218:219], s[54:55], 0, v[130:131]
	s_mov_b32 m0, s47
	s_nop 0
	global_load_lds_dwordx4 v[218:219], off
	s_mov_b32 m0, s60
	s_nop 0
	global_load_lds_dwordx4 v[220:221], off
	s_waitcnt vmcnt(8)
	s_waitcnt lgkmcnt(0)
	s_barrier
	s_setprio 1
	v_mfma_f32_16x16x32_bf16 v[60:63], v[140:143], v[184:187], 0
	v_mfma_f32_16x16x32_bf16 v[60:63], v[150:153], v[188:191], v[60:63]
	v_mfma_f32_16x16x32_bf16 v[56:59], v[154:157], v[184:187], 0
	v_mfma_f32_16x16x32_bf16 v[56:59], v[158:161], v[188:191], v[56:59]
	v_mfma_f32_16x16x32_bf16 v[44:47], v[140:143], v[192:195], 0
	v_mfma_f32_16x16x32_bf16 v[44:47], v[150:153], v[196:199], v[44:47]
	v_mfma_f32_16x16x32_bf16 v[40:43], v[154:157], v[192:195], 0
	v_mfma_f32_16x16x32_bf16 v[40:43], v[158:161], v[196:199], v[40:43]
	v_mfma_f32_16x16x32_bf16 v[28:31], v[140:143], v[200:203], 0
	v_mfma_f32_16x16x32_bf16 v[28:31], v[150:153], v[204:207], v[28:31]
	v_mfma_f32_16x16x32_bf16 v[24:27], v[154:157], v[200:203], 0
	v_mfma_f32_16x16x32_bf16 v[24:27], v[158:161], v[204:207], v[24:27]
	v_mfma_f32_16x16x32_bf16 v[12:15], v[140:143], v[208:211], 0
	v_mfma_f32_16x16x32_bf16 v[12:15], v[150:153], v[212:215], v[12:15]
	v_mfma_f32_16x16x32_bf16 v[8:11], v[154:157], v[208:211], 0
	v_mfma_f32_16x16x32_bf16 v[8:11], v[158:161], v[212:215], v[8:11]
	v_mfma_f32_16x16x32_bf16 v[52:55], v[162:165], v[184:187], 0
	v_mfma_f32_16x16x32_bf16 v[52:55], v[166:169], v[188:191], v[52:55]
	v_mfma_f32_16x16x32_bf16 v[48:51], v[170:173], v[184:187], 0
	v_mfma_f32_16x16x32_bf16 v[48:51], v[174:177], v[188:191], v[48:51]
	v_mfma_f32_16x16x32_bf16 v[36:39], v[162:165], v[192:195], 0
	v_mfma_f32_16x16x32_bf16 v[36:39], v[166:169], v[196:199], v[36:39]
	v_mfma_f32_16x16x32_bf16 v[32:35], v[170:173], v[192:195], 0
	v_mfma_f32_16x16x32_bf16 v[32:35], v[174:177], v[196:199], v[32:35]
	v_mfma_f32_16x16x32_bf16 v[20:23], v[162:165], v[200:203], 0
	v_mfma_f32_16x16x32_bf16 v[20:23], v[166:169], v[204:207], v[20:23]
	v_mfma_f32_16x16x32_bf16 v[16:19], v[170:173], v[200:203], 0
	v_mfma_f32_16x16x32_bf16 v[16:19], v[174:177], v[204:207], v[16:19]
	v_mfma_f32_16x16x32_bf16 v[4:7], v[162:165], v[208:211], 0
	v_mfma_f32_16x16x32_bf16 v[4:7], v[166:169], v[212:215], v[4:7]
	v_mfma_f32_16x16x32_bf16 v[0:3], v[170:173], v[208:211], 0
	v_mfma_f32_16x16x32_bf16 v[0:3], v[174:177], v[212:215], v[0:3]
	s_setprio 0
	s_barrier
	s_branch .Lmid_gemm4
.LBB0_724:
	ds_read_b128 v[140:143], v147
	ds_read_b128 v[150:153], v147 offset:1024
	ds_read_b128 v[154:157], v147 offset:2048
	ds_read_b128 v[158:161], v147 offset:3072
	ds_read_b128 v[162:165], v148
	ds_read_b128 v[166:169], v148 offset:1024
	ds_read_b128 v[170:173], v148 offset:2048
	ds_read_b128 v[174:177], v148 offset:3072
	s_add_u32 s52, s48, 0xfffc0080
	s_addc_u32 s53, s49, -1
	s_cmp_eq_u32 s74, 12
	s_cselect_b32 s55, s31, s53
	s_cselect_b32 s54, s70, s52
	s_cselect_b32 s53, s19, s73
	s_cselect_b32 s52, s71, s72
	v_lshl_add_u64 v[178:179], s[48:49], 0, v[132:133]
	s_add_i32 m0, s47, 0xc000
	ds_read_b128 v[184:187], v149
	ds_read_b128 v[188:191], v149 offset:1024
	ds_read_b128 v[192:195], v149 offset:2048
	ds_read_b128 v[196:199], v149 offset:3072
	ds_read_b128 v[200:203], v149 offset:4096
	ds_read_b128 v[204:207], v149 offset:5120
	ds_read_b128 v[208:211], v149 offset:6144
	ds_read_b128 v[212:215], v149 offset:7168
	global_load_lds_dwordx4 v[178:179], off
	v_lshl_add_u64 v[178:179], s[48:49], 0, v[134:135]
	s_add_i32 m0, s47, 0xe000
	s_nop 0
	global_load_lds_dwordx4 v[178:179], off
	s_waitcnt vmcnt(8)
	s_waitcnt lgkmcnt(0)
	s_barrier
	s_setprio 1
	v_mfma_f32_16x16x32_bf16 v[124:127], v[140:143], v[184:187], v[124:127]
	v_mfma_f32_16x16x32_bf16 v[124:127], v[150:153], v[188:191], v[124:127]
	v_mfma_f32_16x16x32_bf16 v[120:123], v[154:157], v[184:187], v[120:123]
	v_mfma_f32_16x16x32_bf16 v[120:123], v[158:161], v[188:191], v[120:123]
	v_mfma_f32_16x16x32_bf16 v[108:111], v[140:143], v[192:195], v[108:111]
	v_mfma_f32_16x16x32_bf16 v[108:111], v[150:153], v[196:199], v[108:111]
	v_mfma_f32_16x16x32_bf16 v[104:107], v[154:157], v[192:195], v[104:107]
	v_mfma_f32_16x16x32_bf16 v[104:107], v[158:161], v[196:199], v[104:107]
	v_mfma_f32_16x16x32_bf16 v[92:95], v[140:143], v[200:203], v[92:95]
	v_mfma_f32_16x16x32_bf16 v[92:95], v[150:153], v[204:207], v[92:95]
	v_mfma_f32_16x16x32_bf16 v[88:91], v[154:157], v[200:203], v[88:91]
	v_mfma_f32_16x16x32_bf16 v[88:91], v[158:161], v[204:207], v[88:91]
	v_mfma_f32_16x16x32_bf16 v[76:79], v[140:143], v[208:211], v[76:79]
	v_mfma_f32_16x16x32_bf16 v[76:79], v[150:153], v[212:215], v[76:79]
	v_mfma_f32_16x16x32_bf16 v[72:75], v[154:157], v[208:211], v[72:75]
	v_mfma_f32_16x16x32_bf16 v[72:75], v[158:161], v[212:215], v[72:75]
	v_mfma_f32_16x16x32_bf16 v[116:119], v[162:165], v[184:187], v[116:119]
	v_mfma_f32_16x16x32_bf16 v[116:119], v[166:169], v[188:191], v[116:119]
	v_mfma_f32_16x16x32_bf16 v[112:115], v[170:173], v[184:187], v[112:115]
	v_mfma_f32_16x16x32_bf16 v[112:115], v[174:177], v[188:191], v[112:115]
	v_mfma_f32_16x16x32_bf16 v[100:103], v[162:165], v[192:195], v[100:103]
	v_mfma_f32_16x16x32_bf16 v[100:103], v[166:169], v[196:199], v[100:103]
	v_mfma_f32_16x16x32_bf16 v[96:99], v[170:173], v[192:195], v[96:99]
	v_mfma_f32_16x16x32_bf16 v[96:99], v[174:177], v[196:199], v[96:99]
	v_mfma_f32_16x16x32_bf16 v[84:87], v[162:165], v[200:203], v[84:87]
	v_mfma_f32_16x16x32_bf16 v[84:87], v[166:169], v[204:207], v[84:87]
	v_mfma_f32_16x16x32_bf16 v[80:83], v[170:173], v[200:203], v[80:83]
	v_mfma_f32_16x16x32_bf16 v[80:83], v[174:177], v[204:207], v[80:83]
	v_mfma_f32_16x16x32_bf16 v[68:71], v[162:165], v[208:211], v[68:71]
	v_mfma_f32_16x16x32_bf16 v[68:71], v[166:169], v[212:215], v[68:71]
	v_mfma_f32_16x16x32_bf16 v[64:67], v[170:173], v[208:211], v[64:67]
	v_mfma_f32_16x16x32_bf16 v[64:67], v[174:177], v[212:215], v[64:67]
	s_setprio 0
	s_barrier
	s_add_i32 s75, s66, s58
	v_lshl_add_u64 v[178:179], s[52:53], 0, v[130:131]
	s_mov_b32 m0, s75
	ds_read_b128 v[184:187], v149 offset:16384
	ds_read_b128 v[188:191], v149 offset:17408
	ds_read_b128 v[192:195], v149 offset:18432
	ds_read_b128 v[196:199], v149 offset:19456
	ds_read_b128 v[200:203], v149 offset:20480
	ds_read_b128 v[204:207], v149 offset:21504
	ds_read_b128 v[208:211], v149 offset:22528
	ds_read_b128 v[212:215], v149 offset:23552
	global_load_lds_dwordx4 v[178:179], off
	s_add_i32 m0, s75, 0x2000
	s_add_u32 s76, s52, 0x40000
	v_lshl_add_u64 v[216:217], s[52:53], 0, v[128:129]
	s_addc_u32 s77, s53, 0
	s_add_i32 s75, s67, s58
	global_load_lds_dwordx4 v[216:217], off
	v_lshl_add_u64 v[218:219], s[76:77], 0, v[130:131]
	s_mov_b32 m0, s75
	v_lshl_add_u64 v[220:221], s[54:55], 0, v[128:129]
	global_load_lds_dwordx4 v[218:219], off
	v_lshl_add_u64 v[218:219], s[76:77], 0, v[128:129]
	s_add_i32 m0, s75, 0x2000
	s_nop 0
	global_load_lds_dwordx4 v[218:219], off
	v_lshl_add_u64 v[218:219], s[54:55], 0, v[130:131]
	s_mov_b32 m0, s47
	s_nop 0
	global_load_lds_dwordx4 v[218:219], off
	s_mov_b32 m0, s60
	s_nop 0
	global_load_lds_dwordx4 v[220:221], off
	s_waitcnt vmcnt(8)
	s_waitcnt lgkmcnt(0)
	s_barrier
	s_setprio 1
	v_mfma_f32_16x16x32_bf16 v[60:63], v[140:143], v[184:187], v[60:63]
	v_mfma_f32_16x16x32_bf16 v[60:63], v[150:153], v[188:191], v[60:63]
	v_mfma_f32_16x16x32_bf16 v[56:59], v[154:157], v[184:187], v[56:59]
	v_mfma_f32_16x16x32_bf16 v[56:59], v[158:161], v[188:191], v[56:59]
	v_mfma_f32_16x16x32_bf16 v[44:47], v[140:143], v[192:195], v[44:47]
	v_mfma_f32_16x16x32_bf16 v[44:47], v[150:153], v[196:199], v[44:47]
	v_mfma_f32_16x16x32_bf16 v[40:43], v[154:157], v[192:195], v[40:43]
	v_mfma_f32_16x16x32_bf16 v[40:43], v[158:161], v[196:199], v[40:43]
	v_mfma_f32_16x16x32_bf16 v[28:31], v[140:143], v[200:203], v[28:31]
	v_mfma_f32_16x16x32_bf16 v[28:31], v[150:153], v[204:207], v[28:31]
	v_mfma_f32_16x16x32_bf16 v[24:27], v[154:157], v[200:203], v[24:27]
	v_mfma_f32_16x16x32_bf16 v[24:27], v[158:161], v[204:207], v[24:27]
	v_mfma_f32_16x16x32_bf16 v[12:15], v[140:143], v[208:211], v[12:15]
	v_mfma_f32_16x16x32_bf16 v[12:15], v[150:153], v[212:215], v[12:15]
	v_mfma_f32_16x16x32_bf16 v[8:11], v[154:157], v[208:211], v[8:11]
	v_mfma_f32_16x16x32_bf16 v[8:11], v[158:161], v[212:215], v[8:11]
	v_mfma_f32_16x16x32_bf16 v[52:55], v[162:165], v[184:187], v[52:55]
	v_mfma_f32_16x16x32_bf16 v[52:55], v[166:169], v[188:191], v[52:55]
	v_mfma_f32_16x16x32_bf16 v[48:51], v[170:173], v[184:187], v[48:51]
	v_mfma_f32_16x16x32_bf16 v[48:51], v[174:177], v[188:191], v[48:51]
	v_mfma_f32_16x16x32_bf16 v[36:39], v[162:165], v[192:195], v[36:39]
	v_mfma_f32_16x16x32_bf16 v[36:39], v[166:169], v[196:199], v[36:39]
	v_mfma_f32_16x16x32_bf16 v[32:35], v[170:173], v[192:195], v[32:35]
	v_mfma_f32_16x16x32_bf16 v[32:35], v[174:177], v[196:199], v[32:35]
	v_mfma_f32_16x16x32_bf16 v[20:23], v[162:165], v[200:203], v[20:23]
	v_mfma_f32_16x16x32_bf16 v[20:23], v[166:169], v[204:207], v[20:23]
	v_mfma_f32_16x16x32_bf16 v[16:19], v[170:173], v[200:203], v[16:19]
	v_mfma_f32_16x16x32_bf16 v[16:19], v[174:177], v[204:207], v[16:19]
	v_mfma_f32_16x16x32_bf16 v[4:7], v[162:165], v[208:211], v[4:7]
	v_mfma_f32_16x16x32_bf16 v[4:7], v[166:169], v[212:215], v[4:7]
	v_mfma_f32_16x16x32_bf16 v[0:3], v[170:173], v[208:211], v[0:3]
	v_mfma_f32_16x16x32_bf16 v[0:3], v[174:177], v[212:215], v[0:3]
	s_setprio 0
	s_barrier
.Lmid_gemm4:
	s_add_i32 s75, 0, 0x18000
	s_add_i32 s76, 0, 0x1c000
	v_add_u32_e32 v158, s75, v145
	v_add_u32_e32 v174, s76, v145
	ds_read_b128 v[140:143], v158
	ds_read_b128 v[150:153], v158 offset:1024
	ds_read_b128 v[154:157], v158 offset:2048
	ds_read_b128 v[158:161], v158 offset:3072
	ds_read_b128 v[162:165], v174
	ds_read_b128 v[166:169], v174 offset:1024
	ds_read_b128 v[170:173], v174 offset:2048
	ds_read_b128 v[174:177], v174 offset:3072
	s_add_u32 s54, s54, 0x40000
	s_addc_u32 s55, s55, 0
	s_mov_b32 m0, s61
	v_lshl_add_u64 v[222:223], s[54:55], 0, v[130:131]
	ds_read_b128 v[184:187], v149 offset:32768
	ds_read_b128 v[188:191], v149 offset:33792
	ds_read_b128 v[192:195], v149 offset:34816
	ds_read_b128 v[196:199], v149 offset:35840
	ds_read_b128 v[200:203], v149 offset:36864
	ds_read_b128 v[204:207], v149 offset:37888
	ds_read_b128 v[208:211], v149 offset:38912
	ds_read_b128 v[212:215], v149 offset:39936
	global_load_lds_dwordx4 v[222:223], off
	v_lshl_add_u64 v[222:223], s[54:55], 0, v[128:129]
	s_mov_b32 m0, s62
	s_nop 0
	global_load_lds_dwordx4 v[222:223], off
	s_waitcnt vmcnt(8)
	s_waitcnt lgkmcnt(0)
	s_barrier
	s_setprio 1
	v_mfma_f32_16x16x32_bf16 v[124:127], v[140:143], v[184:187], v[124:127]
	v_mfma_f32_16x16x32_bf16 v[124:127], v[150:153], v[188:191], v[124:127]
	v_mfma_f32_16x16x32_bf16 v[120:123], v[154:157], v[184:187], v[120:123]
	v_mfma_f32_16x16x32_bf16 v[120:123], v[158:161], v[188:191], v[120:123]
	v_mfma_f32_16x16x32_bf16 v[108:111], v[140:143], v[192:195], v[108:111]
	v_mfma_f32_16x16x32_bf16 v[108:111], v[150:153], v[196:199], v[108:111]
	v_mfma_f32_16x16x32_bf16 v[104:107], v[154:157], v[192:195], v[104:107]
	v_mfma_f32_16x16x32_bf16 v[104:107], v[158:161], v[196:199], v[104:107]
	v_mfma_f32_16x16x32_bf16 v[92:95], v[140:143], v[200:203], v[92:95]
	v_mfma_f32_16x16x32_bf16 v[92:95], v[150:153], v[204:207], v[92:95]
	v_mfma_f32_16x16x32_bf16 v[88:91], v[154:157], v[200:203], v[88:91]
	v_mfma_f32_16x16x32_bf16 v[88:91], v[158:161], v[204:207], v[88:91]
	v_mfma_f32_16x16x32_bf16 v[76:79], v[140:143], v[208:211], v[76:79]
	v_mfma_f32_16x16x32_bf16 v[76:79], v[150:153], v[212:215], v[76:79]
	v_mfma_f32_16x16x32_bf16 v[72:75], v[154:157], v[208:211], v[72:75]
	v_mfma_f32_16x16x32_bf16 v[72:75], v[158:161], v[212:215], v[72:75]
	v_mfma_f32_16x16x32_bf16 v[116:119], v[162:165], v[184:187], v[116:119]
	v_mfma_f32_16x16x32_bf16 v[116:119], v[166:169], v[188:191], v[116:119]
	v_mfma_f32_16x16x32_bf16 v[112:115], v[170:173], v[184:187], v[112:115]
	v_mfma_f32_16x16x32_bf16 v[112:115], v[174:177], v[188:191], v[112:115]
	v_mfma_f32_16x16x32_bf16 v[100:103], v[162:165], v[192:195], v[100:103]
	v_mfma_f32_16x16x32_bf16 v[100:103], v[166:169], v[196:199], v[100:103]
	v_mfma_f32_16x16x32_bf16 v[96:99], v[170:173], v[192:195], v[96:99]
	v_mfma_f32_16x16x32_bf16 v[96:99], v[174:177], v[196:199], v[96:99]
	v_mfma_f32_16x16x32_bf16 v[84:87], v[162:165], v[200:203], v[84:87]
	v_mfma_f32_16x16x32_bf16 v[84:87], v[166:169], v[204:207], v[84:87]
	v_mfma_f32_16x16x32_bf16 v[80:83], v[170:173], v[200:203], v[80:83]
	v_mfma_f32_16x16x32_bf16 v[80:83], v[174:177], v[204:207], v[80:83]
	v_mfma_f32_16x16x32_bf16 v[68:71], v[162:165], v[208:211], v[68:71]
	v_mfma_f32_16x16x32_bf16 v[68:71], v[166:169], v[212:215], v[68:71]
	v_mfma_f32_16x16x32_bf16 v[64:67], v[170:173], v[208:211], v[64:67]
	v_mfma_f32_16x16x32_bf16 v[64:67], v[174:177], v[212:215], v[64:67]
	s_setprio 0
	s_barrier
	s_add_i32 s54, s75, s58
	v_lshl_add_u64 v[178:179], v[178:179], 0, s[12:13]
	s_mov_b32 m0, s54
	ds_read_b128 v[184:187], v149 offset:49152
	ds_read_b128 v[188:191], v149 offset:50176
	ds_read_b128 v[192:195], v149 offset:51200
	ds_read_b128 v[196:199], v149 offset:52224
	ds_read_b128 v[200:203], v149 offset:53248
	ds_read_b128 v[204:207], v149 offset:54272
	ds_read_b128 v[208:211], v149 offset:55296
	ds_read_b128 v[212:215], v149 offset:56320
	global_load_lds_dwordx4 v[178:179], off
	s_add_i32 m0, s54, 0x2000
	s_add_u32 s52, s52, 0x40080
	v_lshl_add_u64 v[178:179], v[216:217], 0, s[12:13]
	s_addc_u32 s53, s53, 0
	s_add_i32 s54, s76, s58
	global_load_lds_dwordx4 v[178:179], off
	v_lshl_add_u64 v[178:179], s[52:53], 0, v[130:131]
	s_mov_b32 m0, s54
	s_nop 0
	global_load_lds_dwordx4 v[178:179], off
	v_lshl_add_u64 v[178:179], s[52:53], 0, v[128:129]
	s_add_i32 m0, s54, 0x2000
	s_nop 0
	global_load_lds_dwordx4 v[178:179], off
	v_lshl_add_u64 v[178:179], v[218:219], 0, s[12:13]
	s_mov_b32 m0, s64
	s_nop 0
	global_load_lds_dwordx4 v[178:179], off
	v_lshl_add_u64 v[178:179], v[220:221], 0, s[12:13]
	s_mov_b32 m0, s65
	s_nop 0
	global_load_lds_dwordx4 v[178:179], off
	s_waitcnt vmcnt(8)
	s_waitcnt lgkmcnt(0)
	s_barrier
	s_setprio 1
	v_mfma_f32_16x16x32_bf16 v[60:63], v[140:143], v[184:187], v[60:63]
	v_mfma_f32_16x16x32_bf16 v[60:63], v[150:153], v[188:191], v[60:63]
	v_mfma_f32_16x16x32_bf16 v[56:59], v[154:157], v[184:187], v[56:59]
	v_mfma_f32_16x16x32_bf16 v[56:59], v[158:161], v[188:191], v[56:59]
	v_mfma_f32_16x16x32_bf16 v[44:47], v[140:143], v[192:195], v[44:47]
	v_mfma_f32_16x16x32_bf16 v[44:47], v[150:153], v[196:199], v[44:47]
	v_mfma_f32_16x16x32_bf16 v[40:43], v[154:157], v[192:195], v[40:43]
	v_mfma_f32_16x16x32_bf16 v[40:43], v[158:161], v[196:199], v[40:43]
	v_mfma_f32_16x16x32_bf16 v[28:31], v[140:143], v[200:203], v[28:31]
	v_mfma_f32_16x16x32_bf16 v[28:31], v[150:153], v[204:207], v[28:31]
	v_mfma_f32_16x16x32_bf16 v[24:27], v[154:157], v[200:203], v[24:27]
	v_mfma_f32_16x16x32_bf16 v[24:27], v[158:161], v[204:207], v[24:27]
	v_mfma_f32_16x16x32_bf16 v[12:15], v[140:143], v[208:211], v[12:15]
	v_mfma_f32_16x16x32_bf16 v[12:15], v[150:153], v[212:215], v[12:15]
	v_mfma_f32_16x16x32_bf16 v[8:11], v[154:157], v[208:211], v[8:11]
	v_mfma_f32_16x16x32_bf16 v[8:11], v[158:161], v[212:215], v[8:11]
	v_mfma_f32_16x16x32_bf16 v[52:55], v[162:165], v[184:187], v[52:55]
	v_mfma_f32_16x16x32_bf16 v[52:55], v[166:169], v[188:191], v[52:55]
	v_mfma_f32_16x16x32_bf16 v[48:51], v[170:173], v[184:187], v[48:51]
	v_mfma_f32_16x16x32_bf16 v[48:51], v[174:177], v[188:191], v[48:51]
	v_mfma_f32_16x16x32_bf16 v[36:39], v[162:165], v[192:195], v[36:39]
	v_mfma_f32_16x16x32_bf16 v[36:39], v[166:169], v[196:199], v[36:39]
	v_mfma_f32_16x16x32_bf16 v[32:35], v[170:173], v[192:195], v[32:35]
	v_mfma_f32_16x16x32_bf16 v[32:35], v[174:177], v[196:199], v[32:35]
	v_mfma_f32_16x16x32_bf16 v[20:23], v[162:165], v[200:203], v[20:23]
	v_mfma_f32_16x16x32_bf16 v[20:23], v[166:169], v[204:207], v[20:23]
	v_mfma_f32_16x16x32_bf16 v[16:19], v[170:173], v[200:203], v[16:19]
	v_mfma_f32_16x16x32_bf16 v[16:19], v[174:177], v[204:207], v[16:19]
	v_mfma_f32_16x16x32_bf16 v[4:7], v[162:165], v[208:211], v[4:7]
	v_mfma_f32_16x16x32_bf16 v[4:7], v[166:169], v[212:215], v[4:7]
	v_mfma_f32_16x16x32_bf16 v[0:3], v[170:173], v[208:211], v[0:3]
	v_mfma_f32_16x16x32_bf16 v[0:3], v[174:177], v[212:215], v[0:3]
	s_setprio 0
	s_barrier
	s_add_i32 s74, s74, 2
	s_add_u32 s48, s48, 0x100
	s_addc_u32 s49, s49, 0
	s_add_u32 s72, s72, 0x100
	s_addc_u32 s73, s73, 0
	s_cmp_gt_u32 s74, 13
	s_cbranch_scc0 .LBB0_724
	s_and_b64 vcc, exec, s[16:17]
	s_cbranch_vccz .LBB0_727
	s_barrier

.LBB0_803:
	s_add_u32 s84, s54, 0x100
	s_addc_u32 s85, s55, 0
	s_mov_b32 s86, -2
	ds_read_b128 v[152:155], v149
	ds_read_b128 v[156:159], v149 offset:1024
	ds_read_b128 v[160:163], v149 offset:2048
	ds_read_b128 v[164:167], v149 offset:3072
	ds_read_b128 v[168:171], v150
	ds_read_b128 v[172:175], v150 offset:1024
	ds_read_b128 v[176:179], v150 offset:2048
	ds_read_b128 v[184:187], v150 offset:3072
	s_add_u32 s54, s52, 0x100
	s_addc_u32 s55, s53, 0
	s_cmp_eq_u32 s86, 40
	s_cselect_b32 s59, s13, s55
	s_cselect_b32 s58, s12, s54
	s_cselect_b32 s57, s49, s85
	s_cselect_b32 s56, s48, s84
	v_lshl_add_u64 v[144:145], s[52:53], 0, v[136:137]
	s_add_i32 m0, s63, 0xc000
	ds_read_b128 v[188:191], v151
	ds_read_b128 v[192:195], v151 offset:1024
	ds_read_b128 v[196:199], v151 offset:2048
	ds_read_b128 v[200:203], v151 offset:3072
	ds_read_b128 v[204:207], v151 offset:4096
	ds_read_b128 v[208:211], v151 offset:5120
	ds_read_b128 v[212:215], v151 offset:6144
	ds_read_b128 v[216:219], v151 offset:7168
	global_load_lds_dwordx4 v[144:145], off
	v_lshl_add_u64 v[144:145], s[52:53], 0, v[138:139]
	s_add_i32 m0, s63, 0xe000
	s_nop 0
	global_load_lds_dwordx4 v[144:145], off
	s_waitcnt vmcnt(8)
	s_waitcnt lgkmcnt(0)
	s_barrier
	s_setprio 1
	v_mfma_f32_16x16x32_bf16 v[124:127], v[152:155], v[188:191], 0
	v_mfma_f32_16x16x32_bf16 v[124:127], v[156:159], v[192:195], v[124:127]
	v_mfma_f32_16x16x32_bf16 v[120:123], v[160:163], v[188:191], 0
	v_mfma_f32_16x16x32_bf16 v[120:123], v[164:167], v[192:195], v[120:123]
	v_mfma_f32_16x16x32_bf16 v[116:119], v[152:155], v[196:199], 0
	v_mfma_f32_16x16x32_bf16 v[116:119], v[156:159], v[200:203], v[116:119]
	v_mfma_f32_16x16x32_bf16 v[108:111], v[160:163], v[196:199], 0
	v_mfma_f32_16x16x32_bf16 v[108:111], v[164:167], v[200:203], v[108:111]
	v_mfma_f32_16x16x32_bf16 v[100:103], v[152:155], v[204:207], 0
	v_mfma_f32_16x16x32_bf16 v[100:103], v[156:159], v[208:211], v[100:103]
	v_mfma_f32_16x16x32_bf16 v[92:95], v[160:163], v[204:207], 0
	v_mfma_f32_16x16x32_bf16 v[92:95], v[164:167], v[208:211], v[92:95]
	v_mfma_f32_16x16x32_bf16 v[84:87], v[152:155], v[212:215], 0
	v_mfma_f32_16x16x32_bf16 v[84:87], v[156:159], v[216:219], v[84:87]
	v_mfma_f32_16x16x32_bf16 v[76:79], v[160:163], v[212:215], 0
	v_mfma_f32_16x16x32_bf16 v[76:79], v[164:167], v[216:219], v[76:79]
	v_mfma_f32_16x16x32_bf16 v[112:115], v[168:171], v[188:191], 0
	v_mfma_f32_16x16x32_bf16 v[112:115], v[172:175], v[192:195], v[112:115]
	v_mfma_f32_16x16x32_bf16 v[104:107], v[176:179], v[188:191], 0
	v_mfma_f32_16x16x32_bf16 v[104:107], v[184:187], v[192:195], v[104:107]
	v_mfma_f32_16x16x32_bf16 v[96:99], v[168:171], v[196:199], 0
	v_mfma_f32_16x16x32_bf16 v[96:99], v[172:175], v[200:203], v[96:99]
	v_mfma_f32_16x16x32_bf16 v[88:91], v[176:179], v[196:199], 0
	v_mfma_f32_16x16x32_bf16 v[88:91], v[184:187], v[200:203], v[88:91]
	v_mfma_f32_16x16x32_bf16 v[80:83], v[168:171], v[204:207], 0
	v_mfma_f32_16x16x32_bf16 v[80:83], v[172:175], v[208:211], v[80:83]
	v_mfma_f32_16x16x32_bf16 v[72:75], v[176:179], v[204:207], 0
	v_mfma_f32_16x16x32_bf16 v[72:75], v[184:187], v[208:211], v[72:75]
	v_mfma_f32_16x16x32_bf16 v[68:71], v[168:171], v[212:215], 0
	v_mfma_f32_16x16x32_bf16 v[68:71], v[172:175], v[216:219], v[68:71]
	v_mfma_f32_16x16x32_bf16 v[64:67], v[176:179], v[212:215], 0
	v_mfma_f32_16x16x32_bf16 v[64:67], v[184:187], v[216:219], v[64:67]
	s_setprio 0
	s_barrier
	s_add_i32 s52, s70, s62
	v_lshl_add_u64 v[144:145], s[56:57], 0, v[130:131]
	s_mov_b32 m0, s52
	ds_read_b128 v[188:191], v151 offset:16384
	ds_read_b128 v[192:195], v151 offset:17408
	ds_read_b128 v[196:199], v151 offset:18432
	ds_read_b128 v[200:203], v151 offset:19456
	ds_read_b128 v[204:207], v151 offset:20480
	ds_read_b128 v[208:211], v151 offset:21504
	ds_read_b128 v[212:215], v151 offset:22528
	ds_read_b128 v[216:219], v151 offset:23552
	global_load_lds_dwordx4 v[144:145], off
	s_add_i32 m0, s52, 0x2000
	s_add_u32 s52, s56, 0xb0000
	v_lshl_add_u64 v[220:221], s[56:57], 0, v[134:135]
	s_addc_u32 s53, s57, 0
	s_add_i32 s79, s71, s62
	global_load_lds_dwordx4 v[220:221], off
	v_lshl_add_u64 v[222:223], s[52:53], 0, v[130:131]
	s_mov_b32 m0, s79
	v_lshl_add_u64 v[224:225], s[58:59], 0, v[132:133]
	global_load_lds_dwordx4 v[222:223], off
	v_lshl_add_u64 v[222:223], s[52:53], 0, v[134:135]
	s_add_i32 m0, s79, 0x2000
	s_nop 0
	global_load_lds_dwordx4 v[222:223], off
	v_lshl_add_u64 v[222:223], s[58:59], 0, v[128:129]
	s_mov_b32 m0, s63
	s_nop 0
	global_load_lds_dwordx4 v[222:223], off
	s_mov_b32 m0, s64
	s_nop 0
	global_load_lds_dwordx4 v[224:225], off
	s_waitcnt vmcnt(8)
	s_waitcnt lgkmcnt(0)
	s_barrier
	s_setprio 1
	v_mfma_f32_16x16x32_bf16 v[60:63], v[152:155], v[188:191], 0
	v_mfma_f32_16x16x32_bf16 v[60:63], v[156:159], v[192:195], v[60:63]
	v_mfma_f32_16x16x32_bf16 v[56:59], v[160:163], v[188:191], 0
	v_mfma_f32_16x16x32_bf16 v[56:59], v[164:167], v[192:195], v[56:59]
	v_mfma_f32_16x16x32_bf16 v[52:55], v[152:155], v[196:199], 0
	v_mfma_f32_16x16x32_bf16 v[52:55], v[156:159], v[200:203], v[52:55]
	v_mfma_f32_16x16x32_bf16 v[44:47], v[160:163], v[196:199], 0
	v_mfma_f32_16x16x32_bf16 v[44:47], v[164:167], v[200:203], v[44:47]
	v_mfma_f32_16x16x32_bf16 v[36:39], v[152:155], v[204:207], 0
	v_mfma_f32_16x16x32_bf16 v[36:39], v[156:159], v[208:211], v[36:39]
	v_mfma_f32_16x16x32_bf16 v[28:31], v[160:163], v[204:207], 0
	v_mfma_f32_16x16x32_bf16 v[28:31], v[164:167], v[208:211], v[28:31]
	v_mfma_f32_16x16x32_bf16 v[20:23], v[152:155], v[212:215], 0
	v_mfma_f32_16x16x32_bf16 v[20:23], v[156:159], v[216:219], v[20:23]
	v_mfma_f32_16x16x32_bf16 v[12:15], v[160:163], v[212:215], 0
	v_mfma_f32_16x16x32_bf16 v[12:15], v[164:167], v[216:219], v[12:15]
	v_mfma_f32_16x16x32_bf16 v[48:51], v[168:171], v[188:191], 0
	v_mfma_f32_16x16x32_bf16 v[48:51], v[172:175], v[192:195], v[48:51]
	v_mfma_f32_16x16x32_bf16 v[40:43], v[176:179], v[188:191], 0
	v_mfma_f32_16x16x32_bf16 v[40:43], v[184:187], v[192:195], v[40:43]
	v_mfma_f32_16x16x32_bf16 v[32:35], v[168:171], v[196:199], 0
	v_mfma_f32_16x16x32_bf16 v[32:35], v[172:175], v[200:203], v[32:35]
	v_mfma_f32_16x16x32_bf16 v[24:27], v[176:179], v[196:199], 0
	v_mfma_f32_16x16x32_bf16 v[24:27], v[184:187], v[200:203], v[24:27]
	v_mfma_f32_16x16x32_bf16 v[16:19], v[168:171], v[204:207], 0
	v_mfma_f32_16x16x32_bf16 v[16:19], v[172:175], v[208:211], v[16:19]
	v_mfma_f32_16x16x32_bf16 v[8:11], v[176:179], v[204:207], 0
	v_mfma_f32_16x16x32_bf16 v[8:11], v[184:187], v[208:211], v[8:11]
	v_mfma_f32_16x16x32_bf16 v[4:7], v[168:171], v[212:215], 0
	v_mfma_f32_16x16x32_bf16 v[4:7], v[172:175], v[216:219], v[4:7]
	v_mfma_f32_16x16x32_bf16 v[0:3], v[176:179], v[212:215], 0
	v_mfma_f32_16x16x32_bf16 v[0:3], v[184:187], v[216:219], v[0:3]
	s_setprio 0
	s_barrier
	s_branch .Lmid_gemm5
.LBB0_804:
	ds_read_b128 v[152:155], v149
	ds_read_b128 v[156:159], v149 offset:1024
	ds_read_b128 v[160:163], v149 offset:2048
	ds_read_b128 v[164:167], v149 offset:3072
	ds_read_b128 v[168:171], v150
	ds_read_b128 v[172:175], v150 offset:1024
	ds_read_b128 v[176:179], v150 offset:2048
	ds_read_b128 v[184:187], v150 offset:3072
	s_add_u32 s54, s52, 0x100
	s_addc_u32 s55, s53, 0
	s_cmp_eq_u32 s86, 40
	s_cselect_b32 s59, s13, s55
	s_cselect_b32 s58, s12, s54
	s_cselect_b32 s57, s49, s85
	s_cselect_b32 s56, s48, s84
	v_lshl_add_u64 v[144:145], s[52:53], 0, v[136:137]
	s_add_i32 m0, s63, 0xc000
	ds_read_b128 v[188:191], v151
	ds_read_b128 v[192:195], v151 offset:1024
	ds_read_b128 v[196:199], v151 offset:2048
	ds_read_b128 v[200:203], v151 offset:3072
	ds_read_b128 v[204:207], v151 offset:4096
	ds_read_b128 v[208:211], v151 offset:5120
	ds_read_b128 v[212:215], v151 offset:6144
	ds_read_b128 v[216:219], v151 offset:7168
	global_load_lds_dwordx4 v[144:145], off
	v_lshl_add_u64 v[144:145], s[52:53], 0, v[138:139]
	s_add_i32 m0, s63, 0xe000
	s_nop 0
	global_load_lds_dwordx4 v[144:145], off
	s_waitcnt vmcnt(8)
	s_waitcnt lgkmcnt(0)
	s_barrier
	s_setprio 1
	v_mfma_f32_16x16x32_bf16 v[124:127], v[152:155], v[188:191], v[124:127]
	v_mfma_f32_16x16x32_bf16 v[124:127], v[156:159], v[192:195], v[124:127]
	v_mfma_f32_16x16x32_bf16 v[120:123], v[160:163], v[188:191], v[120:123]
	v_mfma_f32_16x16x32_bf16 v[120:123], v[164:167], v[192:195], v[120:123]
	v_mfma_f32_16x16x32_bf16 v[116:119], v[152:155], v[196:199], v[116:119]
	v_mfma_f32_16x16x32_bf16 v[116:119], v[156:159], v[200:203], v[116:119]
	v_mfma_f32_16x16x32_bf16 v[108:111], v[160:163], v[196:199], v[108:111]
	v_mfma_f32_16x16x32_bf16 v[108:111], v[164:167], v[200:203], v[108:111]
	v_mfma_f32_16x16x32_bf16 v[100:103], v[152:155], v[204:207], v[100:103]
	v_mfma_f32_16x16x32_bf16 v[100:103], v[156:159], v[208:211], v[100:103]
	v_mfma_f32_16x16x32_bf16 v[92:95], v[160:163], v[204:207], v[92:95]
	v_mfma_f32_16x16x32_bf16 v[92:95], v[164:167], v[208:211], v[92:95]
	v_mfma_f32_16x16x32_bf16 v[84:87], v[152:155], v[212:215], v[84:87]
	v_mfma_f32_16x16x32_bf16 v[84:87], v[156:159], v[216:219], v[84:87]
	v_mfma_f32_16x16x32_bf16 v[76:79], v[160:163], v[212:215], v[76:79]
	v_mfma_f32_16x16x32_bf16 v[76:79], v[164:167], v[216:219], v[76:79]
	v_mfma_f32_16x16x32_bf16 v[112:115], v[168:171], v[188:191], v[112:115]
	v_mfma_f32_16x16x32_bf16 v[112:115], v[172:175], v[192:195], v[112:115]
	v_mfma_f32_16x16x32_bf16 v[104:107], v[176:179], v[188:191], v[104:107]
	v_mfma_f32_16x16x32_bf16 v[104:107], v[184:187], v[192:195], v[104:107]
	v_mfma_f32_16x16x32_bf16 v[96:99], v[168:171], v[196:199], v[96:99]
	v_mfma_f32_16x16x32_bf16 v[96:99], v[172:175], v[200:203], v[96:99]
	v_mfma_f32_16x16x32_bf16 v[88:91], v[176:179], v[196:199], v[88:91]
	v_mfma_f32_16x16x32_bf16 v[88:91], v[184:187], v[200:203], v[88:91]
	v_mfma_f32_16x16x32_bf16 v[80:83], v[168:171], v[204:207], v[80:83]
	v_mfma_f32_16x16x32_bf16 v[80:83], v[172:175], v[208:211], v[80:83]
	v_mfma_f32_16x16x32_bf16 v[72:75], v[176:179], v[204:207], v[72:75]
	v_mfma_f32_16x16x32_bf16 v[72:75], v[184:187], v[208:211], v[72:75]
	v_mfma_f32_16x16x32_bf16 v[68:71], v[168:171], v[212:215], v[68:71]
	v_mfma_f32_16x16x32_bf16 v[68:71], v[172:175], v[216:219], v[68:71]
	v_mfma_f32_16x16x32_bf16 v[64:67], v[176:179], v[212:215], v[64:67]
	v_mfma_f32_16x16x32_bf16 v[64:67], v[184:187], v[216:219], v[64:67]
	s_setprio 0
	s_barrier
	s_add_i32 s52, s70, s62
	v_lshl_add_u64 v[144:145], s[56:57], 0, v[130:131]
	s_mov_b32 m0, s52
	ds_read_b128 v[188:191], v151 offset:16384
	ds_read_b128 v[192:195], v151 offset:17408
	ds_read_b128 v[196:199], v151 offset:18432
	ds_read_b128 v[200:203], v151 offset:19456
	ds_read_b128 v[204:207], v151 offset:20480
	ds_read_b128 v[208:211], v151 offset:21504
	ds_read_b128 v[212:215], v151 offset:22528
	ds_read_b128 v[216:219], v151 offset:23552
	global_load_lds_dwordx4 v[144:145], off
	s_add_i32 m0, s52, 0x2000
	s_add_u32 s52, s56, 0xb0000
	v_lshl_add_u64 v[220:221], s[56:57], 0, v[134:135]
	s_addc_u32 s53, s57, 0
	s_add_i32 s79, s71, s62
	global_load_lds_dwordx4 v[220:221], off
	v_lshl_add_u64 v[222:223], s[52:53], 0, v[130:131]
	s_mov_b32 m0, s79
	v_lshl_add_u64 v[224:225], s[58:59], 0, v[132:133]
	global_load_lds_dwordx4 v[222:223], off
	v_lshl_add_u64 v[222:223], s[52:53], 0, v[134:135]
	s_add_i32 m0, s79, 0x2000
	s_nop 0
	global_load_lds_dwordx4 v[222:223], off
	v_lshl_add_u64 v[222:223], s[58:59], 0, v[128:129]
	s_mov_b32 m0, s63
	s_nop 0
	global_load_lds_dwordx4 v[222:223], off
	s_mov_b32 m0, s64
	s_nop 0
	global_load_lds_dwordx4 v[224:225], off
	s_waitcnt vmcnt(8)
	s_waitcnt lgkmcnt(0)
	s_barrier
	s_setprio 1
	v_mfma_f32_16x16x32_bf16 v[60:63], v[152:155], v[188:191], v[60:63]
	v_mfma_f32_16x16x32_bf16 v[60:63], v[156:159], v[192:195], v[60:63]
	v_mfma_f32_16x16x32_bf16 v[56:59], v[160:163], v[188:191], v[56:59]
	v_mfma_f32_16x16x32_bf16 v[56:59], v[164:167], v[192:195], v[56:59]
	v_mfma_f32_16x16x32_bf16 v[52:55], v[152:155], v[196:199], v[52:55]
	v_mfma_f32_16x16x32_bf16 v[52:55], v[156:159], v[200:203], v[52:55]
	v_mfma_f32_16x16x32_bf16 v[44:47], v[160:163], v[196:199], v[44:47]
	v_mfma_f32_16x16x32_bf16 v[44:47], v[164:167], v[200:203], v[44:47]
	v_mfma_f32_16x16x32_bf16 v[36:39], v[152:155], v[204:207], v[36:39]
	v_mfma_f32_16x16x32_bf16 v[36:39], v[156:159], v[208:211], v[36:39]
	v_mfma_f32_16x16x32_bf16 v[28:31], v[160:163], v[204:207], v[28:31]
	v_mfma_f32_16x16x32_bf16 v[28:31], v[164:167], v[208:211], v[28:31]
	v_mfma_f32_16x16x32_bf16 v[20:23], v[152:155], v[212:215], v[20:23]
	v_mfma_f32_16x16x32_bf16 v[20:23], v[156:159], v[216:219], v[20:23]
	v_mfma_f32_16x16x32_bf16 v[12:15], v[160:163], v[212:215], v[12:15]
	v_mfma_f32_16x16x32_bf16 v[12:15], v[164:167], v[216:219], v[12:15]
	v_mfma_f32_16x16x32_bf16 v[48:51], v[168:171], v[188:191], v[48:51]
	v_mfma_f32_16x16x32_bf16 v[48:51], v[172:175], v[192:195], v[48:51]
	v_mfma_f32_16x16x32_bf16 v[40:43], v[176:179], v[188:191], v[40:43]
	v_mfma_f32_16x16x32_bf16 v[40:43], v[184:187], v[192:195], v[40:43]
	v_mfma_f32_16x16x32_bf16 v[32:35], v[168:171], v[196:199], v[32:35]
	v_mfma_f32_16x16x32_bf16 v[32:35], v[172:175], v[200:203], v[32:35]
	v_mfma_f32_16x16x32_bf16 v[24:27], v[176:179], v[196:199], v[24:27]
	v_mfma_f32_16x16x32_bf16 v[24:27], v[184:187], v[200:203], v[24:27]
	v_mfma_f32_16x16x32_bf16 v[16:19], v[168:171], v[204:207], v[16:19]
	v_mfma_f32_16x16x32_bf16 v[16:19], v[172:175], v[208:211], v[16:19]
	v_mfma_f32_16x16x32_bf16 v[8:11], v[176:179], v[204:207], v[8:11]
	v_mfma_f32_16x16x32_bf16 v[8:11], v[184:187], v[208:211], v[8:11]
	v_mfma_f32_16x16x32_bf16 v[4:7], v[168:171], v[212:215], v[4:7]
	v_mfma_f32_16x16x32_bf16 v[4:7], v[172:175], v[216:219], v[4:7]
	v_mfma_f32_16x16x32_bf16 v[0:3], v[176:179], v[212:215], v[0:3]
	v_mfma_f32_16x16x32_bf16 v[0:3], v[184:187], v[216:219], v[0:3]
	s_setprio 0
	s_barrier
.Lmid_gemm5:
	s_add_i32 s79, 0, 0x18000
	s_add_i32 s87, 0, 0x1c000
	v_add_u32_e32 v164, s79, v147
	v_add_u32_e32 v181, s87, v147
	ds_read_b128 v[152:155], v164
	ds_read_b128 v[156:159], v164 offset:1024
	ds_read_b128 v[160:163], v164 offset:2048
	ds_read_b128 v[164:167], v164 offset:3072
	ds_read_b128 v[168:171], v181
	ds_read_b128 v[172:175], v181 offset:1024
	ds_read_b128 v[176:179], v181 offset:2048
	ds_read_b128 v[184:187], v181 offset:3072
	s_add_u32 s52, s58, 0xb0000
	s_addc_u32 s53, s59, 0
	s_mov_b32 m0, s65
	v_lshl_add_u64 v[226:227], s[52:53], 0, v[128:129]
	ds_read_b128 v[188:191], v151 offset:32768
	ds_read_b128 v[192:195], v151 offset:33792
	ds_read_b128 v[196:199], v151 offset:34816
	ds_read_b128 v[200:203], v151 offset:35840
	ds_read_b128 v[204:207], v151 offset:36864
	ds_read_b128 v[208:211], v151 offset:37888
	ds_read_b128 v[212:215], v151 offset:38912
	ds_read_b128 v[216:219], v151 offset:39936
	global_load_lds_dwordx4 v[226:227], off
	v_lshl_add_u64 v[226:227], s[52:53], 0, v[132:133]
	s_mov_b32 m0, s66
	s_nop 0
	global_load_lds_dwordx4 v[226:227], off
	s_waitcnt vmcnt(8)
	s_waitcnt lgkmcnt(0)
	s_barrier
	s_setprio 1
	v_mfma_f32_16x16x32_bf16 v[124:127], v[152:155], v[188:191], v[124:127]
	v_mfma_f32_16x16x32_bf16 v[124:127], v[156:159], v[192:195], v[124:127]
	v_mfma_f32_16x16x32_bf16 v[120:123], v[160:163], v[188:191], v[120:123]
	v_mfma_f32_16x16x32_bf16 v[120:123], v[164:167], v[192:195], v[120:123]
	v_mfma_f32_16x16x32_bf16 v[116:119], v[152:155], v[196:199], v[116:119]
	v_mfma_f32_16x16x32_bf16 v[116:119], v[156:159], v[200:203], v[116:119]
	v_mfma_f32_16x16x32_bf16 v[108:111], v[160:163], v[196:199], v[108:111]
	v_mfma_f32_16x16x32_bf16 v[108:111], v[164:167], v[200:203], v[108:111]
	v_mfma_f32_16x16x32_bf16 v[100:103], v[152:155], v[204:207], v[100:103]
	v_mfma_f32_16x16x32_bf16 v[100:103], v[156:159], v[208:211], v[100:103]
	v_mfma_f32_16x16x32_bf16 v[92:95], v[160:163], v[204:207], v[92:95]
	v_mfma_f32_16x16x32_bf16 v[92:95], v[164:167], v[208:211], v[92:95]
	v_mfma_f32_16x16x32_bf16 v[84:87], v[152:155], v[212:215], v[84:87]
	v_mfma_f32_16x16x32_bf16 v[84:87], v[156:159], v[216:219], v[84:87]
	v_mfma_f32_16x16x32_bf16 v[76:79], v[160:163], v[212:215], v[76:79]
	v_mfma_f32_16x16x32_bf16 v[76:79], v[164:167], v[216:219], v[76:79]
	v_mfma_f32_16x16x32_bf16 v[112:115], v[168:171], v[188:191], v[112:115]
	v_mfma_f32_16x16x32_bf16 v[112:115], v[172:175], v[192:195], v[112:115]
	v_mfma_f32_16x16x32_bf16 v[104:107], v[176:179], v[188:191], v[104:107]
	v_mfma_f32_16x16x32_bf16 v[104:107], v[184:187], v[192:195], v[104:107]
	v_mfma_f32_16x16x32_bf16 v[96:99], v[168:171], v[196:199], v[96:99]
	v_mfma_f32_16x16x32_bf16 v[96:99], v[172:175], v[200:203], v[96:99]
	v_mfma_f32_16x16x32_bf16 v[88:91], v[176:179], v[196:199], v[88:91]
	v_mfma_f32_16x16x32_bf16 v[88:91], v[184:187], v[200:203], v[88:91]
	v_mfma_f32_16x16x32_bf16 v[80:83], v[168:171], v[204:207], v[80:83]
	v_mfma_f32_16x16x32_bf16 v[80:83], v[172:175], v[208:211], v[80:83]
	v_mfma_f32_16x16x32_bf16 v[72:75], v[176:179], v[204:207], v[72:75]
	v_mfma_f32_16x16x32_bf16 v[72:75], v[184:187], v[208:211], v[72:75]
	v_mfma_f32_16x16x32_bf16 v[68:71], v[168:171], v[212:215], v[68:71]
	v_mfma_f32_16x16x32_bf16 v[68:71], v[172:175], v[216:219], v[68:71]
	v_mfma_f32_16x16x32_bf16 v[64:67], v[176:179], v[212:215], v[64:67]
	v_mfma_f32_16x16x32_bf16 v[64:67], v[184:187], v[216:219], v[64:67]
	s_setprio 0
	s_barrier
	s_add_i32 s52, s79, s62
	v_lshl_add_u64 v[144:145], v[144:145], 0, s[16:17]
	s_mov_b32 m0, s52
	ds_read_b128 v[188:191], v151 offset:49152
	ds_read_b128 v[192:195], v151 offset:50176
	ds_read_b128 v[196:199], v151 offset:51200
	ds_read_b128 v[200:203], v151 offset:52224
	ds_read_b128 v[204:207], v151 offset:53248
	ds_read_b128 v[208:211], v151 offset:54272
	ds_read_b128 v[212:215], v151 offset:55296
	ds_read_b128 v[216:219], v151 offset:56320
	global_load_lds_dwordx4 v[144:145], off
	s_add_i32 m0, s52, 0x2000
	s_add_u32 s52, s56, 0xb0080
	v_lshl_add_u64 v[144:145], v[220:221], 0, s[16:17]
	s_addc_u32 s53, s57, 0
	s_add_i32 s56, s87, s62
	global_load_lds_dwordx4 v[144:145], off
	v_lshl_add_u64 v[144:145], s[52:53], 0, v[130:131]
	s_mov_b32 m0, s56
	s_nop 0
	global_load_lds_dwordx4 v[144:145], off
	v_lshl_add_u64 v[144:145], s[52:53], 0, v[134:135]
	s_add_i32 m0, s56, 0x2000
	s_nop 0
	global_load_lds_dwordx4 v[144:145], off
	v_lshl_add_u64 v[144:145], v[222:223], 0, s[16:17]
	s_mov_b32 m0, s68
	s_nop 0
	global_load_lds_dwordx4 v[144:145], off
	v_lshl_add_u64 v[144:145], v[224:225], 0, s[16:17]
	s_mov_b32 m0, s69
	s_nop 0
	global_load_lds_dwordx4 v[144:145], off
	s_waitcnt vmcnt(8)
	s_waitcnt lgkmcnt(0)
	s_barrier
	s_setprio 1
	v_mfma_f32_16x16x32_bf16 v[60:63], v[152:155], v[188:191], v[60:63]
	v_mfma_f32_16x16x32_bf16 v[60:63], v[156:159], v[192:195], v[60:63]
	v_mfma_f32_16x16x32_bf16 v[56:59], v[160:163], v[188:191], v[56:59]
	v_mfma_f32_16x16x32_bf16 v[56:59], v[164:167], v[192:195], v[56:59]
	v_mfma_f32_16x16x32_bf16 v[52:55], v[152:155], v[196:199], v[52:55]
	v_mfma_f32_16x16x32_bf16 v[52:55], v[156:159], v[200:203], v[52:55]
	v_mfma_f32_16x16x32_bf16 v[44:47], v[160:163], v[196:199], v[44:47]
	v_mfma_f32_16x16x32_bf16 v[44:47], v[164:167], v[200:203], v[44:47]
	v_mfma_f32_16x16x32_bf16 v[36:39], v[152:155], v[204:207], v[36:39]
	v_mfma_f32_16x16x32_bf16 v[36:39], v[156:159], v[208:211], v[36:39]
	v_mfma_f32_16x16x32_bf16 v[28:31], v[160:163], v[204:207], v[28:31]
	v_mfma_f32_16x16x32_bf16 v[28:31], v[164:167], v[208:211], v[28:31]
	v_mfma_f32_16x16x32_bf16 v[20:23], v[152:155], v[212:215], v[20:23]
	v_mfma_f32_16x16x32_bf16 v[20:23], v[156:159], v[216:219], v[20:23]
	v_mfma_f32_16x16x32_bf16 v[12:15], v[160:163], v[212:215], v[12:15]
	v_mfma_f32_16x16x32_bf16 v[12:15], v[164:167], v[216:219], v[12:15]
	v_mfma_f32_16x16x32_bf16 v[48:51], v[168:171], v[188:191], v[48:51]
	v_mfma_f32_16x16x32_bf16 v[48:51], v[172:175], v[192:195], v[48:51]
	v_mfma_f32_16x16x32_bf16 v[40:43], v[176:179], v[188:191], v[40:43]
	v_mfma_f32_16x16x32_bf16 v[40:43], v[184:187], v[192:195], v[40:43]
	v_mfma_f32_16x16x32_bf16 v[32:35], v[168:171], v[196:199], v[32:35]
	v_mfma_f32_16x16x32_bf16 v[32:35], v[172:175], v[200:203], v[32:35]
	v_mfma_f32_16x16x32_bf16 v[24:27], v[176:179], v[196:199], v[24:27]
	v_mfma_f32_16x16x32_bf16 v[24:27], v[184:187], v[200:203], v[24:27]
	v_mfma_f32_16x16x32_bf16 v[16:19], v[168:171], v[204:207], v[16:19]
	v_mfma_f32_16x16x32_bf16 v[16:19], v[172:175], v[208:211], v[16:19]
	v_mfma_f32_16x16x32_bf16 v[8:11], v[176:179], v[204:207], v[8:11]
	v_mfma_f32_16x16x32_bf16 v[8:11], v[184:187], v[208:211], v[8:11]
	v_mfma_f32_16x16x32_bf16 v[4:7], v[168:171], v[212:215], v[4:7]
	v_mfma_f32_16x16x32_bf16 v[4:7], v[172:175], v[216:219], v[4:7]
	v_mfma_f32_16x16x32_bf16 v[0:3], v[176:179], v[212:215], v[0:3]
	v_mfma_f32_16x16x32_bf16 v[0:3], v[184:187], v[216:219], v[0:3]
	s_setprio 0
	s_barrier
	s_add_i32 s86, s86, 2
	s_add_u32 s84, s84, 0x100
	s_addc_u32 s85, s85, 0
	s_cmp_gt_u32 s86, 41
	s_mov_b64 s[52:53], s[54:55]
	s_cbranch_scc0 .LBB0_804
	s_and_b64 vcc, exec, s[18:19]
	s_cbranch_vccz .LBB0_807
	s_barrier

.LBB0_934:
	s_ashr_i32 s53, s52, 31
	s_lshl_b64 s[54:55], s[52:53], 19
	s_add_u32 s54, s80, s54
	s_addc_u32 s55, s81, s55
	s_and_b64 s[56:57], s[10:11], exec
	s_cselect_b32 s53, s55, s61
	s_cselect_b32 s83, s54, s60
	s_ashr_i32 s49, s48, 31
	s_lshl_b64 s[56:57], s[48:49], 19
	s_add_u32 s56, s66, s56
	s_addc_u32 s57, s67, s57
	s_and_b64 s[64:65], s[10:11], exec
	s_cselect_b32 s49, s57, s63
	s_cselect_b32 s84, s56, s62
	s_add_u32 s60, s60, 0x40080
	s_addc_u32 s61, s61, 0
	s_add_u32 s85, s62, 0x100
	s_addc_u32 s86, s63, 0
	s_mov_b32 s87, -2
	ds_read_b128 v[152:155], v148
	ds_read_b128 v[156:159], v148 offset:1024
	ds_read_b128 v[160:163], v148 offset:2048
	ds_read_b128 v[164:167], v148 offset:3072
	ds_read_b128 v[168:171], v149
	ds_read_b128 v[172:175], v149 offset:1024
	ds_read_b128 v[176:179], v149 offset:2048
	ds_read_b128 v[184:187], v149 offset:3072
	s_add_u32 s62, s60, 0xfffc0080
	s_addc_u32 s63, s61, -1
	s_cmp_eq_u32 s87, 12
	s_cselect_b32 s65, s53, s63
	s_cselect_b32 s64, s83, s62
	s_cselect_b32 s63, s49, s86
	s_cselect_b32 s62, s84, s85
	v_lshl_add_u64 v[220:221], s[60:61], 0, v[138:139]
	s_add_i32 m0, s69, 0xc000
	ds_read_b128 v[188:191], v150
	ds_read_b128 v[192:195], v150 offset:1024
	ds_read_b128 v[196:199], v150 offset:2048
	ds_read_b128 v[200:203], v150 offset:3072
	ds_read_b128 v[204:207], v150 offset:4096
	ds_read_b128 v[208:211], v150 offset:5120
	ds_read_b128 v[212:215], v150 offset:6144
	ds_read_b128 v[216:219], v150 offset:7168
	global_load_lds_dwordx4 v[220:221], off
	v_lshl_add_u64 v[220:221], s[60:61], 0, v[140:141]
	s_add_i32 m0, s69, 0xe000
	s_nop 0
	global_load_lds_dwordx4 v[220:221], off
	s_waitcnt vmcnt(8)
	s_waitcnt lgkmcnt(0)
	s_barrier
	s_setprio 1
	v_mfma_f32_16x16x32_bf16 v[124:127], v[152:155], v[188:191], 0
	v_mfma_f32_16x16x32_bf16 v[124:127], v[156:159], v[192:195], v[124:127]
	v_mfma_f32_16x16x32_bf16 v[120:123], v[160:163], v[188:191], 0
	v_mfma_f32_16x16x32_bf16 v[120:123], v[164:167], v[192:195], v[120:123]
	v_mfma_f32_16x16x32_bf16 v[116:119], v[152:155], v[196:199], 0
	v_mfma_f32_16x16x32_bf16 v[116:119], v[156:159], v[200:203], v[116:119]
	v_mfma_f32_16x16x32_bf16 v[112:115], v[160:163], v[196:199], 0
	v_mfma_f32_16x16x32_bf16 v[112:115], v[164:167], v[200:203], v[112:115]
	v_mfma_f32_16x16x32_bf16 v[108:111], v[152:155], v[204:207], 0
	v_mfma_f32_16x16x32_bf16 v[108:111], v[156:159], v[208:211], v[108:111]
	v_mfma_f32_16x16x32_bf16 v[104:107], v[160:163], v[204:207], 0
	v_mfma_f32_16x16x32_bf16 v[104:107], v[164:167], v[208:211], v[104:107]
	v_mfma_f32_16x16x32_bf16 v[100:103], v[152:155], v[212:215], 0
	v_mfma_f32_16x16x32_bf16 v[100:103], v[156:159], v[216:219], v[100:103]
	v_mfma_f32_16x16x32_bf16 v[96:99], v[160:163], v[212:215], 0
	v_mfma_f32_16x16x32_bf16 v[96:99], v[164:167], v[216:219], v[96:99]
	v_mfma_f32_16x16x32_bf16 v[76:79], v[168:171], v[188:191], 0
	v_mfma_f32_16x16x32_bf16 v[76:79], v[172:175], v[192:195], v[76:79]
	v_mfma_f32_16x16x32_bf16 v[68:71], v[176:179], v[188:191], 0
	v_mfma_f32_16x16x32_bf16 v[68:71], v[184:187], v[192:195], v[68:71]
	v_mfma_f32_16x16x32_bf16 v[60:63], v[168:171], v[196:199], 0
	v_mfma_f32_16x16x32_bf16 v[60:63], v[172:175], v[200:203], v[60:63]
	v_mfma_f32_16x16x32_bf16 v[52:55], v[176:179], v[196:199], 0
	v_mfma_f32_16x16x32_bf16 v[52:55], v[184:187], v[200:203], v[52:55]
	v_mfma_f32_16x16x32_bf16 v[44:47], v[168:171], v[204:207], 0
	v_mfma_f32_16x16x32_bf16 v[44:47], v[172:175], v[208:211], v[44:47]
	v_mfma_f32_16x16x32_bf16 v[40:43], v[176:179], v[204:207], 0
	v_mfma_f32_16x16x32_bf16 v[40:43], v[184:187], v[208:211], v[40:43]
	v_mfma_f32_16x16x32_bf16 v[36:39], v[168:171], v[212:215], 0
	v_mfma_f32_16x16x32_bf16 v[36:39], v[172:175], v[216:219], v[36:39]
	v_mfma_f32_16x16x32_bf16 v[32:35], v[176:179], v[212:215], 0
	v_mfma_f32_16x16x32_bf16 v[32:35], v[184:187], v[216:219], v[32:35]
	s_setprio 0
	s_barrier
	s_add_i32 s79, s77, s68
	v_lshl_add_u64 v[220:221], s[62:63], 0, v[130:131]
	s_mov_b32 m0, s79
	ds_read_b128 v[188:191], v150 offset:16384
	ds_read_b128 v[192:195], v150 offset:17408
	ds_read_b128 v[196:199], v150 offset:18432
	ds_read_b128 v[200:203], v150 offset:19456
	ds_read_b128 v[204:207], v150 offset:20480
	ds_read_b128 v[208:211], v150 offset:21504
	ds_read_b128 v[212:215], v150 offset:22528
	ds_read_b128 v[216:219], v150 offset:23552
	global_load_lds_dwordx4 v[220:221], off
	s_add_i32 m0, s79, 0x2000
	s_add_u32 s88, s62, 0x40000
	v_lshl_add_u64 v[222:223], s[62:63], 0, v[134:135]
	s_addc_u32 s89, s63, 0
	s_add_i32 s79, s82, s68
	global_load_lds_dwordx4 v[222:223], off
	v_lshl_add_u64 v[224:225], s[88:89], 0, v[130:131]
	s_mov_b32 m0, s79
	v_lshl_add_u64 v[226:227], s[64:65], 0, v[132:133]
	global_load_lds_dwordx4 v[224:225], off
	v_lshl_add_u64 v[224:225], s[88:89], 0, v[134:135]
	s_add_i32 m0, s79, 0x2000
	s_nop 0
	global_load_lds_dwordx4 v[224:225], off
	v_lshl_add_u64 v[224:225], s[64:65], 0, v[128:129]
	s_mov_b32 m0, s69
	s_nop 0
	global_load_lds_dwordx4 v[224:225], off
	s_mov_b32 m0, s70
	s_nop 0
	global_load_lds_dwordx4 v[226:227], off
	s_waitcnt vmcnt(8)
	s_waitcnt lgkmcnt(0)
	s_barrier
	s_setprio 1
	v_mfma_f32_16x16x32_bf16 v[92:95], v[152:155], v[188:191], 0
	v_mfma_f32_16x16x32_bf16 v[92:95], v[156:159], v[192:195], v[92:95]
	v_mfma_f32_16x16x32_bf16 v[88:91], v[160:163], v[188:191], 0
	v_mfma_f32_16x16x32_bf16 v[88:91], v[164:167], v[192:195], v[88:91]
	v_mfma_f32_16x16x32_bf16 v[84:87], v[152:155], v[196:199], 0
	v_mfma_f32_16x16x32_bf16 v[84:87], v[156:159], v[200:203], v[84:87]
	v_mfma_f32_16x16x32_bf16 v[80:83], v[160:163], v[196:199], 0
	v_mfma_f32_16x16x32_bf16 v[80:83], v[164:167], v[200:203], v[80:83]
	v_mfma_f32_16x16x32_bf16 v[72:75], v[152:155], v[204:207], 0
	v_mfma_f32_16x16x32_bf16 v[72:75], v[156:159], v[208:211], v[72:75]
	v_mfma_f32_16x16x32_bf16 v[64:67], v[160:163], v[204:207], 0
	v_mfma_f32_16x16x32_bf16 v[64:67], v[164:167], v[208:211], v[64:67]
	v_mfma_f32_16x16x32_bf16 v[56:59], v[152:155], v[212:215], 0
	v_mfma_f32_16x16x32_bf16 v[56:59], v[156:159], v[216:219], v[56:59]
	v_mfma_f32_16x16x32_bf16 v[48:51], v[160:163], v[212:215], 0
	v_mfma_f32_16x16x32_bf16 v[48:51], v[164:167], v[216:219], v[48:51]
	v_mfma_f32_16x16x32_bf16 v[28:31], v[168:171], v[188:191], 0
	v_mfma_f32_16x16x32_bf16 v[28:31], v[172:175], v[192:195], v[28:31]
	v_mfma_f32_16x16x32_bf16 v[24:27], v[176:179], v[188:191], 0
	v_mfma_f32_16x16x32_bf16 v[24:27], v[184:187], v[192:195], v[24:27]
	v_mfma_f32_16x16x32_bf16 v[20:23], v[168:171], v[196:199], 0
	v_mfma_f32_16x16x32_bf16 v[20:23], v[172:175], v[200:203], v[20:23]
	v_mfma_f32_16x16x32_bf16 v[16:19], v[176:179], v[196:199], 0
	v_mfma_f32_16x16x32_bf16 v[16:19], v[184:187], v[200:203], v[16:19]
	v_mfma_f32_16x16x32_bf16 v[12:15], v[168:171], v[204:207], 0
	v_mfma_f32_16x16x32_bf16 v[12:15], v[172:175], v[208:211], v[12:15]
	v_mfma_f32_16x16x32_bf16 v[8:11], v[176:179], v[204:207], 0
	v_mfma_f32_16x16x32_bf16 v[8:11], v[184:187], v[208:211], v[8:11]
	v_mfma_f32_16x16x32_bf16 v[4:7], v[168:171], v[212:215], 0
	v_mfma_f32_16x16x32_bf16 v[4:7], v[172:175], v[216:219], v[4:7]
	v_mfma_f32_16x16x32_bf16 v[0:3], v[176:179], v[212:215], 0
	v_mfma_f32_16x16x32_bf16 v[0:3], v[184:187], v[216:219], v[0:3]
	s_setprio 0
	s_barrier
	s_branch .Lmid_gemm6
.LBB0_935:
	ds_read_b128 v[152:155], v148
	ds_read_b128 v[156:159], v148 offset:1024
	ds_read_b128 v[160:163], v148 offset:2048
	ds_read_b128 v[164:167], v148 offset:3072
	ds_read_b128 v[168:171], v149
	ds_read_b128 v[172:175], v149 offset:1024
	ds_read_b128 v[176:179], v149 offset:2048
	ds_read_b128 v[184:187], v149 offset:3072
	s_add_u32 s62, s60, 0xfffc0080
	s_addc_u32 s63, s61, -1
	s_cmp_eq_u32 s87, 12
	s_cselect_b32 s65, s53, s63
	s_cselect_b32 s64, s83, s62
	s_cselect_b32 s63, s49, s86
	s_cselect_b32 s62, s84, s85
	v_lshl_add_u64 v[220:221], s[60:61], 0, v[138:139]
	s_add_i32 m0, s69, 0xc000
	ds_read_b128 v[188:191], v150
	ds_read_b128 v[192:195], v150 offset:1024
	ds_read_b128 v[196:199], v150 offset:2048
	ds_read_b128 v[200:203], v150 offset:3072
	ds_read_b128 v[204:207], v150 offset:4096
	ds_read_b128 v[208:211], v150 offset:5120
	ds_read_b128 v[212:215], v150 offset:6144
	ds_read_b128 v[216:219], v150 offset:7168
	global_load_lds_dwordx4 v[220:221], off
	v_lshl_add_u64 v[220:221], s[60:61], 0, v[140:141]
	s_add_i32 m0, s69, 0xe000
	s_nop 0
	global_load_lds_dwordx4 v[220:221], off
	s_waitcnt vmcnt(8)
	s_waitcnt lgkmcnt(0)
	s_barrier
	s_setprio 1
	v_mfma_f32_16x16x32_bf16 v[124:127], v[152:155], v[188:191], v[124:127]
	v_mfma_f32_16x16x32_bf16 v[124:127], v[156:159], v[192:195], v[124:127]
	v_mfma_f32_16x16x32_bf16 v[120:123], v[160:163], v[188:191], v[120:123]
	v_mfma_f32_16x16x32_bf16 v[120:123], v[164:167], v[192:195], v[120:123]
	v_mfma_f32_16x16x32_bf16 v[116:119], v[152:155], v[196:199], v[116:119]
	v_mfma_f32_16x16x32_bf16 v[116:119], v[156:159], v[200:203], v[116:119]
	v_mfma_f32_16x16x32_bf16 v[112:115], v[160:163], v[196:199], v[112:115]
	v_mfma_f32_16x16x32_bf16 v[112:115], v[164:167], v[200:203], v[112:115]
	v_mfma_f32_16x16x32_bf16 v[108:111], v[152:155], v[204:207], v[108:111]
	v_mfma_f32_16x16x32_bf16 v[108:111], v[156:159], v[208:211], v[108:111]
	v_mfma_f32_16x16x32_bf16 v[104:107], v[160:163], v[204:207], v[104:107]
	v_mfma_f32_16x16x32_bf16 v[104:107], v[164:167], v[208:211], v[104:107]
	v_mfma_f32_16x16x32_bf16 v[100:103], v[152:155], v[212:215], v[100:103]
	v_mfma_f32_16x16x32_bf16 v[100:103], v[156:159], v[216:219], v[100:103]
	v_mfma_f32_16x16x32_bf16 v[96:99], v[160:163], v[212:215], v[96:99]
	v_mfma_f32_16x16x32_bf16 v[96:99], v[164:167], v[216:219], v[96:99]
	v_mfma_f32_16x16x32_bf16 v[76:79], v[168:171], v[188:191], v[76:79]
	v_mfma_f32_16x16x32_bf16 v[76:79], v[172:175], v[192:195], v[76:79]
	v_mfma_f32_16x16x32_bf16 v[68:71], v[176:179], v[188:191], v[68:71]
	v_mfma_f32_16x16x32_bf16 v[68:71], v[184:187], v[192:195], v[68:71]
	v_mfma_f32_16x16x32_bf16 v[60:63], v[168:171], v[196:199], v[60:63]
	v_mfma_f32_16x16x32_bf16 v[60:63], v[172:175], v[200:203], v[60:63]
	v_mfma_f32_16x16x32_bf16 v[52:55], v[176:179], v[196:199], v[52:55]
	v_mfma_f32_16x16x32_bf16 v[52:55], v[184:187], v[200:203], v[52:55]
	v_mfma_f32_16x16x32_bf16 v[44:47], v[168:171], v[204:207], v[44:47]
	v_mfma_f32_16x16x32_bf16 v[44:47], v[172:175], v[208:211], v[44:47]
	v_mfma_f32_16x16x32_bf16 v[40:43], v[176:179], v[204:207], v[40:43]
	v_mfma_f32_16x16x32_bf16 v[40:43], v[184:187], v[208:211], v[40:43]
	v_mfma_f32_16x16x32_bf16 v[36:39], v[168:171], v[212:215], v[36:39]
	v_mfma_f32_16x16x32_bf16 v[36:39], v[172:175], v[216:219], v[36:39]
	v_mfma_f32_16x16x32_bf16 v[32:35], v[176:179], v[212:215], v[32:35]
	v_mfma_f32_16x16x32_bf16 v[32:35], v[184:187], v[216:219], v[32:35]
	s_setprio 0
	s_barrier
	s_add_i32 s79, s77, s68
	v_lshl_add_u64 v[220:221], s[62:63], 0, v[130:131]
	s_mov_b32 m0, s79
	ds_read_b128 v[188:191], v150 offset:16384
	ds_read_b128 v[192:195], v150 offset:17408
	ds_read_b128 v[196:199], v150 offset:18432
	ds_read_b128 v[200:203], v150 offset:19456
	ds_read_b128 v[204:207], v150 offset:20480
	ds_read_b128 v[208:211], v150 offset:21504
	ds_read_b128 v[212:215], v150 offset:22528
	ds_read_b128 v[216:219], v150 offset:23552
	global_load_lds_dwordx4 v[220:221], off
	s_add_i32 m0, s79, 0x2000
	s_add_u32 s88, s62, 0x40000
	v_lshl_add_u64 v[222:223], s[62:63], 0, v[134:135]
	s_addc_u32 s89, s63, 0
	s_add_i32 s79, s82, s68
	global_load_lds_dwordx4 v[222:223], off
	v_lshl_add_u64 v[224:225], s[88:89], 0, v[130:131]
	s_mov_b32 m0, s79
	v_lshl_add_u64 v[226:227], s[64:65], 0, v[132:133]
	global_load_lds_dwordx4 v[224:225], off
	v_lshl_add_u64 v[224:225], s[88:89], 0, v[134:135]
	s_add_i32 m0, s79, 0x2000
	s_nop 0
	global_load_lds_dwordx4 v[224:225], off
	v_lshl_add_u64 v[224:225], s[64:65], 0, v[128:129]
	s_mov_b32 m0, s69
	s_nop 0
	global_load_lds_dwordx4 v[224:225], off
	s_mov_b32 m0, s70
	s_nop 0
	global_load_lds_dwordx4 v[226:227], off
	s_waitcnt vmcnt(8)
	s_waitcnt lgkmcnt(0)
	s_barrier
	s_setprio 1
	v_mfma_f32_16x16x32_bf16 v[92:95], v[152:155], v[188:191], v[92:95]
	v_mfma_f32_16x16x32_bf16 v[92:95], v[156:159], v[192:195], v[92:95]
	v_mfma_f32_16x16x32_bf16 v[88:91], v[160:163], v[188:191], v[88:91]
	v_mfma_f32_16x16x32_bf16 v[88:91], v[164:167], v[192:195], v[88:91]
	v_mfma_f32_16x16x32_bf16 v[84:87], v[152:155], v[196:199], v[84:87]
	v_mfma_f32_16x16x32_bf16 v[84:87], v[156:159], v[200:203], v[84:87]
	v_mfma_f32_16x16x32_bf16 v[80:83], v[160:163], v[196:199], v[80:83]
	v_mfma_f32_16x16x32_bf16 v[80:83], v[164:167], v[200:203], v[80:83]
	v_mfma_f32_16x16x32_bf16 v[72:75], v[152:155], v[204:207], v[72:75]
	v_mfma_f32_16x16x32_bf16 v[72:75], v[156:159], v[208:211], v[72:75]
	v_mfma_f32_16x16x32_bf16 v[64:67], v[160:163], v[204:207], v[64:67]
	v_mfma_f32_16x16x32_bf16 v[64:67], v[164:167], v[208:211], v[64:67]
	v_mfma_f32_16x16x32_bf16 v[56:59], v[152:155], v[212:215], v[56:59]
	v_mfma_f32_16x16x32_bf16 v[56:59], v[156:159], v[216:219], v[56:59]
	v_mfma_f32_16x16x32_bf16 v[48:51], v[160:163], v[212:215], v[48:51]
	v_mfma_f32_16x16x32_bf16 v[48:51], v[164:167], v[216:219], v[48:51]
	v_mfma_f32_16x16x32_bf16 v[28:31], v[168:171], v[188:191], v[28:31]
	v_mfma_f32_16x16x32_bf16 v[28:31], v[172:175], v[192:195], v[28:31]
	v_mfma_f32_16x16x32_bf16 v[24:27], v[176:179], v[188:191], v[24:27]
	v_mfma_f32_16x16x32_bf16 v[24:27], v[184:187], v[192:195], v[24:27]
	v_mfma_f32_16x16x32_bf16 v[20:23], v[168:171], v[196:199], v[20:23]
	v_mfma_f32_16x16x32_bf16 v[20:23], v[172:175], v[200:203], v[20:23]
	v_mfma_f32_16x16x32_bf16 v[16:19], v[176:179], v[196:199], v[16:19]
	v_mfma_f32_16x16x32_bf16 v[16:19], v[184:187], v[200:203], v[16:19]
	v_mfma_f32_16x16x32_bf16 v[12:15], v[168:171], v[204:207], v[12:15]
	v_mfma_f32_16x16x32_bf16 v[12:15], v[172:175], v[208:211], v[12:15]
	v_mfma_f32_16x16x32_bf16 v[8:11], v[176:179], v[204:207], v[8:11]
	v_mfma_f32_16x16x32_bf16 v[8:11], v[184:187], v[208:211], v[8:11]
	v_mfma_f32_16x16x32_bf16 v[4:7], v[168:171], v[212:215], v[4:7]
	v_mfma_f32_16x16x32_bf16 v[4:7], v[172:175], v[216:219], v[4:7]
	v_mfma_f32_16x16x32_bf16 v[0:3], v[176:179], v[212:215], v[0:3]
	v_mfma_f32_16x16x32_bf16 v[0:3], v[184:187], v[216:219], v[0:3]
	s_setprio 0
	s_barrier
.Lmid_gemm6:
	s_add_i32 s79, 0, 0x18000
	v_add_u32_e32 v151, s79, v147
	s_add_i32 s88, 0, 0x1c000
	ds_read_b128 v[152:155], v151
	ds_read_b128 v[156:159], v151 offset:1024
	ds_read_b128 v[160:163], v151 offset:2048
	ds_read_b128 v[164:167], v151 offset:3072
	v_add_u32_e32 v151, s88, v147
	ds_read_b128 v[168:171], v151
	ds_read_b128 v[172:175], v151 offset:1024
	ds_read_b128 v[176:179], v151 offset:2048
	ds_read_b128 v[184:187], v151 offset:3072
	s_add_u32 s64, s64, 0x40000
	s_addc_u32 s65, s65, 0
	s_mov_b32 m0, s71
	v_lshl_add_u64 v[228:229], s[64:65], 0, v[128:129]
	ds_read_b128 v[188:191], v150 offset:32768
	ds_read_b128 v[192:195], v150 offset:33792
	ds_read_b128 v[196:199], v150 offset:34816
	ds_read_b128 v[200:203], v150 offset:35840
	ds_read_b128 v[204:207], v150 offset:36864
	ds_read_b128 v[208:211], v150 offset:37888
	ds_read_b128 v[212:215], v150 offset:38912
	ds_read_b128 v[216:219], v150 offset:39936
	global_load_lds_dwordx4 v[228:229], off
	v_lshl_add_u64 v[228:229], s[64:65], 0, v[132:133]
	s_mov_b32 m0, s72
	s_nop 0
	global_load_lds_dwordx4 v[228:229], off
	s_waitcnt vmcnt(8)
	s_waitcnt lgkmcnt(0)
	s_barrier
	s_setprio 1
	v_mfma_f32_16x16x32_bf16 v[124:127], v[152:155], v[188:191], v[124:127]
	v_mfma_f32_16x16x32_bf16 v[124:127], v[156:159], v[192:195], v[124:127]
	v_mfma_f32_16x16x32_bf16 v[120:123], v[160:163], v[188:191], v[120:123]
	v_mfma_f32_16x16x32_bf16 v[120:123], v[164:167], v[192:195], v[120:123]
	v_mfma_f32_16x16x32_bf16 v[116:119], v[152:155], v[196:199], v[116:119]
	v_mfma_f32_16x16x32_bf16 v[116:119], v[156:159], v[200:203], v[116:119]
	v_mfma_f32_16x16x32_bf16 v[112:115], v[160:163], v[196:199], v[112:115]
	v_mfma_f32_16x16x32_bf16 v[112:115], v[164:167], v[200:203], v[112:115]
	v_mfma_f32_16x16x32_bf16 v[108:111], v[152:155], v[204:207], v[108:111]
	v_mfma_f32_16x16x32_bf16 v[108:111], v[156:159], v[208:211], v[108:111]
	v_mfma_f32_16x16x32_bf16 v[104:107], v[160:163], v[204:207], v[104:107]
	v_mfma_f32_16x16x32_bf16 v[104:107], v[164:167], v[208:211], v[104:107]
	v_mfma_f32_16x16x32_bf16 v[100:103], v[152:155], v[212:215], v[100:103]
	v_mfma_f32_16x16x32_bf16 v[100:103], v[156:159], v[216:219], v[100:103]
	v_mfma_f32_16x16x32_bf16 v[96:99], v[160:163], v[212:215], v[96:99]
	v_mfma_f32_16x16x32_bf16 v[96:99], v[164:167], v[216:219], v[96:99]
	v_mfma_f32_16x16x32_bf16 v[76:79], v[168:171], v[188:191], v[76:79]
	v_mfma_f32_16x16x32_bf16 v[76:79], v[172:175], v[192:195], v[76:79]
	v_mfma_f32_16x16x32_bf16 v[68:71], v[176:179], v[188:191], v[68:71]
	v_mfma_f32_16x16x32_bf16 v[68:71], v[184:187], v[192:195], v[68:71]
	v_mfma_f32_16x16x32_bf16 v[60:63], v[168:171], v[196:199], v[60:63]
	v_mfma_f32_16x16x32_bf16 v[60:63], v[172:175], v[200:203], v[60:63]
	v_mfma_f32_16x16x32_bf16 v[52:55], v[176:179], v[196:199], v[52:55]
	v_mfma_f32_16x16x32_bf16 v[52:55], v[184:187], v[200:203], v[52:55]
	v_mfma_f32_16x16x32_bf16 v[44:47], v[168:171], v[204:207], v[44:47]
	v_mfma_f32_16x16x32_bf16 v[44:47], v[172:175], v[208:211], v[44:47]
	v_mfma_f32_16x16x32_bf16 v[40:43], v[176:179], v[204:207], v[40:43]
	v_mfma_f32_16x16x32_bf16 v[40:43], v[184:187], v[208:211], v[40:43]
	v_mfma_f32_16x16x32_bf16 v[36:39], v[168:171], v[212:215], v[36:39]
	v_mfma_f32_16x16x32_bf16 v[36:39], v[172:175], v[216:219], v[36:39]
	v_mfma_f32_16x16x32_bf16 v[32:35], v[176:179], v[212:215], v[32:35]
	v_mfma_f32_16x16x32_bf16 v[32:35], v[184:187], v[216:219], v[32:35]
	s_setprio 0
	s_barrier
	s_add_i32 s64, s79, s68
	v_lshl_add_u64 v[220:221], v[220:221], 0, s[12:13]
	s_mov_b32 m0, s64
	ds_read_b128 v[188:191], v150 offset:49152
	ds_read_b128 v[192:195], v150 offset:50176
	ds_read_b128 v[196:199], v150 offset:51200
	ds_read_b128 v[200:203], v150 offset:52224
	ds_read_b128 v[204:207], v150 offset:53248
	ds_read_b128 v[208:211], v150 offset:54272
	ds_read_b128 v[212:215], v150 offset:55296
	ds_read_b128 v[216:219], v150 offset:56320
	global_load_lds_dwordx4 v[220:221], off
	s_add_i32 m0, s64, 0x2000
	s_add_u32 s62, s62, 0x40080
	v_lshl_add_u64 v[220:221], v[222:223], 0, s[12:13]
	s_addc_u32 s63, s63, 0
	s_add_i32 s64, s88, s68
	global_load_lds_dwordx4 v[220:221], off
	v_lshl_add_u64 v[220:221], s[62:63], 0, v[130:131]
	s_mov_b32 m0, s64
	s_nop 0
	global_load_lds_dwordx4 v[220:221], off
	v_lshl_add_u64 v[220:221], s[62:63], 0, v[134:135]
	s_add_i32 m0, s64, 0x2000
	s_nop 0
	global_load_lds_dwordx4 v[220:221], off
	v_lshl_add_u64 v[220:221], v[224:225], 0, s[12:13]
	s_mov_b32 m0, s75
	s_nop 0
	global_load_lds_dwordx4 v[220:221], off
	v_lshl_add_u64 v[220:221], v[226:227], 0, s[12:13]
	s_mov_b32 m0, s76
	s_nop 0
	global_load_lds_dwordx4 v[220:221], off
	s_waitcnt vmcnt(8)
	s_waitcnt lgkmcnt(0)
	s_barrier
	s_setprio 1
	v_mfma_f32_16x16x32_bf16 v[92:95], v[152:155], v[188:191], v[92:95]
	v_mfma_f32_16x16x32_bf16 v[92:95], v[156:159], v[192:195], v[92:95]
	v_mfma_f32_16x16x32_bf16 v[88:91], v[160:163], v[188:191], v[88:91]
	v_mfma_f32_16x16x32_bf16 v[88:91], v[164:167], v[192:195], v[88:91]
	v_mfma_f32_16x16x32_bf16 v[84:87], v[152:155], v[196:199], v[84:87]
	v_mfma_f32_16x16x32_bf16 v[84:87], v[156:159], v[200:203], v[84:87]
	v_mfma_f32_16x16x32_bf16 v[80:83], v[160:163], v[196:199], v[80:83]
	v_mfma_f32_16x16x32_bf16 v[80:83], v[164:167], v[200:203], v[80:83]
	v_mfma_f32_16x16x32_bf16 v[72:75], v[152:155], v[204:207], v[72:75]
	v_mfma_f32_16x16x32_bf16 v[72:75], v[156:159], v[208:211], v[72:75]
	v_mfma_f32_16x16x32_bf16 v[64:67], v[160:163], v[204:207], v[64:67]
	v_mfma_f32_16x16x32_bf16 v[64:67], v[164:167], v[208:211], v[64:67]
	v_mfma_f32_16x16x32_bf16 v[56:59], v[152:155], v[212:215], v[56:59]
	v_mfma_f32_16x16x32_bf16 v[56:59], v[156:159], v[216:219], v[56:59]
	v_mfma_f32_16x16x32_bf16 v[48:51], v[160:163], v[212:215], v[48:51]
	v_mfma_f32_16x16x32_bf16 v[48:51], v[164:167], v[216:219], v[48:51]
	v_mfma_f32_16x16x32_bf16 v[28:31], v[168:171], v[188:191], v[28:31]
	v_mfma_f32_16x16x32_bf16 v[28:31], v[172:175], v[192:195], v[28:31]
	v_mfma_f32_16x16x32_bf16 v[24:27], v[176:179], v[188:191], v[24:27]
	v_mfma_f32_16x16x32_bf16 v[24:27], v[184:187], v[192:195], v[24:27]
	v_mfma_f32_16x16x32_bf16 v[20:23], v[168:171], v[196:199], v[20:23]
	v_mfma_f32_16x16x32_bf16 v[20:23], v[172:175], v[200:203], v[20:23]
	v_mfma_f32_16x16x32_bf16 v[16:19], v[176:179], v[196:199], v[16:19]
	v_mfma_f32_16x16x32_bf16 v[16:19], v[184:187], v[200:203], v[16:19]
	v_mfma_f32_16x16x32_bf16 v[12:15], v[168:171], v[204:207], v[12:15]
	v_mfma_f32_16x16x32_bf16 v[12:15], v[172:175], v[208:211], v[12:15]
	v_mfma_f32_16x16x32_bf16 v[8:11], v[176:179], v[204:207], v[8:11]
	v_mfma_f32_16x16x32_bf16 v[8:11], v[184:187], v[208:211], v[8:11]
	v_mfma_f32_16x16x32_bf16 v[4:7], v[168:171], v[212:215], v[4:7]
	v_mfma_f32_16x16x32_bf16 v[4:7], v[172:175], v[216:219], v[4:7]
	v_mfma_f32_16x16x32_bf16 v[0:3], v[176:179], v[212:215], v[0:3]
	v_mfma_f32_16x16x32_bf16 v[0:3], v[184:187], v[216:219], v[0:3]
	s_setprio 0
	s_barrier
	s_add_i32 s87, s87, 2
	s_add_u32 s60, s60, 0x100
	s_addc_u32 s61, s61, 0
	s_add_u32 s85, s85, 0x100
	s_addc_u32 s86, s86, 0
	s_cmp_gt_u32 s87, 13
	s_cbranch_scc0 .LBB0_935
	s_and_b64 vcc, exec, s[16:17]
	s_cbranch_vccz .LBB0_938
	s_barrier

.LBB0_950:
	s_ashr_i32 s37, s36, 31
	s_lshl_b64 s[44:45], s[36:37], 19
	s_add_u32 s44, s80, s44
	s_addc_u32 s45, s81, s45
	s_and_b64 s[46:47], s[10:11], exec
	s_cselect_b32 s37, s45, s53
	s_cselect_b32 s72, s44, s52
	s_ashr_i32 s19, s18, 31
	s_lshl_b64 s[46:47], s[18:19], 19
	s_add_u32 s46, s58, s46
	s_addc_u32 s47, s59, s47
	s_and_b64 s[56:57], s[10:11], exec
	s_cselect_b32 s19, s47, s55
	s_cselect_b32 s73, s46, s54
	s_add_u32 s52, s52, 0x40080
	s_addc_u32 s53, s53, 0
	s_add_u32 s74, s54, 0x100
	s_addc_u32 s75, s55, 0
	s_mov_b32 s76, -2
	ds_read_b128 v[140:143], v147
	ds_read_b128 v[150:153], v147 offset:1024
	ds_read_b128 v[154:157], v147 offset:2048
	ds_read_b128 v[158:161], v147 offset:3072
	ds_read_b128 v[162:165], v148
	ds_read_b128 v[166:169], v148 offset:1024
	ds_read_b128 v[170:173], v148 offset:2048
	ds_read_b128 v[174:177], v148 offset:3072
	s_add_u32 s54, s52, 0xfffc0080
	s_addc_u32 s55, s53, -1
	s_cmp_eq_u32 s76, 12
	s_cselect_b32 s57, s37, s55
	s_cselect_b32 s56, s72, s54
	s_cselect_b32 s55, s19, s75
	s_cselect_b32 s54, s73, s74
	v_lshl_add_u64 v[178:179], s[52:53], 0, v[132:133]
	s_add_i32 m0, s49, 0xc000
	ds_read_b128 v[184:187], v149
	ds_read_b128 v[188:191], v149 offset:1024
	ds_read_b128 v[192:195], v149 offset:2048
	ds_read_b128 v[196:199], v149 offset:3072
	ds_read_b128 v[200:203], v149 offset:4096
	ds_read_b128 v[204:207], v149 offset:5120
	ds_read_b128 v[208:211], v149 offset:6144
	ds_read_b128 v[212:215], v149 offset:7168
	global_load_lds_dwordx4 v[178:179], off
	v_lshl_add_u64 v[178:179], s[52:53], 0, v[134:135]
	s_add_i32 m0, s49, 0xe000
	s_nop 0
	global_load_lds_dwordx4 v[178:179], off
	s_waitcnt vmcnt(8)
	s_waitcnt lgkmcnt(0)
	s_barrier
	s_setprio 1
	v_mfma_f32_16x16x32_bf16 v[124:127], v[140:143], v[184:187], 0
	v_mfma_f32_16x16x32_bf16 v[124:127], v[150:153], v[188:191], v[124:127]
	v_mfma_f32_16x16x32_bf16 v[120:123], v[154:157], v[184:187], 0
	v_mfma_f32_16x16x32_bf16 v[120:123], v[158:161], v[188:191], v[120:123]
	v_mfma_f32_16x16x32_bf16 v[108:111], v[140:143], v[192:195], 0
	v_mfma_f32_16x16x32_bf16 v[108:111], v[150:153], v[196:199], v[108:111]
	v_mfma_f32_16x16x32_bf16 v[104:107], v[154:157], v[192:195], 0
	v_mfma_f32_16x16x32_bf16 v[104:107], v[158:161], v[196:199], v[104:107]
	v_mfma_f32_16x16x32_bf16 v[92:95], v[140:143], v[200:203], 0
	v_mfma_f32_16x16x32_bf16 v[92:95], v[150:153], v[204:207], v[92:95]
	v_mfma_f32_16x16x32_bf16 v[88:91], v[154:157], v[200:203], 0
	v_mfma_f32_16x16x32_bf16 v[88:91], v[158:161], v[204:207], v[88:91]
	v_mfma_f32_16x16x32_bf16 v[76:79], v[140:143], v[208:211], 0
	v_mfma_f32_16x16x32_bf16 v[76:79], v[150:153], v[212:215], v[76:79]
	v_mfma_f32_16x16x32_bf16 v[72:75], v[154:157], v[208:211], 0
	v_mfma_f32_16x16x32_bf16 v[72:75], v[158:161], v[212:215], v[72:75]
	v_mfma_f32_16x16x32_bf16 v[116:119], v[162:165], v[184:187], 0
	v_mfma_f32_16x16x32_bf16 v[116:119], v[166:169], v[188:191], v[116:119]
	v_mfma_f32_16x16x32_bf16 v[112:115], v[170:173], v[184:187], 0
	v_mfma_f32_16x16x32_bf16 v[112:115], v[174:177], v[188:191], v[112:115]
	v_mfma_f32_16x16x32_bf16 v[100:103], v[162:165], v[192:195], 0
	v_mfma_f32_16x16x32_bf16 v[100:103], v[166:169], v[196:199], v[100:103]
	v_mfma_f32_16x16x32_bf16 v[96:99], v[170:173], v[192:195], 0
	v_mfma_f32_16x16x32_bf16 v[96:99], v[174:177], v[196:199], v[96:99]
	v_mfma_f32_16x16x32_bf16 v[84:87], v[162:165], v[200:203], 0
	v_mfma_f32_16x16x32_bf16 v[84:87], v[166:169], v[204:207], v[84:87]
	v_mfma_f32_16x16x32_bf16 v[80:83], v[170:173], v[200:203], 0
	v_mfma_f32_16x16x32_bf16 v[80:83], v[174:177], v[204:207], v[80:83]
	v_mfma_f32_16x16x32_bf16 v[68:71], v[162:165], v[208:211], 0
	v_mfma_f32_16x16x32_bf16 v[68:71], v[166:169], v[212:215], v[68:71]
	v_mfma_f32_16x16x32_bf16 v[64:67], v[170:173], v[208:211], 0
	v_mfma_f32_16x16x32_bf16 v[64:67], v[174:177], v[212:215], v[64:67]
	s_setprio 0
	s_barrier
	s_add_i32 s77, s68, s60
	v_lshl_add_u64 v[178:179], s[54:55], 0, v[130:131]
	s_mov_b32 m0, s77
	ds_read_b128 v[184:187], v149 offset:16384
	ds_read_b128 v[188:191], v149 offset:17408
	ds_read_b128 v[192:195], v149 offset:18432
	ds_read_b128 v[196:199], v149 offset:19456
	ds_read_b128 v[200:203], v149 offset:20480
	ds_read_b128 v[204:207], v149 offset:21504
	ds_read_b128 v[208:211], v149 offset:22528
	ds_read_b128 v[212:215], v149 offset:23552
	global_load_lds_dwordx4 v[178:179], off
	s_add_i32 m0, s77, 0x2000
	s_add_u32 s82, s54, 0x40000
	v_lshl_add_u64 v[216:217], s[54:55], 0, v[128:129]
	s_addc_u32 s83, s55, 0
	s_add_i32 s77, s69, s60
	global_load_lds_dwordx4 v[216:217], off
	v_lshl_add_u64 v[218:219], s[82:83], 0, v[130:131]
	s_mov_b32 m0, s77
	v_lshl_add_u64 v[220:221], s[56:57], 0, v[128:129]
	global_load_lds_dwordx4 v[218:219], off
	v_lshl_add_u64 v[218:219], s[82:83], 0, v[128:129]
	s_add_i32 m0, s77, 0x2000
	s_nop 0
	global_load_lds_dwordx4 v[218:219], off
	v_lshl_add_u64 v[218:219], s[56:57], 0, v[130:131]
	s_mov_b32 m0, s49
	s_nop 0
	global_load_lds_dwordx4 v[218:219], off
	s_mov_b32 m0, s62
	s_nop 0
	global_load_lds_dwordx4 v[220:221], off
	s_waitcnt vmcnt(8)
	s_waitcnt lgkmcnt(0)
	s_barrier
	s_setprio 1
	v_mfma_f32_16x16x32_bf16 v[60:63], v[140:143], v[184:187], 0
	v_mfma_f32_16x16x32_bf16 v[60:63], v[150:153], v[188:191], v[60:63]
	v_mfma_f32_16x16x32_bf16 v[56:59], v[154:157], v[184:187], 0
	v_mfma_f32_16x16x32_bf16 v[56:59], v[158:161], v[188:191], v[56:59]
	v_mfma_f32_16x16x32_bf16 v[44:47], v[140:143], v[192:195], 0
	v_mfma_f32_16x16x32_bf16 v[44:47], v[150:153], v[196:199], v[44:47]
	v_mfma_f32_16x16x32_bf16 v[40:43], v[154:157], v[192:195], 0
	v_mfma_f32_16x16x32_bf16 v[40:43], v[158:161], v[196:199], v[40:43]
	v_mfma_f32_16x16x32_bf16 v[28:31], v[140:143], v[200:203], 0
	v_mfma_f32_16x16x32_bf16 v[28:31], v[150:153], v[204:207], v[28:31]
	v_mfma_f32_16x16x32_bf16 v[24:27], v[154:157], v[200:203], 0
	v_mfma_f32_16x16x32_bf16 v[24:27], v[158:161], v[204:207], v[24:27]
	v_mfma_f32_16x16x32_bf16 v[12:15], v[140:143], v[208:211], 0
	v_mfma_f32_16x16x32_bf16 v[12:15], v[150:153], v[212:215], v[12:15]
	v_mfma_f32_16x16x32_bf16 v[8:11], v[154:157], v[208:211], 0
	v_mfma_f32_16x16x32_bf16 v[8:11], v[158:161], v[212:215], v[8:11]
	v_mfma_f32_16x16x32_bf16 v[52:55], v[162:165], v[184:187], 0
	v_mfma_f32_16x16x32_bf16 v[52:55], v[166:169], v[188:191], v[52:55]
	v_mfma_f32_16x16x32_bf16 v[48:51], v[170:173], v[184:187], 0
	v_mfma_f32_16x16x32_bf16 v[48:51], v[174:177], v[188:191], v[48:51]
	v_mfma_f32_16x16x32_bf16 v[36:39], v[162:165], v[192:195], 0
	v_mfma_f32_16x16x32_bf16 v[36:39], v[166:169], v[196:199], v[36:39]
	v_mfma_f32_16x16x32_bf16 v[32:35], v[170:173], v[192:195], 0
	v_mfma_f32_16x16x32_bf16 v[32:35], v[174:177], v[196:199], v[32:35]
	v_mfma_f32_16x16x32_bf16 v[20:23], v[162:165], v[200:203], 0
	v_mfma_f32_16x16x32_bf16 v[20:23], v[166:169], v[204:207], v[20:23]
	v_mfma_f32_16x16x32_bf16 v[16:19], v[170:173], v[200:203], 0
	v_mfma_f32_16x16x32_bf16 v[16:19], v[174:177], v[204:207], v[16:19]
	v_mfma_f32_16x16x32_bf16 v[4:7], v[162:165], v[208:211], 0
	v_mfma_f32_16x16x32_bf16 v[4:7], v[166:169], v[212:215], v[4:7]
	v_mfma_f32_16x16x32_bf16 v[0:3], v[170:173], v[208:211], 0
	v_mfma_f32_16x16x32_bf16 v[0:3], v[174:177], v[212:215], v[0:3]
	s_setprio 0
	s_barrier
	s_branch .Lmid_gemm7
.LBB0_951:
	ds_read_b128 v[140:143], v147
	ds_read_b128 v[150:153], v147 offset:1024
	ds_read_b128 v[154:157], v147 offset:2048
	ds_read_b128 v[158:161], v147 offset:3072
	ds_read_b128 v[162:165], v148
	ds_read_b128 v[166:169], v148 offset:1024
	ds_read_b128 v[170:173], v148 offset:2048
	ds_read_b128 v[174:177], v148 offset:3072
	s_add_u32 s54, s52, 0xfffc0080
	s_addc_u32 s55, s53, -1
	s_cmp_eq_u32 s76, 12
	s_cselect_b32 s57, s37, s55
	s_cselect_b32 s56, s72, s54
	s_cselect_b32 s55, s19, s75
	s_cselect_b32 s54, s73, s74
	v_lshl_add_u64 v[178:179], s[52:53], 0, v[132:133]
	s_add_i32 m0, s49, 0xc000
	ds_read_b128 v[184:187], v149
	ds_read_b128 v[188:191], v149 offset:1024
	ds_read_b128 v[192:195], v149 offset:2048
	ds_read_b128 v[196:199], v149 offset:3072
	ds_read_b128 v[200:203], v149 offset:4096
	ds_read_b128 v[204:207], v149 offset:5120
	ds_read_b128 v[208:211], v149 offset:6144
	ds_read_b128 v[212:215], v149 offset:7168
	global_load_lds_dwordx4 v[178:179], off
	v_lshl_add_u64 v[178:179], s[52:53], 0, v[134:135]
	s_add_i32 m0, s49, 0xe000
	s_nop 0
	global_load_lds_dwordx4 v[178:179], off
	s_waitcnt vmcnt(8)
	s_waitcnt lgkmcnt(0)
	s_barrier
	s_setprio 1
	v_mfma_f32_16x16x32_bf16 v[124:127], v[140:143], v[184:187], v[124:127]
	v_mfma_f32_16x16x32_bf16 v[124:127], v[150:153], v[188:191], v[124:127]
	v_mfma_f32_16x16x32_bf16 v[120:123], v[154:157], v[184:187], v[120:123]
	v_mfma_f32_16x16x32_bf16 v[120:123], v[158:161], v[188:191], v[120:123]
	v_mfma_f32_16x16x32_bf16 v[108:111], v[140:143], v[192:195], v[108:111]
	v_mfma_f32_16x16x32_bf16 v[108:111], v[150:153], v[196:199], v[108:111]
	v_mfma_f32_16x16x32_bf16 v[104:107], v[154:157], v[192:195], v[104:107]
	v_mfma_f32_16x16x32_bf16 v[104:107], v[158:161], v[196:199], v[104:107]
	v_mfma_f32_16x16x32_bf16 v[92:95], v[140:143], v[200:203], v[92:95]
	v_mfma_f32_16x16x32_bf16 v[92:95], v[150:153], v[204:207], v[92:95]
	v_mfma_f32_16x16x32_bf16 v[88:91], v[154:157], v[200:203], v[88:91]
	v_mfma_f32_16x16x32_bf16 v[88:91], v[158:161], v[204:207], v[88:91]
	v_mfma_f32_16x16x32_bf16 v[76:79], v[140:143], v[208:211], v[76:79]
	v_mfma_f32_16x16x32_bf16 v[76:79], v[150:153], v[212:215], v[76:79]
	v_mfma_f32_16x16x32_bf16 v[72:75], v[154:157], v[208:211], v[72:75]
	v_mfma_f32_16x16x32_bf16 v[72:75], v[158:161], v[212:215], v[72:75]
	v_mfma_f32_16x16x32_bf16 v[116:119], v[162:165], v[184:187], v[116:119]
	v_mfma_f32_16x16x32_bf16 v[116:119], v[166:169], v[188:191], v[116:119]
	v_mfma_f32_16x16x32_bf16 v[112:115], v[170:173], v[184:187], v[112:115]
	v_mfma_f32_16x16x32_bf16 v[112:115], v[174:177], v[188:191], v[112:115]
	v_mfma_f32_16x16x32_bf16 v[100:103], v[162:165], v[192:195], v[100:103]
	v_mfma_f32_16x16x32_bf16 v[100:103], v[166:169], v[196:199], v[100:103]
	v_mfma_f32_16x16x32_bf16 v[96:99], v[170:173], v[192:195], v[96:99]
	v_mfma_f32_16x16x32_bf16 v[96:99], v[174:177], v[196:199], v[96:99]
	v_mfma_f32_16x16x32_bf16 v[84:87], v[162:165], v[200:203], v[84:87]
	v_mfma_f32_16x16x32_bf16 v[84:87], v[166:169], v[204:207], v[84:87]
	v_mfma_f32_16x16x32_bf16 v[80:83], v[170:173], v[200:203], v[80:83]
	v_mfma_f32_16x16x32_bf16 v[80:83], v[174:177], v[204:207], v[80:83]
	v_mfma_f32_16x16x32_bf16 v[68:71], v[162:165], v[208:211], v[68:71]
	v_mfma_f32_16x16x32_bf16 v[68:71], v[166:169], v[212:215], v[68:71]
	v_mfma_f32_16x16x32_bf16 v[64:67], v[170:173], v[208:211], v[64:67]
	v_mfma_f32_16x16x32_bf16 v[64:67], v[174:177], v[212:215], v[64:67]
	s_setprio 0
	s_barrier
	s_add_i32 s77, s68, s60
	v_lshl_add_u64 v[178:179], s[54:55], 0, v[130:131]
	s_mov_b32 m0, s77
	ds_read_b128 v[184:187], v149 offset:16384
	ds_read_b128 v[188:191], v149 offset:17408
	ds_read_b128 v[192:195], v149 offset:18432
	ds_read_b128 v[196:199], v149 offset:19456
	ds_read_b128 v[200:203], v149 offset:20480
	ds_read_b128 v[204:207], v149 offset:21504
	ds_read_b128 v[208:211], v149 offset:22528
	ds_read_b128 v[212:215], v149 offset:23552
	global_load_lds_dwordx4 v[178:179], off
	s_add_i32 m0, s77, 0x2000
	s_add_u32 s82, s54, 0x40000
	v_lshl_add_u64 v[216:217], s[54:55], 0, v[128:129]
	s_addc_u32 s83, s55, 0
	s_add_i32 s77, s69, s60
	global_load_lds_dwordx4 v[216:217], off
	v_lshl_add_u64 v[218:219], s[82:83], 0, v[130:131]
	s_mov_b32 m0, s77
	v_lshl_add_u64 v[220:221], s[56:57], 0, v[128:129]
	global_load_lds_dwordx4 v[218:219], off
	v_lshl_add_u64 v[218:219], s[82:83], 0, v[128:129]
	s_add_i32 m0, s77, 0x2000
	s_nop 0
	global_load_lds_dwordx4 v[218:219], off
	v_lshl_add_u64 v[218:219], s[56:57], 0, v[130:131]
	s_mov_b32 m0, s49
	s_nop 0
	global_load_lds_dwordx4 v[218:219], off
	s_mov_b32 m0, s62
	s_nop 0
	global_load_lds_dwordx4 v[220:221], off
	s_waitcnt vmcnt(8)
	s_waitcnt lgkmcnt(0)
	s_barrier
	s_setprio 1
	v_mfma_f32_16x16x32_bf16 v[60:63], v[140:143], v[184:187], v[60:63]
	v_mfma_f32_16x16x32_bf16 v[60:63], v[150:153], v[188:191], v[60:63]
	v_mfma_f32_16x16x32_bf16 v[56:59], v[154:157], v[184:187], v[56:59]
	v_mfma_f32_16x16x32_bf16 v[56:59], v[158:161], v[188:191], v[56:59]
	v_mfma_f32_16x16x32_bf16 v[44:47], v[140:143], v[192:195], v[44:47]
	v_mfma_f32_16x16x32_bf16 v[44:47], v[150:153], v[196:199], v[44:47]
	v_mfma_f32_16x16x32_bf16 v[40:43], v[154:157], v[192:195], v[40:43]
	v_mfma_f32_16x16x32_bf16 v[40:43], v[158:161], v[196:199], v[40:43]
	v_mfma_f32_16x16x32_bf16 v[28:31], v[140:143], v[200:203], v[28:31]
	v_mfma_f32_16x16x32_bf16 v[28:31], v[150:153], v[204:207], v[28:31]
	v_mfma_f32_16x16x32_bf16 v[24:27], v[154:157], v[200:203], v[24:27]
	v_mfma_f32_16x16x32_bf16 v[24:27], v[158:161], v[204:207], v[24:27]
	v_mfma_f32_16x16x32_bf16 v[12:15], v[140:143], v[208:211], v[12:15]
	v_mfma_f32_16x16x32_bf16 v[12:15], v[150:153], v[212:215], v[12:15]
	v_mfma_f32_16x16x32_bf16 v[8:11], v[154:157], v[208:211], v[8:11]
	v_mfma_f32_16x16x32_bf16 v[8:11], v[158:161], v[212:215], v[8:11]
	v_mfma_f32_16x16x32_bf16 v[52:55], v[162:165], v[184:187], v[52:55]
	v_mfma_f32_16x16x32_bf16 v[52:55], v[166:169], v[188:191], v[52:55]
	v_mfma_f32_16x16x32_bf16 v[48:51], v[170:173], v[184:187], v[48:51]
	v_mfma_f32_16x16x32_bf16 v[48:51], v[174:177], v[188:191], v[48:51]
	v_mfma_f32_16x16x32_bf16 v[36:39], v[162:165], v[192:195], v[36:39]
	v_mfma_f32_16x16x32_bf16 v[36:39], v[166:169], v[196:199], v[36:39]
	v_mfma_f32_16x16x32_bf16 v[32:35], v[170:173], v[192:195], v[32:35]
	v_mfma_f32_16x16x32_bf16 v[32:35], v[174:177], v[196:199], v[32:35]
	v_mfma_f32_16x16x32_bf16 v[20:23], v[162:165], v[200:203], v[20:23]
	v_mfma_f32_16x16x32_bf16 v[20:23], v[166:169], v[204:207], v[20:23]
	v_mfma_f32_16x16x32_bf16 v[16:19], v[170:173], v[200:203], v[16:19]
	v_mfma_f32_16x16x32_bf16 v[16:19], v[174:177], v[204:207], v[16:19]
	v_mfma_f32_16x16x32_bf16 v[4:7], v[162:165], v[208:211], v[4:7]
	v_mfma_f32_16x16x32_bf16 v[4:7], v[166:169], v[212:215], v[4:7]
	v_mfma_f32_16x16x32_bf16 v[0:3], v[170:173], v[208:211], v[0:3]
	v_mfma_f32_16x16x32_bf16 v[0:3], v[174:177], v[212:215], v[0:3]
	s_setprio 0
	s_barrier
.Lmid_gemm7:
	s_add_i32 s77, 0, 0x18000
	s_add_i32 s79, 0, 0x1c000
	v_add_u32_e32 v158, s77, v145
	v_add_u32_e32 v174, s79, v145
	ds_read_b128 v[140:143], v158
	ds_read_b128 v[150:153], v158 offset:1024
	ds_read_b128 v[154:157], v158 offset:2048
	ds_read_b128 v[158:161], v158 offset:3072
	ds_read_b128 v[162:165], v174
	ds_read_b128 v[166:169], v174 offset:1024
	ds_read_b128 v[170:173], v174 offset:2048
	ds_read_b128 v[174:177], v174 offset:3072
	s_add_u32 s56, s56, 0x40000
	s_addc_u32 s57, s57, 0
	s_mov_b32 m0, s63
	v_lshl_add_u64 v[222:223], s[56:57], 0, v[130:131]
	ds_read_b128 v[184:187], v149 offset:32768
	ds_read_b128 v[188:191], v149 offset:33792
	ds_read_b128 v[192:195], v149 offset:34816
	ds_read_b128 v[196:199], v149 offset:35840
	ds_read_b128 v[200:203], v149 offset:36864
	ds_read_b128 v[204:207], v149 offset:37888
	ds_read_b128 v[208:211], v149 offset:38912
	ds_read_b128 v[212:215], v149 offset:39936
	global_load_lds_dwordx4 v[222:223], off
	v_lshl_add_u64 v[222:223], s[56:57], 0, v[128:129]
	s_mov_b32 m0, s64
	s_nop 0
	global_load_lds_dwordx4 v[222:223], off
	s_waitcnt vmcnt(8)
	s_waitcnt lgkmcnt(0)
	s_barrier
	s_setprio 1
	v_mfma_f32_16x16x32_bf16 v[124:127], v[140:143], v[184:187], v[124:127]
	v_mfma_f32_16x16x32_bf16 v[124:127], v[150:153], v[188:191], v[124:127]
	v_mfma_f32_16x16x32_bf16 v[120:123], v[154:157], v[184:187], v[120:123]
	v_mfma_f32_16x16x32_bf16 v[120:123], v[158:161], v[188:191], v[120:123]
	v_mfma_f32_16x16x32_bf16 v[108:111], v[140:143], v[192:195], v[108:111]
	v_mfma_f32_16x16x32_bf16 v[108:111], v[150:153], v[196:199], v[108:111]
	v_mfma_f32_16x16x32_bf16 v[104:107], v[154:157], v[192:195], v[104:107]
	v_mfma_f32_16x16x32_bf16 v[104:107], v[158:161], v[196:199], v[104:107]
	v_mfma_f32_16x16x32_bf16 v[92:95], v[140:143], v[200:203], v[92:95]
	v_mfma_f32_16x16x32_bf16 v[92:95], v[150:153], v[204:207], v[92:95]
	v_mfma_f32_16x16x32_bf16 v[88:91], v[154:157], v[200:203], v[88:91]
	v_mfma_f32_16x16x32_bf16 v[88:91], v[158:161], v[204:207], v[88:91]
	v_mfma_f32_16x16x32_bf16 v[76:79], v[140:143], v[208:211], v[76:79]
	v_mfma_f32_16x16x32_bf16 v[76:79], v[150:153], v[212:215], v[76:79]
	v_mfma_f32_16x16x32_bf16 v[72:75], v[154:157], v[208:211], v[72:75]
	v_mfma_f32_16x16x32_bf16 v[72:75], v[158:161], v[212:215], v[72:75]
	v_mfma_f32_16x16x32_bf16 v[116:119], v[162:165], v[184:187], v[116:119]
	v_mfma_f32_16x16x32_bf16 v[116:119], v[166:169], v[188:191], v[116:119]
	v_mfma_f32_16x16x32_bf16 v[112:115], v[170:173], v[184:187], v[112:115]
	v_mfma_f32_16x16x32_bf16 v[112:115], v[174:177], v[188:191], v[112:115]
	v_mfma_f32_16x16x32_bf16 v[100:103], v[162:165], v[192:195], v[100:103]
	v_mfma_f32_16x16x32_bf16 v[100:103], v[166:169], v[196:199], v[100:103]
	v_mfma_f32_16x16x32_bf16 v[96:99], v[170:173], v[192:195], v[96:99]
	v_mfma_f32_16x16x32_bf16 v[96:99], v[174:177], v[196:199], v[96:99]
	v_mfma_f32_16x16x32_bf16 v[84:87], v[162:165], v[200:203], v[84:87]
	v_mfma_f32_16x16x32_bf16 v[84:87], v[166:169], v[204:207], v[84:87]
	v_mfma_f32_16x16x32_bf16 v[80:83], v[170:173], v[200:203], v[80:83]
	v_mfma_f32_16x16x32_bf16 v[80:83], v[174:177], v[204:207], v[80:83]
	v_mfma_f32_16x16x32_bf16 v[68:71], v[162:165], v[208:211], v[68:71]
	v_mfma_f32_16x16x32_bf16 v[68:71], v[166:169], v[212:215], v[68:71]
	v_mfma_f32_16x16x32_bf16 v[64:67], v[170:173], v[208:211], v[64:67]
	v_mfma_f32_16x16x32_bf16 v[64:67], v[174:177], v[212:215], v[64:67]
	s_setprio 0
	s_barrier
	s_add_i32 s56, s77, s60
	v_lshl_add_u64 v[178:179], v[178:179], 0, s[12:13]
	s_mov_b32 m0, s56
	ds_read_b128 v[184:187], v149 offset:49152
	ds_read_b128 v[188:191], v149 offset:50176
	ds_read_b128 v[192:195], v149 offset:51200
	ds_read_b128 v[196:199], v149 offset:52224
	ds_read_b128 v[200:203], v149 offset:53248
	ds_read_b128 v[204:207], v149 offset:54272
	ds_read_b128 v[208:211], v149 offset:55296
	ds_read_b128 v[212:215], v149 offset:56320
	global_load_lds_dwordx4 v[178:179], off
	s_add_i32 m0, s56, 0x2000
	s_add_u32 s54, s54, 0x40080
	v_lshl_add_u64 v[178:179], v[216:217], 0, s[12:13]
	s_addc_u32 s55, s55, 0
	s_add_i32 s56, s79, s60
	global_load_lds_dwordx4 v[178:179], off
	v_lshl_add_u64 v[178:179], s[54:55], 0, v[130:131]
	s_mov_b32 m0, s56
	s_nop 0
	global_load_lds_dwordx4 v[178:179], off
	v_lshl_add_u64 v[178:179], s[54:55], 0, v[128:129]
	s_add_i32 m0, s56, 0x2000
	s_nop 0
	global_load_lds_dwordx4 v[178:179], off
	v_lshl_add_u64 v[178:179], v[218:219], 0, s[12:13]
	s_mov_b32 m0, s66
	s_nop 0
	global_load_lds_dwordx4 v[178:179], off
	v_lshl_add_u64 v[178:179], v[220:221], 0, s[12:13]
	s_mov_b32 m0, s67
	s_nop 0
	global_load_lds_dwordx4 v[178:179], off
	s_waitcnt vmcnt(8)
	s_waitcnt lgkmcnt(0)
	s_barrier
	s_setprio 1
	v_mfma_f32_16x16x32_bf16 v[60:63], v[140:143], v[184:187], v[60:63]
	v_mfma_f32_16x16x32_bf16 v[60:63], v[150:153], v[188:191], v[60:63]
	v_mfma_f32_16x16x32_bf16 v[56:59], v[154:157], v[184:187], v[56:59]
	v_mfma_f32_16x16x32_bf16 v[56:59], v[158:161], v[188:191], v[56:59]
	v_mfma_f32_16x16x32_bf16 v[44:47], v[140:143], v[192:195], v[44:47]
	v_mfma_f32_16x16x32_bf16 v[44:47], v[150:153], v[196:199], v[44:47]
	v_mfma_f32_16x16x32_bf16 v[40:43], v[154:157], v[192:195], v[40:43]
	v_mfma_f32_16x16x32_bf16 v[40:43], v[158:161], v[196:199], v[40:43]
	v_mfma_f32_16x16x32_bf16 v[28:31], v[140:143], v[200:203], v[28:31]
	v_mfma_f32_16x16x32_bf16 v[28:31], v[150:153], v[204:207], v[28:31]
	v_mfma_f32_16x16x32_bf16 v[24:27], v[154:157], v[200:203], v[24:27]
	v_mfma_f32_16x16x32_bf16 v[24:27], v[158:161], v[204:207], v[24:27]
	v_mfma_f32_16x16x32_bf16 v[12:15], v[140:143], v[208:211], v[12:15]
	v_mfma_f32_16x16x32_bf16 v[12:15], v[150:153], v[212:215], v[12:15]
	v_mfma_f32_16x16x32_bf16 v[8:11], v[154:157], v[208:211], v[8:11]
	v_mfma_f32_16x16x32_bf16 v[8:11], v[158:161], v[212:215], v[8:11]
	v_mfma_f32_16x16x32_bf16 v[52:55], v[162:165], v[184:187], v[52:55]
	v_mfma_f32_16x16x32_bf16 v[52:55], v[166:169], v[188:191], v[52:55]
	v_mfma_f32_16x16x32_bf16 v[48:51], v[170:173], v[184:187], v[48:51]
	v_mfma_f32_16x16x32_bf16 v[48:51], v[174:177], v[188:191], v[48:51]
	v_mfma_f32_16x16x32_bf16 v[36:39], v[162:165], v[192:195], v[36:39]
	v_mfma_f32_16x16x32_bf16 v[36:39], v[166:169], v[196:199], v[36:39]
	v_mfma_f32_16x16x32_bf16 v[32:35], v[170:173], v[192:195], v[32:35]
	v_mfma_f32_16x16x32_bf16 v[32:35], v[174:177], v[196:199], v[32:35]
	v_mfma_f32_16x16x32_bf16 v[20:23], v[162:165], v[200:203], v[20:23]
	v_mfma_f32_16x16x32_bf16 v[20:23], v[166:169], v[204:207], v[20:23]
	v_mfma_f32_16x16x32_bf16 v[16:19], v[170:173], v[200:203], v[16:19]
	v_mfma_f32_16x16x32_bf16 v[16:19], v[174:177], v[204:207], v[16:19]
	v_mfma_f32_16x16x32_bf16 v[4:7], v[162:165], v[208:211], v[4:7]
	v_mfma_f32_16x16x32_bf16 v[4:7], v[166:169], v[212:215], v[4:7]
	v_mfma_f32_16x16x32_bf16 v[0:3], v[170:173], v[208:211], v[0:3]
	v_mfma_f32_16x16x32_bf16 v[0:3], v[174:177], v[212:215], v[0:3]
	s_setprio 0
	s_barrier
	s_add_i32 s76, s76, 2
	s_add_u32 s52, s52, 0x100
	s_addc_u32 s53, s53, 0
	s_add_u32 s74, s74, 0x100
	s_addc_u32 s75, s75, 0
	s_cmp_gt_u32 s76, 13
	s_cbranch_scc0 .LBB0_951
	s_and_b64 vcc, exec, s[16:17]
	s_cbranch_vccz .LBB0_954
	s_barrier

.LBB0_1030:
	s_add_u32 s86, s56, 0x100
	s_addc_u32 s87, s57, 0
	s_mov_b32 s88, -2
	ds_read_b128 v[152:155], v149
	ds_read_b128 v[156:159], v149 offset:1024
	ds_read_b128 v[160:163], v149 offset:2048
	ds_read_b128 v[164:167], v149 offset:3072
	ds_read_b128 v[168:171], v150
	ds_read_b128 v[172:175], v150 offset:1024
	ds_read_b128 v[176:179], v150 offset:2048
	ds_read_b128 v[184:187], v150 offset:3072
	s_add_u32 s56, s54, 0x100
	s_addc_u32 s57, s55, 0
	s_cmp_eq_u32 s88, 40
	s_cselect_b32 s61, s13, s57
	s_cselect_b32 s60, s12, s56
	s_cselect_b32 s59, s53, s87
	s_cselect_b32 s58, s52, s86
	v_lshl_add_u64 v[144:145], s[54:55], 0, v[136:137]
	s_add_i32 m0, s65, 0xc000
	ds_read_b128 v[188:191], v151
	ds_read_b128 v[192:195], v151 offset:1024
	ds_read_b128 v[196:199], v151 offset:2048
	ds_read_b128 v[200:203], v151 offset:3072
	ds_read_b128 v[204:207], v151 offset:4096
	ds_read_b128 v[208:211], v151 offset:5120
	ds_read_b128 v[212:215], v151 offset:6144
	ds_read_b128 v[216:219], v151 offset:7168
	global_load_lds_dwordx4 v[144:145], off
	v_lshl_add_u64 v[144:145], s[54:55], 0, v[138:139]
	s_add_i32 m0, s65, 0xe000
	s_nop 0
	global_load_lds_dwordx4 v[144:145], off
	s_waitcnt vmcnt(8)
	s_waitcnt lgkmcnt(0)
	s_barrier
	s_setprio 1
	v_mfma_f32_16x16x32_bf16 v[124:127], v[152:155], v[188:191], 0
	v_mfma_f32_16x16x32_bf16 v[124:127], v[156:159], v[192:195], v[124:127]
	v_mfma_f32_16x16x32_bf16 v[120:123], v[160:163], v[188:191], 0
	v_mfma_f32_16x16x32_bf16 v[120:123], v[164:167], v[192:195], v[120:123]
	v_mfma_f32_16x16x32_bf16 v[116:119], v[152:155], v[196:199], 0
	v_mfma_f32_16x16x32_bf16 v[116:119], v[156:159], v[200:203], v[116:119]
	v_mfma_f32_16x16x32_bf16 v[108:111], v[160:163], v[196:199], 0
	v_mfma_f32_16x16x32_bf16 v[108:111], v[164:167], v[200:203], v[108:111]
	v_mfma_f32_16x16x32_bf16 v[100:103], v[152:155], v[204:207], 0
	v_mfma_f32_16x16x32_bf16 v[100:103], v[156:159], v[208:211], v[100:103]
	v_mfma_f32_16x16x32_bf16 v[92:95], v[160:163], v[204:207], 0
	v_mfma_f32_16x16x32_bf16 v[92:95], v[164:167], v[208:211], v[92:95]
	v_mfma_f32_16x16x32_bf16 v[84:87], v[152:155], v[212:215], 0
	v_mfma_f32_16x16x32_bf16 v[84:87], v[156:159], v[216:219], v[84:87]
	v_mfma_f32_16x16x32_bf16 v[76:79], v[160:163], v[212:215], 0
	v_mfma_f32_16x16x32_bf16 v[76:79], v[164:167], v[216:219], v[76:79]
	v_mfma_f32_16x16x32_bf16 v[112:115], v[168:171], v[188:191], 0
	v_mfma_f32_16x16x32_bf16 v[112:115], v[172:175], v[192:195], v[112:115]
	v_mfma_f32_16x16x32_bf16 v[104:107], v[176:179], v[188:191], 0
	v_mfma_f32_16x16x32_bf16 v[104:107], v[184:187], v[192:195], v[104:107]
	v_mfma_f32_16x16x32_bf16 v[96:99], v[168:171], v[196:199], 0
	v_mfma_f32_16x16x32_bf16 v[96:99], v[172:175], v[200:203], v[96:99]
	v_mfma_f32_16x16x32_bf16 v[88:91], v[176:179], v[196:199], 0
	v_mfma_f32_16x16x32_bf16 v[88:91], v[184:187], v[200:203], v[88:91]
	v_mfma_f32_16x16x32_bf16 v[80:83], v[168:171], v[204:207], 0
	v_mfma_f32_16x16x32_bf16 v[80:83], v[172:175], v[208:211], v[80:83]
	v_mfma_f32_16x16x32_bf16 v[72:75], v[176:179], v[204:207], 0
	v_mfma_f32_16x16x32_bf16 v[72:75], v[184:187], v[208:211], v[72:75]
	v_mfma_f32_16x16x32_bf16 v[68:71], v[168:171], v[212:215], 0
	v_mfma_f32_16x16x32_bf16 v[68:71], v[172:175], v[216:219], v[68:71]
	v_mfma_f32_16x16x32_bf16 v[64:67], v[176:179], v[212:215], 0
	v_mfma_f32_16x16x32_bf16 v[64:67], v[184:187], v[216:219], v[64:67]
	s_setprio 0
	s_barrier
	s_add_i32 s54, s72, s64
	v_lshl_add_u64 v[144:145], s[58:59], 0, v[130:131]
	s_mov_b32 m0, s54
	ds_read_b128 v[188:191], v151 offset:16384
	ds_read_b128 v[192:195], v151 offset:17408
	ds_read_b128 v[196:199], v151 offset:18432
	ds_read_b128 v[200:203], v151 offset:19456
	ds_read_b128 v[204:207], v151 offset:20480
	ds_read_b128 v[208:211], v151 offset:21504
	ds_read_b128 v[212:215], v151 offset:22528
	ds_read_b128 v[216:219], v151 offset:23552
	global_load_lds_dwordx4 v[144:145], off
	s_add_i32 m0, s54, 0x2000
	s_add_u32 s54, s58, 0xb0000
	v_lshl_add_u64 v[220:221], s[58:59], 0, v[134:135]
	s_addc_u32 s55, s59, 0
	s_add_i32 s79, s73, s64
	global_load_lds_dwordx4 v[220:221], off
	v_lshl_add_u64 v[222:223], s[54:55], 0, v[130:131]
	s_mov_b32 m0, s79
	v_lshl_add_u64 v[224:225], s[60:61], 0, v[132:133]
	global_load_lds_dwordx4 v[222:223], off
	v_lshl_add_u64 v[222:223], s[54:55], 0, v[134:135]
	s_add_i32 m0, s79, 0x2000
	s_nop 0
	global_load_lds_dwordx4 v[222:223], off
	v_lshl_add_u64 v[222:223], s[60:61], 0, v[128:129]
	s_mov_b32 m0, s65
	s_nop 0
	global_load_lds_dwordx4 v[222:223], off
	s_mov_b32 m0, s66
	s_nop 0
	global_load_lds_dwordx4 v[224:225], off
	s_waitcnt vmcnt(8)
	s_waitcnt lgkmcnt(0)
	s_barrier
	s_setprio 1
	v_mfma_f32_16x16x32_bf16 v[60:63], v[152:155], v[188:191], 0
	v_mfma_f32_16x16x32_bf16 v[60:63], v[156:159], v[192:195], v[60:63]
	v_mfma_f32_16x16x32_bf16 v[56:59], v[160:163], v[188:191], 0
	v_mfma_f32_16x16x32_bf16 v[56:59], v[164:167], v[192:195], v[56:59]
	v_mfma_f32_16x16x32_bf16 v[52:55], v[152:155], v[196:199], 0
	v_mfma_f32_16x16x32_bf16 v[52:55], v[156:159], v[200:203], v[52:55]
	v_mfma_f32_16x16x32_bf16 v[44:47], v[160:163], v[196:199], 0
	v_mfma_f32_16x16x32_bf16 v[44:47], v[164:167], v[200:203], v[44:47]
	v_mfma_f32_16x16x32_bf16 v[36:39], v[152:155], v[204:207], 0
	v_mfma_f32_16x16x32_bf16 v[36:39], v[156:159], v[208:211], v[36:39]
	v_mfma_f32_16x16x32_bf16 v[28:31], v[160:163], v[204:207], 0
	v_mfma_f32_16x16x32_bf16 v[28:31], v[164:167], v[208:211], v[28:31]
	v_mfma_f32_16x16x32_bf16 v[20:23], v[152:155], v[212:215], 0
	v_mfma_f32_16x16x32_bf16 v[20:23], v[156:159], v[216:219], v[20:23]
	v_mfma_f32_16x16x32_bf16 v[12:15], v[160:163], v[212:215], 0
	v_mfma_f32_16x16x32_bf16 v[12:15], v[164:167], v[216:219], v[12:15]
	v_mfma_f32_16x16x32_bf16 v[48:51], v[168:171], v[188:191], 0
	v_mfma_f32_16x16x32_bf16 v[48:51], v[172:175], v[192:195], v[48:51]
	v_mfma_f32_16x16x32_bf16 v[40:43], v[176:179], v[188:191], 0
	v_mfma_f32_16x16x32_bf16 v[40:43], v[184:187], v[192:195], v[40:43]
	v_mfma_f32_16x16x32_bf16 v[32:35], v[168:171], v[196:199], 0
	v_mfma_f32_16x16x32_bf16 v[32:35], v[172:175], v[200:203], v[32:35]
	v_mfma_f32_16x16x32_bf16 v[24:27], v[176:179], v[196:199], 0
	v_mfma_f32_16x16x32_bf16 v[24:27], v[184:187], v[200:203], v[24:27]
	v_mfma_f32_16x16x32_bf16 v[16:19], v[168:171], v[204:207], 0
	v_mfma_f32_16x16x32_bf16 v[16:19], v[172:175], v[208:211], v[16:19]
	v_mfma_f32_16x16x32_bf16 v[8:11], v[176:179], v[204:207], 0
	v_mfma_f32_16x16x32_bf16 v[8:11], v[184:187], v[208:211], v[8:11]
	v_mfma_f32_16x16x32_bf16 v[4:7], v[168:171], v[212:215], 0
	v_mfma_f32_16x16x32_bf16 v[4:7], v[172:175], v[216:219], v[4:7]
	v_mfma_f32_16x16x32_bf16 v[0:3], v[176:179], v[212:215], 0
	v_mfma_f32_16x16x32_bf16 v[0:3], v[184:187], v[216:219], v[0:3]
	s_setprio 0
	s_barrier
	s_branch .Lmid_gemm8
.LBB0_1031:
	ds_read_b128 v[152:155], v149
	ds_read_b128 v[156:159], v149 offset:1024
	ds_read_b128 v[160:163], v149 offset:2048
	ds_read_b128 v[164:167], v149 offset:3072
	ds_read_b128 v[168:171], v150
	ds_read_b128 v[172:175], v150 offset:1024
	ds_read_b128 v[176:179], v150 offset:2048
	ds_read_b128 v[184:187], v150 offset:3072
	s_add_u32 s56, s54, 0x100
	s_addc_u32 s57, s55, 0
	s_cmp_eq_u32 s88, 40
	s_cselect_b32 s61, s13, s57
	s_cselect_b32 s60, s12, s56
	s_cselect_b32 s59, s53, s87
	s_cselect_b32 s58, s52, s86
	v_lshl_add_u64 v[144:145], s[54:55], 0, v[136:137]
	s_add_i32 m0, s65, 0xc000
	ds_read_b128 v[188:191], v151
	ds_read_b128 v[192:195], v151 offset:1024
	ds_read_b128 v[196:199], v151 offset:2048
	ds_read_b128 v[200:203], v151 offset:3072
	ds_read_b128 v[204:207], v151 offset:4096
	ds_read_b128 v[208:211], v151 offset:5120
	ds_read_b128 v[212:215], v151 offset:6144
	ds_read_b128 v[216:219], v151 offset:7168
	global_load_lds_dwordx4 v[144:145], off
	v_lshl_add_u64 v[144:145], s[54:55], 0, v[138:139]
	s_add_i32 m0, s65, 0xe000
	s_nop 0
	global_load_lds_dwordx4 v[144:145], off
	s_waitcnt vmcnt(8)
	s_waitcnt lgkmcnt(0)
	s_barrier
	s_setprio 1
	v_mfma_f32_16x16x32_bf16 v[124:127], v[152:155], v[188:191], v[124:127]
	v_mfma_f32_16x16x32_bf16 v[124:127], v[156:159], v[192:195], v[124:127]
	v_mfma_f32_16x16x32_bf16 v[120:123], v[160:163], v[188:191], v[120:123]
	v_mfma_f32_16x16x32_bf16 v[120:123], v[164:167], v[192:195], v[120:123]
	v_mfma_f32_16x16x32_bf16 v[116:119], v[152:155], v[196:199], v[116:119]
	v_mfma_f32_16x16x32_bf16 v[116:119], v[156:159], v[200:203], v[116:119]
	v_mfma_f32_16x16x32_bf16 v[108:111], v[160:163], v[196:199], v[108:111]
	v_mfma_f32_16x16x32_bf16 v[108:111], v[164:167], v[200:203], v[108:111]
	v_mfma_f32_16x16x32_bf16 v[100:103], v[152:155], v[204:207], v[100:103]
	v_mfma_f32_16x16x32_bf16 v[100:103], v[156:159], v[208:211], v[100:103]
	v_mfma_f32_16x16x32_bf16 v[92:95], v[160:163], v[204:207], v[92:95]
	v_mfma_f32_16x16x32_bf16 v[92:95], v[164:167], v[208:211], v[92:95]
	v_mfma_f32_16x16x32_bf16 v[84:87], v[152:155], v[212:215], v[84:87]
	v_mfma_f32_16x16x32_bf16 v[84:87], v[156:159], v[216:219], v[84:87]
	v_mfma_f32_16x16x32_bf16 v[76:79], v[160:163], v[212:215], v[76:79]
	v_mfma_f32_16x16x32_bf16 v[76:79], v[164:167], v[216:219], v[76:79]
	v_mfma_f32_16x16x32_bf16 v[112:115], v[168:171], v[188:191], v[112:115]
	v_mfma_f32_16x16x32_bf16 v[112:115], v[172:175], v[192:195], v[112:115]
	v_mfma_f32_16x16x32_bf16 v[104:107], v[176:179], v[188:191], v[104:107]
	v_mfma_f32_16x16x32_bf16 v[104:107], v[184:187], v[192:195], v[104:107]
	v_mfma_f32_16x16x32_bf16 v[96:99], v[168:171], v[196:199], v[96:99]
	v_mfma_f32_16x16x32_bf16 v[96:99], v[172:175], v[200:203], v[96:99]
	v_mfma_f32_16x16x32_bf16 v[88:91], v[176:179], v[196:199], v[88:91]
	v_mfma_f32_16x16x32_bf16 v[88:91], v[184:187], v[200:203], v[88:91]
	v_mfma_f32_16x16x32_bf16 v[80:83], v[168:171], v[204:207], v[80:83]
	v_mfma_f32_16x16x32_bf16 v[80:83], v[172:175], v[208:211], v[80:83]
	v_mfma_f32_16x16x32_bf16 v[72:75], v[176:179], v[204:207], v[72:75]
	v_mfma_f32_16x16x32_bf16 v[72:75], v[184:187], v[208:211], v[72:75]
	v_mfma_f32_16x16x32_bf16 v[68:71], v[168:171], v[212:215], v[68:71]
	v_mfma_f32_16x16x32_bf16 v[68:71], v[172:175], v[216:219], v[68:71]
	v_mfma_f32_16x16x32_bf16 v[64:67], v[176:179], v[212:215], v[64:67]
	v_mfma_f32_16x16x32_bf16 v[64:67], v[184:187], v[216:219], v[64:67]
	s_setprio 0
	s_barrier
	s_add_i32 s54, s72, s64
	v_lshl_add_u64 v[144:145], s[58:59], 0, v[130:131]
	s_mov_b32 m0, s54
	ds_read_b128 v[188:191], v151 offset:16384
	ds_read_b128 v[192:195], v151 offset:17408
	ds_read_b128 v[196:199], v151 offset:18432
	ds_read_b128 v[200:203], v151 offset:19456
	ds_read_b128 v[204:207], v151 offset:20480
	ds_read_b128 v[208:211], v151 offset:21504
	ds_read_b128 v[212:215], v151 offset:22528
	ds_read_b128 v[216:219], v151 offset:23552
	global_load_lds_dwordx4 v[144:145], off
	s_add_i32 m0, s54, 0x2000
	s_add_u32 s54, s58, 0xb0000
	v_lshl_add_u64 v[220:221], s[58:59], 0, v[134:135]
	s_addc_u32 s55, s59, 0
	s_add_i32 s79, s73, s64
	global_load_lds_dwordx4 v[220:221], off
	v_lshl_add_u64 v[222:223], s[54:55], 0, v[130:131]
	s_mov_b32 m0, s79
	v_lshl_add_u64 v[224:225], s[60:61], 0, v[132:133]
	global_load_lds_dwordx4 v[222:223], off
	v_lshl_add_u64 v[222:223], s[54:55], 0, v[134:135]
	s_add_i32 m0, s79, 0x2000
	s_nop 0
	global_load_lds_dwordx4 v[222:223], off
	v_lshl_add_u64 v[222:223], s[60:61], 0, v[128:129]
	s_mov_b32 m0, s65
	s_nop 0
	global_load_lds_dwordx4 v[222:223], off
	s_mov_b32 m0, s66
	s_nop 0
	global_load_lds_dwordx4 v[224:225], off
	s_waitcnt vmcnt(8)
	s_waitcnt lgkmcnt(0)
	s_barrier
	s_setprio 1
	v_mfma_f32_16x16x32_bf16 v[60:63], v[152:155], v[188:191], v[60:63]
	v_mfma_f32_16x16x32_bf16 v[60:63], v[156:159], v[192:195], v[60:63]
	v_mfma_f32_16x16x32_bf16 v[56:59], v[160:163], v[188:191], v[56:59]
	v_mfma_f32_16x16x32_bf16 v[56:59], v[164:167], v[192:195], v[56:59]
	v_mfma_f32_16x16x32_bf16 v[52:55], v[152:155], v[196:199], v[52:55]
	v_mfma_f32_16x16x32_bf16 v[52:55], v[156:159], v[200:203], v[52:55]
	v_mfma_f32_16x16x32_bf16 v[44:47], v[160:163], v[196:199], v[44:47]
	v_mfma_f32_16x16x32_bf16 v[44:47], v[164:167], v[200:203], v[44:47]
	v_mfma_f32_16x16x32_bf16 v[36:39], v[152:155], v[204:207], v[36:39]
	v_mfma_f32_16x16x32_bf16 v[36:39], v[156:159], v[208:211], v[36:39]
	v_mfma_f32_16x16x32_bf16 v[28:31], v[160:163], v[204:207], v[28:31]
	v_mfma_f32_16x16x32_bf16 v[28:31], v[164:167], v[208:211], v[28:31]
	v_mfma_f32_16x16x32_bf16 v[20:23], v[152:155], v[212:215], v[20:23]
	v_mfma_f32_16x16x32_bf16 v[20:23], v[156:159], v[216:219], v[20:23]
	v_mfma_f32_16x16x32_bf16 v[12:15], v[160:163], v[212:215], v[12:15]
	v_mfma_f32_16x16x32_bf16 v[12:15], v[164:167], v[216:219], v[12:15]
	v_mfma_f32_16x16x32_bf16 v[48:51], v[168:171], v[188:191], v[48:51]
	v_mfma_f32_16x16x32_bf16 v[48:51], v[172:175], v[192:195], v[48:51]
	v_mfma_f32_16x16x32_bf16 v[40:43], v[176:179], v[188:191], v[40:43]
	v_mfma_f32_16x16x32_bf16 v[40:43], v[184:187], v[192:195], v[40:43]
	v_mfma_f32_16x16x32_bf16 v[32:35], v[168:171], v[196:199], v[32:35]
	v_mfma_f32_16x16x32_bf16 v[32:35], v[172:175], v[200:203], v[32:35]
	v_mfma_f32_16x16x32_bf16 v[24:27], v[176:179], v[196:199], v[24:27]
	v_mfma_f32_16x16x32_bf16 v[24:27], v[184:187], v[200:203], v[24:27]
	v_mfma_f32_16x16x32_bf16 v[16:19], v[168:171], v[204:207], v[16:19]
	v_mfma_f32_16x16x32_bf16 v[16:19], v[172:175], v[208:211], v[16:19]
	v_mfma_f32_16x16x32_bf16 v[8:11], v[176:179], v[204:207], v[8:11]
	v_mfma_f32_16x16x32_bf16 v[8:11], v[184:187], v[208:211], v[8:11]
	v_mfma_f32_16x16x32_bf16 v[4:7], v[168:171], v[212:215], v[4:7]
	v_mfma_f32_16x16x32_bf16 v[4:7], v[172:175], v[216:219], v[4:7]
	v_mfma_f32_16x16x32_bf16 v[0:3], v[176:179], v[212:215], v[0:3]
	v_mfma_f32_16x16x32_bf16 v[0:3], v[184:187], v[216:219], v[0:3]
	s_setprio 0
	s_barrier
.Lmid_gemm8:
	s_add_i32 s79, 0, 0x18000
	s_add_i32 s89, 0, 0x1c000
	v_add_u32_e32 v164, s79, v147
	v_add_u32_e32 v181, s89, v147
	ds_read_b128 v[152:155], v164
	ds_read_b128 v[156:159], v164 offset:1024
	ds_read_b128 v[160:163], v164 offset:2048
	ds_read_b128 v[164:167], v164 offset:3072
	ds_read_b128 v[168:171], v181
	ds_read_b128 v[172:175], v181 offset:1024
	ds_read_b128 v[176:179], v181 offset:2048
	ds_read_b128 v[184:187], v181 offset:3072
	s_add_u32 s54, s60, 0xb0000
	s_addc_u32 s55, s61, 0
	s_mov_b32 m0, s67
	v_lshl_add_u64 v[226:227], s[54:55], 0, v[128:129]
	ds_read_b128 v[188:191], v151 offset:32768
	ds_read_b128 v[192:195], v151 offset:33792
	ds_read_b128 v[196:199], v151 offset:34816
	ds_read_b128 v[200:203], v151 offset:35840
	ds_read_b128 v[204:207], v151 offset:36864
	ds_read_b128 v[208:211], v151 offset:37888
	ds_read_b128 v[212:215], v151 offset:38912
	ds_read_b128 v[216:219], v151 offset:39936
	global_load_lds_dwordx4 v[226:227], off
	v_lshl_add_u64 v[226:227], s[54:55], 0, v[132:133]
	s_mov_b32 m0, s68
	s_nop 0
	global_load_lds_dwordx4 v[226:227], off
	s_waitcnt vmcnt(8)
	s_waitcnt lgkmcnt(0)
	s_barrier
	s_setprio 1
	v_mfma_f32_16x16x32_bf16 v[124:127], v[152:155], v[188:191], v[124:127]
	v_mfma_f32_16x16x32_bf16 v[124:127], v[156:159], v[192:195], v[124:127]
	v_mfma_f32_16x16x32_bf16 v[120:123], v[160:163], v[188:191], v[120:123]
	v_mfma_f32_16x16x32_bf16 v[120:123], v[164:167], v[192:195], v[120:123]
	v_mfma_f32_16x16x32_bf16 v[116:119], v[152:155], v[196:199], v[116:119]
	v_mfma_f32_16x16x32_bf16 v[116:119], v[156:159], v[200:203], v[116:119]
	v_mfma_f32_16x16x32_bf16 v[108:111], v[160:163], v[196:199], v[108:111]
	v_mfma_f32_16x16x32_bf16 v[108:111], v[164:167], v[200:203], v[108:111]
	v_mfma_f32_16x16x32_bf16 v[100:103], v[152:155], v[204:207], v[100:103]
	v_mfma_f32_16x16x32_bf16 v[100:103], v[156:159], v[208:211], v[100:103]
	v_mfma_f32_16x16x32_bf16 v[92:95], v[160:163], v[204:207], v[92:95]
	v_mfma_f32_16x16x32_bf16 v[92:95], v[164:167], v[208:211], v[92:95]
	v_mfma_f32_16x16x32_bf16 v[84:87], v[152:155], v[212:215], v[84:87]
	v_mfma_f32_16x16x32_bf16 v[84:87], v[156:159], v[216:219], v[84:87]
	v_mfma_f32_16x16x32_bf16 v[76:79], v[160:163], v[212:215], v[76:79]
	v_mfma_f32_16x16x32_bf16 v[76:79], v[164:167], v[216:219], v[76:79]
	v_mfma_f32_16x16x32_bf16 v[112:115], v[168:171], v[188:191], v[112:115]
	v_mfma_f32_16x16x32_bf16 v[112:115], v[172:175], v[192:195], v[112:115]
	v_mfma_f32_16x16x32_bf16 v[104:107], v[176:179], v[188:191], v[104:107]
	v_mfma_f32_16x16x32_bf16 v[104:107], v[184:187], v[192:195], v[104:107]
	v_mfma_f32_16x16x32_bf16 v[96:99], v[168:171], v[196:199], v[96:99]
	v_mfma_f32_16x16x32_bf16 v[96:99], v[172:175], v[200:203], v[96:99]
	v_mfma_f32_16x16x32_bf16 v[88:91], v[176:179], v[196:199], v[88:91]
	v_mfma_f32_16x16x32_bf16 v[88:91], v[184:187], v[200:203], v[88:91]
	v_mfma_f32_16x16x32_bf16 v[80:83], v[168:171], v[204:207], v[80:83]
	v_mfma_f32_16x16x32_bf16 v[80:83], v[172:175], v[208:211], v[80:83]
	v_mfma_f32_16x16x32_bf16 v[72:75], v[176:179], v[204:207], v[72:75]
	v_mfma_f32_16x16x32_bf16 v[72:75], v[184:187], v[208:211], v[72:75]
	v_mfma_f32_16x16x32_bf16 v[68:71], v[168:171], v[212:215], v[68:71]
	v_mfma_f32_16x16x32_bf16 v[68:71], v[172:175], v[216:219], v[68:71]
	v_mfma_f32_16x16x32_bf16 v[64:67], v[176:179], v[212:215], v[64:67]
	v_mfma_f32_16x16x32_bf16 v[64:67], v[184:187], v[216:219], v[64:67]
	s_setprio 0
	s_barrier
	s_add_i32 s54, s79, s64
	v_lshl_add_u64 v[144:145], v[144:145], 0, s[16:17]
	s_mov_b32 m0, s54
	ds_read_b128 v[188:191], v151 offset:49152
	ds_read_b128 v[192:195], v151 offset:50176
	ds_read_b128 v[196:199], v151 offset:51200
	ds_read_b128 v[200:203], v151 offset:52224
	ds_read_b128 v[204:207], v151 offset:53248
	ds_read_b128 v[208:211], v151 offset:54272
	ds_read_b128 v[212:215], v151 offset:55296
	ds_read_b128 v[216:219], v151 offset:56320
	global_load_lds_dwordx4 v[144:145], off
	s_add_i32 m0, s54, 0x2000
	s_add_u32 s54, s58, 0xb0080
	v_lshl_add_u64 v[144:145], v[220:221], 0, s[16:17]
	s_addc_u32 s55, s59, 0
	s_add_i32 s58, s89, s64
	global_load_lds_dwordx4 v[144:145], off
	v_lshl_add_u64 v[144:145], s[54:55], 0, v[130:131]
	s_mov_b32 m0, s58
	s_nop 0
	global_load_lds_dwordx4 v[144:145], off
	v_lshl_add_u64 v[144:145], s[54:55], 0, v[134:135]
	s_add_i32 m0, s58, 0x2000
	s_nop 0
	global_load_lds_dwordx4 v[144:145], off
	v_lshl_add_u64 v[144:145], v[222:223], 0, s[16:17]
	s_mov_b32 m0, s70
	s_nop 0
	global_load_lds_dwordx4 v[144:145], off
	v_lshl_add_u64 v[144:145], v[224:225], 0, s[16:17]
	s_mov_b32 m0, s71
	s_nop 0
	global_load_lds_dwordx4 v[144:145], off
	s_waitcnt vmcnt(8)
	s_waitcnt lgkmcnt(0)
	s_barrier
	s_setprio 1
	v_mfma_f32_16x16x32_bf16 v[60:63], v[152:155], v[188:191], v[60:63]
	v_mfma_f32_16x16x32_bf16 v[60:63], v[156:159], v[192:195], v[60:63]
	v_mfma_f32_16x16x32_bf16 v[56:59], v[160:163], v[188:191], v[56:59]
	v_mfma_f32_16x16x32_bf16 v[56:59], v[164:167], v[192:195], v[56:59]
	v_mfma_f32_16x16x32_bf16 v[52:55], v[152:155], v[196:199], v[52:55]
	v_mfma_f32_16x16x32_bf16 v[52:55], v[156:159], v[200:203], v[52:55]
	v_mfma_f32_16x16x32_bf16 v[44:47], v[160:163], v[196:199], v[44:47]
	v_mfma_f32_16x16x32_bf16 v[44:47], v[164:167], v[200:203], v[44:47]
	v_mfma_f32_16x16x32_bf16 v[36:39], v[152:155], v[204:207], v[36:39]
	v_mfma_f32_16x16x32_bf16 v[36:39], v[156:159], v[208:211], v[36:39]
	v_mfma_f32_16x16x32_bf16 v[28:31], v[160:163], v[204:207], v[28:31]
	v_mfma_f32_16x16x32_bf16 v[28:31], v[164:167], v[208:211], v[28:31]
	v_mfma_f32_16x16x32_bf16 v[20:23], v[152:155], v[212:215], v[20:23]
	v_mfma_f32_16x16x32_bf16 v[20:23], v[156:159], v[216:219], v[20:23]
	v_mfma_f32_16x16x32_bf16 v[12:15], v[160:163], v[212:215], v[12:15]
	v_mfma_f32_16x16x32_bf16 v[12:15], v[164:167], v[216:219], v[12:15]
	v_mfma_f32_16x16x32_bf16 v[48:51], v[168:171], v[188:191], v[48:51]
	v_mfma_f32_16x16x32_bf16 v[48:51], v[172:175], v[192:195], v[48:51]
	v_mfma_f32_16x16x32_bf16 v[40:43], v[176:179], v[188:191], v[40:43]
	v_mfma_f32_16x16x32_bf16 v[40:43], v[184:187], v[192:195], v[40:43]
	v_mfma_f32_16x16x32_bf16 v[32:35], v[168:171], v[196:199], v[32:35]
	v_mfma_f32_16x16x32_bf16 v[32:35], v[172:175], v[200:203], v[32:35]
	v_mfma_f32_16x16x32_bf16 v[24:27], v[176:179], v[196:199], v[24:27]
	v_mfma_f32_16x16x32_bf16 v[24:27], v[184:187], v[200:203], v[24:27]
	v_mfma_f32_16x16x32_bf16 v[16:19], v[168:171], v[204:207], v[16:19]
	v_mfma_f32_16x16x32_bf16 v[16:19], v[172:175], v[208:211], v[16:19]
	v_mfma_f32_16x16x32_bf16 v[8:11], v[176:179], v[204:207], v[8:11]
	v_mfma_f32_16x16x32_bf16 v[8:11], v[184:187], v[208:211], v[8:11]
	v_mfma_f32_16x16x32_bf16 v[4:7], v[168:171], v[212:215], v[4:7]
	v_mfma_f32_16x16x32_bf16 v[4:7], v[172:175], v[216:219], v[4:7]
	v_mfma_f32_16x16x32_bf16 v[0:3], v[176:179], v[212:215], v[0:3]
	v_mfma_f32_16x16x32_bf16 v[0:3], v[184:187], v[216:219], v[0:3]
	s_setprio 0
	s_barrier
	s_add_i32 s88, s88, 2
	s_add_u32 s86, s86, 0x100
	s_addc_u32 s87, s87, 0
	s_cmp_gt_u32 s88, 41
	s_mov_b64 s[54:55], s[56:57]
	s_cbranch_scc0 .LBB0_1031
	s_and_b64 vcc, exec, s[18:19]
	s_cbranch_vccz .LBB0_1034
	s_barrier

.LBB0_1161:
	s_ashr_i32 s53, s52, 31
	s_lshl_b64 s[54:55], s[52:53], 19
	s_add_u32 s54, s80, s54
	s_addc_u32 s55, s81, s55
	s_and_b64 s[56:57], s[10:11], exec
	s_cselect_b32 s53, s55, s61
	s_cselect_b32 s83, s54, s60
	s_ashr_i32 s49, s48, 31
	s_lshl_b64 s[56:57], s[48:49], 19
	s_add_u32 s56, s66, s56
	s_addc_u32 s57, s67, s57
	s_and_b64 s[64:65], s[10:11], exec
	s_cselect_b32 s49, s57, s63
	s_cselect_b32 s84, s56, s62
	s_add_u32 s60, s60, 0x40080
	s_addc_u32 s61, s61, 0
	s_add_u32 s85, s62, 0x100
	s_addc_u32 s86, s63, 0
	s_mov_b32 s87, -2
	ds_read_b128 v[152:155], v148
	ds_read_b128 v[156:159], v148 offset:1024
	ds_read_b128 v[160:163], v148 offset:2048
	ds_read_b128 v[164:167], v148 offset:3072
	ds_read_b128 v[168:171], v149
	ds_read_b128 v[172:175], v149 offset:1024
	ds_read_b128 v[176:179], v149 offset:2048
	ds_read_b128 v[184:187], v149 offset:3072
	s_add_u32 s62, s60, 0xfffc0080
	s_addc_u32 s63, s61, -1
	s_cmp_eq_u32 s87, 12
	s_cselect_b32 s65, s53, s63
	s_cselect_b32 s64, s83, s62
	s_cselect_b32 s63, s49, s86
	s_cselect_b32 s62, s84, s85
	v_lshl_add_u64 v[220:221], s[60:61], 0, v[138:139]
	s_add_i32 m0, s69, 0xc000
	ds_read_b128 v[188:191], v150
	ds_read_b128 v[192:195], v150 offset:1024
	ds_read_b128 v[196:199], v150 offset:2048
	ds_read_b128 v[200:203], v150 offset:3072
	ds_read_b128 v[204:207], v150 offset:4096
	ds_read_b128 v[208:211], v150 offset:5120
	ds_read_b128 v[212:215], v150 offset:6144
	ds_read_b128 v[216:219], v150 offset:7168
	global_load_lds_dwordx4 v[220:221], off
	v_lshl_add_u64 v[220:221], s[60:61], 0, v[140:141]
	s_add_i32 m0, s69, 0xe000
	s_nop 0
	global_load_lds_dwordx4 v[220:221], off
	s_waitcnt vmcnt(8)
	s_waitcnt lgkmcnt(0)
	s_barrier
	s_setprio 1
	v_mfma_f32_16x16x32_bf16 v[124:127], v[152:155], v[188:191], 0
	v_mfma_f32_16x16x32_bf16 v[124:127], v[156:159], v[192:195], v[124:127]
	v_mfma_f32_16x16x32_bf16 v[120:123], v[160:163], v[188:191], 0
	v_mfma_f32_16x16x32_bf16 v[120:123], v[164:167], v[192:195], v[120:123]
	v_mfma_f32_16x16x32_bf16 v[116:119], v[152:155], v[196:199], 0
	v_mfma_f32_16x16x32_bf16 v[116:119], v[156:159], v[200:203], v[116:119]
	v_mfma_f32_16x16x32_bf16 v[112:115], v[160:163], v[196:199], 0
	v_mfma_f32_16x16x32_bf16 v[112:115], v[164:167], v[200:203], v[112:115]
	v_mfma_f32_16x16x32_bf16 v[108:111], v[152:155], v[204:207], 0
	v_mfma_f32_16x16x32_bf16 v[108:111], v[156:159], v[208:211], v[108:111]
	v_mfma_f32_16x16x32_bf16 v[104:107], v[160:163], v[204:207], 0
	v_mfma_f32_16x16x32_bf16 v[104:107], v[164:167], v[208:211], v[104:107]
	v_mfma_f32_16x16x32_bf16 v[100:103], v[152:155], v[212:215], 0
	v_mfma_f32_16x16x32_bf16 v[100:103], v[156:159], v[216:219], v[100:103]
	v_mfma_f32_16x16x32_bf16 v[96:99], v[160:163], v[212:215], 0
	v_mfma_f32_16x16x32_bf16 v[96:99], v[164:167], v[216:219], v[96:99]
	v_mfma_f32_16x16x32_bf16 v[68:71], v[168:171], v[188:191], 0
	v_mfma_f32_16x16x32_bf16 v[68:71], v[172:175], v[192:195], v[68:71]
	v_mfma_f32_16x16x32_bf16 v[64:67], v[176:179], v[188:191], 0
	v_mfma_f32_16x16x32_bf16 v[64:67], v[184:187], v[192:195], v[64:67]
	v_mfma_f32_16x16x32_bf16 v[52:55], v[168:171], v[196:199], 0
	v_mfma_f32_16x16x32_bf16 v[52:55], v[172:175], v[200:203], v[52:55]
	v_mfma_f32_16x16x32_bf16 v[48:51], v[176:179], v[196:199], 0
	v_mfma_f32_16x16x32_bf16 v[48:51], v[184:187], v[200:203], v[48:51]
	v_mfma_f32_16x16x32_bf16 v[44:47], v[168:171], v[204:207], 0
	v_mfma_f32_16x16x32_bf16 v[44:47], v[172:175], v[208:211], v[44:47]
	v_mfma_f32_16x16x32_bf16 v[40:43], v[176:179], v[204:207], 0
	v_mfma_f32_16x16x32_bf16 v[40:43], v[184:187], v[208:211], v[40:43]
	v_mfma_f32_16x16x32_bf16 v[36:39], v[168:171], v[212:215], 0
	v_mfma_f32_16x16x32_bf16 v[36:39], v[172:175], v[216:219], v[36:39]
	v_mfma_f32_16x16x32_bf16 v[32:35], v[176:179], v[212:215], 0
	v_mfma_f32_16x16x32_bf16 v[32:35], v[184:187], v[216:219], v[32:35]
	s_setprio 0
	s_barrier
	s_add_i32 s79, s77, s68
	v_lshl_add_u64 v[220:221], s[62:63], 0, v[130:131]
	s_mov_b32 m0, s79
	ds_read_b128 v[188:191], v150 offset:16384
	ds_read_b128 v[192:195], v150 offset:17408
	ds_read_b128 v[196:199], v150 offset:18432
	ds_read_b128 v[200:203], v150 offset:19456
	ds_read_b128 v[204:207], v150 offset:20480
	ds_read_b128 v[208:211], v150 offset:21504
	ds_read_b128 v[212:215], v150 offset:22528
	ds_read_b128 v[216:219], v150 offset:23552
	global_load_lds_dwordx4 v[220:221], off
	s_add_i32 m0, s79, 0x2000
	s_add_u32 s88, s62, 0x40000
	v_lshl_add_u64 v[222:223], s[62:63], 0, v[134:135]
	s_addc_u32 s89, s63, 0
	s_add_i32 s79, s82, s68
	global_load_lds_dwordx4 v[222:223], off
	v_lshl_add_u64 v[224:225], s[88:89], 0, v[130:131]
	s_mov_b32 m0, s79
	v_lshl_add_u64 v[226:227], s[64:65], 0, v[132:133]
	global_load_lds_dwordx4 v[224:225], off
	v_lshl_add_u64 v[224:225], s[88:89], 0, v[134:135]
	s_add_i32 m0, s79, 0x2000
	s_nop 0
	global_load_lds_dwordx4 v[224:225], off
	v_lshl_add_u64 v[224:225], s[64:65], 0, v[128:129]
	s_mov_b32 m0, s69
	s_nop 0
	global_load_lds_dwordx4 v[224:225], off
	s_mov_b32 m0, s70
	s_nop 0
	global_load_lds_dwordx4 v[226:227], off
	s_waitcnt vmcnt(8)
	s_waitcnt lgkmcnt(0)
	s_barrier
	s_setprio 1
	v_mfma_f32_16x16x32_bf16 v[92:95], v[152:155], v[188:191], 0
	v_mfma_f32_16x16x32_bf16 v[92:95], v[156:159], v[192:195], v[92:95]
	v_mfma_f32_16x16x32_bf16 v[88:91], v[160:163], v[188:191], 0
	v_mfma_f32_16x16x32_bf16 v[88:91], v[164:167], v[192:195], v[88:91]
	v_mfma_f32_16x16x32_bf16 v[84:87], v[152:155], v[196:199], 0
	v_mfma_f32_16x16x32_bf16 v[84:87], v[156:159], v[200:203], v[84:87]
	v_mfma_f32_16x16x32_bf16 v[80:83], v[160:163], v[196:199], 0
	v_mfma_f32_16x16x32_bf16 v[80:83], v[164:167], v[200:203], v[80:83]
	v_mfma_f32_16x16x32_bf16 v[76:79], v[152:155], v[204:207], 0
	v_mfma_f32_16x16x32_bf16 v[76:79], v[156:159], v[208:211], v[76:79]
	v_mfma_f32_16x16x32_bf16 v[72:75], v[160:163], v[204:207], 0
	v_mfma_f32_16x16x32_bf16 v[72:75], v[164:167], v[208:211], v[72:75]
	v_mfma_f32_16x16x32_bf16 v[60:63], v[152:155], v[212:215], 0
	v_mfma_f32_16x16x32_bf16 v[60:63], v[156:159], v[216:219], v[60:63]
	v_mfma_f32_16x16x32_bf16 v[56:59], v[160:163], v[212:215], 0
	v_mfma_f32_16x16x32_bf16 v[56:59], v[164:167], v[216:219], v[56:59]
	v_mfma_f32_16x16x32_bf16 v[28:31], v[168:171], v[188:191], 0
	v_mfma_f32_16x16x32_bf16 v[28:31], v[172:175], v[192:195], v[28:31]
	v_mfma_f32_16x16x32_bf16 v[24:27], v[176:179], v[188:191], 0
	v_mfma_f32_16x16x32_bf16 v[24:27], v[184:187], v[192:195], v[24:27]
	v_mfma_f32_16x16x32_bf16 v[20:23], v[168:171], v[196:199], 0
	v_mfma_f32_16x16x32_bf16 v[20:23], v[172:175], v[200:203], v[20:23]
	v_mfma_f32_16x16x32_bf16 v[16:19], v[176:179], v[196:199], 0
	v_mfma_f32_16x16x32_bf16 v[16:19], v[184:187], v[200:203], v[16:19]
	v_mfma_f32_16x16x32_bf16 v[12:15], v[168:171], v[204:207], 0
	v_mfma_f32_16x16x32_bf16 v[12:15], v[172:175], v[208:211], v[12:15]
	v_mfma_f32_16x16x32_bf16 v[8:11], v[176:179], v[204:207], 0
	v_mfma_f32_16x16x32_bf16 v[8:11], v[184:187], v[208:211], v[8:11]
	v_mfma_f32_16x16x32_bf16 v[4:7], v[168:171], v[212:215], 0
	v_mfma_f32_16x16x32_bf16 v[4:7], v[172:175], v[216:219], v[4:7]
	v_mfma_f32_16x16x32_bf16 v[0:3], v[176:179], v[212:215], 0
	v_mfma_f32_16x16x32_bf16 v[0:3], v[184:187], v[216:219], v[0:3]
	s_setprio 0
	s_barrier
	s_branch .Lmid_gemm9
.LBB0_1162:
	ds_read_b128 v[152:155], v148
	ds_read_b128 v[156:159], v148 offset:1024
	ds_read_b128 v[160:163], v148 offset:2048
	ds_read_b128 v[164:167], v148 offset:3072
	ds_read_b128 v[168:171], v149
	ds_read_b128 v[172:175], v149 offset:1024
	ds_read_b128 v[176:179], v149 offset:2048
	ds_read_b128 v[184:187], v149 offset:3072
	s_add_u32 s62, s60, 0xfffc0080
	s_addc_u32 s63, s61, -1
	s_cmp_eq_u32 s87, 12
	s_cselect_b32 s65, s53, s63
	s_cselect_b32 s64, s83, s62
	s_cselect_b32 s63, s49, s86
	s_cselect_b32 s62, s84, s85
	v_lshl_add_u64 v[220:221], s[60:61], 0, v[138:139]
	s_add_i32 m0, s69, 0xc000
	ds_read_b128 v[188:191], v150
	ds_read_b128 v[192:195], v150 offset:1024
	ds_read_b128 v[196:199], v150 offset:2048
	ds_read_b128 v[200:203], v150 offset:3072
	ds_read_b128 v[204:207], v150 offset:4096
	ds_read_b128 v[208:211], v150 offset:5120
	ds_read_b128 v[212:215], v150 offset:6144
	ds_read_b128 v[216:219], v150 offset:7168
	global_load_lds_dwordx4 v[220:221], off
	v_lshl_add_u64 v[220:221], s[60:61], 0, v[140:141]
	s_add_i32 m0, s69, 0xe000
	s_nop 0
	global_load_lds_dwordx4 v[220:221], off
	s_waitcnt vmcnt(8)
	s_waitcnt lgkmcnt(0)
	s_barrier
	s_setprio 1
	v_mfma_f32_16x16x32_bf16 v[124:127], v[152:155], v[188:191], v[124:127]
	v_mfma_f32_16x16x32_bf16 v[124:127], v[156:159], v[192:195], v[124:127]
	v_mfma_f32_16x16x32_bf16 v[120:123], v[160:163], v[188:191], v[120:123]
	v_mfma_f32_16x16x32_bf16 v[120:123], v[164:167], v[192:195], v[120:123]
	v_mfma_f32_16x16x32_bf16 v[116:119], v[152:155], v[196:199], v[116:119]
	v_mfma_f32_16x16x32_bf16 v[116:119], v[156:159], v[200:203], v[116:119]
	v_mfma_f32_16x16x32_bf16 v[112:115], v[160:163], v[196:199], v[112:115]
	v_mfma_f32_16x16x32_bf16 v[112:115], v[164:167], v[200:203], v[112:115]
	v_mfma_f32_16x16x32_bf16 v[108:111], v[152:155], v[204:207], v[108:111]
	v_mfma_f32_16x16x32_bf16 v[108:111], v[156:159], v[208:211], v[108:111]
	v_mfma_f32_16x16x32_bf16 v[104:107], v[160:163], v[204:207], v[104:107]
	v_mfma_f32_16x16x32_bf16 v[104:107], v[164:167], v[208:211], v[104:107]
	v_mfma_f32_16x16x32_bf16 v[100:103], v[152:155], v[212:215], v[100:103]
	v_mfma_f32_16x16x32_bf16 v[100:103], v[156:159], v[216:219], v[100:103]
	v_mfma_f32_16x16x32_bf16 v[96:99], v[160:163], v[212:215], v[96:99]
	v_mfma_f32_16x16x32_bf16 v[96:99], v[164:167], v[216:219], v[96:99]
	v_mfma_f32_16x16x32_bf16 v[68:71], v[168:171], v[188:191], v[68:71]
	v_mfma_f32_16x16x32_bf16 v[68:71], v[172:175], v[192:195], v[68:71]
	v_mfma_f32_16x16x32_bf16 v[64:67], v[176:179], v[188:191], v[64:67]
	v_mfma_f32_16x16x32_bf16 v[64:67], v[184:187], v[192:195], v[64:67]
	v_mfma_f32_16x16x32_bf16 v[52:55], v[168:171], v[196:199], v[52:55]
	v_mfma_f32_16x16x32_bf16 v[52:55], v[172:175], v[200:203], v[52:55]
	v_mfma_f32_16x16x32_bf16 v[48:51], v[176:179], v[196:199], v[48:51]
	v_mfma_f32_16x16x32_bf16 v[48:51], v[184:187], v[200:203], v[48:51]
	v_mfma_f32_16x16x32_bf16 v[44:47], v[168:171], v[204:207], v[44:47]
	v_mfma_f32_16x16x32_bf16 v[44:47], v[172:175], v[208:211], v[44:47]
	v_mfma_f32_16x16x32_bf16 v[40:43], v[176:179], v[204:207], v[40:43]
	v_mfma_f32_16x16x32_bf16 v[40:43], v[184:187], v[208:211], v[40:43]
	v_mfma_f32_16x16x32_bf16 v[36:39], v[168:171], v[212:215], v[36:39]
	v_mfma_f32_16x16x32_bf16 v[36:39], v[172:175], v[216:219], v[36:39]
	v_mfma_f32_16x16x32_bf16 v[32:35], v[176:179], v[212:215], v[32:35]
	v_mfma_f32_16x16x32_bf16 v[32:35], v[184:187], v[216:219], v[32:35]
	s_setprio 0
	s_barrier
	s_add_i32 s79, s77, s68
	v_lshl_add_u64 v[220:221], s[62:63], 0, v[130:131]
	s_mov_b32 m0, s79
	ds_read_b128 v[188:191], v150 offset:16384
	ds_read_b128 v[192:195], v150 offset:17408
	ds_read_b128 v[196:199], v150 offset:18432
	ds_read_b128 v[200:203], v150 offset:19456
	ds_read_b128 v[204:207], v150 offset:20480
	ds_read_b128 v[208:211], v150 offset:21504
	ds_read_b128 v[212:215], v150 offset:22528
	ds_read_b128 v[216:219], v150 offset:23552
	global_load_lds_dwordx4 v[220:221], off
	s_add_i32 m0, s79, 0x2000
	s_add_u32 s88, s62, 0x40000
	v_lshl_add_u64 v[222:223], s[62:63], 0, v[134:135]
	s_addc_u32 s89, s63, 0
	s_add_i32 s79, s82, s68
	global_load_lds_dwordx4 v[222:223], off
	v_lshl_add_u64 v[224:225], s[88:89], 0, v[130:131]
	s_mov_b32 m0, s79
	v_lshl_add_u64 v[226:227], s[64:65], 0, v[132:133]
	global_load_lds_dwordx4 v[224:225], off
	v_lshl_add_u64 v[224:225], s[88:89], 0, v[134:135]
	s_add_i32 m0, s79, 0x2000
	s_nop 0
	global_load_lds_dwordx4 v[224:225], off
	v_lshl_add_u64 v[224:225], s[64:65], 0, v[128:129]
	s_mov_b32 m0, s69
	s_nop 0
	global_load_lds_dwordx4 v[224:225], off
	s_mov_b32 m0, s70
	s_nop 0
	global_load_lds_dwordx4 v[226:227], off
	s_waitcnt vmcnt(8)
	s_waitcnt lgkmcnt(0)
	s_barrier
	s_setprio 1
	v_mfma_f32_16x16x32_bf16 v[92:95], v[152:155], v[188:191], v[92:95]
	v_mfma_f32_16x16x32_bf16 v[92:95], v[156:159], v[192:195], v[92:95]
	v_mfma_f32_16x16x32_bf16 v[88:91], v[160:163], v[188:191], v[88:91]
	v_mfma_f32_16x16x32_bf16 v[88:91], v[164:167], v[192:195], v[88:91]
	v_mfma_f32_16x16x32_bf16 v[84:87], v[152:155], v[196:199], v[84:87]
	v_mfma_f32_16x16x32_bf16 v[84:87], v[156:159], v[200:203], v[84:87]
	v_mfma_f32_16x16x32_bf16 v[80:83], v[160:163], v[196:199], v[80:83]
	v_mfma_f32_16x16x32_bf16 v[80:83], v[164:167], v[200:203], v[80:83]
	v_mfma_f32_16x16x32_bf16 v[76:79], v[152:155], v[204:207], v[76:79]
	v_mfma_f32_16x16x32_bf16 v[76:79], v[156:159], v[208:211], v[76:79]
	v_mfma_f32_16x16x32_bf16 v[72:75], v[160:163], v[204:207], v[72:75]
	v_mfma_f32_16x16x32_bf16 v[72:75], v[164:167], v[208:211], v[72:75]
	v_mfma_f32_16x16x32_bf16 v[60:63], v[152:155], v[212:215], v[60:63]
	v_mfma_f32_16x16x32_bf16 v[60:63], v[156:159], v[216:219], v[60:63]
	v_mfma_f32_16x16x32_bf16 v[56:59], v[160:163], v[212:215], v[56:59]
	v_mfma_f32_16x16x32_bf16 v[56:59], v[164:167], v[216:219], v[56:59]
	v_mfma_f32_16x16x32_bf16 v[28:31], v[168:171], v[188:191], v[28:31]
	v_mfma_f32_16x16x32_bf16 v[28:31], v[172:175], v[192:195], v[28:31]
	v_mfma_f32_16x16x32_bf16 v[24:27], v[176:179], v[188:191], v[24:27]
	v_mfma_f32_16x16x32_bf16 v[24:27], v[184:187], v[192:195], v[24:27]
	v_mfma_f32_16x16x32_bf16 v[20:23], v[168:171], v[196:199], v[20:23]
	v_mfma_f32_16x16x32_bf16 v[20:23], v[172:175], v[200:203], v[20:23]
	v_mfma_f32_16x16x32_bf16 v[16:19], v[176:179], v[196:199], v[16:19]
	v_mfma_f32_16x16x32_bf16 v[16:19], v[184:187], v[200:203], v[16:19]
	v_mfma_f32_16x16x32_bf16 v[12:15], v[168:171], v[204:207], v[12:15]
	v_mfma_f32_16x16x32_bf16 v[12:15], v[172:175], v[208:211], v[12:15]
	v_mfma_f32_16x16x32_bf16 v[8:11], v[176:179], v[204:207], v[8:11]
	v_mfma_f32_16x16x32_bf16 v[8:11], v[184:187], v[208:211], v[8:11]
	v_mfma_f32_16x16x32_bf16 v[4:7], v[168:171], v[212:215], v[4:7]
	v_mfma_f32_16x16x32_bf16 v[4:7], v[172:175], v[216:219], v[4:7]
	v_mfma_f32_16x16x32_bf16 v[0:3], v[176:179], v[212:215], v[0:3]
	v_mfma_f32_16x16x32_bf16 v[0:3], v[184:187], v[216:219], v[0:3]
	s_setprio 0
	s_barrier
.Lmid_gemm9:
	s_add_i32 s79, 0, 0x18000
	s_add_i32 s88, 0, 0x1c000
	v_add_u32_e32 v164, s79, v147
	v_add_u32_e32 v181, s88, v147
	ds_read_b128 v[152:155], v164
	ds_read_b128 v[156:159], v164 offset:1024
	ds_read_b128 v[160:163], v164 offset:2048
	ds_read_b128 v[164:167], v164 offset:3072
	ds_read_b128 v[168:171], v181
	ds_read_b128 v[172:175], v181 offset:1024
	ds_read_b128 v[176:179], v181 offset:2048
	ds_read_b128 v[184:187], v181 offset:3072
	s_add_u32 s64, s64, 0x40000
	s_addc_u32 s65, s65, 0
	s_mov_b32 m0, s71
	v_lshl_add_u64 v[228:229], s[64:65], 0, v[128:129]
	ds_read_b128 v[188:191], v150 offset:32768
	ds_read_b128 v[192:195], v150 offset:33792
	ds_read_b128 v[196:199], v150 offset:34816
	ds_read_b128 v[200:203], v150 offset:35840
	ds_read_b128 v[204:207], v150 offset:36864
	ds_read_b128 v[208:211], v150 offset:37888
	ds_read_b128 v[212:215], v150 offset:38912
	ds_read_b128 v[216:219], v150 offset:39936
	global_load_lds_dwordx4 v[228:229], off
	v_lshl_add_u64 v[228:229], s[64:65], 0, v[132:133]
	s_mov_b32 m0, s72
	s_nop 0
	global_load_lds_dwordx4 v[228:229], off
	s_waitcnt vmcnt(8)
	s_waitcnt lgkmcnt(0)
	s_barrier
	s_setprio 1
	v_mfma_f32_16x16x32_bf16 v[124:127], v[152:155], v[188:191], v[124:127]
	v_mfma_f32_16x16x32_bf16 v[124:127], v[156:159], v[192:195], v[124:127]
	v_mfma_f32_16x16x32_bf16 v[120:123], v[160:163], v[188:191], v[120:123]
	v_mfma_f32_16x16x32_bf16 v[120:123], v[164:167], v[192:195], v[120:123]
	v_mfma_f32_16x16x32_bf16 v[116:119], v[152:155], v[196:199], v[116:119]
	v_mfma_f32_16x16x32_bf16 v[116:119], v[156:159], v[200:203], v[116:119]
	v_mfma_f32_16x16x32_bf16 v[112:115], v[160:163], v[196:199], v[112:115]
	v_mfma_f32_16x16x32_bf16 v[112:115], v[164:167], v[200:203], v[112:115]
	v_mfma_f32_16x16x32_bf16 v[108:111], v[152:155], v[204:207], v[108:111]
	v_mfma_f32_16x16x32_bf16 v[108:111], v[156:159], v[208:211], v[108:111]
	v_mfma_f32_16x16x32_bf16 v[104:107], v[160:163], v[204:207], v[104:107]
	v_mfma_f32_16x16x32_bf16 v[104:107], v[164:167], v[208:211], v[104:107]
	v_mfma_f32_16x16x32_bf16 v[100:103], v[152:155], v[212:215], v[100:103]
	v_mfma_f32_16x16x32_bf16 v[100:103], v[156:159], v[216:219], v[100:103]
	v_mfma_f32_16x16x32_bf16 v[96:99], v[160:163], v[212:215], v[96:99]
	v_mfma_f32_16x16x32_bf16 v[96:99], v[164:167], v[216:219], v[96:99]
	v_mfma_f32_16x16x32_bf16 v[68:71], v[168:171], v[188:191], v[68:71]
	v_mfma_f32_16x16x32_bf16 v[68:71], v[172:175], v[192:195], v[68:71]
	v_mfma_f32_16x16x32_bf16 v[64:67], v[176:179], v[188:191], v[64:67]
	v_mfma_f32_16x16x32_bf16 v[64:67], v[184:187], v[192:195], v[64:67]
	v_mfma_f32_16x16x32_bf16 v[52:55], v[168:171], v[196:199], v[52:55]
	v_mfma_f32_16x16x32_bf16 v[52:55], v[172:175], v[200:203], v[52:55]
	v_mfma_f32_16x16x32_bf16 v[48:51], v[176:179], v[196:199], v[48:51]
	v_mfma_f32_16x16x32_bf16 v[48:51], v[184:187], v[200:203], v[48:51]
	v_mfma_f32_16x16x32_bf16 v[44:47], v[168:171], v[204:207], v[44:47]
	v_mfma_f32_16x16x32_bf16 v[44:47], v[172:175], v[208:211], v[44:47]
	v_mfma_f32_16x16x32_bf16 v[40:43], v[176:179], v[204:207], v[40:43]
	v_mfma_f32_16x16x32_bf16 v[40:43], v[184:187], v[208:211], v[40:43]
	v_mfma_f32_16x16x32_bf16 v[36:39], v[168:171], v[212:215], v[36:39]
	v_mfma_f32_16x16x32_bf16 v[36:39], v[172:175], v[216:219], v[36:39]
	v_mfma_f32_16x16x32_bf16 v[32:35], v[176:179], v[212:215], v[32:35]
	v_mfma_f32_16x16x32_bf16 v[32:35], v[184:187], v[216:219], v[32:35]
	s_setprio 0
	s_barrier
	s_add_i32 s64, s79, s68
	v_lshl_add_u64 v[220:221], v[220:221], 0, s[12:13]
	s_mov_b32 m0, s64
	ds_read_b128 v[188:191], v150 offset:49152
	ds_read_b128 v[192:195], v150 offset:50176
	ds_read_b128 v[196:199], v150 offset:51200
	ds_read_b128 v[200:203], v150 offset:52224
	ds_read_b128 v[204:207], v150 offset:53248
	ds_read_b128 v[208:211], v150 offset:54272
	ds_read_b128 v[212:215], v150 offset:55296
	ds_read_b128 v[216:219], v150 offset:56320
	global_load_lds_dwordx4 v[220:221], off
	s_add_i32 m0, s64, 0x2000
	s_add_u32 s62, s62, 0x40080
	v_lshl_add_u64 v[220:221], v[222:223], 0, s[12:13]
	s_addc_u32 s63, s63, 0
	s_add_i32 s64, s88, s68
	global_load_lds_dwordx4 v[220:221], off
	v_lshl_add_u64 v[220:221], s[62:63], 0, v[130:131]
	s_mov_b32 m0, s64
	s_nop 0
	global_load_lds_dwordx4 v[220:221], off
	v_lshl_add_u64 v[220:221], s[62:63], 0, v[134:135]
	s_add_i32 m0, s64, 0x2000
	s_nop 0
	global_load_lds_dwordx4 v[220:221], off
	v_lshl_add_u64 v[220:221], v[224:225], 0, s[12:13]
	s_mov_b32 m0, s75
	s_nop 0
	global_load_lds_dwordx4 v[220:221], off
	v_lshl_add_u64 v[220:221], v[226:227], 0, s[12:13]
	s_mov_b32 m0, s76
	s_nop 0
	global_load_lds_dwordx4 v[220:221], off
	s_waitcnt vmcnt(8)
	s_waitcnt lgkmcnt(0)
	s_barrier
	s_setprio 1
	v_mfma_f32_16x16x32_bf16 v[92:95], v[152:155], v[188:191], v[92:95]
	v_mfma_f32_16x16x32_bf16 v[92:95], v[156:159], v[192:195], v[92:95]
	v_mfma_f32_16x16x32_bf16 v[88:91], v[160:163], v[188:191], v[88:91]
	v_mfma_f32_16x16x32_bf16 v[88:91], v[164:167], v[192:195], v[88:91]
	v_mfma_f32_16x16x32_bf16 v[84:87], v[152:155], v[196:199], v[84:87]
	v_mfma_f32_16x16x32_bf16 v[84:87], v[156:159], v[200:203], v[84:87]
	v_mfma_f32_16x16x32_bf16 v[80:83], v[160:163], v[196:199], v[80:83]
	v_mfma_f32_16x16x32_bf16 v[80:83], v[164:167], v[200:203], v[80:83]
	v_mfma_f32_16x16x32_bf16 v[76:79], v[152:155], v[204:207], v[76:79]
	v_mfma_f32_16x16x32_bf16 v[76:79], v[156:159], v[208:211], v[76:79]
	v_mfma_f32_16x16x32_bf16 v[72:75], v[160:163], v[204:207], v[72:75]
	v_mfma_f32_16x16x32_bf16 v[72:75], v[164:167], v[208:211], v[72:75]
	v_mfma_f32_16x16x32_bf16 v[60:63], v[152:155], v[212:215], v[60:63]
	v_mfma_f32_16x16x32_bf16 v[60:63], v[156:159], v[216:219], v[60:63]
	v_mfma_f32_16x16x32_bf16 v[56:59], v[160:163], v[212:215], v[56:59]
	v_mfma_f32_16x16x32_bf16 v[56:59], v[164:167], v[216:219], v[56:59]
	v_mfma_f32_16x16x32_bf16 v[28:31], v[168:171], v[188:191], v[28:31]
	v_mfma_f32_16x16x32_bf16 v[28:31], v[172:175], v[192:195], v[28:31]
	v_mfma_f32_16x16x32_bf16 v[24:27], v[176:179], v[188:191], v[24:27]
	v_mfma_f32_16x16x32_bf16 v[24:27], v[184:187], v[192:195], v[24:27]
	v_mfma_f32_16x16x32_bf16 v[20:23], v[168:171], v[196:199], v[20:23]
	v_mfma_f32_16x16x32_bf16 v[20:23], v[172:175], v[200:203], v[20:23]
	v_mfma_f32_16x16x32_bf16 v[16:19], v[176:179], v[196:199], v[16:19]
	v_mfma_f32_16x16x32_bf16 v[16:19], v[184:187], v[200:203], v[16:19]
	v_mfma_f32_16x16x32_bf16 v[12:15], v[168:171], v[204:207], v[12:15]
	v_mfma_f32_16x16x32_bf16 v[12:15], v[172:175], v[208:211], v[12:15]
	v_mfma_f32_16x16x32_bf16 v[8:11], v[176:179], v[204:207], v[8:11]
	v_mfma_f32_16x16x32_bf16 v[8:11], v[184:187], v[208:211], v[8:11]
	v_mfma_f32_16x16x32_bf16 v[4:7], v[168:171], v[212:215], v[4:7]
	v_mfma_f32_16x16x32_bf16 v[4:7], v[172:175], v[216:219], v[4:7]
	v_mfma_f32_16x16x32_bf16 v[0:3], v[176:179], v[212:215], v[0:3]
	v_mfma_f32_16x16x32_bf16 v[0:3], v[184:187], v[216:219], v[0:3]
	s_setprio 0
	s_barrier
	s_add_i32 s87, s87, 2
	s_add_u32 s60, s60, 0x100
	s_addc_u32 s61, s61, 0
	s_add_u32 s85, s85, 0x100
	s_addc_u32 s86, s86, 0
	s_cmp_gt_u32 s87, 13
	s_cbranch_scc0 .LBB0_1162
	s_and_b64 vcc, exec, s[16:17]
	s_cbranch_vccz .LBB0_1165
	s_barrier

.LBB0_1310:
	s_ashr_i32 s49, s48, 31
	s_lshl_b64 s[50:51], s[48:49], 19
	s_add_u32 s50, s38, s50
	s_addc_u32 s51, s39, s51
	s_and_b64 s[52:53], s[10:11], exec
	s_cselect_b32 s49, s51, s57
	s_cselect_b32 s82, s50, s56
	s_ashr_i32 s47, s46, 31
	s_lshl_b64 s[52:53], s[46:47], 19
	s_add_u32 s52, s62, s52
	s_addc_u32 s53, s63, s53
	s_and_b64 s[60:61], s[10:11], exec
	s_cselect_b32 s47, s53, s59
	s_cselect_b32 s83, s52, s58
	s_add_u32 s56, s56, 0x40080
	s_addc_u32 s57, s57, 0
	s_add_u32 s84, s58, 0x100
	s_addc_u32 s85, s59, 0
	s_mov_b32 s86, -2
	ds_read_b128 v[152:155], v149
	ds_read_b128 v[156:159], v149 offset:1024
	ds_read_b128 v[160:163], v149 offset:2048
	ds_read_b128 v[164:167], v149 offset:3072
	ds_read_b128 v[168:171], v150
	ds_read_b128 v[172:175], v150 offset:1024
	ds_read_b128 v[176:179], v150 offset:2048
	ds_read_b128 v[184:187], v150 offset:3072
	s_add_u32 s58, s56, 0xfffc0080
	s_addc_u32 s59, s57, -1
	s_cmp_eq_u32 s86, 12
	s_cselect_b32 s61, s49, s59
	s_cselect_b32 s60, s82, s58
	s_cselect_b32 s59, s47, s85
	s_cselect_b32 s58, s83, s84
	v_lshl_add_u64 v[144:145], s[56:57], 0, v[136:137]
	s_add_i32 m0, s55, 0xc000
	ds_read_b128 v[188:191], v151
	ds_read_b128 v[192:195], v151 offset:1024
	ds_read_b128 v[196:199], v151 offset:2048
	ds_read_b128 v[200:203], v151 offset:3072
	ds_read_b128 v[204:207], v151 offset:4096
	ds_read_b128 v[208:211], v151 offset:5120
	ds_read_b128 v[212:215], v151 offset:6144
	ds_read_b128 v[216:219], v151 offset:7168
	global_load_lds_dwordx4 v[144:145], off
	v_lshl_add_u64 v[144:145], s[56:57], 0, v[138:139]
	s_add_i32 m0, s55, 0xe000
	s_nop 0
	global_load_lds_dwordx4 v[144:145], off
	s_waitcnt vmcnt(8)
	s_waitcnt lgkmcnt(0)
	s_barrier
	s_setprio 1
	v_mfma_f32_16x16x32_bf16 v[124:127], v[152:155], v[188:191], 0
	v_mfma_f32_16x16x32_bf16 v[124:127], v[156:159], v[192:195], v[124:127]
	v_mfma_f32_16x16x32_bf16 v[120:123], v[160:163], v[188:191], 0
	v_mfma_f32_16x16x32_bf16 v[120:123], v[164:167], v[192:195], v[120:123]
	v_mfma_f32_16x16x32_bf16 v[116:119], v[152:155], v[196:199], 0
	v_mfma_f32_16x16x32_bf16 v[116:119], v[156:159], v[200:203], v[116:119]
	v_mfma_f32_16x16x32_bf16 v[108:111], v[160:163], v[196:199], 0
	v_mfma_f32_16x16x32_bf16 v[108:111], v[164:167], v[200:203], v[108:111]
	v_mfma_f32_16x16x32_bf16 v[100:103], v[152:155], v[204:207], 0
	v_mfma_f32_16x16x32_bf16 v[100:103], v[156:159], v[208:211], v[100:103]
	v_mfma_f32_16x16x32_bf16 v[92:95], v[160:163], v[204:207], 0
	v_mfma_f32_16x16x32_bf16 v[92:95], v[164:167], v[208:211], v[92:95]
	v_mfma_f32_16x16x32_bf16 v[84:87], v[152:155], v[212:215], 0
	v_mfma_f32_16x16x32_bf16 v[84:87], v[156:159], v[216:219], v[84:87]
	v_mfma_f32_16x16x32_bf16 v[76:79], v[160:163], v[212:215], 0
	v_mfma_f32_16x16x32_bf16 v[76:79], v[164:167], v[216:219], v[76:79]
	v_mfma_f32_16x16x32_bf16 v[112:115], v[168:171], v[188:191], 0
	v_mfma_f32_16x16x32_bf16 v[112:115], v[172:175], v[192:195], v[112:115]
	v_mfma_f32_16x16x32_bf16 v[104:107], v[176:179], v[188:191], 0
	v_mfma_f32_16x16x32_bf16 v[104:107], v[184:187], v[192:195], v[104:107]
	v_mfma_f32_16x16x32_bf16 v[96:99], v[168:171], v[196:199], 0
	v_mfma_f32_16x16x32_bf16 v[96:99], v[172:175], v[200:203], v[96:99]
	v_mfma_f32_16x16x32_bf16 v[88:91], v[176:179], v[196:199], 0
	v_mfma_f32_16x16x32_bf16 v[88:91], v[184:187], v[200:203], v[88:91]
	v_mfma_f32_16x16x32_bf16 v[80:83], v[168:171], v[204:207], 0
	v_mfma_f32_16x16x32_bf16 v[80:83], v[172:175], v[208:211], v[80:83]
	v_mfma_f32_16x16x32_bf16 v[72:75], v[176:179], v[204:207], 0
	v_mfma_f32_16x16x32_bf16 v[72:75], v[184:187], v[208:211], v[72:75]
	v_mfma_f32_16x16x32_bf16 v[68:71], v[168:171], v[212:215], 0
	v_mfma_f32_16x16x32_bf16 v[68:71], v[172:175], v[216:219], v[68:71]
	v_mfma_f32_16x16x32_bf16 v[64:67], v[176:179], v[212:215], 0
	v_mfma_f32_16x16x32_bf16 v[64:67], v[184:187], v[216:219], v[64:67]
	s_setprio 0
	s_barrier
	s_add_i32 s79, s71, s64
	v_lshl_add_u64 v[144:145], s[58:59], 0, v[130:131]
	s_mov_b32 m0, s79
	ds_read_b128 v[188:191], v151 offset:16384
	ds_read_b128 v[192:195], v151 offset:17408
	ds_read_b128 v[196:199], v151 offset:18432
	ds_read_b128 v[200:203], v151 offset:19456
	ds_read_b128 v[204:207], v151 offset:20480
	ds_read_b128 v[208:211], v151 offset:21504
	ds_read_b128 v[212:215], v151 offset:22528
	ds_read_b128 v[216:219], v151 offset:23552
	global_load_lds_dwordx4 v[144:145], off
	s_add_i32 m0, s79, 0x2000
	s_add_u32 s88, s58, 0x40000
	v_lshl_add_u64 v[220:221], s[58:59], 0, v[134:135]
	s_addc_u32 s89, s59, 0
	s_add_i32 s79, s72, s64
	global_load_lds_dwordx4 v[220:221], off
	v_lshl_add_u64 v[222:223], s[88:89], 0, v[130:131]
	s_mov_b32 m0, s79
	v_lshl_add_u64 v[224:225], s[60:61], 0, v[132:133]
	global_load_lds_dwordx4 v[222:223], off
	v_lshl_add_u64 v[222:223], s[88:89], 0, v[134:135]
	s_add_i32 m0, s79, 0x2000
	s_nop 0
	global_load_lds_dwordx4 v[222:223], off
	v_lshl_add_u64 v[222:223], s[60:61], 0, v[128:129]
	s_mov_b32 m0, s55
	s_nop 0
	global_load_lds_dwordx4 v[222:223], off
	s_mov_b32 m0, s65
	s_nop 0
	global_load_lds_dwordx4 v[224:225], off
	s_waitcnt vmcnt(8)
	s_waitcnt lgkmcnt(0)
	s_barrier
	s_setprio 1
	v_mfma_f32_16x16x32_bf16 v[60:63], v[152:155], v[188:191], 0
	v_mfma_f32_16x16x32_bf16 v[60:63], v[156:159], v[192:195], v[60:63]
	v_mfma_f32_16x16x32_bf16 v[56:59], v[160:163], v[188:191], 0
	v_mfma_f32_16x16x32_bf16 v[56:59], v[164:167], v[192:195], v[56:59]
	v_mfma_f32_16x16x32_bf16 v[52:55], v[152:155], v[196:199], 0
	v_mfma_f32_16x16x32_bf16 v[52:55], v[156:159], v[200:203], v[52:55]
	v_mfma_f32_16x16x32_bf16 v[44:47], v[160:163], v[196:199], 0
	v_mfma_f32_16x16x32_bf16 v[44:47], v[164:167], v[200:203], v[44:47]
	v_mfma_f32_16x16x32_bf16 v[36:39], v[152:155], v[204:207], 0
	v_mfma_f32_16x16x32_bf16 v[36:39], v[156:159], v[208:211], v[36:39]
	v_mfma_f32_16x16x32_bf16 v[28:31], v[160:163], v[204:207], 0
	v_mfma_f32_16x16x32_bf16 v[28:31], v[164:167], v[208:211], v[28:31]
	v_mfma_f32_16x16x32_bf16 v[20:23], v[152:155], v[212:215], 0
	v_mfma_f32_16x16x32_bf16 v[20:23], v[156:159], v[216:219], v[20:23]
	v_mfma_f32_16x16x32_bf16 v[12:15], v[160:163], v[212:215], 0
	v_mfma_f32_16x16x32_bf16 v[12:15], v[164:167], v[216:219], v[12:15]
	v_mfma_f32_16x16x32_bf16 v[48:51], v[168:171], v[188:191], 0
	v_mfma_f32_16x16x32_bf16 v[48:51], v[172:175], v[192:195], v[48:51]
	v_mfma_f32_16x16x32_bf16 v[40:43], v[176:179], v[188:191], 0
	v_mfma_f32_16x16x32_bf16 v[40:43], v[184:187], v[192:195], v[40:43]
	v_mfma_f32_16x16x32_bf16 v[32:35], v[168:171], v[196:199], 0
	v_mfma_f32_16x16x32_bf16 v[32:35], v[172:175], v[200:203], v[32:35]
	v_mfma_f32_16x16x32_bf16 v[24:27], v[176:179], v[196:199], 0
	v_mfma_f32_16x16x32_bf16 v[24:27], v[184:187], v[200:203], v[24:27]
	v_mfma_f32_16x16x32_bf16 v[16:19], v[168:171], v[204:207], 0
	v_mfma_f32_16x16x32_bf16 v[16:19], v[172:175], v[208:211], v[16:19]
	v_mfma_f32_16x16x32_bf16 v[8:11], v[176:179], v[204:207], 0
	v_mfma_f32_16x16x32_bf16 v[8:11], v[184:187], v[208:211], v[8:11]
	v_mfma_f32_16x16x32_bf16 v[4:7], v[168:171], v[212:215], 0
	v_mfma_f32_16x16x32_bf16 v[4:7], v[172:175], v[216:219], v[4:7]
	v_mfma_f32_16x16x32_bf16 v[0:3], v[176:179], v[212:215], 0
	v_mfma_f32_16x16x32_bf16 v[0:3], v[184:187], v[216:219], v[0:3]
	s_setprio 0
	s_barrier
	s_branch .Lmid_gemm10
.LBB0_1311:
	ds_read_b128 v[152:155], v149
	ds_read_b128 v[156:159], v149 offset:1024
	ds_read_b128 v[160:163], v149 offset:2048
	ds_read_b128 v[164:167], v149 offset:3072
	ds_read_b128 v[168:171], v150
	ds_read_b128 v[172:175], v150 offset:1024
	ds_read_b128 v[176:179], v150 offset:2048
	ds_read_b128 v[184:187], v150 offset:3072
	s_add_u32 s58, s56, 0xfffc0080
	s_addc_u32 s59, s57, -1
	s_cmp_eq_u32 s86, 12
	s_cselect_b32 s61, s49, s59
	s_cselect_b32 s60, s82, s58
	s_cselect_b32 s59, s47, s85
	s_cselect_b32 s58, s83, s84
	v_lshl_add_u64 v[144:145], s[56:57], 0, v[136:137]
	s_add_i32 m0, s55, 0xc000
	ds_read_b128 v[188:191], v151
	ds_read_b128 v[192:195], v151 offset:1024
	ds_read_b128 v[196:199], v151 offset:2048
	ds_read_b128 v[200:203], v151 offset:3072
	ds_read_b128 v[204:207], v151 offset:4096
	ds_read_b128 v[208:211], v151 offset:5120
	ds_read_b128 v[212:215], v151 offset:6144
	ds_read_b128 v[216:219], v151 offset:7168
	global_load_lds_dwordx4 v[144:145], off
	v_lshl_add_u64 v[144:145], s[56:57], 0, v[138:139]
	s_add_i32 m0, s55, 0xe000
	s_nop 0
	global_load_lds_dwordx4 v[144:145], off
	s_waitcnt vmcnt(8)
	s_waitcnt lgkmcnt(0)
	s_barrier
	s_setprio 1
	v_mfma_f32_16x16x32_bf16 v[124:127], v[152:155], v[188:191], v[124:127]
	v_mfma_f32_16x16x32_bf16 v[124:127], v[156:159], v[192:195], v[124:127]
	v_mfma_f32_16x16x32_bf16 v[120:123], v[160:163], v[188:191], v[120:123]
	v_mfma_f32_16x16x32_bf16 v[120:123], v[164:167], v[192:195], v[120:123]
	v_mfma_f32_16x16x32_bf16 v[116:119], v[152:155], v[196:199], v[116:119]
	v_mfma_f32_16x16x32_bf16 v[116:119], v[156:159], v[200:203], v[116:119]
	v_mfma_f32_16x16x32_bf16 v[108:111], v[160:163], v[196:199], v[108:111]
	v_mfma_f32_16x16x32_bf16 v[108:111], v[164:167], v[200:203], v[108:111]
	v_mfma_f32_16x16x32_bf16 v[100:103], v[152:155], v[204:207], v[100:103]
	v_mfma_f32_16x16x32_bf16 v[100:103], v[156:159], v[208:211], v[100:103]
	v_mfma_f32_16x16x32_bf16 v[92:95], v[160:163], v[204:207], v[92:95]
	v_mfma_f32_16x16x32_bf16 v[92:95], v[164:167], v[208:211], v[92:95]
	v_mfma_f32_16x16x32_bf16 v[84:87], v[152:155], v[212:215], v[84:87]
	v_mfma_f32_16x16x32_bf16 v[84:87], v[156:159], v[216:219], v[84:87]
	v_mfma_f32_16x16x32_bf16 v[76:79], v[160:163], v[212:215], v[76:79]
	v_mfma_f32_16x16x32_bf16 v[76:79], v[164:167], v[216:219], v[76:79]
	v_mfma_f32_16x16x32_bf16 v[112:115], v[168:171], v[188:191], v[112:115]
	v_mfma_f32_16x16x32_bf16 v[112:115], v[172:175], v[192:195], v[112:115]
	v_mfma_f32_16x16x32_bf16 v[104:107], v[176:179], v[188:191], v[104:107]
	v_mfma_f32_16x16x32_bf16 v[104:107], v[184:187], v[192:195], v[104:107]
	v_mfma_f32_16x16x32_bf16 v[96:99], v[168:171], v[196:199], v[96:99]
	v_mfma_f32_16x16x32_bf16 v[96:99], v[172:175], v[200:203], v[96:99]
	v_mfma_f32_16x16x32_bf16 v[88:91], v[176:179], v[196:199], v[88:91]
	v_mfma_f32_16x16x32_bf16 v[88:91], v[184:187], v[200:203], v[88:91]
	v_mfma_f32_16x16x32_bf16 v[80:83], v[168:171], v[204:207], v[80:83]
	v_mfma_f32_16x16x32_bf16 v[80:83], v[172:175], v[208:211], v[80:83]
	v_mfma_f32_16x16x32_bf16 v[72:75], v[176:179], v[204:207], v[72:75]
	v_mfma_f32_16x16x32_bf16 v[72:75], v[184:187], v[208:211], v[72:75]
	v_mfma_f32_16x16x32_bf16 v[68:71], v[168:171], v[212:215], v[68:71]
	v_mfma_f32_16x16x32_bf16 v[68:71], v[172:175], v[216:219], v[68:71]
	v_mfma_f32_16x16x32_bf16 v[64:67], v[176:179], v[212:215], v[64:67]
	v_mfma_f32_16x16x32_bf16 v[64:67], v[184:187], v[216:219], v[64:67]
	s_setprio 0
	s_barrier
	s_add_i32 s79, s71, s64
	v_lshl_add_u64 v[144:145], s[58:59], 0, v[130:131]
	s_mov_b32 m0, s79
	ds_read_b128 v[188:191], v151 offset:16384
	ds_read_b128 v[192:195], v151 offset:17408
	ds_read_b128 v[196:199], v151 offset:18432
	ds_read_b128 v[200:203], v151 offset:19456
	ds_read_b128 v[204:207], v151 offset:20480
	ds_read_b128 v[208:211], v151 offset:21504
	ds_read_b128 v[212:215], v151 offset:22528
	ds_read_b128 v[216:219], v151 offset:23552
	global_load_lds_dwordx4 v[144:145], off
	s_add_i32 m0, s79, 0x2000
	s_add_u32 s88, s58, 0x40000
	v_lshl_add_u64 v[220:221], s[58:59], 0, v[134:135]
	s_addc_u32 s89, s59, 0
	s_add_i32 s79, s72, s64
	global_load_lds_dwordx4 v[220:221], off
	v_lshl_add_u64 v[222:223], s[88:89], 0, v[130:131]
	s_mov_b32 m0, s79
	v_lshl_add_u64 v[224:225], s[60:61], 0, v[132:133]
	global_load_lds_dwordx4 v[222:223], off
	v_lshl_add_u64 v[222:223], s[88:89], 0, v[134:135]
	s_add_i32 m0, s79, 0x2000
	s_nop 0
	global_load_lds_dwordx4 v[222:223], off
	v_lshl_add_u64 v[222:223], s[60:61], 0, v[128:129]
	s_mov_b32 m0, s55
	s_nop 0
	global_load_lds_dwordx4 v[222:223], off
	s_mov_b32 m0, s65
	s_nop 0
	global_load_lds_dwordx4 v[224:225], off
	s_waitcnt vmcnt(8)
	s_waitcnt lgkmcnt(0)
	s_barrier
	s_setprio 1
	v_mfma_f32_16x16x32_bf16 v[60:63], v[152:155], v[188:191], v[60:63]
	v_mfma_f32_16x16x32_bf16 v[60:63], v[156:159], v[192:195], v[60:63]
	v_mfma_f32_16x16x32_bf16 v[56:59], v[160:163], v[188:191], v[56:59]
	v_mfma_f32_16x16x32_bf16 v[56:59], v[164:167], v[192:195], v[56:59]
	v_mfma_f32_16x16x32_bf16 v[52:55], v[152:155], v[196:199], v[52:55]
	v_mfma_f32_16x16x32_bf16 v[52:55], v[156:159], v[200:203], v[52:55]
	v_mfma_f32_16x16x32_bf16 v[44:47], v[160:163], v[196:199], v[44:47]
	v_mfma_f32_16x16x32_bf16 v[44:47], v[164:167], v[200:203], v[44:47]
	v_mfma_f32_16x16x32_bf16 v[36:39], v[152:155], v[204:207], v[36:39]
	v_mfma_f32_16x16x32_bf16 v[36:39], v[156:159], v[208:211], v[36:39]
	v_mfma_f32_16x16x32_bf16 v[28:31], v[160:163], v[204:207], v[28:31]
	v_mfma_f32_16x16x32_bf16 v[28:31], v[164:167], v[208:211], v[28:31]
	v_mfma_f32_16x16x32_bf16 v[20:23], v[152:155], v[212:215], v[20:23]
	v_mfma_f32_16x16x32_bf16 v[20:23], v[156:159], v[216:219], v[20:23]
	v_mfma_f32_16x16x32_bf16 v[12:15], v[160:163], v[212:215], v[12:15]
	v_mfma_f32_16x16x32_bf16 v[12:15], v[164:167], v[216:219], v[12:15]
	v_mfma_f32_16x16x32_bf16 v[48:51], v[168:171], v[188:191], v[48:51]
	v_mfma_f32_16x16x32_bf16 v[48:51], v[172:175], v[192:195], v[48:51]
	v_mfma_f32_16x16x32_bf16 v[40:43], v[176:179], v[188:191], v[40:43]
	v_mfma_f32_16x16x32_bf16 v[40:43], v[184:187], v[192:195], v[40:43]
	v_mfma_f32_16x16x32_bf16 v[32:35], v[168:171], v[196:199], v[32:35]
	v_mfma_f32_16x16x32_bf16 v[32:35], v[172:175], v[200:203], v[32:35]
	v_mfma_f32_16x16x32_bf16 v[24:27], v[176:179], v[196:199], v[24:27]
	v_mfma_f32_16x16x32_bf16 v[24:27], v[184:187], v[200:203], v[24:27]
	v_mfma_f32_16x16x32_bf16 v[16:19], v[168:171], v[204:207], v[16:19]
	v_mfma_f32_16x16x32_bf16 v[16:19], v[172:175], v[208:211], v[16:19]
	v_mfma_f32_16x16x32_bf16 v[8:11], v[176:179], v[204:207], v[8:11]
	v_mfma_f32_16x16x32_bf16 v[8:11], v[184:187], v[208:211], v[8:11]
	v_mfma_f32_16x16x32_bf16 v[4:7], v[168:171], v[212:215], v[4:7]
	v_mfma_f32_16x16x32_bf16 v[4:7], v[172:175], v[216:219], v[4:7]
	v_mfma_f32_16x16x32_bf16 v[0:3], v[176:179], v[212:215], v[0:3]
	v_mfma_f32_16x16x32_bf16 v[0:3], v[184:187], v[216:219], v[0:3]
	s_setprio 0
	s_barrier
.Lmid_gemm10:
	s_add_i32 s79, 0, 0x18000
	s_add_i32 s87, 0, 0x1c000
	v_add_u32_e32 v164, s79, v147
	v_add_u32_e32 v181, s87, v147
	ds_read_b128 v[152:155], v164
	ds_read_b128 v[156:159], v164 offset:1024
	ds_read_b128 v[160:163], v164 offset:2048
	ds_read_b128 v[164:167], v164 offset:3072
	ds_read_b128 v[168:171], v181
	ds_read_b128 v[172:175], v181 offset:1024
	ds_read_b128 v[176:179], v181 offset:2048
	ds_read_b128 v[184:187], v181 offset:3072
	s_add_u32 s60, s60, 0x40000
	s_addc_u32 s61, s61, 0
	s_mov_b32 m0, s66
	v_lshl_add_u64 v[226:227], s[60:61], 0, v[128:129]
	ds_read_b128 v[188:191], v151 offset:32768
	ds_read_b128 v[192:195], v151 offset:33792
	ds_read_b128 v[196:199], v151 offset:34816
	ds_read_b128 v[200:203], v151 offset:35840
	ds_read_b128 v[204:207], v151 offset:36864
	ds_read_b128 v[208:211], v151 offset:37888
	ds_read_b128 v[212:215], v151 offset:38912
	ds_read_b128 v[216:219], v151 offset:39936
	global_load_lds_dwordx4 v[226:227], off
	v_lshl_add_u64 v[226:227], s[60:61], 0, v[132:133]
	s_mov_b32 m0, s67
	s_nop 0
	global_load_lds_dwordx4 v[226:227], off
	s_waitcnt vmcnt(8)
	s_waitcnt lgkmcnt(0)
	s_barrier
	s_setprio 1
	v_mfma_f32_16x16x32_bf16 v[124:127], v[152:155], v[188:191], v[124:127]
	v_mfma_f32_16x16x32_bf16 v[124:127], v[156:159], v[192:195], v[124:127]
	v_mfma_f32_16x16x32_bf16 v[120:123], v[160:163], v[188:191], v[120:123]
	v_mfma_f32_16x16x32_bf16 v[120:123], v[164:167], v[192:195], v[120:123]
	v_mfma_f32_16x16x32_bf16 v[116:119], v[152:155], v[196:199], v[116:119]
	v_mfma_f32_16x16x32_bf16 v[116:119], v[156:159], v[200:203], v[116:119]
	v_mfma_f32_16x16x32_bf16 v[108:111], v[160:163], v[196:199], v[108:111]
	v_mfma_f32_16x16x32_bf16 v[108:111], v[164:167], v[200:203], v[108:111]
	v_mfma_f32_16x16x32_bf16 v[100:103], v[152:155], v[204:207], v[100:103]
	v_mfma_f32_16x16x32_bf16 v[100:103], v[156:159], v[208:211], v[100:103]
	v_mfma_f32_16x16x32_bf16 v[92:95], v[160:163], v[204:207], v[92:95]
	v_mfma_f32_16x16x32_bf16 v[92:95], v[164:167], v[208:211], v[92:95]
	v_mfma_f32_16x16x32_bf16 v[84:87], v[152:155], v[212:215], v[84:87]
	v_mfma_f32_16x16x32_bf16 v[84:87], v[156:159], v[216:219], v[84:87]
	v_mfma_f32_16x16x32_bf16 v[76:79], v[160:163], v[212:215], v[76:79]
	v_mfma_f32_16x16x32_bf16 v[76:79], v[164:167], v[216:219], v[76:79]
	v_mfma_f32_16x16x32_bf16 v[112:115], v[168:171], v[188:191], v[112:115]
	v_mfma_f32_16x16x32_bf16 v[112:115], v[172:175], v[192:195], v[112:115]
	v_mfma_f32_16x16x32_bf16 v[104:107], v[176:179], v[188:191], v[104:107]
	v_mfma_f32_16x16x32_bf16 v[104:107], v[184:187], v[192:195], v[104:107]
	v_mfma_f32_16x16x32_bf16 v[96:99], v[168:171], v[196:199], v[96:99]
	v_mfma_f32_16x16x32_bf16 v[96:99], v[172:175], v[200:203], v[96:99]
	v_mfma_f32_16x16x32_bf16 v[88:91], v[176:179], v[196:199], v[88:91]
	v_mfma_f32_16x16x32_bf16 v[88:91], v[184:187], v[200:203], v[88:91]
	v_mfma_f32_16x16x32_bf16 v[80:83], v[168:171], v[204:207], v[80:83]
	v_mfma_f32_16x16x32_bf16 v[80:83], v[172:175], v[208:211], v[80:83]
	v_mfma_f32_16x16x32_bf16 v[72:75], v[176:179], v[204:207], v[72:75]
	v_mfma_f32_16x16x32_bf16 v[72:75], v[184:187], v[208:211], v[72:75]
	v_mfma_f32_16x16x32_bf16 v[68:71], v[168:171], v[212:215], v[68:71]
	v_mfma_f32_16x16x32_bf16 v[68:71], v[172:175], v[216:219], v[68:71]
	v_mfma_f32_16x16x32_bf16 v[64:67], v[176:179], v[212:215], v[64:67]
	v_mfma_f32_16x16x32_bf16 v[64:67], v[184:187], v[216:219], v[64:67]
	s_setprio 0
	s_barrier
	s_add_i32 s60, s79, s64
	v_lshl_add_u64 v[144:145], v[144:145], 0, s[16:17]
	s_mov_b32 m0, s60
	ds_read_b128 v[188:191], v151 offset:49152
	ds_read_b128 v[192:195], v151 offset:50176
	ds_read_b128 v[196:199], v151 offset:51200
	ds_read_b128 v[200:203], v151 offset:52224
	ds_read_b128 v[204:207], v151 offset:53248
	ds_read_b128 v[208:211], v151 offset:54272
	ds_read_b128 v[212:215], v151 offset:55296
	ds_read_b128 v[216:219], v151 offset:56320
	global_load_lds_dwordx4 v[144:145], off
	s_add_i32 m0, s60, 0x2000
	s_add_u32 s58, s58, 0x40080
	v_lshl_add_u64 v[144:145], v[220:221], 0, s[16:17]
	s_addc_u32 s59, s59, 0
	s_add_i32 s60, s87, s64
	global_load_lds_dwordx4 v[144:145], off
	v_lshl_add_u64 v[144:145], s[58:59], 0, v[130:131]
	s_mov_b32 m0, s60
	s_nop 0
	global_load_lds_dwordx4 v[144:145], off
	v_lshl_add_u64 v[144:145], s[58:59], 0, v[134:135]
	s_add_i32 m0, s60, 0x2000
	s_nop 0
	global_load_lds_dwordx4 v[144:145], off
	v_lshl_add_u64 v[144:145], v[222:223], 0, s[16:17]
	s_mov_b32 m0, s69
	s_nop 0
	global_load_lds_dwordx4 v[144:145], off
	v_lshl_add_u64 v[144:145], v[224:225], 0, s[16:17]
	s_mov_b32 m0, s70
	s_nop 0
	global_load_lds_dwordx4 v[144:145], off
	s_waitcnt vmcnt(8)
	s_waitcnt lgkmcnt(0)
	s_barrier
	s_setprio 1
	v_mfma_f32_16x16x32_bf16 v[60:63], v[152:155], v[188:191], v[60:63]
	v_mfma_f32_16x16x32_bf16 v[60:63], v[156:159], v[192:195], v[60:63]
	v_mfma_f32_16x16x32_bf16 v[56:59], v[160:163], v[188:191], v[56:59]
	v_mfma_f32_16x16x32_bf16 v[56:59], v[164:167], v[192:195], v[56:59]
	v_mfma_f32_16x16x32_bf16 v[52:55], v[152:155], v[196:199], v[52:55]
	v_mfma_f32_16x16x32_bf16 v[52:55], v[156:159], v[200:203], v[52:55]
	v_mfma_f32_16x16x32_bf16 v[44:47], v[160:163], v[196:199], v[44:47]
	v_mfma_f32_16x16x32_bf16 v[44:47], v[164:167], v[200:203], v[44:47]
	v_mfma_f32_16x16x32_bf16 v[36:39], v[152:155], v[204:207], v[36:39]
	v_mfma_f32_16x16x32_bf16 v[36:39], v[156:159], v[208:211], v[36:39]
	v_mfma_f32_16x16x32_bf16 v[28:31], v[160:163], v[204:207], v[28:31]
	v_mfma_f32_16x16x32_bf16 v[28:31], v[164:167], v[208:211], v[28:31]
	v_mfma_f32_16x16x32_bf16 v[20:23], v[152:155], v[212:215], v[20:23]
	v_mfma_f32_16x16x32_bf16 v[20:23], v[156:159], v[216:219], v[20:23]
	v_mfma_f32_16x16x32_bf16 v[12:15], v[160:163], v[212:215], v[12:15]
	v_mfma_f32_16x16x32_bf16 v[12:15], v[164:167], v[216:219], v[12:15]
	v_mfma_f32_16x16x32_bf16 v[48:51], v[168:171], v[188:191], v[48:51]
	v_mfma_f32_16x16x32_bf16 v[48:51], v[172:175], v[192:195], v[48:51]
	v_mfma_f32_16x16x32_bf16 v[40:43], v[176:179], v[188:191], v[40:43]
	v_mfma_f32_16x16x32_bf16 v[40:43], v[184:187], v[192:195], v[40:43]
	v_mfma_f32_16x16x32_bf16 v[32:35], v[168:171], v[196:199], v[32:35]
	v_mfma_f32_16x16x32_bf16 v[32:35], v[172:175], v[200:203], v[32:35]
	v_mfma_f32_16x16x32_bf16 v[24:27], v[176:179], v[196:199], v[24:27]
	v_mfma_f32_16x16x32_bf16 v[24:27], v[184:187], v[200:203], v[24:27]
	v_mfma_f32_16x16x32_bf16 v[16:19], v[168:171], v[204:207], v[16:19]
	v_mfma_f32_16x16x32_bf16 v[16:19], v[172:175], v[208:211], v[16:19]
	v_mfma_f32_16x16x32_bf16 v[8:11], v[176:179], v[204:207], v[8:11]
	v_mfma_f32_16x16x32_bf16 v[8:11], v[184:187], v[208:211], v[8:11]
	v_mfma_f32_16x16x32_bf16 v[4:7], v[168:171], v[212:215], v[4:7]
	v_mfma_f32_16x16x32_bf16 v[4:7], v[172:175], v[216:219], v[4:7]
	v_mfma_f32_16x16x32_bf16 v[0:3], v[176:179], v[212:215], v[0:3]
	v_mfma_f32_16x16x32_bf16 v[0:3], v[184:187], v[216:219], v[0:3]
	s_setprio 0
	s_barrier
	s_add_i32 s86, s86, 2
	s_add_u32 s56, s56, 0x100
	s_addc_u32 s57, s57, 0
	s_add_u32 s84, s84, 0x100
	s_addc_u32 s85, s85, 0
	s_cmp_gt_u32 s86, 13
	s_cbranch_scc0 .LBB0_1311
	s_and_b64 vcc, exec, s[18:19]
	s_cbranch_vccz .LBB0_1314
	s_barrier

.LBB0_1433:
	s_ashr_i32 s19, s18, 31
	s_lshl_b64 s[30:31], s[18:19], 19
	s_add_u32 s30, s80, s30
	s_addc_u32 s31, s81, s31
	s_and_b64 s[36:37], s[8:9], exec
	s_cselect_b32 s19, s31, s47
	s_cselect_b32 s66, s30, s46
	s_ashr_i32 s17, s16, 31
	s_lshl_b64 s[36:37], s[16:17], 19
	s_add_u32 s36, s52, s36
	s_addc_u32 s37, s53, s37
	s_and_b64 s[50:51], s[8:9], exec
	s_cselect_b32 s17, s37, s49
	s_cselect_b32 s67, s36, s48
	s_add_u32 s46, s46, 0x40080
	s_addc_u32 s47, s47, 0
	s_add_u32 s68, s48, 0x100
	s_addc_u32 s69, s49, 0
	s_mov_b32 s70, -2
	ds_read_b128 v[140:143], v147
	ds_read_b128 v[150:153], v147 offset:1024
	ds_read_b128 v[154:157], v147 offset:2048
	ds_read_b128 v[158:161], v147 offset:3072
	ds_read_b128 v[162:165], v148
	ds_read_b128 v[166:169], v148 offset:1024
	ds_read_b128 v[170:173], v148 offset:2048
	ds_read_b128 v[174:177], v148 offset:3072
	s_add_u32 s48, s46, 0xfffc0080
	s_addc_u32 s49, s47, -1
	s_cmp_eq_u32 s70, 12
	s_cselect_b32 s51, s19, s49
	s_cselect_b32 s50, s66, s48
	s_cselect_b32 s49, s17, s69
	s_cselect_b32 s48, s67, s68
	v_lshl_add_u64 v[178:179], s[46:47], 0, v[132:133]
	s_add_i32 m0, s45, 0xc000
	ds_read_b128 v[184:187], v149
	ds_read_b128 v[188:191], v149 offset:1024
	ds_read_b128 v[192:195], v149 offset:2048
	ds_read_b128 v[196:199], v149 offset:3072
	ds_read_b128 v[200:203], v149 offset:4096
	ds_read_b128 v[204:207], v149 offset:5120
	ds_read_b128 v[208:211], v149 offset:6144
	ds_read_b128 v[212:215], v149 offset:7168
	global_load_lds_dwordx4 v[178:179], off
	v_lshl_add_u64 v[178:179], s[46:47], 0, v[134:135]
	s_add_i32 m0, s45, 0xe000
	s_nop 0
	global_load_lds_dwordx4 v[178:179], off
	s_waitcnt vmcnt(8)
	s_waitcnt lgkmcnt(0)
	s_barrier
	s_setprio 1
	v_mfma_f32_16x16x32_bf16 v[124:127], v[140:143], v[184:187], 0
	v_mfma_f32_16x16x32_bf16 v[124:127], v[150:153], v[188:191], v[124:127]
	v_mfma_f32_16x16x32_bf16 v[120:123], v[154:157], v[184:187], 0
	v_mfma_f32_16x16x32_bf16 v[120:123], v[158:161], v[188:191], v[120:123]
	v_mfma_f32_16x16x32_bf16 v[108:111], v[140:143], v[192:195], 0
	v_mfma_f32_16x16x32_bf16 v[108:111], v[150:153], v[196:199], v[108:111]
	v_mfma_f32_16x16x32_bf16 v[104:107], v[154:157], v[192:195], 0
	v_mfma_f32_16x16x32_bf16 v[104:107], v[158:161], v[196:199], v[104:107]
	v_mfma_f32_16x16x32_bf16 v[92:95], v[140:143], v[200:203], 0
	v_mfma_f32_16x16x32_bf16 v[92:95], v[150:153], v[204:207], v[92:95]
	v_mfma_f32_16x16x32_bf16 v[88:91], v[154:157], v[200:203], 0
	v_mfma_f32_16x16x32_bf16 v[88:91], v[158:161], v[204:207], v[88:91]
	v_mfma_f32_16x16x32_bf16 v[76:79], v[140:143], v[208:211], 0
	v_mfma_f32_16x16x32_bf16 v[76:79], v[150:153], v[212:215], v[76:79]
	v_mfma_f32_16x16x32_bf16 v[72:75], v[154:157], v[208:211], 0
	v_mfma_f32_16x16x32_bf16 v[72:75], v[158:161], v[212:215], v[72:75]
	v_mfma_f32_16x16x32_bf16 v[116:119], v[162:165], v[184:187], 0
	v_mfma_f32_16x16x32_bf16 v[116:119], v[166:169], v[188:191], v[116:119]
	v_mfma_f32_16x16x32_bf16 v[112:115], v[170:173], v[184:187], 0
	v_mfma_f32_16x16x32_bf16 v[112:115], v[174:177], v[188:191], v[112:115]
	v_mfma_f32_16x16x32_bf16 v[100:103], v[162:165], v[192:195], 0
	v_mfma_f32_16x16x32_bf16 v[100:103], v[166:169], v[196:199], v[100:103]
	v_mfma_f32_16x16x32_bf16 v[96:99], v[170:173], v[192:195], 0
	v_mfma_f32_16x16x32_bf16 v[96:99], v[174:177], v[196:199], v[96:99]
	v_mfma_f32_16x16x32_bf16 v[84:87], v[162:165], v[200:203], 0
	v_mfma_f32_16x16x32_bf16 v[84:87], v[166:169], v[204:207], v[84:87]
	v_mfma_f32_16x16x32_bf16 v[80:83], v[170:173], v[200:203], 0
	v_mfma_f32_16x16x32_bf16 v[80:83], v[174:177], v[204:207], v[80:83]
	v_mfma_f32_16x16x32_bf16 v[68:71], v[162:165], v[208:211], 0
	v_mfma_f32_16x16x32_bf16 v[68:71], v[166:169], v[212:215], v[68:71]
	v_mfma_f32_16x16x32_bf16 v[64:67], v[170:173], v[208:211], 0
	v_mfma_f32_16x16x32_bf16 v[64:67], v[174:177], v[212:215], v[64:67]
	s_setprio 0
	s_barrier
	s_add_i32 s71, s62, s54
	v_lshl_add_u64 v[178:179], s[48:49], 0, v[130:131]
	s_mov_b32 m0, s71
	ds_read_b128 v[184:187], v149 offset:16384
	ds_read_b128 v[188:191], v149 offset:17408
	ds_read_b128 v[192:195], v149 offset:18432
	ds_read_b128 v[196:199], v149 offset:19456
	ds_read_b128 v[200:203], v149 offset:20480
	ds_read_b128 v[204:207], v149 offset:21504
	ds_read_b128 v[208:211], v149 offset:22528
	ds_read_b128 v[212:215], v149 offset:23552
	global_load_lds_dwordx4 v[178:179], off
	s_add_i32 m0, s71, 0x2000
	s_add_u32 s72, s48, 0x40000
	v_lshl_add_u64 v[216:217], s[48:49], 0, v[128:129]
	s_addc_u32 s73, s49, 0
	s_add_i32 s71, s63, s54
	global_load_lds_dwordx4 v[216:217], off
	v_lshl_add_u64 v[218:219], s[72:73], 0, v[130:131]
	s_mov_b32 m0, s71
	v_lshl_add_u64 v[220:221], s[50:51], 0, v[128:129]
	global_load_lds_dwordx4 v[218:219], off
	v_lshl_add_u64 v[218:219], s[72:73], 0, v[128:129]
	s_add_i32 m0, s71, 0x2000
	s_nop 0
	global_load_lds_dwordx4 v[218:219], off
	v_lshl_add_u64 v[218:219], s[50:51], 0, v[130:131]
	s_mov_b32 m0, s45
	s_nop 0
	global_load_lds_dwordx4 v[218:219], off
	s_mov_b32 m0, s56
	s_nop 0
	global_load_lds_dwordx4 v[220:221], off
	s_waitcnt vmcnt(8)
	s_waitcnt lgkmcnt(0)
	s_barrier
	s_setprio 1
	v_mfma_f32_16x16x32_bf16 v[60:63], v[140:143], v[184:187], 0
	v_mfma_f32_16x16x32_bf16 v[60:63], v[150:153], v[188:191], v[60:63]
	v_mfma_f32_16x16x32_bf16 v[56:59], v[154:157], v[184:187], 0
	v_mfma_f32_16x16x32_bf16 v[56:59], v[158:161], v[188:191], v[56:59]
	v_mfma_f32_16x16x32_bf16 v[44:47], v[140:143], v[192:195], 0
	v_mfma_f32_16x16x32_bf16 v[44:47], v[150:153], v[196:199], v[44:47]
	v_mfma_f32_16x16x32_bf16 v[40:43], v[154:157], v[192:195], 0
	v_mfma_f32_16x16x32_bf16 v[40:43], v[158:161], v[196:199], v[40:43]
	v_mfma_f32_16x16x32_bf16 v[28:31], v[140:143], v[200:203], 0
	v_mfma_f32_16x16x32_bf16 v[28:31], v[150:153], v[204:207], v[28:31]
	v_mfma_f32_16x16x32_bf16 v[24:27], v[154:157], v[200:203], 0
	v_mfma_f32_16x16x32_bf16 v[24:27], v[158:161], v[204:207], v[24:27]
	v_mfma_f32_16x16x32_bf16 v[12:15], v[140:143], v[208:211], 0
	v_mfma_f32_16x16x32_bf16 v[12:15], v[150:153], v[212:215], v[12:15]
	v_mfma_f32_16x16x32_bf16 v[8:11], v[154:157], v[208:211], 0
	v_mfma_f32_16x16x32_bf16 v[8:11], v[158:161], v[212:215], v[8:11]
	v_mfma_f32_16x16x32_bf16 v[52:55], v[162:165], v[184:187], 0
	v_mfma_f32_16x16x32_bf16 v[52:55], v[166:169], v[188:191], v[52:55]
	v_mfma_f32_16x16x32_bf16 v[48:51], v[170:173], v[184:187], 0
	v_mfma_f32_16x16x32_bf16 v[48:51], v[174:177], v[188:191], v[48:51]
	v_mfma_f32_16x16x32_bf16 v[36:39], v[162:165], v[192:195], 0
	v_mfma_f32_16x16x32_bf16 v[36:39], v[166:169], v[196:199], v[36:39]
	v_mfma_f32_16x16x32_bf16 v[32:35], v[170:173], v[192:195], 0
	v_mfma_f32_16x16x32_bf16 v[32:35], v[174:177], v[196:199], v[32:35]
	v_mfma_f32_16x16x32_bf16 v[20:23], v[162:165], v[200:203], 0
	v_mfma_f32_16x16x32_bf16 v[20:23], v[166:169], v[204:207], v[20:23]
	v_mfma_f32_16x16x32_bf16 v[16:19], v[170:173], v[200:203], 0
	v_mfma_f32_16x16x32_bf16 v[16:19], v[174:177], v[204:207], v[16:19]
	v_mfma_f32_16x16x32_bf16 v[4:7], v[162:165], v[208:211], 0
	v_mfma_f32_16x16x32_bf16 v[4:7], v[166:169], v[212:215], v[4:7]
	v_mfma_f32_16x16x32_bf16 v[0:3], v[170:173], v[208:211], 0
	v_mfma_f32_16x16x32_bf16 v[0:3], v[174:177], v[212:215], v[0:3]
	s_setprio 0
	s_barrier
	s_branch .Lmid_gemm11
.LBB0_1434:
	ds_read_b128 v[140:143], v147
	ds_read_b128 v[150:153], v147 offset:1024
	ds_read_b128 v[154:157], v147 offset:2048
	ds_read_b128 v[158:161], v147 offset:3072
	ds_read_b128 v[162:165], v148
	ds_read_b128 v[166:169], v148 offset:1024
	ds_read_b128 v[170:173], v148 offset:2048
	ds_read_b128 v[174:177], v148 offset:3072
	s_add_u32 s48, s46, 0xfffc0080
	s_addc_u32 s49, s47, -1
	s_cmp_eq_u32 s70, 12
	s_cselect_b32 s51, s19, s49
	s_cselect_b32 s50, s66, s48
	s_cselect_b32 s49, s17, s69
	s_cselect_b32 s48, s67, s68
	v_lshl_add_u64 v[178:179], s[46:47], 0, v[132:133]
	s_add_i32 m0, s45, 0xc000
	ds_read_b128 v[184:187], v149
	ds_read_b128 v[188:191], v149 offset:1024
	ds_read_b128 v[192:195], v149 offset:2048
	ds_read_b128 v[196:199], v149 offset:3072
	ds_read_b128 v[200:203], v149 offset:4096
	ds_read_b128 v[204:207], v149 offset:5120
	ds_read_b128 v[208:211], v149 offset:6144
	ds_read_b128 v[212:215], v149 offset:7168
	global_load_lds_dwordx4 v[178:179], off
	v_lshl_add_u64 v[178:179], s[46:47], 0, v[134:135]
	s_add_i32 m0, s45, 0xe000
	s_nop 0
	global_load_lds_dwordx4 v[178:179], off
	s_waitcnt vmcnt(8)
	s_waitcnt lgkmcnt(0)
	s_barrier
	s_setprio 1
	v_mfma_f32_16x16x32_bf16 v[124:127], v[140:143], v[184:187], v[124:127]
	v_mfma_f32_16x16x32_bf16 v[124:127], v[150:153], v[188:191], v[124:127]
	v_mfma_f32_16x16x32_bf16 v[120:123], v[154:157], v[184:187], v[120:123]
	v_mfma_f32_16x16x32_bf16 v[120:123], v[158:161], v[188:191], v[120:123]
	v_mfma_f32_16x16x32_bf16 v[108:111], v[140:143], v[192:195], v[108:111]
	v_mfma_f32_16x16x32_bf16 v[108:111], v[150:153], v[196:199], v[108:111]
	v_mfma_f32_16x16x32_bf16 v[104:107], v[154:157], v[192:195], v[104:107]
	v_mfma_f32_16x16x32_bf16 v[104:107], v[158:161], v[196:199], v[104:107]
	v_mfma_f32_16x16x32_bf16 v[92:95], v[140:143], v[200:203], v[92:95]
	v_mfma_f32_16x16x32_bf16 v[92:95], v[150:153], v[204:207], v[92:95]
	v_mfma_f32_16x16x32_bf16 v[88:91], v[154:157], v[200:203], v[88:91]
	v_mfma_f32_16x16x32_bf16 v[88:91], v[158:161], v[204:207], v[88:91]
	v_mfma_f32_16x16x32_bf16 v[76:79], v[140:143], v[208:211], v[76:79]
	v_mfma_f32_16x16x32_bf16 v[76:79], v[150:153], v[212:215], v[76:79]
	v_mfma_f32_16x16x32_bf16 v[72:75], v[154:157], v[208:211], v[72:75]
	v_mfma_f32_16x16x32_bf16 v[72:75], v[158:161], v[212:215], v[72:75]
	v_mfma_f32_16x16x32_bf16 v[116:119], v[162:165], v[184:187], v[116:119]
	v_mfma_f32_16x16x32_bf16 v[116:119], v[166:169], v[188:191], v[116:119]
	v_mfma_f32_16x16x32_bf16 v[112:115], v[170:173], v[184:187], v[112:115]
	v_mfma_f32_16x16x32_bf16 v[112:115], v[174:177], v[188:191], v[112:115]
	v_mfma_f32_16x16x32_bf16 v[100:103], v[162:165], v[192:195], v[100:103]
	v_mfma_f32_16x16x32_bf16 v[100:103], v[166:169], v[196:199], v[100:103]
	v_mfma_f32_16x16x32_bf16 v[96:99], v[170:173], v[192:195], v[96:99]
	v_mfma_f32_16x16x32_bf16 v[96:99], v[174:177], v[196:199], v[96:99]
	v_mfma_f32_16x16x32_bf16 v[84:87], v[162:165], v[200:203], v[84:87]
	v_mfma_f32_16x16x32_bf16 v[84:87], v[166:169], v[204:207], v[84:87]
	v_mfma_f32_16x16x32_bf16 v[80:83], v[170:173], v[200:203], v[80:83]
	v_mfma_f32_16x16x32_bf16 v[80:83], v[174:177], v[204:207], v[80:83]
	v_mfma_f32_16x16x32_bf16 v[68:71], v[162:165], v[208:211], v[68:71]
	v_mfma_f32_16x16x32_bf16 v[68:71], v[166:169], v[212:215], v[68:71]
	v_mfma_f32_16x16x32_bf16 v[64:67], v[170:173], v[208:211], v[64:67]
	v_mfma_f32_16x16x32_bf16 v[64:67], v[174:177], v[212:215], v[64:67]
	s_setprio 0
	s_barrier
	s_add_i32 s71, s62, s54
	v_lshl_add_u64 v[178:179], s[48:49], 0, v[130:131]
	s_mov_b32 m0, s71
	ds_read_b128 v[184:187], v149 offset:16384
	ds_read_b128 v[188:191], v149 offset:17408
	ds_read_b128 v[192:195], v149 offset:18432
	ds_read_b128 v[196:199], v149 offset:19456
	ds_read_b128 v[200:203], v149 offset:20480
	ds_read_b128 v[204:207], v149 offset:21504
	ds_read_b128 v[208:211], v149 offset:22528
	ds_read_b128 v[212:215], v149 offset:23552
	global_load_lds_dwordx4 v[178:179], off
	s_add_i32 m0, s71, 0x2000
	s_add_u32 s72, s48, 0x40000
	v_lshl_add_u64 v[216:217], s[48:49], 0, v[128:129]
	s_addc_u32 s73, s49, 0
	s_add_i32 s71, s63, s54
	global_load_lds_dwordx4 v[216:217], off
	v_lshl_add_u64 v[218:219], s[72:73], 0, v[130:131]
	s_mov_b32 m0, s71
	v_lshl_add_u64 v[220:221], s[50:51], 0, v[128:129]
	global_load_lds_dwordx4 v[218:219], off
	v_lshl_add_u64 v[218:219], s[72:73], 0, v[128:129]
	s_add_i32 m0, s71, 0x2000
	s_nop 0
	global_load_lds_dwordx4 v[218:219], off
	v_lshl_add_u64 v[218:219], s[50:51], 0, v[130:131]
	s_mov_b32 m0, s45
	s_nop 0
	global_load_lds_dwordx4 v[218:219], off
	s_mov_b32 m0, s56
	s_nop 0
	global_load_lds_dwordx4 v[220:221], off
	s_waitcnt vmcnt(8)
	s_waitcnt lgkmcnt(0)
	s_barrier
	s_setprio 1
	v_mfma_f32_16x16x32_bf16 v[60:63], v[140:143], v[184:187], v[60:63]
	v_mfma_f32_16x16x32_bf16 v[60:63], v[150:153], v[188:191], v[60:63]
	v_mfma_f32_16x16x32_bf16 v[56:59], v[154:157], v[184:187], v[56:59]
	v_mfma_f32_16x16x32_bf16 v[56:59], v[158:161], v[188:191], v[56:59]
	v_mfma_f32_16x16x32_bf16 v[44:47], v[140:143], v[192:195], v[44:47]
	v_mfma_f32_16x16x32_bf16 v[44:47], v[150:153], v[196:199], v[44:47]
	v_mfma_f32_16x16x32_bf16 v[40:43], v[154:157], v[192:195], v[40:43]
	v_mfma_f32_16x16x32_bf16 v[40:43], v[158:161], v[196:199], v[40:43]
	v_mfma_f32_16x16x32_bf16 v[28:31], v[140:143], v[200:203], v[28:31]
	v_mfma_f32_16x16x32_bf16 v[28:31], v[150:153], v[204:207], v[28:31]
	v_mfma_f32_16x16x32_bf16 v[24:27], v[154:157], v[200:203], v[24:27]
	v_mfma_f32_16x16x32_bf16 v[24:27], v[158:161], v[204:207], v[24:27]
	v_mfma_f32_16x16x32_bf16 v[12:15], v[140:143], v[208:211], v[12:15]
	v_mfma_f32_16x16x32_bf16 v[12:15], v[150:153], v[212:215], v[12:15]
	v_mfma_f32_16x16x32_bf16 v[8:11], v[154:157], v[208:211], v[8:11]
	v_mfma_f32_16x16x32_bf16 v[8:11], v[158:161], v[212:215], v[8:11]
	v_mfma_f32_16x16x32_bf16 v[52:55], v[162:165], v[184:187], v[52:55]
	v_mfma_f32_16x16x32_bf16 v[52:55], v[166:169], v[188:191], v[52:55]
	v_mfma_f32_16x16x32_bf16 v[48:51], v[170:173], v[184:187], v[48:51]
	v_mfma_f32_16x16x32_bf16 v[48:51], v[174:177], v[188:191], v[48:51]
	v_mfma_f32_16x16x32_bf16 v[36:39], v[162:165], v[192:195], v[36:39]
	v_mfma_f32_16x16x32_bf16 v[36:39], v[166:169], v[196:199], v[36:39]
	v_mfma_f32_16x16x32_bf16 v[32:35], v[170:173], v[192:195], v[32:35]
	v_mfma_f32_16x16x32_bf16 v[32:35], v[174:177], v[196:199], v[32:35]
	v_mfma_f32_16x16x32_bf16 v[20:23], v[162:165], v[200:203], v[20:23]
	v_mfma_f32_16x16x32_bf16 v[20:23], v[166:169], v[204:207], v[20:23]
	v_mfma_f32_16x16x32_bf16 v[16:19], v[170:173], v[200:203], v[16:19]
	v_mfma_f32_16x16x32_bf16 v[16:19], v[174:177], v[204:207], v[16:19]
	v_mfma_f32_16x16x32_bf16 v[4:7], v[162:165], v[208:211], v[4:7]
	v_mfma_f32_16x16x32_bf16 v[4:7], v[166:169], v[212:215], v[4:7]
	v_mfma_f32_16x16x32_bf16 v[0:3], v[170:173], v[208:211], v[0:3]
	v_mfma_f32_16x16x32_bf16 v[0:3], v[174:177], v[212:215], v[0:3]
	s_setprio 0
	s_barrier
.Lmid_gemm11:
	s_add_i32 s71, 0, 0x18000
	s_add_i32 s72, 0, 0x1c000
	v_add_u32_e32 v158, s71, v145
	v_add_u32_e32 v174, s72, v145
	ds_read_b128 v[140:143], v158
	ds_read_b128 v[150:153], v158 offset:1024
	ds_read_b128 v[154:157], v158 offset:2048
	ds_read_b128 v[158:161], v158 offset:3072
	ds_read_b128 v[162:165], v174
	ds_read_b128 v[166:169], v174 offset:1024
	ds_read_b128 v[170:173], v174 offset:2048
	ds_read_b128 v[174:177], v174 offset:3072
	s_add_u32 s50, s50, 0x40000
	s_addc_u32 s51, s51, 0
	s_mov_b32 m0, s57
	v_lshl_add_u64 v[222:223], s[50:51], 0, v[130:131]
	ds_read_b128 v[184:187], v149 offset:32768
	ds_read_b128 v[188:191], v149 offset:33792
	ds_read_b128 v[192:195], v149 offset:34816
	ds_read_b128 v[196:199], v149 offset:35840
	ds_read_b128 v[200:203], v149 offset:36864
	ds_read_b128 v[204:207], v149 offset:37888
	ds_read_b128 v[208:211], v149 offset:38912
	ds_read_b128 v[212:215], v149 offset:39936
	global_load_lds_dwordx4 v[222:223], off
	v_lshl_add_u64 v[222:223], s[50:51], 0, v[128:129]
	s_mov_b32 m0, s58
	s_nop 0
	global_load_lds_dwordx4 v[222:223], off
	s_waitcnt vmcnt(8)
	s_waitcnt lgkmcnt(0)
	s_barrier
	s_setprio 1
	v_mfma_f32_16x16x32_bf16 v[124:127], v[140:143], v[184:187], v[124:127]
	v_mfma_f32_16x16x32_bf16 v[124:127], v[150:153], v[188:191], v[124:127]
	v_mfma_f32_16x16x32_bf16 v[120:123], v[154:157], v[184:187], v[120:123]
	v_mfma_f32_16x16x32_bf16 v[120:123], v[158:161], v[188:191], v[120:123]
	v_mfma_f32_16x16x32_bf16 v[108:111], v[140:143], v[192:195], v[108:111]
	v_mfma_f32_16x16x32_bf16 v[108:111], v[150:153], v[196:199], v[108:111]
	v_mfma_f32_16x16x32_bf16 v[104:107], v[154:157], v[192:195], v[104:107]
	v_mfma_f32_16x16x32_bf16 v[104:107], v[158:161], v[196:199], v[104:107]
	v_mfma_f32_16x16x32_bf16 v[92:95], v[140:143], v[200:203], v[92:95]
	v_mfma_f32_16x16x32_bf16 v[92:95], v[150:153], v[204:207], v[92:95]
	v_mfma_f32_16x16x32_bf16 v[88:91], v[154:157], v[200:203], v[88:91]
	v_mfma_f32_16x16x32_bf16 v[88:91], v[158:161], v[204:207], v[88:91]
	v_mfma_f32_16x16x32_bf16 v[76:79], v[140:143], v[208:211], v[76:79]
	v_mfma_f32_16x16x32_bf16 v[76:79], v[150:153], v[212:215], v[76:79]
	v_mfma_f32_16x16x32_bf16 v[72:75], v[154:157], v[208:211], v[72:75]
	v_mfma_f32_16x16x32_bf16 v[72:75], v[158:161], v[212:215], v[72:75]
	v_mfma_f32_16x16x32_bf16 v[116:119], v[162:165], v[184:187], v[116:119]
	v_mfma_f32_16x16x32_bf16 v[116:119], v[166:169], v[188:191], v[116:119]
	v_mfma_f32_16x16x32_bf16 v[112:115], v[170:173], v[184:187], v[112:115]
	v_mfma_f32_16x16x32_bf16 v[112:115], v[174:177], v[188:191], v[112:115]
	v_mfma_f32_16x16x32_bf16 v[100:103], v[162:165], v[192:195], v[100:103]
	v_mfma_f32_16x16x32_bf16 v[100:103], v[166:169], v[196:199], v[100:103]
	v_mfma_f32_16x16x32_bf16 v[96:99], v[170:173], v[192:195], v[96:99]
	v_mfma_f32_16x16x32_bf16 v[96:99], v[174:177], v[196:199], v[96:99]
	v_mfma_f32_16x16x32_bf16 v[84:87], v[162:165], v[200:203], v[84:87]
	v_mfma_f32_16x16x32_bf16 v[84:87], v[166:169], v[204:207], v[84:87]
	v_mfma_f32_16x16x32_bf16 v[80:83], v[170:173], v[200:203], v[80:83]
	v_mfma_f32_16x16x32_bf16 v[80:83], v[174:177], v[204:207], v[80:83]
	v_mfma_f32_16x16x32_bf16 v[68:71], v[162:165], v[208:211], v[68:71]
	v_mfma_f32_16x16x32_bf16 v[68:71], v[166:169], v[212:215], v[68:71]
	v_mfma_f32_16x16x32_bf16 v[64:67], v[170:173], v[208:211], v[64:67]
	v_mfma_f32_16x16x32_bf16 v[64:67], v[174:177], v[212:215], v[64:67]
	s_setprio 0
	s_barrier
	s_add_i32 s50, s71, s54
	v_lshl_add_u64 v[178:179], v[178:179], 0, s[10:11]
	s_mov_b32 m0, s50
	ds_read_b128 v[184:187], v149 offset:49152
	ds_read_b128 v[188:191], v149 offset:50176
	ds_read_b128 v[192:195], v149 offset:51200
	ds_read_b128 v[196:199], v149 offset:52224
	ds_read_b128 v[200:203], v149 offset:53248
	ds_read_b128 v[204:207], v149 offset:54272
	ds_read_b128 v[208:211], v149 offset:55296
	ds_read_b128 v[212:215], v149 offset:56320
	global_load_lds_dwordx4 v[178:179], off
	s_add_i32 m0, s50, 0x2000
	s_add_u32 s48, s48, 0x40080
	v_lshl_add_u64 v[178:179], v[216:217], 0, s[10:11]
	s_addc_u32 s49, s49, 0
	s_add_i32 s50, s72, s54
	global_load_lds_dwordx4 v[178:179], off
	v_lshl_add_u64 v[178:179], s[48:49], 0, v[130:131]
	s_mov_b32 m0, s50
	s_nop 0
	global_load_lds_dwordx4 v[178:179], off
	v_lshl_add_u64 v[178:179], s[48:49], 0, v[128:129]
	s_add_i32 m0, s50, 0x2000
	s_nop 0
	global_load_lds_dwordx4 v[178:179], off
	v_lshl_add_u64 v[178:179], v[218:219], 0, s[10:11]
	s_mov_b32 m0, s60
	s_nop 0
	global_load_lds_dwordx4 v[178:179], off
	v_lshl_add_u64 v[178:179], v[220:221], 0, s[10:11]
	s_mov_b32 m0, s61
	s_nop 0
	global_load_lds_dwordx4 v[178:179], off
	s_waitcnt vmcnt(8)
	s_waitcnt lgkmcnt(0)
	s_barrier
	s_setprio 1
	v_mfma_f32_16x16x32_bf16 v[60:63], v[140:143], v[184:187], v[60:63]
	v_mfma_f32_16x16x32_bf16 v[60:63], v[150:153], v[188:191], v[60:63]
	v_mfma_f32_16x16x32_bf16 v[56:59], v[154:157], v[184:187], v[56:59]
	v_mfma_f32_16x16x32_bf16 v[56:59], v[158:161], v[188:191], v[56:59]
	v_mfma_f32_16x16x32_bf16 v[44:47], v[140:143], v[192:195], v[44:47]
	v_mfma_f32_16x16x32_bf16 v[44:47], v[150:153], v[196:199], v[44:47]
	v_mfma_f32_16x16x32_bf16 v[40:43], v[154:157], v[192:195], v[40:43]
	v_mfma_f32_16x16x32_bf16 v[40:43], v[158:161], v[196:199], v[40:43]
	v_mfma_f32_16x16x32_bf16 v[28:31], v[140:143], v[200:203], v[28:31]
	v_mfma_f32_16x16x32_bf16 v[28:31], v[150:153], v[204:207], v[28:31]
	v_mfma_f32_16x16x32_bf16 v[24:27], v[154:157], v[200:203], v[24:27]
	v_mfma_f32_16x16x32_bf16 v[24:27], v[158:161], v[204:207], v[24:27]
	v_mfma_f32_16x16x32_bf16 v[12:15], v[140:143], v[208:211], v[12:15]
	v_mfma_f32_16x16x32_bf16 v[12:15], v[150:153], v[212:215], v[12:15]
	v_mfma_f32_16x16x32_bf16 v[8:11], v[154:157], v[208:211], v[8:11]
	v_mfma_f32_16x16x32_bf16 v[8:11], v[158:161], v[212:215], v[8:11]
	v_mfma_f32_16x16x32_bf16 v[52:55], v[162:165], v[184:187], v[52:55]
	v_mfma_f32_16x16x32_bf16 v[52:55], v[166:169], v[188:191], v[52:55]
	v_mfma_f32_16x16x32_bf16 v[48:51], v[170:173], v[184:187], v[48:51]
	v_mfma_f32_16x16x32_bf16 v[48:51], v[174:177], v[188:191], v[48:51]
	v_mfma_f32_16x16x32_bf16 v[36:39], v[162:165], v[192:195], v[36:39]
	v_mfma_f32_16x16x32_bf16 v[36:39], v[166:169], v[196:199], v[36:39]
	v_mfma_f32_16x16x32_bf16 v[32:35], v[170:173], v[192:195], v[32:35]
	v_mfma_f32_16x16x32_bf16 v[32:35], v[174:177], v[196:199], v[32:35]
	v_mfma_f32_16x16x32_bf16 v[20:23], v[162:165], v[200:203], v[20:23]
	v_mfma_f32_16x16x32_bf16 v[20:23], v[166:169], v[204:207], v[20:23]
	v_mfma_f32_16x16x32_bf16 v[16:19], v[170:173], v[200:203], v[16:19]
	v_mfma_f32_16x16x32_bf16 v[16:19], v[174:177], v[204:207], v[16:19]
	v_mfma_f32_16x16x32_bf16 v[4:7], v[162:165], v[208:211], v[4:7]
	v_mfma_f32_16x16x32_bf16 v[4:7], v[166:169], v[212:215], v[4:7]
	v_mfma_f32_16x16x32_bf16 v[0:3], v[170:173], v[208:211], v[0:3]
	v_mfma_f32_16x16x32_bf16 v[0:3], v[174:177], v[212:215], v[0:3]
	s_setprio 0
	s_barrier
	s_add_i32 s70, s70, 2
	s_add_u32 s46, s46, 0x100
	s_addc_u32 s47, s47, 0
	s_add_u32 s68, s68, 0x100
	s_addc_u32 s69, s69, 0
	s_cmp_gt_u32 s70, 13
	s_cbranch_scc0 .LBB0_1434
	s_and_b64 vcc, exec, s[12:13]
	s_cbranch_vccz .LBB0_1437
	s_barrier

.LBB0_1513:
	s_add_u32 s74, s48, 0x100
	s_addc_u32 s75, s49, 0
	s_mov_b32 s76, -2
	ds_read_b128 v[152:155], v149
	ds_read_b128 v[156:159], v149 offset:1024
	ds_read_b128 v[160:163], v149 offset:2048
	ds_read_b128 v[164:167], v149 offset:3072
	ds_read_b128 v[168:171], v150
	ds_read_b128 v[172:175], v150 offset:1024
	ds_read_b128 v[176:179], v150 offset:2048
	ds_read_b128 v[184:187], v150 offset:3072
	s_add_u32 s48, s46, 0x100
	s_addc_u32 s49, s47, 0
	s_cmp_eq_u32 s76, 40
	s_cselect_b32 s53, s9, s49
	s_cselect_b32 s52, s8, s48
	s_cselect_b32 s51, s45, s75
	s_cselect_b32 s50, s44, s74
	v_lshl_add_u64 v[144:145], s[46:47], 0, v[136:137]
	s_add_i32 m0, s57, 0xc000
	ds_read_b128 v[188:191], v151
	ds_read_b128 v[192:195], v151 offset:1024
	ds_read_b128 v[196:199], v151 offset:2048
	ds_read_b128 v[200:203], v151 offset:3072
	ds_read_b128 v[204:207], v151 offset:4096
	ds_read_b128 v[208:211], v151 offset:5120
	ds_read_b128 v[212:215], v151 offset:6144
	ds_read_b128 v[216:219], v151 offset:7168
	global_load_lds_dwordx4 v[144:145], off
	v_lshl_add_u64 v[144:145], s[46:47], 0, v[138:139]
	s_add_i32 m0, s57, 0xe000
	s_nop 0
	global_load_lds_dwordx4 v[144:145], off
	s_waitcnt vmcnt(8)
	s_waitcnt lgkmcnt(0)
	s_barrier
	s_setprio 1
	v_mfma_f32_16x16x32_bf16 v[124:127], v[152:155], v[188:191], 0
	v_mfma_f32_16x16x32_bf16 v[124:127], v[156:159], v[192:195], v[124:127]
	v_mfma_f32_16x16x32_bf16 v[120:123], v[160:163], v[188:191], 0
	v_mfma_f32_16x16x32_bf16 v[120:123], v[164:167], v[192:195], v[120:123]
	v_mfma_f32_16x16x32_bf16 v[116:119], v[152:155], v[196:199], 0
	v_mfma_f32_16x16x32_bf16 v[116:119], v[156:159], v[200:203], v[116:119]
	v_mfma_f32_16x16x32_bf16 v[108:111], v[160:163], v[196:199], 0
	v_mfma_f32_16x16x32_bf16 v[108:111], v[164:167], v[200:203], v[108:111]
	v_mfma_f32_16x16x32_bf16 v[100:103], v[152:155], v[204:207], 0
	v_mfma_f32_16x16x32_bf16 v[100:103], v[156:159], v[208:211], v[100:103]
	v_mfma_f32_16x16x32_bf16 v[92:95], v[160:163], v[204:207], 0
	v_mfma_f32_16x16x32_bf16 v[92:95], v[164:167], v[208:211], v[92:95]
	v_mfma_f32_16x16x32_bf16 v[84:87], v[152:155], v[212:215], 0
	v_mfma_f32_16x16x32_bf16 v[84:87], v[156:159], v[216:219], v[84:87]
	v_mfma_f32_16x16x32_bf16 v[76:79], v[160:163], v[212:215], 0
	v_mfma_f32_16x16x32_bf16 v[76:79], v[164:167], v[216:219], v[76:79]
	v_mfma_f32_16x16x32_bf16 v[112:115], v[168:171], v[188:191], 0
	v_mfma_f32_16x16x32_bf16 v[112:115], v[172:175], v[192:195], v[112:115]
	v_mfma_f32_16x16x32_bf16 v[104:107], v[176:179], v[188:191], 0
	v_mfma_f32_16x16x32_bf16 v[104:107], v[184:187], v[192:195], v[104:107]
	v_mfma_f32_16x16x32_bf16 v[96:99], v[168:171], v[196:199], 0
	v_mfma_f32_16x16x32_bf16 v[96:99], v[172:175], v[200:203], v[96:99]
	v_mfma_f32_16x16x32_bf16 v[88:91], v[176:179], v[196:199], 0
	v_mfma_f32_16x16x32_bf16 v[88:91], v[184:187], v[200:203], v[88:91]
	v_mfma_f32_16x16x32_bf16 v[80:83], v[168:171], v[204:207], 0
	v_mfma_f32_16x16x32_bf16 v[80:83], v[172:175], v[208:211], v[80:83]
	v_mfma_f32_16x16x32_bf16 v[72:75], v[176:179], v[204:207], 0
	v_mfma_f32_16x16x32_bf16 v[72:75], v[184:187], v[208:211], v[72:75]
	v_mfma_f32_16x16x32_bf16 v[68:71], v[168:171], v[212:215], 0
	v_mfma_f32_16x16x32_bf16 v[68:71], v[172:175], v[216:219], v[68:71]
	v_mfma_f32_16x16x32_bf16 v[64:67], v[176:179], v[212:215], 0
	v_mfma_f32_16x16x32_bf16 v[64:67], v[184:187], v[216:219], v[64:67]
	s_setprio 0
	s_barrier
	s_add_i32 s46, s64, s56
	v_lshl_add_u64 v[144:145], s[50:51], 0, v[130:131]
	s_mov_b32 m0, s46
	ds_read_b128 v[188:191], v151 offset:16384
	ds_read_b128 v[192:195], v151 offset:17408
	ds_read_b128 v[196:199], v151 offset:18432
	ds_read_b128 v[200:203], v151 offset:19456
	ds_read_b128 v[204:207], v151 offset:20480
	ds_read_b128 v[208:211], v151 offset:21504
	ds_read_b128 v[212:215], v151 offset:22528
	ds_read_b128 v[216:219], v151 offset:23552
	global_load_lds_dwordx4 v[144:145], off
	s_add_i32 m0, s46, 0x2000
	s_add_u32 s46, s50, 0xb0000
	v_lshl_add_u64 v[220:221], s[50:51], 0, v[134:135]
	s_addc_u32 s47, s51, 0
	s_add_i32 s77, s65, s56
	global_load_lds_dwordx4 v[220:221], off
	v_lshl_add_u64 v[222:223], s[46:47], 0, v[130:131]
	s_mov_b32 m0, s77
	v_lshl_add_u64 v[224:225], s[52:53], 0, v[132:133]
	global_load_lds_dwordx4 v[222:223], off
	v_lshl_add_u64 v[222:223], s[46:47], 0, v[134:135]
	s_add_i32 m0, s77, 0x2000
	s_nop 0
	global_load_lds_dwordx4 v[222:223], off
	v_lshl_add_u64 v[222:223], s[52:53], 0, v[128:129]
	s_mov_b32 m0, s57
	s_nop 0
	global_load_lds_dwordx4 v[222:223], off
	s_mov_b32 m0, s58
	s_nop 0
	global_load_lds_dwordx4 v[224:225], off
	s_waitcnt vmcnt(8)
	s_waitcnt lgkmcnt(0)
	s_barrier
	s_setprio 1
	v_mfma_f32_16x16x32_bf16 v[60:63], v[152:155], v[188:191], 0
	v_mfma_f32_16x16x32_bf16 v[60:63], v[156:159], v[192:195], v[60:63]
	v_mfma_f32_16x16x32_bf16 v[56:59], v[160:163], v[188:191], 0
	v_mfma_f32_16x16x32_bf16 v[56:59], v[164:167], v[192:195], v[56:59]
	v_mfma_f32_16x16x32_bf16 v[52:55], v[152:155], v[196:199], 0
	v_mfma_f32_16x16x32_bf16 v[52:55], v[156:159], v[200:203], v[52:55]
	v_mfma_f32_16x16x32_bf16 v[44:47], v[160:163], v[196:199], 0
	v_mfma_f32_16x16x32_bf16 v[44:47], v[164:167], v[200:203], v[44:47]
	v_mfma_f32_16x16x32_bf16 v[36:39], v[152:155], v[204:207], 0
	v_mfma_f32_16x16x32_bf16 v[36:39], v[156:159], v[208:211], v[36:39]
	v_mfma_f32_16x16x32_bf16 v[28:31], v[160:163], v[204:207], 0
	v_mfma_f32_16x16x32_bf16 v[28:31], v[164:167], v[208:211], v[28:31]
	v_mfma_f32_16x16x32_bf16 v[20:23], v[152:155], v[212:215], 0
	v_mfma_f32_16x16x32_bf16 v[20:23], v[156:159], v[216:219], v[20:23]
	v_mfma_f32_16x16x32_bf16 v[12:15], v[160:163], v[212:215], 0
	v_mfma_f32_16x16x32_bf16 v[12:15], v[164:167], v[216:219], v[12:15]
	v_mfma_f32_16x16x32_bf16 v[48:51], v[168:171], v[188:191], 0
	v_mfma_f32_16x16x32_bf16 v[48:51], v[172:175], v[192:195], v[48:51]
	v_mfma_f32_16x16x32_bf16 v[40:43], v[176:179], v[188:191], 0
	v_mfma_f32_16x16x32_bf16 v[40:43], v[184:187], v[192:195], v[40:43]
	v_mfma_f32_16x16x32_bf16 v[32:35], v[168:171], v[196:199], 0
	v_mfma_f32_16x16x32_bf16 v[32:35], v[172:175], v[200:203], v[32:35]
	v_mfma_f32_16x16x32_bf16 v[24:27], v[176:179], v[196:199], 0
	v_mfma_f32_16x16x32_bf16 v[24:27], v[184:187], v[200:203], v[24:27]
	v_mfma_f32_16x16x32_bf16 v[16:19], v[168:171], v[204:207], 0
	v_mfma_f32_16x16x32_bf16 v[16:19], v[172:175], v[208:211], v[16:19]
	v_mfma_f32_16x16x32_bf16 v[8:11], v[176:179], v[204:207], 0
	v_mfma_f32_16x16x32_bf16 v[8:11], v[184:187], v[208:211], v[8:11]
	v_mfma_f32_16x16x32_bf16 v[4:7], v[168:171], v[212:215], 0
	v_mfma_f32_16x16x32_bf16 v[4:7], v[172:175], v[216:219], v[4:7]
	v_mfma_f32_16x16x32_bf16 v[0:3], v[176:179], v[212:215], 0
	v_mfma_f32_16x16x32_bf16 v[0:3], v[184:187], v[216:219], v[0:3]
	s_setprio 0
	s_barrier
	s_branch .Lmid_gemm12
.LBB0_1514:
	ds_read_b128 v[152:155], v149
	ds_read_b128 v[156:159], v149 offset:1024
	ds_read_b128 v[160:163], v149 offset:2048
	ds_read_b128 v[164:167], v149 offset:3072
	ds_read_b128 v[168:171], v150
	ds_read_b128 v[172:175], v150 offset:1024
	ds_read_b128 v[176:179], v150 offset:2048
	ds_read_b128 v[184:187], v150 offset:3072
	s_add_u32 s48, s46, 0x100
	s_addc_u32 s49, s47, 0
	s_cmp_eq_u32 s76, 40
	s_cselect_b32 s53, s9, s49
	s_cselect_b32 s52, s8, s48
	s_cselect_b32 s51, s45, s75
	s_cselect_b32 s50, s44, s74
	v_lshl_add_u64 v[144:145], s[46:47], 0, v[136:137]
	s_add_i32 m0, s57, 0xc000
	ds_read_b128 v[188:191], v151
	ds_read_b128 v[192:195], v151 offset:1024
	ds_read_b128 v[196:199], v151 offset:2048
	ds_read_b128 v[200:203], v151 offset:3072
	ds_read_b128 v[204:207], v151 offset:4096
	ds_read_b128 v[208:211], v151 offset:5120
	ds_read_b128 v[212:215], v151 offset:6144
	ds_read_b128 v[216:219], v151 offset:7168
	global_load_lds_dwordx4 v[144:145], off
	v_lshl_add_u64 v[144:145], s[46:47], 0, v[138:139]
	s_add_i32 m0, s57, 0xe000
	s_nop 0
	global_load_lds_dwordx4 v[144:145], off
	s_waitcnt vmcnt(8)
	s_waitcnt lgkmcnt(0)
	s_barrier
	s_setprio 1
	v_mfma_f32_16x16x32_bf16 v[124:127], v[152:155], v[188:191], v[124:127]
	v_mfma_f32_16x16x32_bf16 v[124:127], v[156:159], v[192:195], v[124:127]
	v_mfma_f32_16x16x32_bf16 v[120:123], v[160:163], v[188:191], v[120:123]
	v_mfma_f32_16x16x32_bf16 v[120:123], v[164:167], v[192:195], v[120:123]
	v_mfma_f32_16x16x32_bf16 v[116:119], v[152:155], v[196:199], v[116:119]
	v_mfma_f32_16x16x32_bf16 v[116:119], v[156:159], v[200:203], v[116:119]
	v_mfma_f32_16x16x32_bf16 v[108:111], v[160:163], v[196:199], v[108:111]
	v_mfma_f32_16x16x32_bf16 v[108:111], v[164:167], v[200:203], v[108:111]
	v_mfma_f32_16x16x32_bf16 v[100:103], v[152:155], v[204:207], v[100:103]
	v_mfma_f32_16x16x32_bf16 v[100:103], v[156:159], v[208:211], v[100:103]
	v_mfma_f32_16x16x32_bf16 v[92:95], v[160:163], v[204:207], v[92:95]
	v_mfma_f32_16x16x32_bf16 v[92:95], v[164:167], v[208:211], v[92:95]
	v_mfma_f32_16x16x32_bf16 v[84:87], v[152:155], v[212:215], v[84:87]
	v_mfma_f32_16x16x32_bf16 v[84:87], v[156:159], v[216:219], v[84:87]
	v_mfma_f32_16x16x32_bf16 v[76:79], v[160:163], v[212:215], v[76:79]
	v_mfma_f32_16x16x32_bf16 v[76:79], v[164:167], v[216:219], v[76:79]
	v_mfma_f32_16x16x32_bf16 v[112:115], v[168:171], v[188:191], v[112:115]
	v_mfma_f32_16x16x32_bf16 v[112:115], v[172:175], v[192:195], v[112:115]
	v_mfma_f32_16x16x32_bf16 v[104:107], v[176:179], v[188:191], v[104:107]
	v_mfma_f32_16x16x32_bf16 v[104:107], v[184:187], v[192:195], v[104:107]
	v_mfma_f32_16x16x32_bf16 v[96:99], v[168:171], v[196:199], v[96:99]
	v_mfma_f32_16x16x32_bf16 v[96:99], v[172:175], v[200:203], v[96:99]
	v_mfma_f32_16x16x32_bf16 v[88:91], v[176:179], v[196:199], v[88:91]
	v_mfma_f32_16x16x32_bf16 v[88:91], v[184:187], v[200:203], v[88:91]
	v_mfma_f32_16x16x32_bf16 v[80:83], v[168:171], v[204:207], v[80:83]
	v_mfma_f32_16x16x32_bf16 v[80:83], v[172:175], v[208:211], v[80:83]
	v_mfma_f32_16x16x32_bf16 v[72:75], v[176:179], v[204:207], v[72:75]
	v_mfma_f32_16x16x32_bf16 v[72:75], v[184:187], v[208:211], v[72:75]
	v_mfma_f32_16x16x32_bf16 v[68:71], v[168:171], v[212:215], v[68:71]
	v_mfma_f32_16x16x32_bf16 v[68:71], v[172:175], v[216:219], v[68:71]
	v_mfma_f32_16x16x32_bf16 v[64:67], v[176:179], v[212:215], v[64:67]
	v_mfma_f32_16x16x32_bf16 v[64:67], v[184:187], v[216:219], v[64:67]
	s_setprio 0
	s_barrier
	s_add_i32 s46, s64, s56
	v_lshl_add_u64 v[144:145], s[50:51], 0, v[130:131]
	s_mov_b32 m0, s46
	ds_read_b128 v[188:191], v151 offset:16384
	ds_read_b128 v[192:195], v151 offset:17408
	ds_read_b128 v[196:199], v151 offset:18432
	ds_read_b128 v[200:203], v151 offset:19456
	ds_read_b128 v[204:207], v151 offset:20480
	ds_read_b128 v[208:211], v151 offset:21504
	ds_read_b128 v[212:215], v151 offset:22528
	ds_read_b128 v[216:219], v151 offset:23552
	global_load_lds_dwordx4 v[144:145], off
	s_add_i32 m0, s46, 0x2000
	s_add_u32 s46, s50, 0xb0000
	v_lshl_add_u64 v[220:221], s[50:51], 0, v[134:135]
	s_addc_u32 s47, s51, 0
	s_add_i32 s77, s65, s56
	global_load_lds_dwordx4 v[220:221], off
	v_lshl_add_u64 v[222:223], s[46:47], 0, v[130:131]
	s_mov_b32 m0, s77
	v_lshl_add_u64 v[224:225], s[52:53], 0, v[132:133]
	global_load_lds_dwordx4 v[222:223], off
	v_lshl_add_u64 v[222:223], s[46:47], 0, v[134:135]
	s_add_i32 m0, s77, 0x2000
	s_nop 0
	global_load_lds_dwordx4 v[222:223], off
	v_lshl_add_u64 v[222:223], s[52:53], 0, v[128:129]
	s_mov_b32 m0, s57
	s_nop 0
	global_load_lds_dwordx4 v[222:223], off
	s_mov_b32 m0, s58
	s_nop 0
	global_load_lds_dwordx4 v[224:225], off
	s_waitcnt vmcnt(8)
	s_waitcnt lgkmcnt(0)
	s_barrier
	s_setprio 1
	v_mfma_f32_16x16x32_bf16 v[60:63], v[152:155], v[188:191], v[60:63]
	v_mfma_f32_16x16x32_bf16 v[60:63], v[156:159], v[192:195], v[60:63]
	v_mfma_f32_16x16x32_bf16 v[56:59], v[160:163], v[188:191], v[56:59]
	v_mfma_f32_16x16x32_bf16 v[56:59], v[164:167], v[192:195], v[56:59]
	v_mfma_f32_16x16x32_bf16 v[52:55], v[152:155], v[196:199], v[52:55]
	v_mfma_f32_16x16x32_bf16 v[52:55], v[156:159], v[200:203], v[52:55]
	v_mfma_f32_16x16x32_bf16 v[44:47], v[160:163], v[196:199], v[44:47]
	v_mfma_f32_16x16x32_bf16 v[44:47], v[164:167], v[200:203], v[44:47]
	v_mfma_f32_16x16x32_bf16 v[36:39], v[152:155], v[204:207], v[36:39]
	v_mfma_f32_16x16x32_bf16 v[36:39], v[156:159], v[208:211], v[36:39]
	v_mfma_f32_16x16x32_bf16 v[28:31], v[160:163], v[204:207], v[28:31]
	v_mfma_f32_16x16x32_bf16 v[28:31], v[164:167], v[208:211], v[28:31]
	v_mfma_f32_16x16x32_bf16 v[20:23], v[152:155], v[212:215], v[20:23]
	v_mfma_f32_16x16x32_bf16 v[20:23], v[156:159], v[216:219], v[20:23]
	v_mfma_f32_16x16x32_bf16 v[12:15], v[160:163], v[212:215], v[12:15]
	v_mfma_f32_16x16x32_bf16 v[12:15], v[164:167], v[216:219], v[12:15]
	v_mfma_f32_16x16x32_bf16 v[48:51], v[168:171], v[188:191], v[48:51]
	v_mfma_f32_16x16x32_bf16 v[48:51], v[172:175], v[192:195], v[48:51]
	v_mfma_f32_16x16x32_bf16 v[40:43], v[176:179], v[188:191], v[40:43]
	v_mfma_f32_16x16x32_bf16 v[40:43], v[184:187], v[192:195], v[40:43]
	v_mfma_f32_16x16x32_bf16 v[32:35], v[168:171], v[196:199], v[32:35]
	v_mfma_f32_16x16x32_bf16 v[32:35], v[172:175], v[200:203], v[32:35]
	v_mfma_f32_16x16x32_bf16 v[24:27], v[176:179], v[196:199], v[24:27]
	v_mfma_f32_16x16x32_bf16 v[24:27], v[184:187], v[200:203], v[24:27]
	v_mfma_f32_16x16x32_bf16 v[16:19], v[168:171], v[204:207], v[16:19]
	v_mfma_f32_16x16x32_bf16 v[16:19], v[172:175], v[208:211], v[16:19]
	v_mfma_f32_16x16x32_bf16 v[8:11], v[176:179], v[204:207], v[8:11]
	v_mfma_f32_16x16x32_bf16 v[8:11], v[184:187], v[208:211], v[8:11]
	v_mfma_f32_16x16x32_bf16 v[4:7], v[168:171], v[212:215], v[4:7]
	v_mfma_f32_16x16x32_bf16 v[4:7], v[172:175], v[216:219], v[4:7]
	v_mfma_f32_16x16x32_bf16 v[0:3], v[176:179], v[212:215], v[0:3]
	v_mfma_f32_16x16x32_bf16 v[0:3], v[184:187], v[216:219], v[0:3]
	s_setprio 0
	s_barrier
.Lmid_gemm12:
	s_add_i32 s77, 0, 0x18000
	s_add_i32 s79, 0, 0x1c000
	v_add_u32_e32 v164, s77, v147
	v_add_u32_e32 v181, s79, v147
	ds_read_b128 v[152:155], v164
	ds_read_b128 v[156:159], v164 offset:1024
	ds_read_b128 v[160:163], v164 offset:2048
	ds_read_b128 v[164:167], v164 offset:3072
	ds_read_b128 v[168:171], v181
	ds_read_b128 v[172:175], v181 offset:1024
	ds_read_b128 v[176:179], v181 offset:2048
	ds_read_b128 v[184:187], v181 offset:3072
	s_add_u32 s46, s52, 0xb0000
	s_addc_u32 s47, s53, 0
	s_mov_b32 m0, s59
	v_lshl_add_u64 v[226:227], s[46:47], 0, v[128:129]
	ds_read_b128 v[188:191], v151 offset:32768
	ds_read_b128 v[192:195], v151 offset:33792
	ds_read_b128 v[196:199], v151 offset:34816
	ds_read_b128 v[200:203], v151 offset:35840
	ds_read_b128 v[204:207], v151 offset:36864
	ds_read_b128 v[208:211], v151 offset:37888
	ds_read_b128 v[212:215], v151 offset:38912
	ds_read_b128 v[216:219], v151 offset:39936
	global_load_lds_dwordx4 v[226:227], off
	v_lshl_add_u64 v[226:227], s[46:47], 0, v[132:133]
	s_mov_b32 m0, s60
	s_nop 0
	global_load_lds_dwordx4 v[226:227], off
	s_waitcnt vmcnt(8)
	s_waitcnt lgkmcnt(0)
	s_barrier
	s_setprio 1
	v_mfma_f32_16x16x32_bf16 v[124:127], v[152:155], v[188:191], v[124:127]
	v_mfma_f32_16x16x32_bf16 v[124:127], v[156:159], v[192:195], v[124:127]
	v_mfma_f32_16x16x32_bf16 v[120:123], v[160:163], v[188:191], v[120:123]
	v_mfma_f32_16x16x32_bf16 v[120:123], v[164:167], v[192:195], v[120:123]
	v_mfma_f32_16x16x32_bf16 v[116:119], v[152:155], v[196:199], v[116:119]
	v_mfma_f32_16x16x32_bf16 v[116:119], v[156:159], v[200:203], v[116:119]
	v_mfma_f32_16x16x32_bf16 v[108:111], v[160:163], v[196:199], v[108:111]
	v_mfma_f32_16x16x32_bf16 v[108:111], v[164:167], v[200:203], v[108:111]
	v_mfma_f32_16x16x32_bf16 v[100:103], v[152:155], v[204:207], v[100:103]
	v_mfma_f32_16x16x32_bf16 v[100:103], v[156:159], v[208:211], v[100:103]
	v_mfma_f32_16x16x32_bf16 v[92:95], v[160:163], v[204:207], v[92:95]
	v_mfma_f32_16x16x32_bf16 v[92:95], v[164:167], v[208:211], v[92:95]
	v_mfma_f32_16x16x32_bf16 v[84:87], v[152:155], v[212:215], v[84:87]
	v_mfma_f32_16x16x32_bf16 v[84:87], v[156:159], v[216:219], v[84:87]
	v_mfma_f32_16x16x32_bf16 v[76:79], v[160:163], v[212:215], v[76:79]
	v_mfma_f32_16x16x32_bf16 v[76:79], v[164:167], v[216:219], v[76:79]
	v_mfma_f32_16x16x32_bf16 v[112:115], v[168:171], v[188:191], v[112:115]
	v_mfma_f32_16x16x32_bf16 v[112:115], v[172:175], v[192:195], v[112:115]
	v_mfma_f32_16x16x32_bf16 v[104:107], v[176:179], v[188:191], v[104:107]
	v_mfma_f32_16x16x32_bf16 v[104:107], v[184:187], v[192:195], v[104:107]
	v_mfma_f32_16x16x32_bf16 v[96:99], v[168:171], v[196:199], v[96:99]
	v_mfma_f32_16x16x32_bf16 v[96:99], v[172:175], v[200:203], v[96:99]
	v_mfma_f32_16x16x32_bf16 v[88:91], v[176:179], v[196:199], v[88:91]
	v_mfma_f32_16x16x32_bf16 v[88:91], v[184:187], v[200:203], v[88:91]
	v_mfma_f32_16x16x32_bf16 v[80:83], v[168:171], v[204:207], v[80:83]
	v_mfma_f32_16x16x32_bf16 v[80:83], v[172:175], v[208:211], v[80:83]
	v_mfma_f32_16x16x32_bf16 v[72:75], v[176:179], v[204:207], v[72:75]
	v_mfma_f32_16x16x32_bf16 v[72:75], v[184:187], v[208:211], v[72:75]
	v_mfma_f32_16x16x32_bf16 v[68:71], v[168:171], v[212:215], v[68:71]
	v_mfma_f32_16x16x32_bf16 v[68:71], v[172:175], v[216:219], v[68:71]
	v_mfma_f32_16x16x32_bf16 v[64:67], v[176:179], v[212:215], v[64:67]
	v_mfma_f32_16x16x32_bf16 v[64:67], v[184:187], v[216:219], v[64:67]
	s_setprio 0
	s_barrier
	s_add_i32 s46, s77, s56
	v_lshl_add_u64 v[144:145], v[144:145], 0, s[10:11]
	s_mov_b32 m0, s46
	ds_read_b128 v[188:191], v151 offset:49152
	ds_read_b128 v[192:195], v151 offset:50176
	ds_read_b128 v[196:199], v151 offset:51200
	ds_read_b128 v[200:203], v151 offset:52224
	ds_read_b128 v[204:207], v151 offset:53248
	ds_read_b128 v[208:211], v151 offset:54272
	ds_read_b128 v[212:215], v151 offset:55296
	ds_read_b128 v[216:219], v151 offset:56320
	global_load_lds_dwordx4 v[144:145], off
	s_add_i32 m0, s46, 0x2000
	s_add_u32 s46, s50, 0xb0080
	v_lshl_add_u64 v[144:145], v[220:221], 0, s[10:11]
	s_addc_u32 s47, s51, 0
	s_add_i32 s50, s79, s56
	global_load_lds_dwordx4 v[144:145], off
	v_lshl_add_u64 v[144:145], s[46:47], 0, v[130:131]
	s_mov_b32 m0, s50
	s_nop 0
	global_load_lds_dwordx4 v[144:145], off
	v_lshl_add_u64 v[144:145], s[46:47], 0, v[134:135]
	s_add_i32 m0, s50, 0x2000
	s_nop 0
	global_load_lds_dwordx4 v[144:145], off
	v_lshl_add_u64 v[144:145], v[222:223], 0, s[10:11]
	s_mov_b32 m0, s62
	s_nop 0
	global_load_lds_dwordx4 v[144:145], off
	v_lshl_add_u64 v[144:145], v[224:225], 0, s[10:11]
	s_mov_b32 m0, s63
	s_nop 0
	global_load_lds_dwordx4 v[144:145], off
	s_waitcnt vmcnt(8)
	s_waitcnt lgkmcnt(0)
	s_barrier
	s_setprio 1
	v_mfma_f32_16x16x32_bf16 v[60:63], v[152:155], v[188:191], v[60:63]
	v_mfma_f32_16x16x32_bf16 v[60:63], v[156:159], v[192:195], v[60:63]
	v_mfma_f32_16x16x32_bf16 v[56:59], v[160:163], v[188:191], v[56:59]
	v_mfma_f32_16x16x32_bf16 v[56:59], v[164:167], v[192:195], v[56:59]
	v_mfma_f32_16x16x32_bf16 v[52:55], v[152:155], v[196:199], v[52:55]
	v_mfma_f32_16x16x32_bf16 v[52:55], v[156:159], v[200:203], v[52:55]
	v_mfma_f32_16x16x32_bf16 v[44:47], v[160:163], v[196:199], v[44:47]
	v_mfma_f32_16x16x32_bf16 v[44:47], v[164:167], v[200:203], v[44:47]
	v_mfma_f32_16x16x32_bf16 v[36:39], v[152:155], v[204:207], v[36:39]
	v_mfma_f32_16x16x32_bf16 v[36:39], v[156:159], v[208:211], v[36:39]
	v_mfma_f32_16x16x32_bf16 v[28:31], v[160:163], v[204:207], v[28:31]
	v_mfma_f32_16x16x32_bf16 v[28:31], v[164:167], v[208:211], v[28:31]
	v_mfma_f32_16x16x32_bf16 v[20:23], v[152:155], v[212:215], v[20:23]
	v_mfma_f32_16x16x32_bf16 v[20:23], v[156:159], v[216:219], v[20:23]
	v_mfma_f32_16x16x32_bf16 v[12:15], v[160:163], v[212:215], v[12:15]
	v_mfma_f32_16x16x32_bf16 v[12:15], v[164:167], v[216:219], v[12:15]
	v_mfma_f32_16x16x32_bf16 v[48:51], v[168:171], v[188:191], v[48:51]
	v_mfma_f32_16x16x32_bf16 v[48:51], v[172:175], v[192:195], v[48:51]
	v_mfma_f32_16x16x32_bf16 v[40:43], v[176:179], v[188:191], v[40:43]
	v_mfma_f32_16x16x32_bf16 v[40:43], v[184:187], v[192:195], v[40:43]
	v_mfma_f32_16x16x32_bf16 v[32:35], v[168:171], v[196:199], v[32:35]
	v_mfma_f32_16x16x32_bf16 v[32:35], v[172:175], v[200:203], v[32:35]
	v_mfma_f32_16x16x32_bf16 v[24:27], v[176:179], v[196:199], v[24:27]
	v_mfma_f32_16x16x32_bf16 v[24:27], v[184:187], v[200:203], v[24:27]
	v_mfma_f32_16x16x32_bf16 v[16:19], v[168:171], v[204:207], v[16:19]
	v_mfma_f32_16x16x32_bf16 v[16:19], v[172:175], v[208:211], v[16:19]
	v_mfma_f32_16x16x32_bf16 v[8:11], v[176:179], v[204:207], v[8:11]
	v_mfma_f32_16x16x32_bf16 v[8:11], v[184:187], v[208:211], v[8:11]
	v_mfma_f32_16x16x32_bf16 v[4:7], v[168:171], v[212:215], v[4:7]
	v_mfma_f32_16x16x32_bf16 v[4:7], v[172:175], v[216:219], v[4:7]
	v_mfma_f32_16x16x32_bf16 v[0:3], v[176:179], v[212:215], v[0:3]
	v_mfma_f32_16x16x32_bf16 v[0:3], v[184:187], v[216:219], v[0:3]
	s_setprio 0
	s_barrier
	s_add_i32 s76, s76, 2
	s_add_u32 s74, s74, 0x100
	s_addc_u32 s75, s75, 0
	s_cmp_gt_u32 s76, 41
	s_mov_b64 s[46:47], s[48:49]
	s_cbranch_scc0 .LBB0_1514
	s_and_b64 vcc, exec, s[12:13]
	s_cbranch_vccz .LBB0_1517
	s_barrier
